# sc1 (agent-scope, write-through) on all 288 GEMM-epilogue dwordx4 stores so the grid barriers' L2 write-back has less dirty data
# baseline (speedup 1.0000x reference)
; __device__ __forceinline__ unsigned cvtpk(float lo, float hi) { f32x2v_ v = {lo, hi}; bf16x2v_ b = __builtin_convertvector(v, bf16x2v_); return __builtin_bit_cast(unsigned, b); }
; __device__ __forceinline__ float row_rs(const float* ssp, int row) { const unsigned long long v = ((const unsigned long long*)ssp)[row];
;     return __builtin_amdgcn_rsqf((float)v * (1.0f / 4294967296.0f) * (1.0f / 1024.0f) + RMS_EPS); }
;     __device__ __forceinline__ void operator()(const f32x4 (&acc)[2][2][4][2], const Unit& u, int wr, int wc, int fr, int fq) const {
;     ...
;             for (int m = 0; m < 4; ++m) { const int row = row0 + ai * HALF + m * 16; const float rs = row_rs(ss, row);
;                 float hv[8];
; #pragma unroll
;                 for (int n = 0; n < 2; ++n)
; #pragma unroll
;                     for (int i = 0; i < 4; ++i) { const float g = acc[ai][0][m][n][i] * rs, uu = acc[ai][1][m][n][i] * rs;
;                         hv[n * 4 + i] = g * __builtin_amdgcn_rcpf(1.0f + __expf(-g)) * uu; }
;                 u32x4 w; w.x = cvtpk(hv[0], hv[1]); w.y = cvtpk(hv[2], hv[3]); w.z = cvtpk(hv[4], hv[5]); w.w = cvtpk(hv[6], hv[7]);
;                 *(u32x4*)(H + (size_t)row * ldh + col0) = w; }
.LBB0_194:
	v_lshl_or_b32 v160, s66, 7, v154
	v_ashrrev_i32_e32 v161, 31, v160
	v_or_b32_e32 v164, 16, v144
	v_ashrrev_i32_e32 v165, 31, v164
	v_lshl_add_u64 v[168:169], v[164:165], 3, s[6:7]
	v_mov_b64_e32 v[146:147], s[20:21]
	v_mad_i64_i32 v[162:163], s[14:15], v144, s65, v[146:147]
	s_andn2_b64 vcc, exec, s[0:1]
	s_mov_b64 s[0:1], -1
	s_waitcnt vmcnt(7)
	v_cvt_f32_u32_e32 v159, v183
	v_cvt_f32_u32_e32 v145, v182
	v_lshlrev_b64 v[148:149], 1, v[160:161]
	v_lshl_add_u64 v[162:163], v[162:163], 0, v[148:149]
	v_fmamk_f32 v145, v145, 0x2f800000, v159
	v_fmamk_f32 v145, v145, 0x3a800000, v158
	v_rsq_f32_e32 v160, v145
	s_nop 0
	v_mul_f32_e32 v182, 0xbfb8aa3b, v160
	v_mul_f32_e32 v183, v160, v160
	v_pk_mul_f32 v[160:161], v[124:125], v[182:183] op_sel_hi:[1,0]
	v_pk_mul_f32 v[170:171], v[126:127], v[182:183] op_sel_hi:[1,0]
	v_pk_mul_f32 v[172:173], v[120:121], v[182:183] op_sel_hi:[1,0]
	v_pk_mul_f32 v[174:175], v[122:123], v[182:183] op_sel_hi:[1,0]
	v_pk_mul_f32 v[116:117], v[116:117], v[124:125]
	v_pk_mul_f32 v[118:119], v[118:119], v[126:127]
	v_pk_mul_f32 v[120:121], v[112:113], v[120:121]
	v_pk_mul_f32 v[122:123], v[114:115], v[122:123]
	v_exp_f32_e32 v160, v160
	v_exp_f32_e32 v161, v161
	v_exp_f32_e32 v170, v170
	v_exp_f32_e32 v171, v171
	v_exp_f32_e32 v172, v172
	v_exp_f32_e32 v173, v173
	v_exp_f32_e32 v174, v174
	v_exp_f32_e32 v175, v175
	v_pk_mul_f32 v[116:117], v[116:117], v[182:183] op_sel:[0,1] op_sel_hi:[1,1]
	v_pk_mul_f32 v[118:119], v[118:119], v[182:183] op_sel:[0,1] op_sel_hi:[1,1]
	v_pk_mul_f32 v[120:121], v[120:121], v[182:183] op_sel:[0,1] op_sel_hi:[1,1]
	v_pk_mul_f32 v[122:123], v[122:123], v[182:183] op_sel:[0,1] op_sel_hi:[1,1]
	v_pk_add_f32 v[160:161], v[160:161], 1.0 op_sel_hi:[1,0]
	v_pk_add_f32 v[170:171], v[170:171], 1.0 op_sel_hi:[1,0]
	v_pk_add_f32 v[172:173], v[172:173], 1.0 op_sel_hi:[1,0]
	v_pk_add_f32 v[174:175], v[174:175], 1.0 op_sel_hi:[1,0]
	v_rcp_f32_e32 v160, v160
	v_rcp_f32_e32 v161, v161
	v_rcp_f32_e32 v170, v170
	v_rcp_f32_e32 v171, v171
	v_rcp_f32_e32 v172, v172
	v_rcp_f32_e32 v173, v173
	v_rcp_f32_e32 v174, v174
	v_rcp_f32_e32 v175, v175
	v_pk_mul_f32 v[116:117], v[116:117], v[160:161]
	v_pk_mul_f32 v[118:119], v[118:119], v[170:171]
	v_pk_mul_f32 v[120:121], v[120:121], v[172:173]
	v_pk_mul_f32 v[122:123], v[122:123], v[174:175]
	v_cvt_pk_bf16_f32 v112, v116, v117
	v_cvt_pk_bf16_f32 v113, v118, v119
	v_cvt_pk_bf16_f32 v114, v120, v121
	v_cvt_pk_bf16_f32 v115, v122, v123
	global_store_dwordx4 v[162:163], v[112:115], off sc1
	s_nop 0
	s_nop 0
	v_or_b32_e32 v114, 32, v144
	s_waitcnt vmcnt(7)
	v_cvt_f32_u32_e32 v116, v185
	v_cvt_f32_u32_e32 v115, v184
	v_mad_i64_i32 v[112:113], s[14:15], v164, s65, v[146:147]
	v_fmamk_f32 v115, v115, 0x2f800000, v116
	v_fmamk_f32 v115, v115, 0x3a800000, v158
	v_rsq_f32_e32 v116, v115
	v_ashrrev_i32_e32 v115, 31, v114
	v_lshl_add_u64 v[118:119], v[114:115], 3, s[6:7]
	v_lshl_add_u64 v[112:113], v[112:113], 0, v[148:149]
	v_mul_f32_e32 v184, 0xbfb8aa3b, v116
	v_mul_f32_e32 v185, v116, v116
	v_pk_mul_f32 v[116:117], v[108:109], v[184:185] op_sel_hi:[1,0]
	v_pk_mul_f32 v[120:121], v[110:111], v[184:185] op_sel_hi:[1,0]
	v_pk_mul_f32 v[122:123], v[104:105], v[184:185] op_sel_hi:[1,0]
	v_pk_mul_f32 v[124:125], v[106:107], v[184:185] op_sel_hi:[1,0]
	v_pk_mul_f32 v[100:101], v[100:101], v[108:109]
	v_pk_mul_f32 v[102:103], v[102:103], v[110:111]
	v_pk_mul_f32 v[104:105], v[96:97], v[104:105]
	v_pk_mul_f32 v[106:107], v[98:99], v[106:107]
	v_exp_f32_e32 v116, v116
	v_exp_f32_e32 v117, v117
	v_exp_f32_e32 v120, v120
	v_exp_f32_e32 v121, v121
	v_exp_f32_e32 v122, v122
	v_exp_f32_e32 v123, v123
	v_exp_f32_e32 v124, v124
	v_exp_f32_e32 v125, v125
	v_pk_mul_f32 v[100:101], v[100:101], v[184:185] op_sel:[0,1] op_sel_hi:[1,1]
	v_pk_mul_f32 v[102:103], v[102:103], v[184:185] op_sel:[0,1] op_sel_hi:[1,1]
	v_pk_mul_f32 v[104:105], v[104:105], v[184:185] op_sel:[0,1] op_sel_hi:[1,1]
	v_pk_mul_f32 v[106:107], v[106:107], v[184:185] op_sel:[0,1] op_sel_hi:[1,1]
	v_pk_add_f32 v[116:117], v[116:117], 1.0 op_sel_hi:[1,0]
	v_pk_add_f32 v[120:121], v[120:121], 1.0 op_sel_hi:[1,0]
	v_pk_add_f32 v[122:123], v[122:123], 1.0 op_sel_hi:[1,0]
	v_pk_add_f32 v[124:125], v[124:125], 1.0 op_sel_hi:[1,0]
	v_rcp_f32_e32 v116, v116
	v_rcp_f32_e32 v117, v117
	v_rcp_f32_e32 v120, v120
	v_rcp_f32_e32 v121, v121
	v_rcp_f32_e32 v122, v122
	v_rcp_f32_e32 v123, v123
	v_rcp_f32_e32 v124, v124
	v_rcp_f32_e32 v125, v125
	v_pk_mul_f32 v[100:101], v[100:101], v[116:117]
	v_pk_mul_f32 v[102:103], v[102:103], v[120:121]
	v_pk_mul_f32 v[104:105], v[104:105], v[122:123]
	v_pk_mul_f32 v[106:107], v[106:107], v[124:125]
	v_cvt_pk_bf16_f32 v96, v100, v101
	v_cvt_pk_bf16_f32 v97, v102, v103
	v_cvt_pk_bf16_f32 v98, v104, v105
	v_cvt_pk_bf16_f32 v99, v106, v107
	global_store_dwordx4 v[112:113], v[96:99], off sc1
	s_nop 0
	s_nop 0
	v_or_b32_e32 v98, 48, v144
	s_waitcnt vmcnt(7)
; __device__ __forceinline__ unsigned cvtpk(float lo, float hi) { f32x2v_ v = {lo, hi}; bf16x2v_ b = __builtin_convertvector(v, bf16x2v_); return __builtin_bit_cast(unsigned, b); }
;     __device__ __forceinline__ void operator()(const f32x4 (&acc)[2][2][4][2], const Unit& u, int wr, int wc, int fr, int fq) const {
;     ...
;             for (int m = 0; m < 4; ++m) { const int row = row0 + ai * HALF + m * 16; const float rs = row_rs(ss, row);
;                 float hv[8];
; #pragma unroll
;                 for (int n = 0; n < 2; ++n)
; #pragma unroll
;                     for (int i = 0; i < 4; ++i) { const float g = acc[ai][0][m][n][i] * rs, uu = acc[ai][1][m][n][i] * rs;
;                         hv[n * 4 + i] = g * __builtin_amdgcn_rcpf(1.0f + __expf(-g)) * uu; }
;                 u32x4 w; w.x = cvtpk(hv[0], hv[1]); w.y = cvtpk(hv[2], hv[3]); w.z = cvtpk(hv[4], hv[5]); w.w = cvtpk(hv[6], hv[7]);
;                 *(u32x4*)(H + (size_t)row * ldh + col0) = w; }
	v_cvt_f32_u32_e32 v100, v187
	v_cvt_f32_u32_e32 v99, v186
	v_mad_i64_i32 v[96:97], s[14:15], v114, s65, v[146:147]
	v_fmamk_f32 v99, v99, 0x2f800000, v100
	v_fmamk_f32 v99, v99, 0x3a800000, v158
	v_rsq_f32_e32 v100, v99
	v_ashrrev_i32_e32 v99, 31, v98
	v_lshl_add_u64 v[102:103], v[98:99], 3, s[6:7]
	v_lshl_add_u64 v[96:97], v[96:97], 0, v[148:149]
	v_mul_f32_e32 v186, 0xbfb8aa3b, v100
	v_mul_f32_e32 v187, v100, v100
	v_pk_mul_f32 v[100:101], v[92:93], v[186:187] op_sel_hi:[1,0]
	v_pk_mul_f32 v[104:105], v[94:95], v[186:187] op_sel_hi:[1,0]
	v_pk_mul_f32 v[106:107], v[88:89], v[186:187] op_sel_hi:[1,0]
	v_pk_mul_f32 v[108:109], v[90:91], v[186:187] op_sel_hi:[1,0]
	v_pk_mul_f32 v[84:85], v[84:85], v[92:93]
	v_pk_mul_f32 v[86:87], v[86:87], v[94:95]
	v_pk_mul_f32 v[88:89], v[80:81], v[88:89]
	v_pk_mul_f32 v[90:91], v[82:83], v[90:91]
	v_exp_f32_e32 v100, v100
	v_exp_f32_e32 v101, v101
	v_exp_f32_e32 v104, v104
	v_exp_f32_e32 v105, v105
	v_exp_f32_e32 v106, v106
	v_exp_f32_e32 v107, v107
	v_exp_f32_e32 v108, v108
	v_exp_f32_e32 v109, v109
	v_pk_mul_f32 v[84:85], v[84:85], v[186:187] op_sel:[0,1] op_sel_hi:[1,1]
	v_pk_mul_f32 v[86:87], v[86:87], v[186:187] op_sel:[0,1] op_sel_hi:[1,1]
	v_pk_mul_f32 v[88:89], v[88:89], v[186:187] op_sel:[0,1] op_sel_hi:[1,1]
	v_pk_mul_f32 v[90:91], v[90:91], v[186:187] op_sel:[0,1] op_sel_hi:[1,1]
	v_pk_add_f32 v[100:101], v[100:101], 1.0 op_sel_hi:[1,0]
	v_pk_add_f32 v[104:105], v[104:105], 1.0 op_sel_hi:[1,0]
	v_pk_add_f32 v[106:107], v[106:107], 1.0 op_sel_hi:[1,0]
	v_pk_add_f32 v[108:109], v[108:109], 1.0 op_sel_hi:[1,0]
	v_rcp_f32_e32 v100, v100
	v_rcp_f32_e32 v101, v101
	v_rcp_f32_e32 v104, v104
	v_rcp_f32_e32 v105, v105
	v_rcp_f32_e32 v106, v106
	v_rcp_f32_e32 v107, v107
	v_rcp_f32_e32 v108, v108
	v_rcp_f32_e32 v109, v109
	v_pk_mul_f32 v[84:85], v[84:85], v[100:101]
	v_pk_mul_f32 v[86:87], v[86:87], v[104:105]
	v_pk_mul_f32 v[88:89], v[88:89], v[106:107]
	v_pk_mul_f32 v[90:91], v[90:91], v[108:109]
	v_cvt_pk_bf16_f32 v80, v84, v85
	v_cvt_pk_bf16_f32 v81, v86, v87
	v_cvt_pk_bf16_f32 v82, v88, v89
	v_cvt_pk_bf16_f32 v83, v90, v91
	global_store_dwordx4 v[96:97], v[80:83], off sc1
	s_nop 0
	s_waitcnt vmcnt(7)
	v_cvt_f32_u32_e32 v80, v189
	v_cvt_f32_u32_e32 v81, v188
	v_mad_i64_i32 v[82:83], s[14:15], v98, s65, v[146:147]
	v_fmamk_f32 v80, v81, 0x2f800000, v80
	v_fmamk_f32 v80, v80, 0x3a800000, v158
	v_rsq_f32_e32 v80, v80
	v_lshl_add_u64 v[82:83], v[82:83], 0, v[148:149]
	v_mul_f32_e32 v188, 0xbfb8aa3b, v80
	v_mul_f32_e32 v189, v80, v80
	v_pk_mul_f32 v[80:81], v[76:77], v[188:189] op_sel_hi:[1,0]
	v_pk_mul_f32 v[84:85], v[78:79], v[188:189] op_sel_hi:[1,0]
	v_pk_mul_f32 v[86:87], v[72:73], v[188:189] op_sel_hi:[1,0]
	v_pk_mul_f32 v[88:89], v[74:75], v[188:189] op_sel_hi:[1,0]
	v_pk_mul_f32 v[68:69], v[68:69], v[76:77]
	v_pk_mul_f32 v[70:71], v[70:71], v[78:79]
	v_pk_mul_f32 v[72:73], v[64:65], v[72:73]
	v_pk_mul_f32 v[74:75], v[66:67], v[74:75]
	v_exp_f32_e32 v80, v80
	v_exp_f32_e32 v81, v81
	v_exp_f32_e32 v84, v84
	v_exp_f32_e32 v85, v85
	v_exp_f32_e32 v86, v86
	v_exp_f32_e32 v87, v87
	v_exp_f32_e32 v88, v88
	v_exp_f32_e32 v89, v89
	v_pk_mul_f32 v[68:69], v[68:69], v[188:189] op_sel:[0,1] op_sel_hi:[1,1]
	v_pk_mul_f32 v[70:71], v[70:71], v[188:189] op_sel:[0,1] op_sel_hi:[1,1]
	v_pk_mul_f32 v[72:73], v[72:73], v[188:189] op_sel:[0,1] op_sel_hi:[1,1]
	v_pk_mul_f32 v[74:75], v[74:75], v[188:189] op_sel:[0,1] op_sel_hi:[1,1]
	v_pk_add_f32 v[80:81], v[80:81], 1.0 op_sel_hi:[1,0]
	v_pk_add_f32 v[84:85], v[84:85], 1.0 op_sel_hi:[1,0]
	v_pk_add_f32 v[86:87], v[86:87], 1.0 op_sel_hi:[1,0]
	v_pk_add_f32 v[88:89], v[88:89], 1.0 op_sel_hi:[1,0]
	v_rcp_f32_e32 v80, v80
	v_rcp_f32_e32 v81, v81
	v_rcp_f32_e32 v84, v84
	v_rcp_f32_e32 v85, v85
	v_rcp_f32_e32 v86, v86
	v_rcp_f32_e32 v87, v87
	v_rcp_f32_e32 v88, v88
	v_rcp_f32_e32 v89, v89
	v_pk_mul_f32 v[68:69], v[68:69], v[80:81]
	v_pk_mul_f32 v[70:71], v[70:71], v[84:85]
	v_pk_mul_f32 v[72:73], v[72:73], v[86:87]
	v_pk_mul_f32 v[74:75], v[74:75], v[88:89]
	v_cvt_pk_bf16_f32 v64, v68, v69
	v_cvt_pk_bf16_f32 v65, v70, v71
	v_cvt_pk_bf16_f32 v66, v72, v73
	v_cvt_pk_bf16_f32 v67, v74, v75
	global_store_dwordx4 v[82:83], v[64:67], off sc1
	s_nop 0
	s_waitcnt vmcnt(7)
	v_cvt_f32_u32_e32 v64, v191
	v_cvt_f32_u32_e32 v66, v190
	v_add_u32_e32 v65, 0x80, v144
	v_fmamk_f32 v64, v66, 0x2f800000, v64
	v_fmamk_f32 v64, v64, 0x3a800000, v158
	v_rsq_f32_e32 v64, v64
	v_mad_i64_i32 v[66:67], s[14:15], v65, s65, v[146:147]
	v_lshl_add_u64 v[66:67], v[66:67], 0, v[148:149]
	v_mul_f32_e32 v190, 0xbfb8aa3b, v64
	v_mul_f32_e32 v191, v64, v64
	v_pk_mul_f32 v[64:65], v[60:61], v[190:191] op_sel_hi:[1,0]
	v_pk_mul_f32 v[68:69], v[62:63], v[190:191] op_sel_hi:[1,0]
	v_pk_mul_f32 v[70:71], v[56:57], v[190:191] op_sel_hi:[1,0]
	v_pk_mul_f32 v[72:73], v[58:59], v[190:191] op_sel_hi:[1,0]
	v_pk_mul_f32 v[52:53], v[52:53], v[60:61]
	v_pk_mul_f32 v[54:55], v[54:55], v[62:63]
	v_pk_mul_f32 v[56:57], v[48:49], v[56:57]
	v_pk_mul_f32 v[58:59], v[50:51], v[58:59]
	v_exp_f32_e32 v64, v64
	v_exp_f32_e32 v65, v65
	v_exp_f32_e32 v68, v68
	v_exp_f32_e32 v69, v69
	v_exp_f32_e32 v70, v70
	v_exp_f32_e32 v71, v71
	v_exp_f32_e32 v72, v72
	v_exp_f32_e32 v73, v73
	v_pk_mul_f32 v[52:53], v[52:53], v[190:191] op_sel:[0,1] op_sel_hi:[1,1]
	v_pk_mul_f32 v[54:55], v[54:55], v[190:191] op_sel:[0,1] op_sel_hi:[1,1]
	v_pk_mul_f32 v[56:57], v[56:57], v[190:191] op_sel:[0,1] op_sel_hi:[1,1]
	v_pk_mul_f32 v[58:59], v[58:59], v[190:191] op_sel:[0,1] op_sel_hi:[1,1]
	v_pk_add_f32 v[64:65], v[64:65], 1.0 op_sel_hi:[1,0]
	v_pk_add_f32 v[68:69], v[68:69], 1.0 op_sel_hi:[1,0]
	v_pk_add_f32 v[70:71], v[70:71], 1.0 op_sel_hi:[1,0]
	v_pk_add_f32 v[72:73], v[72:73], 1.0 op_sel_hi:[1,0]
	v_rcp_f32_e32 v64, v64
	v_rcp_f32_e32 v65, v65
	v_rcp_f32_e32 v68, v68
	v_rcp_f32_e32 v69, v69
	v_rcp_f32_e32 v70, v70
	v_rcp_f32_e32 v71, v71
	v_rcp_f32_e32 v72, v72
	v_rcp_f32_e32 v73, v73
	v_pk_mul_f32 v[52:53], v[52:53], v[64:65]
	v_pk_mul_f32 v[54:55], v[54:55], v[68:69]
	v_pk_mul_f32 v[56:57], v[56:57], v[70:71]
	v_pk_mul_f32 v[58:59], v[58:59], v[72:73]
	v_cvt_pk_bf16_f32 v48, v52, v53
	v_cvt_pk_bf16_f32 v49, v54, v55
	v_cvt_pk_bf16_f32 v50, v56, v57
	v_cvt_pk_bf16_f32 v51, v58, v59
	global_store_dwordx4 v[66:67], v[48:51], off sc1
	s_nop 0
	s_waitcnt vmcnt(7)
; __device__ __forceinline__ unsigned cvtpk(float lo, float hi) { f32x2v_ v = {lo, hi}; bf16x2v_ b = __builtin_convertvector(v, bf16x2v_); return __builtin_bit_cast(unsigned, b); }
;     __device__ __forceinline__ void operator()(const f32x4 (&acc)[2][2][4][2], const Unit& u, int wr, int wc, int fr, int fq) const {
;     ...
;             for (int m = 0; m < 4; ++m) { const int row = row0 + ai * HALF + m * 16; const float rs = row_rs(ss, row);
;                 float hv[8];
; #pragma unroll
;                 for (int n = 0; n < 2; ++n)
; #pragma unroll
;                     for (int i = 0; i < 4; ++i) { const float g = acc[ai][0][m][n][i] * rs, uu = acc[ai][1][m][n][i] * rs;
;                         hv[n * 4 + i] = g * __builtin_amdgcn_rcpf(1.0f + __expf(-g)) * uu; }
;                 u32x4 w; w.x = cvtpk(hv[0], hv[1]); w.y = cvtpk(hv[2], hv[3]); w.z = cvtpk(hv[4], hv[5]); w.w = cvtpk(hv[6], hv[7]);
;                 *(u32x4*)(H + (size_t)row * ldh + col0) = w; }
	v_cvt_f32_u32_e32 v48, v193
	v_cvt_f32_u32_e32 v50, v192
	v_add_u32_e32 v49, 0x90, v144
	v_fmamk_f32 v48, v50, 0x2f800000, v48
	v_fmamk_f32 v48, v48, 0x3a800000, v158
	v_rsq_f32_e32 v48, v48
	v_mad_i64_i32 v[50:51], s[14:15], v49, s65, v[146:147]
	v_lshl_add_u64 v[50:51], v[50:51], 0, v[148:149]
	v_mul_f32_e32 v192, 0xbfb8aa3b, v48
	v_mul_f32_e32 v193, v48, v48
	v_pk_mul_f32 v[48:49], v[44:45], v[192:193] op_sel_hi:[1,0]
	v_pk_mul_f32 v[52:53], v[46:47], v[192:193] op_sel_hi:[1,0]
	v_pk_mul_f32 v[54:55], v[40:41], v[192:193] op_sel_hi:[1,0]
	v_pk_mul_f32 v[56:57], v[42:43], v[192:193] op_sel_hi:[1,0]
	v_pk_mul_f32 v[36:37], v[36:37], v[44:45]
	v_pk_mul_f32 v[38:39], v[38:39], v[46:47]
	v_pk_mul_f32 v[40:41], v[32:33], v[40:41]
	v_pk_mul_f32 v[42:43], v[34:35], v[42:43]
	v_exp_f32_e32 v48, v48
	v_exp_f32_e32 v49, v49
	v_exp_f32_e32 v52, v52
	v_exp_f32_e32 v53, v53
	v_exp_f32_e32 v54, v54
	v_exp_f32_e32 v55, v55
	v_exp_f32_e32 v56, v56
	v_exp_f32_e32 v57, v57
	v_pk_mul_f32 v[36:37], v[36:37], v[192:193] op_sel:[0,1] op_sel_hi:[1,1]
	v_pk_mul_f32 v[38:39], v[38:39], v[192:193] op_sel:[0,1] op_sel_hi:[1,1]
	v_pk_mul_f32 v[40:41], v[40:41], v[192:193] op_sel:[0,1] op_sel_hi:[1,1]
	v_pk_mul_f32 v[42:43], v[42:43], v[192:193] op_sel:[0,1] op_sel_hi:[1,1]
	v_pk_add_f32 v[48:49], v[48:49], 1.0 op_sel_hi:[1,0]
	v_pk_add_f32 v[52:53], v[52:53], 1.0 op_sel_hi:[1,0]
	v_pk_add_f32 v[54:55], v[54:55], 1.0 op_sel_hi:[1,0]
	v_pk_add_f32 v[56:57], v[56:57], 1.0 op_sel_hi:[1,0]
	v_rcp_f32_e32 v48, v48
	v_rcp_f32_e32 v49, v49
	v_rcp_f32_e32 v52, v52
	v_rcp_f32_e32 v53, v53
	v_rcp_f32_e32 v54, v54
	v_rcp_f32_e32 v55, v55
	v_rcp_f32_e32 v56, v56
	v_rcp_f32_e32 v57, v57
	v_pk_mul_f32 v[36:37], v[36:37], v[48:49]
	v_pk_mul_f32 v[38:39], v[38:39], v[52:53]
	v_pk_mul_f32 v[40:41], v[40:41], v[54:55]
	v_pk_mul_f32 v[42:43], v[42:43], v[56:57]
	v_cvt_pk_bf16_f32 v32, v36, v37
	v_cvt_pk_bf16_f32 v33, v38, v39
	v_cvt_pk_bf16_f32 v34, v40, v41
	v_cvt_pk_bf16_f32 v35, v42, v43
	global_store_dwordx4 v[50:51], v[32:35], off sc1
	s_nop 0
	s_waitcnt vmcnt(7)
	v_cvt_f32_u32_e32 v32, v195
	v_cvt_f32_u32_e32 v34, v194
	v_add_u32_e32 v33, 0xa0, v144
	v_fmamk_f32 v32, v34, 0x2f800000, v32
	v_fmamk_f32 v32, v32, 0x3a800000, v158
	v_rsq_f32_e32 v32, v32
	v_mad_i64_i32 v[34:35], s[14:15], v33, s65, v[146:147]
	v_lshl_add_u64 v[34:35], v[34:35], 0, v[148:149]
	v_mul_f32_e32 v194, 0xbfb8aa3b, v32
	v_mul_f32_e32 v195, v32, v32
	v_pk_mul_f32 v[32:33], v[28:29], v[194:195] op_sel_hi:[1,0]
	v_pk_mul_f32 v[36:37], v[30:31], v[194:195] op_sel_hi:[1,0]
	v_pk_mul_f32 v[38:39], v[24:25], v[194:195] op_sel_hi:[1,0]
	v_pk_mul_f32 v[40:41], v[26:27], v[194:195] op_sel_hi:[1,0]
	v_pk_mul_f32 v[20:21], v[20:21], v[28:29]
	v_pk_mul_f32 v[22:23], v[22:23], v[30:31]
	v_pk_mul_f32 v[24:25], v[16:17], v[24:25]
	v_pk_mul_f32 v[26:27], v[18:19], v[26:27]
	v_exp_f32_e32 v32, v32
	v_exp_f32_e32 v33, v33
	v_exp_f32_e32 v36, v36
	v_exp_f32_e32 v37, v37
	v_exp_f32_e32 v38, v38
	v_exp_f32_e32 v39, v39
	v_exp_f32_e32 v40, v40
	v_exp_f32_e32 v41, v41
	v_pk_mul_f32 v[20:21], v[20:21], v[194:195] op_sel:[0,1] op_sel_hi:[1,1]
	v_pk_mul_f32 v[22:23], v[22:23], v[194:195] op_sel:[0,1] op_sel_hi:[1,1]
	v_pk_mul_f32 v[24:25], v[24:25], v[194:195] op_sel:[0,1] op_sel_hi:[1,1]
	v_pk_mul_f32 v[26:27], v[26:27], v[194:195] op_sel:[0,1] op_sel_hi:[1,1]
	v_pk_add_f32 v[32:33], v[32:33], 1.0 op_sel_hi:[1,0]
	v_pk_add_f32 v[36:37], v[36:37], 1.0 op_sel_hi:[1,0]
	v_pk_add_f32 v[38:39], v[38:39], 1.0 op_sel_hi:[1,0]
	v_pk_add_f32 v[40:41], v[40:41], 1.0 op_sel_hi:[1,0]
	v_rcp_f32_e32 v32, v32
	v_rcp_f32_e32 v33, v33
	v_rcp_f32_e32 v36, v36
	v_rcp_f32_e32 v37, v37
	v_rcp_f32_e32 v38, v38
	v_rcp_f32_e32 v39, v39
	v_rcp_f32_e32 v40, v40
	v_rcp_f32_e32 v41, v41
	v_pk_mul_f32 v[20:21], v[20:21], v[32:33]
	v_pk_mul_f32 v[22:23], v[22:23], v[36:37]
	v_pk_mul_f32 v[24:25], v[24:25], v[38:39]
	v_pk_mul_f32 v[26:27], v[26:27], v[40:41]
	v_cvt_pk_bf16_f32 v16, v20, v21
	v_cvt_pk_bf16_f32 v17, v22, v23
	v_cvt_pk_bf16_f32 v18, v24, v25
	v_cvt_pk_bf16_f32 v19, v26, v27
	global_store_dwordx4 v[34:35], v[16:19], off sc1
	s_nop 0
	s_waitcnt vmcnt(7)
	v_cvt_f32_u32_e32 v16, v197
	v_cvt_f32_u32_e32 v18, v196
	v_add_u32_e32 v17, 0xb0, v144
	v_fmamk_f32 v16, v18, 0x2f800000, v16
	v_fmamk_f32 v16, v16, 0x3a800000, v158
	v_rsq_f32_e32 v16, v16
	v_mad_i64_i32 v[18:19], s[14:15], v17, s65, v[146:147]
	v_lshl_add_u64 v[18:19], v[18:19], 0, v[148:149]
	v_mul_f32_e32 v196, 0xbfb8aa3b, v16
	v_mul_f32_e32 v197, v16, v16
	v_pk_mul_f32 v[16:17], v[12:13], v[196:197] op_sel_hi:[1,0]
	v_pk_mul_f32 v[20:21], v[14:15], v[196:197] op_sel_hi:[1,0]
	v_pk_mul_f32 v[22:23], v[8:9], v[196:197] op_sel_hi:[1,0]
	v_pk_mul_f32 v[24:25], v[10:11], v[196:197] op_sel_hi:[1,0]
	v_pk_mul_f32 v[4:5], v[4:5], v[12:13]
	v_pk_mul_f32 v[6:7], v[6:7], v[14:15]
	v_pk_mul_f32 v[8:9], v[0:1], v[8:9]
	v_pk_mul_f32 v[10:11], v[2:3], v[10:11]
	v_exp_f32_e32 v16, v16
	v_exp_f32_e32 v17, v17
	v_exp_f32_e32 v20, v20
	v_exp_f32_e32 v21, v21
	v_exp_f32_e32 v22, v22
	v_exp_f32_e32 v23, v23
	v_exp_f32_e32 v24, v24
	v_exp_f32_e32 v25, v25
	v_pk_mul_f32 v[4:5], v[4:5], v[196:197] op_sel:[0,1] op_sel_hi:[1,1]
	v_pk_mul_f32 v[6:7], v[6:7], v[196:197] op_sel:[0,1] op_sel_hi:[1,1]
	v_pk_mul_f32 v[8:9], v[8:9], v[196:197] op_sel:[0,1] op_sel_hi:[1,1]
	v_pk_mul_f32 v[10:11], v[10:11], v[196:197] op_sel:[0,1] op_sel_hi:[1,1]
	v_pk_add_f32 v[16:17], v[16:17], 1.0 op_sel_hi:[1,0]
	v_pk_add_f32 v[20:21], v[20:21], 1.0 op_sel_hi:[1,0]
	v_pk_add_f32 v[22:23], v[22:23], 1.0 op_sel_hi:[1,0]
	v_pk_add_f32 v[24:25], v[24:25], 1.0 op_sel_hi:[1,0]
	v_rcp_f32_e32 v16, v16
	v_rcp_f32_e32 v17, v17
	v_rcp_f32_e32 v20, v20
	v_rcp_f32_e32 v21, v21
	v_rcp_f32_e32 v22, v22
	v_rcp_f32_e32 v23, v23
	v_rcp_f32_e32 v24, v24
	v_rcp_f32_e32 v25, v25
	v_pk_mul_f32 v[4:5], v[4:5], v[16:17]
	v_pk_mul_f32 v[6:7], v[6:7], v[20:21]
	v_pk_mul_f32 v[8:9], v[8:9], v[22:23]
	v_pk_mul_f32 v[10:11], v[10:11], v[24:25]
	v_cvt_pk_bf16_f32 v0, v4, v5
	v_cvt_pk_bf16_f32 v1, v6, v7
	v_cvt_pk_bf16_f32 v2, v8, v9
	v_cvt_pk_bf16_f32 v3, v10, v11
	global_store_dwordx4 v[18:19], v[0:3], off sc1
	s_cbranch_vccnz .LBB0_187
	s_andn2_b64 vcc, exec, s[8:9]
	s_cbranch_vccnz .LBB0_186
	s_barrier
	s_branch .LBB0_186

; __device__ __forceinline__ unsigned cvtpk(float lo, float hi) { f32x2v_ v = {lo, hi}; bf16x2v_ b = __builtin_convertvector(v, bf16x2v_); return __builtin_bit_cast(unsigned, b); }
;     __device__ __forceinline__ void operator()(const f32x4 (&acc)[2][2][4][2], const Unit& u, int wr, int wc, int fr, int fq) const {
;     ...
;                     if (xin32) { const float* p = xin32 + off + bj * HALF; a0 = *(const f32x4*)p; a1 = *(const f32x4*)(p + 4); }
;                     else { const u32x4 w = *(const u32x4*)(xb + off + bj * HALF);
;                         a0 = (f32x4){__uint_as_float(w.x << 16), __uint_as_float(w.x & 0xffff0000u), __uint_as_float(w.y << 16), __uint_as_float(w.y & 0xffff0000u)};
;                         a1 = (f32x4){__uint_as_float(w.z << 16), __uint_as_float(w.z & 0xffff0000u), __uint_as_float(w.w << 16), __uint_as_float(w.w & 0xffff0000u)}; }
;                     const f32x4 v0 = a0 + acc[ai][bj][m][0] * alpha, v1 = a1 + acc[ai][bj][m][1] * alpha;
;                     u32x4 w; w.x = cvtpk(v0[0], v0[1]); w.y = cvtpk(v0[2], v0[3]); w.z = cvtpk(v1[0], v1[1]); w.w = cvtpk(v1[2], v1[3]);
;                     *(u32x4*)(xb + off + bj * HALF) = w;
.LBB0_275:
	s_waitcnt vmcnt(0)
	v_pk_fma_f32 v[130:131], v[126:127], 0.5, v[130:131] op_sel_hi:[1,0,1]
	v_pk_fma_f32 v[160:161], v[124:125], 0.5, v[128:129] op_sel_hi:[1,0,1]
	v_pk_fma_f32 v[128:129], v[122:123], 0.5, v[134:135] op_sel_hi:[1,0,1]
	v_pk_fma_f32 v[132:133], v[120:121], 0.5, v[132:133] op_sel_hi:[1,0,1]
	v_cvt_pk_bf16_f32 v120, v160, v161
	v_cvt_pk_bf16_f32 v121, v130, v131
	v_cvt_pk_bf16_f32 v122, v132, v133
	v_cvt_pk_bf16_f32 v123, v128, v129
	s_and_b64 vcc, exec, s[10:11]
	global_store_dwordx4 v[156:157], v[120:123], off sc1
	s_cbranch_vccnz .LBB0_340
	global_load_dwordx4 v[124:127], v[158:159], off offset:528
	global_load_dwordx4 v[120:123], v[158:159], off offset:512
	s_cbranch_execnz .LBB0_278

; __device__ __forceinline__ unsigned cvtpk(float lo, float hi) { f32x2v_ v = {lo, hi}; bf16x2v_ b = __builtin_convertvector(v, bf16x2v_); return __builtin_bit_cast(unsigned, b); }
; __device__ __forceinline__ void fx_add(float* p, size_t idx, float s) { atomicAdd((unsigned long long*)p + idx, (unsigned long long)(long long)(s * 4294967296.0f)); }
;     __device__ __forceinline__ void operator()(const f32x4 (&acc)[2][2][4][2], const Unit& u, int wr, int wc, int fr, int fq) const {
;     ...
;                     const f32x4 v0 = a0 + acc[ai][bj][m][0] * alpha, v1 = a1 + acc[ai][bj][m][1] * alpha;
;                     u32x4 w; w.x = cvtpk(v0[0], v0[1]); w.y = cvtpk(v0[2], v0[3]); w.z = cvtpk(v1[0], v1[1]); w.w = cvtpk(v1[2], v1[3]);
;                     *(u32x4*)(xb + off + bj * HALF) = w;
;                     s += (v0[0] * v0[0] + v0[1] * v0[1]) + (v0[2] * v0[2] + v0[3] * v0[3]) + (v1[0] * v1[0] + v1[1] * v1[1]) + (v1[2] * v1[2] + v1[3] * v1[3]); }
;                 s += __shfl_xor(s, 16); s += __shfl_xor(s, 32);
;                 if (fq == 0) fx_add(ssout, row, s); }
.LBB0_278:
	v_mul_f32_e32 v134, v161, v161
	v_mul_f32_e32 v131, v131, v131
	v_fmac_f32_e32 v134, v160, v160
	v_fmac_f32_e32 v131, v130, v130
	s_waitcnt vmcnt(0)
	v_pk_fma_f32 v[118:119], v[118:119], 0.5, v[122:123] op_sel_hi:[1,0,1]
	v_pk_fma_f32 v[116:117], v[116:117], 0.5, v[120:121] op_sel_hi:[1,0,1]
	v_add_f32_e32 v130, v134, v131
	v_mul_f32_e32 v131, v133, v133
	v_pk_fma_f32 v[122:123], v[112:113], 0.5, v[124:125] op_sel_hi:[1,0,1]
	v_mul_f32_e32 v112, v117, v117
	v_mul_f32_e32 v113, v119, v119
	v_fmac_f32_e32 v131, v132, v132
	v_mul_f32_e32 v129, v129, v129
	v_fmac_f32_e32 v112, v116, v116
	v_fmac_f32_e32 v113, v118, v118
	v_add_f32_e32 v130, v131, v130
	v_fmac_f32_e32 v129, v128, v128
	v_add_f32_e32 v112, v112, v113
	v_mul_f32_e32 v113, v123, v123
	v_add_f32_e32 v129, v129, v130
	v_and_b32_e32 v130, 64, v170
	v_pk_fma_f32 v[120:121], v[114:115], 0.5, v[126:127] op_sel_hi:[1,0,1]
	v_fmac_f32_e32 v113, v122, v122
	v_xor_b32_e32 v128, 16, v170
	v_add_u32_e32 v130, 64, v130
	v_add_f32_e32 v112, v113, v112
	v_mul_f32_e32 v113, v121, v121
	v_cmp_lt_i32_e32 vcc, v128, v130
	v_fmac_f32_e32 v113, v120, v120
	v_add_f32_e32 v112, v113, v112
	v_cndmask_b32_e32 v128, v170, v128, vcc
	v_lshlrev_b32_e32 v128, 2, v128
	v_add_f32_e32 v112, v129, v112
	v_mov_b32_e32 v113, v112
	s_nop 1
	v_permlane16_swap_b32_e32 v113, v112
	v_xor_b32_e32 v131, 32, v170
	v_cmp_lt_i32_e32 vcc, v131, v130
	v_cvt_pk_bf16_f32 v115, v118, v119
	s_waitcnt lgkmcnt(0)
	v_add_f32_e32 v112, v112, v113
	v_cndmask_b32_e32 v114, v170, v131, vcc
	v_lshlrev_b32_e32 v129, 2, v114
	v_mov_b32_e32 v113, v112
	s_nop 1
	v_permlane32_swap_b32_e32 v113, v112
	v_cvt_pk_bf16_f32 v114, v116, v117
	v_cvt_pk_bf16_f32 v116, v122, v123
	v_cvt_pk_bf16_f32 v117, v120, v121
	global_store_dwordx4 v[156:157], v[114:117], off offset:256 sc1
	s_and_saveexec_b64 s[50:51], s[6:7]
	s_cbranch_execz .LBB0_280
	s_waitcnt lgkmcnt(0)
	v_add_f32_e32 v112, v112, v113
	v_mul_f32_e32 v112, 0x4f800000, v112
	v_trunc_f32_e32 v112, v112
	v_mul_f32_e64 v113, |v112|, s67
	v_floor_f32_e32 v113, v113
	v_fma_f32 v114, v113, s86, |v112|
	v_cvt_u32_f32_e32 v112, v114
	v_cvt_u32_f32_e32 v113, v113
	v_lshl_add_u64 v[114:115], v[154:155], 3, s[24:25]
	global_atomic_add_x2 v[114:115], v[112:113], off

; __device__ __forceinline__ unsigned cvtpk(float lo, float hi) { f32x2v_ v = {lo, hi}; bf16x2v_ b = __builtin_convertvector(v, bf16x2v_); return __builtin_bit_cast(unsigned, b); }
;     __device__ __forceinline__ void operator()(const f32x4 (&acc)[2][2][4][2], const Unit& u, int wr, int wc, int fr, int fq) const {
;     ...
;                     if (xin32) { const float* p = xin32 + off + bj * HALF; a0 = *(const f32x4*)p; a1 = *(const f32x4*)(p + 4); }
;                     else { const u32x4 w = *(const u32x4*)(xb + off + bj * HALF);
;                         a0 = (f32x4){__uint_as_float(w.x << 16), __uint_as_float(w.x & 0xffff0000u), __uint_as_float(w.y << 16), __uint_as_float(w.y & 0xffff0000u)};
;                         a1 = (f32x4){__uint_as_float(w.z << 16), __uint_as_float(w.z & 0xffff0000u), __uint_as_float(w.w << 16), __uint_as_float(w.w & 0xffff0000u)}; }
;                     const f32x4 v0 = a0 + acc[ai][bj][m][0] * alpha, v1 = a1 + acc[ai][bj][m][1] * alpha;
;                     u32x4 w; w.x = cvtpk(v0[0], v0[1]); w.y = cvtpk(v0[2], v0[3]); w.z = cvtpk(v1[0], v1[1]); w.w = cvtpk(v1[2], v1[3]);
;                     *(u32x4*)(xb + off + bj * HALF) = w;
.LBB0_283:
	s_waitcnt vmcnt(0)
	v_pk_fma_f32 v[114:115], v[110:111], 0.5, v[114:115] op_sel_hi:[1,0,1]
	v_pk_fma_f32 v[126:127], v[108:109], 0.5, v[112:113] op_sel_hi:[1,0,1]
	v_pk_fma_f32 v[112:113], v[106:107], 0.5, v[118:119] op_sel_hi:[1,0,1]
	v_pk_fma_f32 v[116:117], v[104:105], 0.5, v[116:117] op_sel_hi:[1,0,1]
	v_cvt_pk_bf16_f32 v104, v126, v127
	v_cvt_pk_bf16_f32 v105, v114, v115
	v_cvt_pk_bf16_f32 v106, v116, v117
	v_cvt_pk_bf16_f32 v107, v112, v113
	s_and_b64 vcc, exec, s[10:11]
	global_store_dwordx4 v[122:123], v[104:107], off sc1
	s_cbranch_vccnz .LBB0_342
	global_load_dwordx4 v[108:111], v[124:125], off offset:528
	global_load_dwordx4 v[104:107], v[124:125], off offset:512
	s_cbranch_execnz .LBB0_286

; __device__ __forceinline__ void fx_add(float* p, size_t idx, float s) { atomicAdd((unsigned long long*)p + idx, (unsigned long long)(long long)(s * 4294967296.0f)); }
; __device__ __forceinline__ unsigned cvtpk(float lo, float hi) { f32x2v_ v = {lo, hi}; bf16x2v_ b = __builtin_convertvector(v, bf16x2v_); return __builtin_bit_cast(unsigned, b); }
;     __device__ __forceinline__ void operator()(const f32x4 (&acc)[2][2][4][2], const Unit& u, int wr, int wc, int fr, int fq) const {
;     ...
;                     const f32x4 v0 = a0 + acc[ai][bj][m][0] * alpha, v1 = a1 + acc[ai][bj][m][1] * alpha;
;                     u32x4 w; w.x = cvtpk(v0[0], v0[1]); w.y = cvtpk(v0[2], v0[3]); w.z = cvtpk(v1[0], v1[1]); w.w = cvtpk(v1[2], v1[3]);
;                     *(u32x4*)(xb + off + bj * HALF) = w;
;                     s += (v0[0] * v0[0] + v0[1] * v0[1]) + (v0[2] * v0[2] + v0[3] * v0[3]) + (v1[0] * v1[0] + v1[1] * v1[1]) + (v1[2] * v1[2] + v1[3] * v1[3]); }
;                 s += __shfl_xor(s, 16); s += __shfl_xor(s, 32);
;                 if (fq == 0) fx_add(ssout, row, s); }
.LBB0_286:
	s_waitcnt vmcnt(0)
	v_pk_fma_f32 v[102:103], v[102:103], 0.5, v[106:107] op_sel_hi:[1,0,1]
	v_pk_fma_f32 v[100:101], v[100:101], 0.5, v[104:105] op_sel_hi:[1,0,1]
	v_pk_fma_f32 v[106:107], v[96:97], 0.5, v[108:109] op_sel_hi:[1,0,1]
	v_mul_f32_e32 v96, v101, v101
	v_mul_f32_e32 v97, v103, v103
	v_mul_f32_e32 v118, v127, v127
	v_mul_f32_e32 v115, v115, v115
	v_fmac_f32_e32 v96, v100, v100
	v_fmac_f32_e32 v97, v102, v102
	v_fmac_f32_e32 v118, v126, v126
	v_fmac_f32_e32 v115, v114, v114
	v_add_f32_e32 v96, v96, v97
	v_mul_f32_e32 v97, v107, v107
	v_add_f32_e32 v114, v118, v115
	v_mul_f32_e32 v115, v117, v117
	v_pk_fma_f32 v[104:105], v[98:99], 0.5, v[110:111] op_sel_hi:[1,0,1]
	v_fmac_f32_e32 v97, v106, v106
	v_fmac_f32_e32 v115, v116, v116
	v_mul_f32_e32 v113, v113, v113
	v_add_f32_e32 v96, v97, v96
	v_mul_f32_e32 v97, v105, v105
	v_add_f32_e32 v114, v115, v114
	v_fmac_f32_e32 v113, v112, v112
	v_fmac_f32_e32 v97, v104, v104
	v_add_f32_e32 v112, v113, v114
	v_add_f32_e32 v96, v97, v96
	v_add_f32_e32 v96, v112, v96
	v_mov_b32_e32 v97, v96
	s_nop 1
	v_permlane16_swap_b32_e32 v97, v96
	v_cvt_pk_bf16_f32 v98, v100, v101
	v_cvt_pk_bf16_f32 v99, v102, v103
	v_cvt_pk_bf16_f32 v100, v106, v107
	v_cvt_pk_bf16_f32 v101, v104, v105
	s_waitcnt lgkmcnt(0)
	v_add_f32_e32 v96, v96, v97
	v_mov_b32_e32 v97, v96
	s_nop 1
	v_permlane32_swap_b32_e32 v97, v96
	global_store_dwordx4 v[122:123], v[98:101], off offset:256 sc1
	s_and_saveexec_b64 s[50:51], s[6:7]
	s_cbranch_execz .LBB0_288
	s_waitcnt lgkmcnt(0)
	v_add_f32_e32 v96, v96, v97
	v_mul_f32_e32 v96, 0x4f800000, v96
	v_trunc_f32_e32 v96, v96
	v_mul_f32_e64 v97, |v96|, s67
	v_floor_f32_e32 v97, v97
	v_fma_f32 v98, v97, s86, |v96|
	v_cvt_u32_f32_e32 v96, v98
	v_cvt_u32_f32_e32 v97, v97
	v_lshl_add_u64 v[98:99], v[120:121], 3, s[24:25]
	global_atomic_add_x2 v[98:99], v[96:97], off

; __device__ __forceinline__ unsigned cvtpk(float lo, float hi) { f32x2v_ v = {lo, hi}; bf16x2v_ b = __builtin_convertvector(v, bf16x2v_); return __builtin_bit_cast(unsigned, b); }
;     __device__ __forceinline__ void operator()(const f32x4 (&acc)[2][2][4][2], const Unit& u, int wr, int wc, int fr, int fq) const {
;     ...
;                     if (xin32) { const float* p = xin32 + off + bj * HALF; a0 = *(const f32x4*)p; a1 = *(const f32x4*)(p + 4); }
;                     else { const u32x4 w = *(const u32x4*)(xb + off + bj * HALF);
;                         a0 = (f32x4){__uint_as_float(w.x << 16), __uint_as_float(w.x & 0xffff0000u), __uint_as_float(w.y << 16), __uint_as_float(w.y & 0xffff0000u)};
;                         a1 = (f32x4){__uint_as_float(w.z << 16), __uint_as_float(w.z & 0xffff0000u), __uint_as_float(w.w << 16), __uint_as_float(w.w & 0xffff0000u)}; }
;                     const f32x4 v0 = a0 + acc[ai][bj][m][0] * alpha, v1 = a1 + acc[ai][bj][m][1] * alpha;
;                     u32x4 w; w.x = cvtpk(v0[0], v0[1]); w.y = cvtpk(v0[2], v0[3]); w.z = cvtpk(v1[0], v1[1]); w.w = cvtpk(v1[2], v1[3]);
;                     *(u32x4*)(xb + off + bj * HALF) = w;
.LBB0_291:
	s_waitcnt vmcnt(0)
	v_pk_fma_f32 v[98:99], v[94:95], 0.5, v[98:99] op_sel_hi:[1,0,1]
	v_pk_fma_f32 v[110:111], v[92:93], 0.5, v[96:97] op_sel_hi:[1,0,1]
	v_pk_fma_f32 v[96:97], v[90:91], 0.5, v[102:103] op_sel_hi:[1,0,1]
	v_pk_fma_f32 v[100:101], v[88:89], 0.5, v[100:101] op_sel_hi:[1,0,1]
	v_cvt_pk_bf16_f32 v88, v110, v111
	v_cvt_pk_bf16_f32 v89, v98, v99
	v_cvt_pk_bf16_f32 v90, v100, v101
	v_cvt_pk_bf16_f32 v91, v96, v97
	s_and_b64 vcc, exec, s[10:11]
	global_store_dwordx4 v[106:107], v[88:91], off sc1
	s_cbranch_vccnz .LBB0_344
	global_load_dwordx4 v[92:95], v[108:109], off offset:528
	global_load_dwordx4 v[88:91], v[108:109], off offset:512
	s_cbranch_execnz .LBB0_294

; __device__ __forceinline__ void fx_add(float* p, size_t idx, float s) { atomicAdd((unsigned long long*)p + idx, (unsigned long long)(long long)(s * 4294967296.0f)); }
; __device__ __forceinline__ unsigned cvtpk(float lo, float hi) { f32x2v_ v = {lo, hi}; bf16x2v_ b = __builtin_convertvector(v, bf16x2v_); return __builtin_bit_cast(unsigned, b); }
;     __device__ __forceinline__ void operator()(const f32x4 (&acc)[2][2][4][2], const Unit& u, int wr, int wc, int fr, int fq) const {
;     ...
;                     const f32x4 v0 = a0 + acc[ai][bj][m][0] * alpha, v1 = a1 + acc[ai][bj][m][1] * alpha;
;                     u32x4 w; w.x = cvtpk(v0[0], v0[1]); w.y = cvtpk(v0[2], v0[3]); w.z = cvtpk(v1[0], v1[1]); w.w = cvtpk(v1[2], v1[3]);
;                     *(u32x4*)(xb + off + bj * HALF) = w;
;                     s += (v0[0] * v0[0] + v0[1] * v0[1]) + (v0[2] * v0[2] + v0[3] * v0[3]) + (v1[0] * v1[0] + v1[1] * v1[1]) + (v1[2] * v1[2] + v1[3] * v1[3]); }
;                 s += __shfl_xor(s, 16); s += __shfl_xor(s, 32);
;                 if (fq == 0) fx_add(ssout, row, s); }
.LBB0_294:
	s_waitcnt vmcnt(0)
	v_pk_fma_f32 v[86:87], v[86:87], 0.5, v[90:91] op_sel_hi:[1,0,1]
	v_pk_fma_f32 v[84:85], v[84:85], 0.5, v[88:89] op_sel_hi:[1,0,1]
	v_pk_fma_f32 v[90:91], v[80:81], 0.5, v[92:93] op_sel_hi:[1,0,1]
	v_mul_f32_e32 v80, v85, v85
	v_mul_f32_e32 v81, v87, v87
	v_mul_f32_e32 v102, v111, v111
	v_mul_f32_e32 v99, v99, v99
	v_fmac_f32_e32 v80, v84, v84
	v_fmac_f32_e32 v81, v86, v86
	v_fmac_f32_e32 v102, v110, v110
	v_fmac_f32_e32 v99, v98, v98
	v_add_f32_e32 v80, v80, v81
	v_mul_f32_e32 v81, v91, v91
	v_add_f32_e32 v98, v102, v99
	v_mul_f32_e32 v99, v101, v101
	v_pk_fma_f32 v[88:89], v[82:83], 0.5, v[94:95] op_sel_hi:[1,0,1]
	v_fmac_f32_e32 v81, v90, v90
	v_fmac_f32_e32 v99, v100, v100
	v_mul_f32_e32 v97, v97, v97
	v_add_f32_e32 v80, v81, v80
	v_mul_f32_e32 v81, v89, v89
	v_add_f32_e32 v98, v99, v98
	v_fmac_f32_e32 v97, v96, v96
	v_fmac_f32_e32 v81, v88, v88
	v_add_f32_e32 v96, v97, v98
	v_add_f32_e32 v80, v81, v80
	v_add_f32_e32 v80, v96, v80
	v_mov_b32_e32 v81, v80
	s_nop 1
	v_permlane16_swap_b32_e32 v81, v80
	v_cvt_pk_bf16_f32 v82, v84, v85
	v_cvt_pk_bf16_f32 v83, v86, v87
	v_cvt_pk_bf16_f32 v84, v90, v91
	v_cvt_pk_bf16_f32 v85, v88, v89
	s_waitcnt lgkmcnt(0)
	v_add_f32_e32 v80, v80, v81
	v_mov_b32_e32 v81, v80
	s_nop 1
	v_permlane32_swap_b32_e32 v81, v80
	global_store_dwordx4 v[106:107], v[82:85], off offset:256 sc1
	s_and_saveexec_b64 s[50:51], s[6:7]
	s_cbranch_execz .LBB0_296
	s_waitcnt lgkmcnt(0)
	v_add_f32_e32 v80, v80, v81
	v_mul_f32_e32 v80, 0x4f800000, v80
	v_trunc_f32_e32 v80, v80
	v_mul_f32_e64 v81, |v80|, s67
	v_floor_f32_e32 v81, v81
	v_fma_f32 v82, v81, s86, |v80|
	v_cvt_u32_f32_e32 v80, v82
	v_cvt_u32_f32_e32 v81, v81
	v_lshl_add_u64 v[82:83], v[104:105], 3, s[24:25]
	global_atomic_add_x2 v[82:83], v[80:81], off

; __device__ __forceinline__ unsigned cvtpk(float lo, float hi) { f32x2v_ v = {lo, hi}; bf16x2v_ b = __builtin_convertvector(v, bf16x2v_); return __builtin_bit_cast(unsigned, b); }
;     __device__ __forceinline__ void operator()(const f32x4 (&acc)[2][2][4][2], const Unit& u, int wr, int wc, int fr, int fq) const {
;     ...
;                     if (xin32) { const float* p = xin32 + off + bj * HALF; a0 = *(const f32x4*)p; a1 = *(const f32x4*)(p + 4); }
;                     else { const u32x4 w = *(const u32x4*)(xb + off + bj * HALF);
;                         a0 = (f32x4){__uint_as_float(w.x << 16), __uint_as_float(w.x & 0xffff0000u), __uint_as_float(w.y << 16), __uint_as_float(w.y & 0xffff0000u)};
;                         a1 = (f32x4){__uint_as_float(w.z << 16), __uint_as_float(w.z & 0xffff0000u), __uint_as_float(w.w << 16), __uint_as_float(w.w & 0xffff0000u)}; }
;                     const f32x4 v0 = a0 + acc[ai][bj][m][0] * alpha, v1 = a1 + acc[ai][bj][m][1] * alpha;
;                     u32x4 w; w.x = cvtpk(v0[0], v0[1]); w.y = cvtpk(v0[2], v0[3]); w.z = cvtpk(v1[0], v1[1]); w.w = cvtpk(v1[2], v1[3]);
;                     *(u32x4*)(xb + off + bj * HALF) = w;
.LBB0_299:
	s_waitcnt vmcnt(0)
	v_pk_fma_f32 v[82:83], v[78:79], 0.5, v[82:83] op_sel_hi:[1,0,1]
	v_pk_fma_f32 v[94:95], v[76:77], 0.5, v[80:81] op_sel_hi:[1,0,1]
	v_pk_fma_f32 v[80:81], v[74:75], 0.5, v[86:87] op_sel_hi:[1,0,1]
	v_pk_fma_f32 v[84:85], v[72:73], 0.5, v[84:85] op_sel_hi:[1,0,1]
	v_cvt_pk_bf16_f32 v72, v94, v95
	v_cvt_pk_bf16_f32 v73, v82, v83
	v_cvt_pk_bf16_f32 v74, v84, v85
	v_cvt_pk_bf16_f32 v75, v80, v81
	s_and_b64 vcc, exec, s[10:11]
	global_store_dwordx4 v[90:91], v[72:75], off sc1
	s_cbranch_vccnz .LBB0_346
	global_load_dwordx4 v[76:79], v[92:93], off offset:528
	global_load_dwordx4 v[72:75], v[92:93], off offset:512
	s_cbranch_execnz .LBB0_302

; __device__ __forceinline__ void fx_add(float* p, size_t idx, float s) { atomicAdd((unsigned long long*)p + idx, (unsigned long long)(long long)(s * 4294967296.0f)); }
; __device__ __forceinline__ unsigned cvtpk(float lo, float hi) { f32x2v_ v = {lo, hi}; bf16x2v_ b = __builtin_convertvector(v, bf16x2v_); return __builtin_bit_cast(unsigned, b); }
;     __device__ __forceinline__ void operator()(const f32x4 (&acc)[2][2][4][2], const Unit& u, int wr, int wc, int fr, int fq) const {
;     ...
;                     const f32x4 v0 = a0 + acc[ai][bj][m][0] * alpha, v1 = a1 + acc[ai][bj][m][1] * alpha;
;                     u32x4 w; w.x = cvtpk(v0[0], v0[1]); w.y = cvtpk(v0[2], v0[3]); w.z = cvtpk(v1[0], v1[1]); w.w = cvtpk(v1[2], v1[3]);
;                     *(u32x4*)(xb + off + bj * HALF) = w;
;                     s += (v0[0] * v0[0] + v0[1] * v0[1]) + (v0[2] * v0[2] + v0[3] * v0[3]) + (v1[0] * v1[0] + v1[1] * v1[1]) + (v1[2] * v1[2] + v1[3] * v1[3]); }
;                 s += __shfl_xor(s, 16); s += __shfl_xor(s, 32);
;                 if (fq == 0) fx_add(ssout, row, s); }
.LBB0_302:
	s_waitcnt vmcnt(0)
	v_pk_fma_f32 v[70:71], v[70:71], 0.5, v[74:75] op_sel_hi:[1,0,1]
	v_pk_fma_f32 v[68:69], v[68:69], 0.5, v[72:73] op_sel_hi:[1,0,1]
	v_pk_fma_f32 v[74:75], v[64:65], 0.5, v[76:77] op_sel_hi:[1,0,1]
	v_mul_f32_e32 v64, v69, v69
	v_mul_f32_e32 v65, v71, v71
	v_mul_f32_e32 v86, v95, v95
	v_mul_f32_e32 v83, v83, v83
	v_fmac_f32_e32 v64, v68, v68
	v_fmac_f32_e32 v65, v70, v70
	v_fmac_f32_e32 v86, v94, v94
	v_fmac_f32_e32 v83, v82, v82
	v_add_f32_e32 v64, v64, v65
	v_mul_f32_e32 v65, v75, v75
	v_add_f32_e32 v82, v86, v83
	v_mul_f32_e32 v83, v85, v85
	v_pk_fma_f32 v[72:73], v[66:67], 0.5, v[78:79] op_sel_hi:[1,0,1]
	v_fmac_f32_e32 v65, v74, v74
	v_fmac_f32_e32 v83, v84, v84
	v_mul_f32_e32 v81, v81, v81
	v_add_f32_e32 v64, v65, v64
	v_mul_f32_e32 v65, v73, v73
	v_add_f32_e32 v82, v83, v82
	v_fmac_f32_e32 v81, v80, v80
	v_fmac_f32_e32 v65, v72, v72
	v_add_f32_e32 v80, v81, v82
	v_add_f32_e32 v64, v65, v64
	v_add_f32_e32 v64, v80, v64
	v_mov_b32_e32 v65, v64
	s_nop 1
	v_permlane16_swap_b32_e32 v65, v64
	v_cvt_pk_bf16_f32 v66, v68, v69
	v_cvt_pk_bf16_f32 v67, v70, v71
	v_cvt_pk_bf16_f32 v68, v74, v75
	v_cvt_pk_bf16_f32 v69, v72, v73
	s_waitcnt lgkmcnt(0)
	v_add_f32_e32 v64, v64, v65
	v_mov_b32_e32 v65, v64
	s_nop 1
	v_permlane32_swap_b32_e32 v65, v64
	global_store_dwordx4 v[90:91], v[66:69], off offset:256 sc1
	s_and_saveexec_b64 s[50:51], s[6:7]
	s_cbranch_execz .LBB0_304
	s_waitcnt lgkmcnt(0)
	v_add_f32_e32 v64, v64, v65
	v_mul_f32_e32 v64, 0x4f800000, v64
	v_trunc_f32_e32 v64, v64
	v_mul_f32_e64 v65, |v64|, s67
	v_floor_f32_e32 v65, v65
	v_fma_f32 v66, v65, s86, |v64|
	v_cvt_u32_f32_e32 v64, v66
	v_cvt_u32_f32_e32 v65, v65
	v_lshl_add_u64 v[66:67], v[88:89], 3, s[24:25]
	global_atomic_add_x2 v[66:67], v[64:65], off

; __device__ __forceinline__ unsigned cvtpk(float lo, float hi) { f32x2v_ v = {lo, hi}; bf16x2v_ b = __builtin_convertvector(v, bf16x2v_); return __builtin_bit_cast(unsigned, b); }
;     __device__ __forceinline__ void operator()(const f32x4 (&acc)[2][2][4][2], const Unit& u, int wr, int wc, int fr, int fq) const {
;     ...
;                     if (xin32) { const float* p = xin32 + off + bj * HALF; a0 = *(const f32x4*)p; a1 = *(const f32x4*)(p + 4); }
;                     else { const u32x4 w = *(const u32x4*)(xb + off + bj * HALF);
;                         a0 = (f32x4){__uint_as_float(w.x << 16), __uint_as_float(w.x & 0xffff0000u), __uint_as_float(w.y << 16), __uint_as_float(w.y & 0xffff0000u)};
;                         a1 = (f32x4){__uint_as_float(w.z << 16), __uint_as_float(w.z & 0xffff0000u), __uint_as_float(w.w << 16), __uint_as_float(w.w & 0xffff0000u)}; }
;                     const f32x4 v0 = a0 + acc[ai][bj][m][0] * alpha, v1 = a1 + acc[ai][bj][m][1] * alpha;
;                     u32x4 w; w.x = cvtpk(v0[0], v0[1]); w.y = cvtpk(v0[2], v0[3]); w.z = cvtpk(v1[0], v1[1]); w.w = cvtpk(v1[2], v1[3]);
;                     *(u32x4*)(xb + off + bj * HALF) = w;
.LBB0_307:
	s_waitcnt vmcnt(0)
	v_pk_fma_f32 v[66:67], v[62:63], 0.5, v[66:67] op_sel_hi:[1,0,1]
	v_pk_fma_f32 v[78:79], v[60:61], 0.5, v[64:65] op_sel_hi:[1,0,1]
	v_pk_fma_f32 v[64:65], v[58:59], 0.5, v[70:71] op_sel_hi:[1,0,1]
	v_pk_fma_f32 v[68:69], v[56:57], 0.5, v[68:69] op_sel_hi:[1,0,1]
	v_cvt_pk_bf16_f32 v56, v78, v79
	v_cvt_pk_bf16_f32 v57, v66, v67
	v_cvt_pk_bf16_f32 v58, v68, v69
	v_cvt_pk_bf16_f32 v59, v64, v65
	s_and_b64 vcc, exec, s[10:11]
	global_store_dwordx4 v[74:75], v[56:59], off sc1
	s_cbranch_vccnz .LBB0_348
	global_load_dwordx4 v[60:63], v[76:77], off offset:528
	global_load_dwordx4 v[56:59], v[76:77], off offset:512
	s_cbranch_execnz .LBB0_310

; __device__ __forceinline__ void fx_add(float* p, size_t idx, float s) { atomicAdd((unsigned long long*)p + idx, (unsigned long long)(long long)(s * 4294967296.0f)); }
; __device__ __forceinline__ unsigned cvtpk(float lo, float hi) { f32x2v_ v = {lo, hi}; bf16x2v_ b = __builtin_convertvector(v, bf16x2v_); return __builtin_bit_cast(unsigned, b); }
;     __device__ __forceinline__ void operator()(const f32x4 (&acc)[2][2][4][2], const Unit& u, int wr, int wc, int fr, int fq) const {
;     ...
;                     const f32x4 v0 = a0 + acc[ai][bj][m][0] * alpha, v1 = a1 + acc[ai][bj][m][1] * alpha;
;                     u32x4 w; w.x = cvtpk(v0[0], v0[1]); w.y = cvtpk(v0[2], v0[3]); w.z = cvtpk(v1[0], v1[1]); w.w = cvtpk(v1[2], v1[3]);
;                     *(u32x4*)(xb + off + bj * HALF) = w;
;                     s += (v0[0] * v0[0] + v0[1] * v0[1]) + (v0[2] * v0[2] + v0[3] * v0[3]) + (v1[0] * v1[0] + v1[1] * v1[1]) + (v1[2] * v1[2] + v1[3] * v1[3]); }
;                 s += __shfl_xor(s, 16); s += __shfl_xor(s, 32);
;                 if (fq == 0) fx_add(ssout, row, s); }
.LBB0_310:
	s_waitcnt vmcnt(0)
	v_pk_fma_f32 v[54:55], v[54:55], 0.5, v[58:59] op_sel_hi:[1,0,1]
	v_pk_fma_f32 v[52:53], v[52:53], 0.5, v[56:57] op_sel_hi:[1,0,1]
	v_pk_fma_f32 v[58:59], v[48:49], 0.5, v[60:61] op_sel_hi:[1,0,1]
	v_mul_f32_e32 v48, v53, v53
	v_mul_f32_e32 v49, v55, v55
	v_mul_f32_e32 v70, v79, v79
	v_mul_f32_e32 v67, v67, v67
	v_fmac_f32_e32 v48, v52, v52
	v_fmac_f32_e32 v49, v54, v54
	v_fmac_f32_e32 v70, v78, v78
	v_fmac_f32_e32 v67, v66, v66
	v_add_f32_e32 v48, v48, v49
	v_mul_f32_e32 v49, v59, v59
	v_add_f32_e32 v66, v70, v67
	v_mul_f32_e32 v67, v69, v69
	v_pk_fma_f32 v[56:57], v[50:51], 0.5, v[62:63] op_sel_hi:[1,0,1]
	v_fmac_f32_e32 v49, v58, v58
	v_fmac_f32_e32 v67, v68, v68
	v_mul_f32_e32 v65, v65, v65
	v_add_f32_e32 v48, v49, v48
	v_mul_f32_e32 v49, v57, v57
	v_add_f32_e32 v66, v67, v66
	v_fmac_f32_e32 v65, v64, v64
	v_fmac_f32_e32 v49, v56, v56
	v_add_f32_e32 v64, v65, v66
	v_add_f32_e32 v48, v49, v48
	v_add_f32_e32 v48, v64, v48
	v_mov_b32_e32 v49, v48
	s_nop 1
	v_permlane16_swap_b32_e32 v49, v48
	v_cvt_pk_bf16_f32 v50, v52, v53
	v_cvt_pk_bf16_f32 v51, v54, v55
	v_cvt_pk_bf16_f32 v52, v58, v59
	v_cvt_pk_bf16_f32 v53, v56, v57
	s_waitcnt lgkmcnt(0)
	v_add_f32_e32 v48, v48, v49
	v_mov_b32_e32 v49, v48
	s_nop 1
	v_permlane32_swap_b32_e32 v49, v48
	global_store_dwordx4 v[74:75], v[50:53], off offset:256 sc1
	s_and_saveexec_b64 s[50:51], s[6:7]
	s_cbranch_execz .LBB0_312
	s_waitcnt lgkmcnt(0)
	v_add_f32_e32 v48, v48, v49
	v_mul_f32_e32 v48, 0x4f800000, v48
	v_trunc_f32_e32 v48, v48
	v_mul_f32_e64 v49, |v48|, s67
	v_floor_f32_e32 v49, v49
	v_fma_f32 v50, v49, s86, |v48|
	v_cvt_u32_f32_e32 v48, v50
	v_cvt_u32_f32_e32 v49, v49
	v_lshl_add_u64 v[50:51], v[72:73], 3, s[24:25]
	global_atomic_add_x2 v[50:51], v[48:49], off

; __device__ __forceinline__ unsigned cvtpk(float lo, float hi) { f32x2v_ v = {lo, hi}; bf16x2v_ b = __builtin_convertvector(v, bf16x2v_); return __builtin_bit_cast(unsigned, b); }
;     __device__ __forceinline__ void operator()(const f32x4 (&acc)[2][2][4][2], const Unit& u, int wr, int wc, int fr, int fq) const {
;     ...
;                 for (int bj = 0; bj < 2; ++bj) { f32x4 a0, a1;
;                     if (xin32) { const float* p = xin32 + off + bj * HALF; a0 = *(const f32x4*)p; a1 = *(const f32x4*)(p + 4); }
;                     else { const u32x4 w = *(const u32x4*)(xb + off + bj * HALF);
;                         a0 = (f32x4){__uint_as_float(w.x << 16), __uint_as_float(w.x & 0xffff0000u), __uint_as_float(w.y << 16), __uint_as_float(w.y & 0xffff0000u)};
;                         a1 = (f32x4){__uint_as_float(w.z << 16), __uint_as_float(w.z & 0xffff0000u), __uint_as_float(w.w << 16), __uint_as_float(w.w & 0xffff0000u)}; }
;                     const f32x4 v0 = a0 + acc[ai][bj][m][0] * alpha, v1 = a1 + acc[ai][bj][m][1] * alpha;
;                     u32x4 w; w.x = cvtpk(v0[0], v0[1]); w.y = cvtpk(v0[2], v0[3]); w.z = cvtpk(v1[0], v1[1]); w.w = cvtpk(v1[2], v1[3]);
;                     *(u32x4*)(xb + off + bj * HALF) = w;
.LBB0_315:
	s_waitcnt vmcnt(0)
	v_pk_fma_f32 v[50:51], v[46:47], 0.5, v[50:51] op_sel_hi:[1,0,1]
	v_pk_fma_f32 v[62:63], v[44:45], 0.5, v[48:49] op_sel_hi:[1,0,1]
	v_pk_fma_f32 v[48:49], v[42:43], 0.5, v[54:55] op_sel_hi:[1,0,1]
	v_pk_fma_f32 v[52:53], v[40:41], 0.5, v[52:53] op_sel_hi:[1,0,1]
	v_cvt_pk_bf16_f32 v40, v62, v63
	v_cvt_pk_bf16_f32 v41, v50, v51
	v_cvt_pk_bf16_f32 v42, v52, v53
	v_cvt_pk_bf16_f32 v43, v48, v49
	s_and_b64 vcc, exec, s[10:11]
	global_store_dwordx4 v[58:59], v[40:43], off sc1
	s_cbranch_vccnz .LBB0_350
	global_load_dwordx4 v[44:47], v[60:61], off offset:528
	global_load_dwordx4 v[40:43], v[60:61], off offset:512
	s_cbranch_execnz .LBB0_318

; __device__ __forceinline__ void fx_add(float* p, size_t idx, float s) { atomicAdd((unsigned long long*)p + idx, (unsigned long long)(long long)(s * 4294967296.0f)); }
; __device__ __forceinline__ unsigned cvtpk(float lo, float hi) { f32x2v_ v = {lo, hi}; bf16x2v_ b = __builtin_convertvector(v, bf16x2v_); return __builtin_bit_cast(unsigned, b); }
;     __device__ __forceinline__ void operator()(const f32x4 (&acc)[2][2][4][2], const Unit& u, int wr, int wc, int fr, int fq) const {
;     ...
;                     const f32x4 v0 = a0 + acc[ai][bj][m][0] * alpha, v1 = a1 + acc[ai][bj][m][1] * alpha;
;                     u32x4 w; w.x = cvtpk(v0[0], v0[1]); w.y = cvtpk(v0[2], v0[3]); w.z = cvtpk(v1[0], v1[1]); w.w = cvtpk(v1[2], v1[3]);
;                     *(u32x4*)(xb + off + bj * HALF) = w;
;                     s += (v0[0] * v0[0] + v0[1] * v0[1]) + (v0[2] * v0[2] + v0[3] * v0[3]) + (v1[0] * v1[0] + v1[1] * v1[1]) + (v1[2] * v1[2] + v1[3] * v1[3]); }
;                 s += __shfl_xor(s, 16); s += __shfl_xor(s, 32);
;                 if (fq == 0) fx_add(ssout, row, s); }
.LBB0_318:
	s_waitcnt vmcnt(0)
	v_pk_fma_f32 v[38:39], v[38:39], 0.5, v[42:43] op_sel_hi:[1,0,1]
	v_pk_fma_f32 v[36:37], v[36:37], 0.5, v[40:41] op_sel_hi:[1,0,1]
	v_pk_fma_f32 v[42:43], v[32:33], 0.5, v[44:45] op_sel_hi:[1,0,1]
	v_mul_f32_e32 v32, v37, v37
	v_mul_f32_e32 v33, v39, v39
	v_mul_f32_e32 v54, v63, v63
	v_mul_f32_e32 v51, v51, v51
	v_fmac_f32_e32 v32, v36, v36
	v_fmac_f32_e32 v33, v38, v38
	v_fmac_f32_e32 v54, v62, v62
	v_fmac_f32_e32 v51, v50, v50
	v_add_f32_e32 v32, v32, v33
	v_mul_f32_e32 v33, v43, v43
	v_add_f32_e32 v50, v54, v51
	v_mul_f32_e32 v51, v53, v53
	v_pk_fma_f32 v[40:41], v[34:35], 0.5, v[46:47] op_sel_hi:[1,0,1]
	v_fmac_f32_e32 v33, v42, v42
	v_fmac_f32_e32 v51, v52, v52
	v_mul_f32_e32 v49, v49, v49
	v_add_f32_e32 v32, v33, v32
	v_mul_f32_e32 v33, v41, v41
	v_add_f32_e32 v50, v51, v50
	v_fmac_f32_e32 v49, v48, v48
	v_fmac_f32_e32 v33, v40, v40
	v_add_f32_e32 v48, v49, v50
	v_add_f32_e32 v32, v33, v32
	v_add_f32_e32 v32, v48, v32
	v_mov_b32_e32 v33, v32
	s_nop 1
	v_permlane16_swap_b32_e32 v33, v32
	v_cvt_pk_bf16_f32 v34, v36, v37
	v_cvt_pk_bf16_f32 v35, v38, v39
	v_cvt_pk_bf16_f32 v36, v42, v43
	v_cvt_pk_bf16_f32 v37, v40, v41
	s_waitcnt lgkmcnt(0)
	v_add_f32_e32 v32, v32, v33
	v_mov_b32_e32 v33, v32
	s_nop 1
	v_permlane32_swap_b32_e32 v33, v32
	global_store_dwordx4 v[58:59], v[34:37], off offset:256 sc1
	s_and_saveexec_b64 s[50:51], s[6:7]
	s_cbranch_execz .LBB0_320
	s_waitcnt lgkmcnt(0)
	v_add_f32_e32 v32, v32, v33
	v_mul_f32_e32 v32, 0x4f800000, v32
	v_trunc_f32_e32 v32, v32
	v_mul_f32_e64 v33, |v32|, s67
	v_floor_f32_e32 v33, v33
	v_fma_f32 v34, v33, s86, |v32|
	v_cvt_u32_f32_e32 v32, v34
	v_cvt_u32_f32_e32 v33, v33
	v_lshl_add_u64 v[34:35], v[56:57], 3, s[24:25]
	global_atomic_add_x2 v[34:35], v[32:33], off

; __device__ __forceinline__ unsigned cvtpk(float lo, float hi) { f32x2v_ v = {lo, hi}; bf16x2v_ b = __builtin_convertvector(v, bf16x2v_); return __builtin_bit_cast(unsigned, b); }
;     __device__ __forceinline__ void operator()(const f32x4 (&acc)[2][2][4][2], const Unit& u, int wr, int wc, int fr, int fq) const {
;     ...
;                 for (int bj = 0; bj < 2; ++bj) { f32x4 a0, a1;
;                     if (xin32) { const float* p = xin32 + off + bj * HALF; a0 = *(const f32x4*)p; a1 = *(const f32x4*)(p + 4); }
;                     else { const u32x4 w = *(const u32x4*)(xb + off + bj * HALF);
;                         a0 = (f32x4){__uint_as_float(w.x << 16), __uint_as_float(w.x & 0xffff0000u), __uint_as_float(w.y << 16), __uint_as_float(w.y & 0xffff0000u)};
;                         a1 = (f32x4){__uint_as_float(w.z << 16), __uint_as_float(w.z & 0xffff0000u), __uint_as_float(w.w << 16), __uint_as_float(w.w & 0xffff0000u)}; }
;                     const f32x4 v0 = a0 + acc[ai][bj][m][0] * alpha, v1 = a1 + acc[ai][bj][m][1] * alpha;
;                     u32x4 w; w.x = cvtpk(v0[0], v0[1]); w.y = cvtpk(v0[2], v0[3]); w.z = cvtpk(v1[0], v1[1]); w.w = cvtpk(v1[2], v1[3]);
;                     *(u32x4*)(xb + off + bj * HALF) = w;
.LBB0_323:
	s_waitcnt vmcnt(0)
	v_pk_fma_f32 v[34:35], v[30:31], 0.5, v[34:35] op_sel_hi:[1,0,1]
	v_pk_fma_f32 v[46:47], v[28:29], 0.5, v[32:33] op_sel_hi:[1,0,1]
	v_pk_fma_f32 v[32:33], v[26:27], 0.5, v[38:39] op_sel_hi:[1,0,1]
	v_pk_fma_f32 v[36:37], v[24:25], 0.5, v[36:37] op_sel_hi:[1,0,1]
	v_cvt_pk_bf16_f32 v24, v46, v47
	v_cvt_pk_bf16_f32 v25, v34, v35
	v_cvt_pk_bf16_f32 v26, v36, v37
	v_cvt_pk_bf16_f32 v27, v32, v33
	s_and_b64 vcc, exec, s[10:11]
	global_store_dwordx4 v[42:43], v[24:27], off sc1
	s_cbranch_vccnz .LBB0_352
	global_load_dwordx4 v[28:31], v[44:45], off offset:528
	global_load_dwordx4 v[24:27], v[44:45], off offset:512
	s_cbranch_execnz .LBB0_326

; __device__ __forceinline__ void fx_add(float* p, size_t idx, float s) { atomicAdd((unsigned long long*)p + idx, (unsigned long long)(long long)(s * 4294967296.0f)); }
; __device__ __forceinline__ unsigned cvtpk(float lo, float hi) { f32x2v_ v = {lo, hi}; bf16x2v_ b = __builtin_convertvector(v, bf16x2v_); return __builtin_bit_cast(unsigned, b); }
;     __device__ __forceinline__ void operator()(const f32x4 (&acc)[2][2][4][2], const Unit& u, int wr, int wc, int fr, int fq) const {
;     ...
;                     const f32x4 v0 = a0 + acc[ai][bj][m][0] * alpha, v1 = a1 + acc[ai][bj][m][1] * alpha;
;                     u32x4 w; w.x = cvtpk(v0[0], v0[1]); w.y = cvtpk(v0[2], v0[3]); w.z = cvtpk(v1[0], v1[1]); w.w = cvtpk(v1[2], v1[3]);
;                     *(u32x4*)(xb + off + bj * HALF) = w;
;                     s += (v0[0] * v0[0] + v0[1] * v0[1]) + (v0[2] * v0[2] + v0[3] * v0[3]) + (v1[0] * v1[0] + v1[1] * v1[1]) + (v1[2] * v1[2] + v1[3] * v1[3]); }
;                 s += __shfl_xor(s, 16); s += __shfl_xor(s, 32);
;                 if (fq == 0) fx_add(ssout, row, s); }
.LBB0_326:
	s_waitcnt vmcnt(0)
	v_pk_fma_f32 v[22:23], v[22:23], 0.5, v[26:27] op_sel_hi:[1,0,1]
	v_pk_fma_f32 v[20:21], v[20:21], 0.5, v[24:25] op_sel_hi:[1,0,1]
	v_pk_fma_f32 v[26:27], v[16:17], 0.5, v[28:29] op_sel_hi:[1,0,1]
	v_mul_f32_e32 v16, v21, v21
	v_mul_f32_e32 v17, v23, v23
	v_mul_f32_e32 v38, v47, v47
	v_mul_f32_e32 v35, v35, v35
	v_fmac_f32_e32 v16, v20, v20
	v_fmac_f32_e32 v17, v22, v22
	v_fmac_f32_e32 v38, v46, v46
	v_fmac_f32_e32 v35, v34, v34
	v_add_f32_e32 v16, v16, v17
	v_mul_f32_e32 v17, v27, v27
	v_add_f32_e32 v34, v38, v35
	v_mul_f32_e32 v35, v37, v37
	v_pk_fma_f32 v[24:25], v[18:19], 0.5, v[30:31] op_sel_hi:[1,0,1]
	v_fmac_f32_e32 v17, v26, v26
	v_fmac_f32_e32 v35, v36, v36
	v_mul_f32_e32 v33, v33, v33
	v_add_f32_e32 v16, v17, v16
	v_mul_f32_e32 v17, v25, v25
	v_add_f32_e32 v34, v35, v34
	v_fmac_f32_e32 v33, v32, v32
	v_fmac_f32_e32 v17, v24, v24
	v_add_f32_e32 v32, v33, v34
	v_add_f32_e32 v16, v17, v16
	v_add_f32_e32 v16, v32, v16
	v_mov_b32_e32 v17, v16
	s_nop 1
	v_permlane16_swap_b32_e32 v17, v16
	v_cvt_pk_bf16_f32 v18, v20, v21
	v_cvt_pk_bf16_f32 v19, v22, v23
	v_cvt_pk_bf16_f32 v20, v26, v27
	v_cvt_pk_bf16_f32 v21, v24, v25
	s_waitcnt lgkmcnt(0)
	v_add_f32_e32 v16, v16, v17
	v_mov_b32_e32 v17, v16
	s_nop 1
	v_permlane32_swap_b32_e32 v17, v16
	global_store_dwordx4 v[42:43], v[18:21], off offset:256 sc1
	s_and_saveexec_b64 s[50:51], s[6:7]
	s_cbranch_execz .LBB0_328
	s_waitcnt lgkmcnt(0)
	v_add_f32_e32 v16, v16, v17
	v_mul_f32_e32 v16, 0x4f800000, v16
	v_trunc_f32_e32 v16, v16
	v_mul_f32_e64 v17, |v16|, s67
	v_floor_f32_e32 v17, v17
	v_fma_f32 v18, v17, s86, |v16|
	v_cvt_u32_f32_e32 v16, v18
	v_cvt_u32_f32_e32 v17, v17
	v_lshl_add_u64 v[18:19], v[40:41], 3, s[24:25]
	global_atomic_add_x2 v[18:19], v[16:17], off

; __device__ __forceinline__ unsigned cvtpk(float lo, float hi) { f32x2v_ v = {lo, hi}; bf16x2v_ b = __builtin_convertvector(v, bf16x2v_); return __builtin_bit_cast(unsigned, b); }
;     __device__ __forceinline__ void operator()(const f32x4 (&acc)[2][2][4][2], const Unit& u, int wr, int wc, int fr, int fq) const {
;     ...
;                 for (int bj = 0; bj < 2; ++bj) { f32x4 a0, a1;
;                     if (xin32) { const float* p = xin32 + off + bj * HALF; a0 = *(const f32x4*)p; a1 = *(const f32x4*)(p + 4); }
;                     else { const u32x4 w = *(const u32x4*)(xb + off + bj * HALF);
;                         a0 = (f32x4){__uint_as_float(w.x << 16), __uint_as_float(w.x & 0xffff0000u), __uint_as_float(w.y << 16), __uint_as_float(w.y & 0xffff0000u)};
;                         a1 = (f32x4){__uint_as_float(w.z << 16), __uint_as_float(w.z & 0xffff0000u), __uint_as_float(w.w << 16), __uint_as_float(w.w & 0xffff0000u)}; }
;                     const f32x4 v0 = a0 + acc[ai][bj][m][0] * alpha, v1 = a1 + acc[ai][bj][m][1] * alpha;
;                     u32x4 w; w.x = cvtpk(v0[0], v0[1]); w.y = cvtpk(v0[2], v0[3]); w.z = cvtpk(v1[0], v1[1]); w.w = cvtpk(v1[2], v1[3]);
;                     *(u32x4*)(xb + off + bj * HALF) = w;
.LBB0_331:
	s_waitcnt vmcnt(0)
	v_pk_fma_f32 v[18:19], v[14:15], 0.5, v[18:19] op_sel_hi:[1,0,1]
	v_pk_fma_f32 v[30:31], v[12:13], 0.5, v[16:17] op_sel_hi:[1,0,1]
	v_pk_fma_f32 v[16:17], v[10:11], 0.5, v[22:23] op_sel_hi:[1,0,1]
	v_pk_fma_f32 v[20:21], v[8:9], 0.5, v[20:21] op_sel_hi:[1,0,1]
	v_cvt_pk_bf16_f32 v8, v30, v31
	v_cvt_pk_bf16_f32 v9, v18, v19
	v_cvt_pk_bf16_f32 v10, v20, v21
	v_cvt_pk_bf16_f32 v11, v16, v17
	s_and_b64 vcc, exec, s[10:11]
	global_store_dwordx4 v[26:27], v[8:11], off sc1
	s_cbranch_vccnz .LBB0_354
	global_load_dwordx4 v[12:15], v[28:29], off offset:528
	global_load_dwordx4 v[8:11], v[28:29], off offset:512
	s_cbranch_execnz .LBB0_334

; __device__ __forceinline__ void fx_add(float* p, size_t idx, float s) { atomicAdd((unsigned long long*)p + idx, (unsigned long long)(long long)(s * 4294967296.0f)); }
; __device__ __forceinline__ unsigned cvtpk(float lo, float hi) { f32x2v_ v = {lo, hi}; bf16x2v_ b = __builtin_convertvector(v, bf16x2v_); return __builtin_bit_cast(unsigned, b); }
;     __device__ __forceinline__ void operator()(const f32x4 (&acc)[2][2][4][2], const Unit& u, int wr, int wc, int fr, int fq) const {
;     ...
;                     const f32x4 v0 = a0 + acc[ai][bj][m][0] * alpha, v1 = a1 + acc[ai][bj][m][1] * alpha;
;                     u32x4 w; w.x = cvtpk(v0[0], v0[1]); w.y = cvtpk(v0[2], v0[3]); w.z = cvtpk(v1[0], v1[1]); w.w = cvtpk(v1[2], v1[3]);
;                     *(u32x4*)(xb + off + bj * HALF) = w;
;                     s += (v0[0] * v0[0] + v0[1] * v0[1]) + (v0[2] * v0[2] + v0[3] * v0[3]) + (v1[0] * v1[0] + v1[1] * v1[1]) + (v1[2] * v1[2] + v1[3] * v1[3]); }
;                 s += __shfl_xor(s, 16); s += __shfl_xor(s, 32);
;                 if (fq == 0) fx_add(ssout, row, s); }
.LBB0_334:
	s_waitcnt vmcnt(0)
	v_pk_fma_f32 v[6:7], v[6:7], 0.5, v[10:11] op_sel_hi:[1,0,1]
	v_pk_fma_f32 v[4:5], v[4:5], 0.5, v[8:9] op_sel_hi:[1,0,1]
	v_pk_fma_f32 v[10:11], v[0:1], 0.5, v[12:13] op_sel_hi:[1,0,1]
	v_mul_f32_e32 v0, v5, v5
	v_mul_f32_e32 v1, v7, v7
	v_mul_f32_e32 v22, v31, v31
	v_mul_f32_e32 v19, v19, v19
	v_fmac_f32_e32 v0, v4, v4
	v_fmac_f32_e32 v1, v6, v6
	v_fmac_f32_e32 v22, v30, v30
	v_fmac_f32_e32 v19, v18, v18
	v_add_f32_e32 v0, v0, v1
	v_mul_f32_e32 v1, v11, v11
	v_add_f32_e32 v18, v22, v19
	v_mul_f32_e32 v19, v21, v21
	v_pk_fma_f32 v[8:9], v[2:3], 0.5, v[14:15] op_sel_hi:[1,0,1]
	v_fmac_f32_e32 v1, v10, v10
	v_fmac_f32_e32 v19, v20, v20
	v_mul_f32_e32 v17, v17, v17
	v_add_f32_e32 v0, v1, v0
	v_mul_f32_e32 v1, v9, v9
	v_add_f32_e32 v18, v19, v18
	v_fmac_f32_e32 v17, v16, v16
	v_fmac_f32_e32 v1, v8, v8
	v_add_f32_e32 v16, v17, v18
	v_add_f32_e32 v0, v1, v0
	v_add_f32_e32 v0, v16, v0
	v_mov_b32_e32 v1, v0
	s_nop 1
	v_permlane16_swap_b32_e32 v1, v0
	v_cvt_pk_bf16_f32 v2, v4, v5
	v_cvt_pk_bf16_f32 v3, v6, v7
	v_cvt_pk_bf16_f32 v4, v10, v11
	v_cvt_pk_bf16_f32 v5, v8, v9
	s_waitcnt lgkmcnt(0)
	v_add_f32_e32 v0, v0, v1
	v_mov_b32_e32 v1, v0
	s_nop 1
	v_permlane32_swap_b32_e32 v1, v0
	global_store_dwordx4 v[26:27], v[2:5], off offset:256 sc1
	s_and_saveexec_b64 s[10:11], s[6:7]
	s_cbranch_execz .LBB0_336
	s_waitcnt lgkmcnt(0)
	v_add_f32_e32 v0, v0, v1
	v_mul_f32_e32 v0, 0x4f800000, v0
	v_trunc_f32_e32 v0, v0
	v_mul_f32_e64 v1, |v0|, s67
	v_floor_f32_e32 v1, v1
	v_fma_f32 v2, v1, s86, |v0|
	v_cvt_u32_f32_e32 v0, v2
	v_cvt_u32_f32_e32 v1, v1
	v_lshl_add_u64 v[2:3], v[24:25], 3, s[24:25]
	global_atomic_add_x2 v[2:3], v[0:1], off

; __device__ __forceinline__ unsigned cvtpk(float lo, float hi) { f32x2v_ v = {lo, hi}; bf16x2v_ b = __builtin_convertvector(v, bf16x2v_); return __builtin_bit_cast(unsigned, b); }
;     __device__ __forceinline__ void operator()(const f32x4 (&acc)[2][2][4][2], const Unit& u, int wr, int wc, int fr, int fq) const {
;     ...
;                 const int c = c0 - kbeg, head = c >> dh_shift, d = c & (DH - 1);
;                 float cs[8];
; #pragma unroll
;                 for (int e = 0; e < 8; ++e) cs[e] = 0.f;
; #pragma unroll
;                 for (int ai = 0; ai < 2; ++ai)
; #pragma unroll
;                     for (int m = 0; m < 4; ++m) { const int row = row0 + ai * HALF + m * 16; const float rs = ss ? row_rs(ss, row) : 1.0f;
;                         const f32x4 v0 = acc[ai][bj][m][0] * rs, v1 = acc[ai][bj][m][1] * rs;
;                         const int b = row >> S_shift, pos = row & ((1 << S_shift) - 1);
;                         const size_t tile = ((size_t)(b * kvh + head) << (S_shift - 5)) + (pos >> 5);
;                         u32x4 w; w.x = cvtpk(v0[0], v0[1]); w.y = cvtpk(v0[2], v0[3]); w.z = cvtpk(v1[0], v1[1]); w.w = cvtpk(v1[2], v1[3]);
;                         *(u32x4*)(KP + tile * (size_t)(32 * DH) + ((d >> 3) * 32 + (pos & 31)) * 8) = w;
.LBB0_423:
	s_andn2_b64 vcc, exec, s[54:55]
	s_cbranch_vccnz .LBB0_425
	v_add_u32_e32 v120, 0xfffff800, v158
	v_ashrrev_i32_e32 v159, 6, v120
	v_add_u32_e32 v124, v157, v159
	v_ashrrev_i32_e32 v125, 31, v124
	v_lshlrev_b64 v[124:125], 19, v[124:125]
	v_lshlrev_b32_e32 v136, 7, v156
	v_lshl_add_u64 v[124:125], s[26:27], 0, v[124:125]
	v_and_b32_e32 v136, 0x7e000, v136
	v_lshl_add_u64 v[174:175], v[124:125], 0, v[136:137]
	v_lshlrev_b32_e32 v136, 1, v144
	v_cvt_pk_bf16_f32 v120, v162, v163
	v_cvt_pk_bf16_f32 v121, v126, v127
	v_cvt_pk_bf16_f32 v122, v164, v165
	v_cvt_pk_bf16_f32 v123, v160, v161
	v_lshl_add_u64 v[178:179], v[174:175], 0, v[136:137]
	global_store_dwordx4 v[178:179], v[120:123], off sc1
	v_or_b32_e32 v178, 32, v156
	v_ashrrev_i32_e32 v179, 31, v178
	v_or_b32_e32 v120, 16, v156
	v_ashrrev_i32_e32 v121, 31, v120
	v_lshl_add_u64 v[122:123], v[120:121], 3, s[24:25]
	global_load_dwordx2 v[122:123], v[122:123], off
	v_and_or_b32 v120, v120, 31, v168
	v_mov_b32_e32 v121, v137
	v_lshlrev_b32_e32 v120, 4, v120
	v_lshl_add_u64 v[174:175], v[174:175], 0, v[120:121]
	v_lshl_add_u64 v[182:183], v[178:179], 3, s[24:25]
	s_waitcnt vmcnt(0)
	v_ffbh_u32_e32 v157, v123
	v_min_u32_e32 v157, 32, v157
	v_lshlrev_b64 v[122:123], v157, v[122:123]
	v_min_u32_e32 v122, 1, v122
	v_or_b32_e32 v122, v123, v122
	v_cvt_f32_u32_e32 v122, v122
	v_sub_u32_e32 v123, 32, v157
	v_ldexp_f32 v122, v122, v123
	v_mul_f32_e32 v122, 0x2f800000, v122
	v_fmamk_f32 v122, v122, 0x3a800000, v172
	v_rsq_f32_e32 v122, v122
	s_nop 0
	v_pk_mul_f32 v[184:185], v[118:119], v[122:123] op_sel_hi:[1,0]
	v_pk_mul_f32 v[120:121], v[116:117], v[122:123] op_sel_hi:[1,0]
	v_pk_mul_f32 v[186:187], v[114:115], v[122:123] op_sel_hi:[1,0]
	v_pk_mul_f32 v[122:123], v[112:113], v[122:123] op_sel_hi:[1,0]
	v_cvt_pk_bf16_f32 v120, v120, v121
	v_cvt_pk_bf16_f32 v121, v184, v185
	v_cvt_pk_bf16_f32 v122, v122, v123
	v_cvt_pk_bf16_f32 v123, v186, v187
	global_store_dwordx4 v[174:175], v[120:123], off sc1
	global_load_dwordx2 v[120:121], v[182:183], off
	v_or_b32_e32 v174, 48, v156
	v_lshlrev_b32_e32 v122, 7, v178
	v_mov_b32_e32 v123, v137
	v_and_b32_e32 v122, 0x7f000, v122
	v_lshl_add_u64 v[122:123], v[124:125], 0, v[122:123]
	v_lshl_add_u64 v[182:183], v[122:123], 0, v[136:137]
	v_ashrrev_i32_e32 v175, 31, v174
	v_lshl_add_u64 v[178:179], v[174:175], 3, s[24:25]
	v_mov_b32_e32 v175, v137
	s_waitcnt vmcnt(0)
	v_ffbh_u32_e32 v157, v121
	v_min_u32_e32 v157, 32, v157
	v_lshlrev_b64 v[120:121], v157, v[120:121]
	v_min_u32_e32 v120, 1, v120
	v_or_b32_e32 v120, v121, v120
	v_cvt_f32_u32_e32 v120, v120
	v_sub_u32_e32 v121, 32, v157
	v_ldexp_f32 v120, v120, v121
	v_mul_f32_e32 v120, 0x2f800000, v120
	v_fmamk_f32 v120, v120, 0x3a800000, v172
	v_rsq_f32_e32 v120, v120
	s_nop 0
	v_pk_mul_f32 v[122:123], v[110:111], v[120:121] op_sel_hi:[1,0]
	v_pk_mul_f32 v[184:185], v[108:109], v[120:121] op_sel_hi:[1,0]
	v_pk_mul_f32 v[186:187], v[106:107], v[120:121] op_sel_hi:[1,0]
	v_pk_mul_f32 v[188:189], v[104:105], v[120:121] op_sel_hi:[1,0]
	v_cvt_pk_bf16_f32 v120, v184, v185
	v_cvt_pk_bf16_f32 v121, v122, v123
	v_cvt_pk_bf16_f32 v122, v188, v189
	v_cvt_pk_bf16_f32 v123, v186, v187
	global_store_dwordx4 v[182:183], v[120:123], off sc1
	global_load_dwordx2 v[120:121], v[178:179], off
	s_waitcnt vmcnt(0)
	v_ffbh_u32_e32 v157, v121
	v_min_u32_e32 v157, 32, v157
	v_lshlrev_b64 v[120:121], v157, v[120:121]
	v_min_u32_e32 v120, 1, v120
	v_or_b32_e32 v120, v121, v120
	v_cvt_f32_u32_e32 v120, v120
	v_sub_u32_e32 v157, 32, v157
	v_lshlrev_b32_e32 v122, 7, v174
	v_mov_b32_e32 v123, v137
	v_ldexp_f32 v120, v120, v157
	v_mul_f32_e32 v120, 0x2f800000, v120
	v_fmamk_f32 v120, v120, 0x3a800000, v172
	v_rsq_f32_e32 v120, v120
	v_and_or_b32 v121, v174, 31, v168
	v_and_b32_e32 v122, 0x7f000, v122
	v_lshlrev_b32_e32 v174, 4, v121
	v_lshl_add_u64 v[122:123], v[124:125], 0, v[122:123]
	v_lshl_add_u64 v[124:125], v[122:123], 0, v[174:175]
	v_pk_mul_f32 v[122:123], v[102:103], v[120:121] op_sel_hi:[1,0]
	v_pk_mul_f32 v[174:175], v[100:101], v[120:121] op_sel_hi:[1,0]
	v_pk_mul_f32 v[178:179], v[98:99], v[120:121] op_sel_hi:[1,0]
	v_pk_mul_f32 v[182:183], v[96:97], v[120:121] op_sel_hi:[1,0]
	v_cvt_pk_bf16_f32 v120, v174, v175
	v_cvt_pk_bf16_f32 v121, v122, v123
	v_cvt_pk_bf16_f32 v122, v182, v183
	v_cvt_pk_bf16_f32 v123, v178, v179
	global_store_dwordx4 v[124:125], v[120:123], off sc1
	global_load_dwordx2 v[120:121], v[154:155], off offset:1024
	s_waitcnt vmcnt(0)
; __device__ __forceinline__ unsigned cvtpk(float lo, float hi) { f32x2v_ v = {lo, hi}; bf16x2v_ b = __builtin_convertvector(v, bf16x2v_); return __builtin_bit_cast(unsigned, b); }
;     __device__ __forceinline__ void operator()(const f32x4 (&acc)[2][2][4][2], const Unit& u, int wr, int wc, int fr, int fq) const {
;     ...
;                     for (int m = 0; m < 4; ++m) { const int row = row0 + ai * HALF + m * 16; const float rs = ss ? row_rs(ss, row) : 1.0f;
;                         const f32x4 v0 = acc[ai][bj][m][0] * rs, v1 = acc[ai][bj][m][1] * rs;
;                         const int b = row >> S_shift, pos = row & ((1 << S_shift) - 1);
;                         const size_t tile = ((size_t)(b * kvh + head) << (S_shift - 5)) + (pos >> 5);
;                         u32x4 w; w.x = cvtpk(v0[0], v0[1]); w.y = cvtpk(v0[2], v0[3]); w.z = cvtpk(v1[0], v1[1]); w.w = cvtpk(v1[2], v1[3]);
;                         *(u32x4*)(KP + tile * (size_t)(32 * DH) + ((d >> 3) * 32 + (pos & 31)) * 8) = w;
	v_ffbh_u32_e32 v125, v121
	v_min_u32_e32 v157, 32, v125
	v_lshlrev_b64 v[120:121], v157, v[120:121]
	v_add_u32_e32 v122, 0x80, v156
	v_min_u32_e32 v120, 1, v120
	v_ashrrev_i32_e32 v124, 11, v122
	v_or_b32_e32 v120, v121, v120
	v_and_b32_e32 v124, -2, v124
	v_cvt_f32_u32_e32 v173, v120
	v_add_u32_e32 v124, v124, v159
	v_ashrrev_i32_e32 v125, 31, v124
	v_lshlrev_b64 v[120:121], 19, v[124:125]
	v_sub_u32_e32 v124, 32, v157
	v_ldexp_f32 v124, v173, v124
	v_mul_f32_e32 v124, 0x2f800000, v124
	v_fmamk_f32 v124, v124, 0x3a800000, v172
	v_rsq_f32_e32 v124, v124
	v_lshlrev_b32_e32 v122, 7, v122
	v_mov_b32_e32 v123, v137
	v_and_b32_e32 v122, 0x7e000, v122
	v_lshl_add_u64 v[120:121], s[26:27], 0, v[120:121]
	v_lshl_add_u64 v[120:121], v[120:121], 0, v[122:123]
	v_lshl_add_u64 v[174:175], v[120:121], 0, v[136:137]
	v_pk_mul_f32 v[122:123], v[94:95], v[124:125] op_sel_hi:[1,0]
	v_pk_mul_f32 v[120:121], v[92:93], v[124:125] op_sel_hi:[1,0]
	v_pk_mul_f32 v[178:179], v[90:91], v[124:125] op_sel_hi:[1,0]
	v_pk_mul_f32 v[124:125], v[88:89], v[124:125] op_sel_hi:[1,0]
	v_cvt_pk_bf16_f32 v120, v120, v121
	v_cvt_pk_bf16_f32 v121, v122, v123
	v_cvt_pk_bf16_f32 v122, v124, v125
	v_cvt_pk_bf16_f32 v123, v178, v179
	global_store_dwordx4 v[174:175], v[120:123], off sc1
	global_load_dwordx2 v[120:121], v[154:155], off offset:1152
	v_mov_b32_e32 v125, v137
	v_add_u32_e32 v122, 0x90, v156
	v_lshlrev_b32_e32 v157, 7, v122
	v_ashrrev_i32_e32 v124, 11, v122
	v_and_or_b32 v173, v122, 31, v168
	v_and_b32_e32 v122, 0x7e000, v157
	v_and_b32_e32 v174, -2, v124
	v_lshlrev_b32_e32 v124, 4, v173
	v_add_u32_e32 v174, v174, v159
	v_ashrrev_i32_e32 v175, 31, v174
	v_mov_b32_e32 v123, v137
	s_waitcnt vmcnt(0)
	v_ffbh_u32_e32 v157, v121
	v_min_u32_e32 v157, 32, v157
	v_lshlrev_b64 v[120:121], v157, v[120:121]
	v_min_u32_e32 v120, 1, v120
	v_or_b32_e32 v120, v121, v120
	v_cvt_f32_u32_e32 v173, v120
	v_sub_u32_e32 v157, 32, v157
	v_lshlrev_b64 v[120:121], 19, v[174:175]
	v_lshl_add_u64 v[120:121], s[26:27], 0, v[120:121]
	v_ldexp_f32 v157, v173, v157
	v_mul_f32_e32 v157, 0x2f800000, v157
	v_fmamk_f32 v157, v157, 0x3a800000, v172
	v_rsq_f32_e32 v174, v157
	v_lshl_add_u64 v[120:121], v[120:121], 0, v[122:123]
	v_lshl_add_u64 v[124:125], v[120:121], 0, v[124:125]
	v_pk_mul_f32 v[122:123], v[86:87], v[174:175] op_sel_hi:[1,0]
	v_pk_mul_f32 v[120:121], v[84:85], v[174:175] op_sel_hi:[1,0]
	v_pk_mul_f32 v[178:179], v[82:83], v[174:175] op_sel_hi:[1,0]
	v_pk_mul_f32 v[174:175], v[80:81], v[174:175] op_sel_hi:[1,0]
	v_cvt_pk_bf16_f32 v120, v120, v121
	v_cvt_pk_bf16_f32 v121, v122, v123
	v_cvt_pk_bf16_f32 v122, v174, v175
	v_cvt_pk_bf16_f32 v123, v178, v179
	global_store_dwordx4 v[124:125], v[120:123], off sc1
	global_load_dwordx2 v[120:121], v[154:155], off offset:1280
	s_waitcnt vmcnt(0)
	v_ffbh_u32_e32 v125, v121
	v_min_u32_e32 v157, 32, v125
	v_lshlrev_b64 v[120:121], v157, v[120:121]
	v_add_u32_e32 v122, 0xa0, v156
	v_min_u32_e32 v120, 1, v120
	v_ashrrev_i32_e32 v124, 11, v122
	v_or_b32_e32 v120, v121, v120
	v_and_b32_e32 v124, -2, v124
	v_cvt_f32_u32_e32 v173, v120
	v_add_u32_e32 v124, v124, v159
	v_ashrrev_i32_e32 v125, 31, v124
	v_lshlrev_b64 v[120:121], 19, v[124:125]
	v_sub_u32_e32 v124, 32, v157
	v_ldexp_f32 v124, v173, v124
	v_mul_f32_e32 v124, 0x2f800000, v124
	v_fmamk_f32 v124, v124, 0x3a800000, v172
	v_rsq_f32_e32 v124, v124
	v_lshlrev_b32_e32 v122, 7, v122
	v_mov_b32_e32 v123, v137
	v_and_b32_e32 v122, 0x7f000, v122
	v_lshl_add_u64 v[120:121], s[26:27], 0, v[120:121]
	v_lshl_add_u64 v[120:121], v[120:121], 0, v[122:123]
	v_lshl_add_u64 v[174:175], v[120:121], 0, v[136:137]
	v_pk_mul_f32 v[122:123], v[78:79], v[124:125] op_sel_hi:[1,0]
	v_pk_mul_f32 v[120:121], v[76:77], v[124:125] op_sel_hi:[1,0]
	v_pk_mul_f32 v[178:179], v[74:75], v[124:125] op_sel_hi:[1,0]
	v_pk_mul_f32 v[124:125], v[72:73], v[124:125] op_sel_hi:[1,0]
	v_cvt_pk_bf16_f32 v120, v120, v121
	v_cvt_pk_bf16_f32 v121, v122, v123
	v_cvt_pk_bf16_f32 v122, v124, v125
	v_cvt_pk_bf16_f32 v123, v178, v179
	global_store_dwordx4 v[174:175], v[120:123], off sc1
	global_load_dwordx2 v[120:121], v[154:155], off offset:1408
	s_waitcnt vmcnt(0)
	v_ffbh_u32_e32 v125, v121
	v_min_u32_e32 v125, 32, v125
	v_lshlrev_b64 v[120:121], v125, v[120:121]
	v_add_u32_e32 v122, 0xb0, v156
	v_min_u32_e32 v120, 1, v120
	v_ashrrev_i32_e32 v123, 11, v122
	v_or_b32_e32 v120, v121, v120
	v_lshlrev_b32_e32 v124, 7, v122
	v_and_or_b32 v157, v122, 31, v168
	v_and_b32_e32 v122, -2, v123
	v_cvt_f32_u32_e32 v136, v120
	v_add_u32_e32 v122, v122, v159
	v_ashrrev_i32_e32 v123, 31, v122
	v_lshlrev_b64 v[120:121], 19, v[122:123]
	v_sub_u32_e32 v122, 32, v125
	v_ldexp_f32 v122, v136, v122
	v_mul_f32_e32 v122, 0x2f800000, v122
	v_fmamk_f32 v122, v122, 0x3a800000, v172
	v_rsq_f32_e32 v122, v122
	v_lshl_add_u64 v[120:121], s[26:27], 0, v[120:121]
	v_and_b32_e32 v136, 0x7f000, v124
	v_lshl_add_u64 v[124:125], v[120:121], 0, v[136:137]
	v_lshlrev_b32_e32 v136, 4, v157
	v_pk_mul_f32 v[174:175], v[62:63], v[122:123] op_sel_hi:[1,0]
	v_pk_mul_f32 v[120:121], v[60:61], v[122:123] op_sel_hi:[1,0]
	v_pk_mul_f32 v[178:179], v[58:59], v[122:123] op_sel_hi:[1,0]
	v_pk_mul_f32 v[122:123], v[56:57], v[122:123] op_sel_hi:[1,0]
	v_cvt_pk_bf16_f32 v120, v120, v121
	v_cvt_pk_bf16_f32 v121, v174, v175
	v_cvt_pk_bf16_f32 v122, v122, v123
	v_cvt_pk_bf16_f32 v123, v178, v179
	v_lshl_add_u64 v[124:125], v[124:125], 0, v[136:137]
	global_store_dwordx4 v[124:125], v[120:123], off sc1

; __device__ __forceinline__ unsigned cvtpk(float lo, float hi) { f32x2v_ v = {lo, hi}; bf16x2v_ b = __builtin_convertvector(v, bf16x2v_); return __builtin_bit_cast(unsigned, b); }
;     __device__ __forceinline__ void operator()(const f32x4 (&acc)[2][2][4][2], const Unit& u, int wr, int wc, int fr, int fq) const {
;     ...
;                 for (int ai = 0; ai < 2; ++ai)
; #pragma unroll
;                     for (int m = 0; m < 4; ++m) { const int row = row0 + ai * HALF + m * 16; const float rs = ss ? row_rs(ss, row) : 1.0f;
;                         const f32x4 v0 = acc[ai][bj][m][0] * rs, v1 = acc[ai][bj][m][1] * rs;
;                         u32x4 w; w.x = cvtpk(v0[0], v0[1]); w.y = cvtpk(v0[2], v0[3]); w.z = cvtpk(v1[0], v1[1]); w.w = cvtpk(v1[2], v1[3]);
;                         *(u32x4*)(O + (size_t)row * ldc + c0) = w; }
.LBB0_426:
	s_andn2_b64 vcc, exec, s[54:55]
	v_or_b32_e32 v124, 16, v156
	v_or_b32_e32 v122, 32, v156
	v_or_b32_e32 v120, 48, v156
	v_add_u32_e32 v175, 0x80, v156
	v_add_u32_e32 v174, 0x90, v156
	v_add_u32_e32 v173, 0xa0, v156
	v_add_u32_e32 v157, 0xb0, v156
	s_cbranch_vccnz .LBB0_428
	v_ashrrev_i32_e32 v159, 31, v158
	v_cvt_pk_bf16_f32 v164, v164, v165
	v_cvt_pk_bf16_f32 v165, v160, v161
	v_mov_b64_e32 v[160:161], s[20:21]
	v_cvt_pk_bf16_f32 v162, v162, v163
	v_cvt_pk_bf16_f32 v163, v126, v127
	v_mad_i64_i32 v[178:179], s[14:15], v156, s88, v[160:161]
	v_lshlrev_b64 v[126:127], 1, v[158:159]
	v_lshl_add_u64 v[158:159], v[178:179], 0, v[126:127]
	v_ashrrev_i32_e32 v125, 31, v124
	global_store_dwordx4 v[158:159], v[162:165], off sc1
	v_lshl_add_u64 v[158:159], v[124:125], 3, s[24:25]
	global_load_dwordx2 v[158:159], v[158:159], off
	s_waitcnt vmcnt(0)
	v_ffbh_u32_e32 v121, v159
	v_min_u32_e32 v121, 32, v121
	v_lshlrev_b64 v[158:159], v121, v[158:159]
	v_min_u32_e32 v123, 1, v158
	v_or_b32_e32 v123, v159, v123
	v_cvt_f32_u32_e32 v125, v123
	v_sub_u32_e32 v121, 32, v121
	v_mad_i64_i32 v[158:159], s[14:15], v124, s88, v[160:161]
	v_ldexp_f32 v121, v125, v121
	v_mul_f32_e32 v121, 0x2f800000, v121
	v_fmamk_f32 v121, v121, 0x3a800000, v172
	v_rsq_f32_e32 v136, v121
	v_ashrrev_i32_e32 v123, 31, v122
	v_lshl_add_u64 v[158:159], v[158:159], 0, v[126:127]
	v_lshl_add_u64 v[162:163], v[122:123], 3, s[24:25]
	v_pk_mul_f32 v[118:119], v[118:119], v[136:137] op_sel_hi:[1,0]
	v_pk_mul_f32 v[116:117], v[116:117], v[136:137] op_sel_hi:[1,0]
	v_pk_mul_f32 v[164:165], v[114:115], v[136:137] op_sel_hi:[1,0]
	v_pk_mul_f32 v[114:115], v[112:113], v[136:137] op_sel_hi:[1,0]
	v_cvt_pk_bf16_f32 v112, v116, v117
	v_cvt_pk_bf16_f32 v113, v118, v119
	v_cvt_pk_bf16_f32 v114, v114, v115
	v_cvt_pk_bf16_f32 v115, v164, v165
	global_store_dwordx4 v[158:159], v[112:115], off sc1
	global_load_dwordx2 v[112:113], v[162:163], off
	v_ashrrev_i32_e32 v121, 31, v120
	v_lshl_add_u64 v[116:117], v[120:121], 3, s[24:25]
	s_waitcnt vmcnt(0)
	v_ffbh_u32_e32 v114, v113
	v_min_u32_e32 v114, 32, v114
	v_lshlrev_b64 v[112:113], v114, v[112:113]
	v_min_u32_e32 v112, 1, v112
	v_or_b32_e32 v112, v113, v112
	v_cvt_f32_u32_e32 v112, v112
	v_sub_u32_e32 v113, 32, v114
	v_mad_i64_i32 v[114:115], s[14:15], v122, s88, v[160:161]
	v_ldexp_f32 v112, v112, v113
	v_mul_f32_e32 v112, 0x2f800000, v112
	v_fmamk_f32 v112, v112, 0x3a800000, v172
	v_rsq_f32_e32 v112, v112
	v_lshl_add_u64 v[114:115], v[114:115], 0, v[126:127]
	v_pk_mul_f32 v[110:111], v[110:111], v[112:113] op_sel_hi:[1,0]
	v_pk_mul_f32 v[108:109], v[108:109], v[112:113] op_sel_hi:[1,0]
	v_pk_mul_f32 v[118:119], v[106:107], v[112:113] op_sel_hi:[1,0]
	v_pk_mul_f32 v[106:107], v[104:105], v[112:113] op_sel_hi:[1,0]
	v_cvt_pk_bf16_f32 v104, v108, v109
	v_cvt_pk_bf16_f32 v105, v110, v111
	v_cvt_pk_bf16_f32 v106, v106, v107
	v_cvt_pk_bf16_f32 v107, v118, v119
	global_store_dwordx4 v[114:115], v[104:107], off sc1
	global_load_dwordx2 v[104:105], v[116:117], off
	s_waitcnt vmcnt(0)
	v_ffbh_u32_e32 v106, v105
	v_min_u32_e32 v106, 32, v106
	v_lshlrev_b64 v[104:105], v106, v[104:105]
	v_min_u32_e32 v104, 1, v104
	v_or_b32_e32 v104, v105, v104
	v_cvt_f32_u32_e32 v104, v104
	v_sub_u32_e32 v105, 32, v106
	v_mad_i64_i32 v[106:107], s[14:15], v120, s88, v[160:161]
	v_ldexp_f32 v104, v104, v105
	v_mul_f32_e32 v104, 0x2f800000, v104
	v_fmamk_f32 v104, v104, 0x3a800000, v172
	v_rsq_f32_e32 v104, v104
	v_lshl_add_u64 v[106:107], v[106:107], 0, v[126:127]
	v_pk_mul_f32 v[102:103], v[102:103], v[104:105] op_sel_hi:[1,0]
	v_pk_mul_f32 v[100:101], v[100:101], v[104:105] op_sel_hi:[1,0]
	v_pk_mul_f32 v[108:109], v[98:99], v[104:105] op_sel_hi:[1,0]
	v_pk_mul_f32 v[98:99], v[96:97], v[104:105] op_sel_hi:[1,0]
	v_cvt_pk_bf16_f32 v96, v100, v101
	v_cvt_pk_bf16_f32 v97, v102, v103
	v_cvt_pk_bf16_f32 v98, v98, v99
	v_cvt_pk_bf16_f32 v99, v108, v109
	global_store_dwordx4 v[106:107], v[96:99], off sc1
	global_load_dwordx2 v[96:97], v[154:155], off offset:1024
	s_waitcnt vmcnt(0)
; __device__ __forceinline__ unsigned cvtpk(float lo, float hi) { f32x2v_ v = {lo, hi}; bf16x2v_ b = __builtin_convertvector(v, bf16x2v_); return __builtin_bit_cast(unsigned, b); }
;     __device__ __forceinline__ void operator()(const f32x4 (&acc)[2][2][4][2], const Unit& u, int wr, int wc, int fr, int fq) const {
;     ...
;                     for (int m = 0; m < 4; ++m) { const int row = row0 + ai * HALF + m * 16; const float rs = ss ? row_rs(ss, row) : 1.0f;
;                         const f32x4 v0 = acc[ai][bj][m][0] * rs, v1 = acc[ai][bj][m][1] * rs;
;                         u32x4 w; w.x = cvtpk(v0[0], v0[1]); w.y = cvtpk(v0[2], v0[3]); w.z = cvtpk(v1[0], v1[1]); w.w = cvtpk(v1[2], v1[3]);
;                         *(u32x4*)(O + (size_t)row * ldc + c0) = w; }
	v_ffbh_u32_e32 v98, v97
	v_min_u32_e32 v98, 32, v98
	v_lshlrev_b64 v[96:97], v98, v[96:97]
	v_min_u32_e32 v96, 1, v96
	v_or_b32_e32 v96, v97, v96
	v_cvt_f32_u32_e32 v96, v96
	v_sub_u32_e32 v97, 32, v98
	v_mad_i64_i32 v[98:99], s[14:15], v175, s88, v[160:161]
	v_ldexp_f32 v96, v96, v97
	v_mul_f32_e32 v96, 0x2f800000, v96
	v_fmamk_f32 v96, v96, 0x3a800000, v172
	v_rsq_f32_e32 v96, v96
	v_lshl_add_u64 v[98:99], v[98:99], 0, v[126:127]
	v_pk_mul_f32 v[94:95], v[94:95], v[96:97] op_sel_hi:[1,0]
	v_pk_mul_f32 v[92:93], v[92:93], v[96:97] op_sel_hi:[1,0]
	v_pk_mul_f32 v[100:101], v[90:91], v[96:97] op_sel_hi:[1,0]
	v_pk_mul_f32 v[90:91], v[88:89], v[96:97] op_sel_hi:[1,0]
	v_cvt_pk_bf16_f32 v88, v92, v93
	v_cvt_pk_bf16_f32 v89, v94, v95
	v_cvt_pk_bf16_f32 v90, v90, v91
	v_cvt_pk_bf16_f32 v91, v100, v101
	global_store_dwordx4 v[98:99], v[88:91], off sc1
	global_load_dwordx2 v[88:89], v[154:155], off offset:1152
	s_waitcnt vmcnt(0)
	v_ffbh_u32_e32 v90, v89
	v_min_u32_e32 v90, 32, v90
	v_lshlrev_b64 v[88:89], v90, v[88:89]
	v_min_u32_e32 v88, 1, v88
	v_or_b32_e32 v88, v89, v88
	v_cvt_f32_u32_e32 v88, v88
	v_sub_u32_e32 v89, 32, v90
	v_mad_i64_i32 v[90:91], s[14:15], v174, s88, v[160:161]
	v_ldexp_f32 v88, v88, v89
	v_mul_f32_e32 v88, 0x2f800000, v88
	v_fmamk_f32 v88, v88, 0x3a800000, v172
	v_rsq_f32_e32 v88, v88
	v_lshl_add_u64 v[90:91], v[90:91], 0, v[126:127]
	v_pk_mul_f32 v[86:87], v[86:87], v[88:89] op_sel_hi:[1,0]
	v_pk_mul_f32 v[84:85], v[84:85], v[88:89] op_sel_hi:[1,0]
	v_pk_mul_f32 v[92:93], v[82:83], v[88:89] op_sel_hi:[1,0]
	v_pk_mul_f32 v[82:83], v[80:81], v[88:89] op_sel_hi:[1,0]
	v_cvt_pk_bf16_f32 v80, v84, v85
	v_cvt_pk_bf16_f32 v81, v86, v87
	v_cvt_pk_bf16_f32 v82, v82, v83
	v_cvt_pk_bf16_f32 v83, v92, v93
	global_store_dwordx4 v[90:91], v[80:83], off sc1
	global_load_dwordx2 v[80:81], v[154:155], off offset:1280
	s_waitcnt vmcnt(0)
	v_ffbh_u32_e32 v82, v81
	v_min_u32_e32 v82, 32, v82
	v_lshlrev_b64 v[80:81], v82, v[80:81]
	v_min_u32_e32 v80, 1, v80
	v_or_b32_e32 v80, v81, v80
	v_cvt_f32_u32_e32 v80, v80
	v_sub_u32_e32 v81, 32, v82
	v_mad_i64_i32 v[82:83], s[14:15], v173, s88, v[160:161]
	v_ldexp_f32 v80, v80, v81
	v_mul_f32_e32 v80, 0x2f800000, v80
	v_fmamk_f32 v80, v80, 0x3a800000, v172
	v_rsq_f32_e32 v80, v80
	v_lshl_add_u64 v[82:83], v[82:83], 0, v[126:127]
	v_pk_mul_f32 v[78:79], v[78:79], v[80:81] op_sel_hi:[1,0]
	v_pk_mul_f32 v[76:77], v[76:77], v[80:81] op_sel_hi:[1,0]
	v_pk_mul_f32 v[84:85], v[74:75], v[80:81] op_sel_hi:[1,0]
	v_pk_mul_f32 v[74:75], v[72:73], v[80:81] op_sel_hi:[1,0]
	v_cvt_pk_bf16_f32 v72, v76, v77
	v_cvt_pk_bf16_f32 v73, v78, v79
	v_cvt_pk_bf16_f32 v74, v74, v75
	v_cvt_pk_bf16_f32 v75, v84, v85
	global_store_dwordx4 v[82:83], v[72:75], off sc1
	global_load_dwordx2 v[72:73], v[154:155], off offset:1408
	s_waitcnt vmcnt(0)
	v_ffbh_u32_e32 v74, v73
	v_min_u32_e32 v74, 32, v74
	v_lshlrev_b64 v[72:73], v74, v[72:73]
	v_min_u32_e32 v72, 1, v72
	v_or_b32_e32 v72, v73, v72
	v_cvt_f32_u32_e32 v72, v72
	v_sub_u32_e32 v73, 32, v74
	v_mad_i64_i32 v[74:75], s[14:15], v157, s88, v[160:161]
	v_ldexp_f32 v72, v72, v73
	v_mul_f32_e32 v72, 0x2f800000, v72
	v_fmamk_f32 v72, v72, 0x3a800000, v172
	v_rsq_f32_e32 v72, v72
	s_nop 0
	v_pk_mul_f32 v[62:63], v[62:63], v[72:73] op_sel_hi:[1,0]
	v_pk_mul_f32 v[60:61], v[60:61], v[72:73] op_sel_hi:[1,0]
	v_pk_mul_f32 v[76:77], v[58:59], v[72:73] op_sel_hi:[1,0]
	v_pk_mul_f32 v[58:59], v[56:57], v[72:73] op_sel_hi:[1,0]
	v_cvt_pk_bf16_f32 v56, v60, v61
	v_cvt_pk_bf16_f32 v57, v62, v63
	v_cvt_pk_bf16_f32 v58, v58, v59
	v_cvt_pk_bf16_f32 v59, v76, v77
	v_lshl_add_u64 v[60:61], v[74:75], 0, v[126:127]
	global_store_dwordx4 v[60:61], v[56:59], off sc1

; __device__ __forceinline__ unsigned cvtpk(float lo, float hi) { f32x2v_ v = {lo, hi}; bf16x2v_ b = __builtin_convertvector(v, bf16x2v_); return __builtin_bit_cast(unsigned, b); }
;     __device__ __forceinline__ void operator()(const f32x4 (&acc)[2][2][4][2], const Unit& u, int wr, int wc, int fr, int fq) const {
;     ...
;                 for (int ai = 0; ai < 2; ++ai)
; #pragma unroll
;                     for (int m = 0; m < 4; ++m) { const int row = row0 + ai * HALF + m * 16; const float rs = ss ? row_rs(ss, row) : 1.0f;
;                         const f32x4 v0 = acc[ai][bj][m][0] * rs, v1 = acc[ai][bj][m][1] * rs;
;                         const int b = row >> S_shift, pos = row & ((1 << S_shift) - 1);
;                         const size_t tile = ((size_t)(b * kvh + head) << (S_shift - 5)) + (pos >> 5);
;                         u32x4 w; w.x = cvtpk(v0[0], v0[1]); w.y = cvtpk(v0[2], v0[3]); w.z = cvtpk(v1[0], v1[1]); w.w = cvtpk(v1[2], v1[3]);
;                         *(u32x4*)(KP + tile * (size_t)(32 * DH) + ((d >> 3) * 32 + (pos & 31)) * 8) = w;
.LBB0_433:
	s_andn2_b64 vcc, exec, s[54:55]
	s_cbranch_vccnz .LBB0_435
	v_add_u32_e32 v64, 0xfffff800, v69
	v_ashrrev_i32_e32 v80, 6, v64
	v_add_u32_e32 v70, v70, v80
	v_ashrrev_i32_e32 v71, 31, v70
	v_lshlrev_b64 v[70:71], 19, v[70:71]
	v_lshl_add_u64 v[70:71], s[26:27], 0, v[70:71]
	v_and_b32_e32 v136, 0x7e000, v68
	v_lshl_add_u64 v[68:69], v[70:71], 0, v[136:137]
	v_lshlrev_b32_e32 v136, 1, v144
	v_cvt_pk_bf16_f32 v64, v58, v59
	v_cvt_pk_bf16_f32 v65, v56, v57
	v_cvt_pk_bf16_f32 v66, v62, v63
	v_cvt_pk_bf16_f32 v67, v60, v61
	v_lshl_add_u64 v[72:73], v[68:69], 0, v[136:137]
	v_ashrrev_i32_e32 v125, 31, v124
	global_store_dwordx4 v[72:73], v[64:67], off sc1
	v_ashrrev_i32_e32 v123, 31, v122
	v_lshl_add_u64 v[72:73], v[122:123], 3, s[24:25]
	v_lshl_add_u64 v[64:65], v[124:125], 3, s[24:25]
	global_load_dwordx2 v[64:65], v[64:65], off
	v_and_or_b32 v67, v124, 31, v168
	v_ashrrev_i32_e32 v121, 31, v120
	s_waitcnt vmcnt(0)
	v_ffbh_u32_e32 v66, v65
	v_min_u32_e32 v66, 32, v66
	v_lshlrev_b64 v[64:65], v66, v[64:65]
	v_min_u32_e32 v64, 1, v64
	v_or_b32_e32 v64, v65, v64
	v_cvt_f32_u32_e32 v64, v64
	v_sub_u32_e32 v66, 32, v66
	v_mov_b32_e32 v65, v137
	v_ldexp_f32 v64, v64, v66
	v_mul_f32_e32 v64, 0x2f800000, v64
	v_fmamk_f32 v64, v64, 0x3a800000, v172
	v_rsq_f32_e32 v66, v64
	v_lshlrev_b32_e32 v64, 4, v67
	v_lshl_add_u64 v[68:69], v[68:69], 0, v[64:65]
	v_pk_mul_f32 v[74:75], v[54:55], v[66:67] op_sel_hi:[1,0]
	v_pk_mul_f32 v[64:65], v[52:53], v[66:67] op_sel_hi:[1,0]
	v_pk_mul_f32 v[76:77], v[50:51], v[66:67] op_sel_hi:[1,0]
	v_pk_mul_f32 v[66:67], v[48:49], v[66:67] op_sel_hi:[1,0]
	v_cvt_pk_bf16_f32 v64, v64, v65
	v_cvt_pk_bf16_f32 v65, v74, v75
	v_cvt_pk_bf16_f32 v66, v66, v67
	v_cvt_pk_bf16_f32 v67, v76, v77
	global_store_dwordx4 v[68:69], v[64:67], off sc1
	global_load_dwordx2 v[64:65], v[72:73], off
	s_waitcnt vmcnt(0)
	v_ffbh_u32_e32 v68, v65
	v_min_u32_e32 v68, 32, v68
	v_lshlrev_b64 v[64:65], v68, v[64:65]
	v_min_u32_e32 v64, 1, v64
	v_or_b32_e32 v64, v65, v64
	v_cvt_f32_u32_e32 v64, v64
	v_sub_u32_e32 v65, 32, v68
	v_lshlrev_b32_e32 v66, 7, v122
	v_mov_b32_e32 v67, v137
	v_ldexp_f32 v64, v64, v65
	v_mul_f32_e32 v64, 0x2f800000, v64
	v_fmamk_f32 v64, v64, 0x3a800000, v172
	v_rsq_f32_e32 v64, v64
	v_and_b32_e32 v66, 0x7f000, v66
	v_lshl_add_u64 v[66:67], v[70:71], 0, v[66:67]
	v_lshl_add_u64 v[72:73], v[66:67], 0, v[136:137]
	v_pk_mul_f32 v[66:67], v[46:47], v[64:65] op_sel_hi:[1,0]
	v_pk_mul_f32 v[74:75], v[44:45], v[64:65] op_sel_hi:[1,0]
	v_pk_mul_f32 v[76:77], v[42:43], v[64:65] op_sel_hi:[1,0]
	v_pk_mul_f32 v[78:79], v[40:41], v[64:65] op_sel_hi:[1,0]
	v_cvt_pk_bf16_f32 v64, v74, v75
	v_cvt_pk_bf16_f32 v65, v66, v67
	v_cvt_pk_bf16_f32 v66, v78, v79
	v_cvt_pk_bf16_f32 v67, v76, v77
	v_lshl_add_u64 v[68:69], v[120:121], 3, s[24:25]
	global_store_dwordx4 v[72:73], v[64:67], off sc1
	global_load_dwordx2 v[64:65], v[68:69], off
	v_and_or_b32 v69, v120, 31, v168
	v_lshlrev_b32_e32 v66, 7, v120
	v_mov_b32_e32 v67, v137
	v_and_b32_e32 v66, 0x7f000, v66
	v_lshl_add_u64 v[66:67], v[70:71], 0, v[66:67]
	s_waitcnt vmcnt(0)
	v_ffbh_u32_e32 v68, v65
	v_min_u32_e32 v68, 32, v68
	v_lshlrev_b64 v[64:65], v68, v[64:65]
	v_min_u32_e32 v64, 1, v64
	v_or_b32_e32 v64, v65, v64
	v_cvt_f32_u32_e32 v64, v64
	v_sub_u32_e32 v68, 32, v68
	v_mov_b32_e32 v65, v137
	v_ldexp_f32 v64, v64, v68
	v_mul_f32_e32 v64, 0x2f800000, v64
	v_fmamk_f32 v64, v64, 0x3a800000, v172
	v_rsq_f32_e32 v68, v64
	v_lshlrev_b32_e32 v64, 4, v69
	v_lshl_add_u64 v[70:71], v[66:67], 0, v[64:65]
	v_pk_mul_f32 v[66:67], v[38:39], v[68:69] op_sel_hi:[1,0]
	v_pk_mul_f32 v[64:65], v[36:37], v[68:69] op_sel_hi:[1,0]
	v_pk_mul_f32 v[72:73], v[34:35], v[68:69] op_sel_hi:[1,0]
	v_pk_mul_f32 v[68:69], v[32:33], v[68:69] op_sel_hi:[1,0]
	v_cvt_pk_bf16_f32 v64, v64, v65
	v_cvt_pk_bf16_f32 v65, v66, v67
	v_cvt_pk_bf16_f32 v66, v68, v69
	v_cvt_pk_bf16_f32 v67, v72, v73
	global_store_dwordx4 v[70:71], v[64:67], off sc1
	global_load_dwordx2 v[64:65], v[154:155], off offset:1024
	v_lshlrev_b32_e32 v68, 7, v175
	v_ashrrev_i32_e32 v66, 11, v175
	v_and_b32_e32 v69, -2, v66
	v_and_b32_e32 v66, 0x7e000, v68
	v_add_u32_e32 v68, v69, v80
	v_mov_b32_e32 v67, v137
	s_waitcnt vmcnt(0)
; __device__ __forceinline__ unsigned cvtpk(float lo, float hi) { f32x2v_ v = {lo, hi}; bf16x2v_ b = __builtin_convertvector(v, bf16x2v_); return __builtin_bit_cast(unsigned, b); }
;     __device__ __forceinline__ void operator()(const f32x4 (&acc)[2][2][4][2], const Unit& u, int wr, int wc, int fr, int fq) const {
;     ...
;                     for (int m = 0; m < 4; ++m) { const int row = row0 + ai * HALF + m * 16; const float rs = ss ? row_rs(ss, row) : 1.0f;
;                         const f32x4 v0 = acc[ai][bj][m][0] * rs, v1 = acc[ai][bj][m][1] * rs;
;                         const int b = row >> S_shift, pos = row & ((1 << S_shift) - 1);
;                         const size_t tile = ((size_t)(b * kvh + head) << (S_shift - 5)) + (pos >> 5);
;                         u32x4 w; w.x = cvtpk(v0[0], v0[1]); w.y = cvtpk(v0[2], v0[3]); w.z = cvtpk(v1[0], v1[1]); w.w = cvtpk(v1[2], v1[3]);
;                         *(u32x4*)(KP + tile * (size_t)(32 * DH) + ((d >> 3) * 32 + (pos & 31)) * 8) = w;
	v_ffbh_u32_e32 v69, v65
	v_min_u32_e32 v70, 32, v69
	v_lshlrev_b64 v[64:65], v70, v[64:65]
	v_min_u32_e32 v64, 1, v64
	v_or_b32_e32 v64, v65, v64
	v_cvt_f32_u32_e32 v71, v64
	v_ashrrev_i32_e32 v69, 31, v68
	v_lshlrev_b64 v[64:65], 19, v[68:69]
	v_sub_u32_e32 v68, 32, v70
	v_ldexp_f32 v68, v71, v68
	v_mul_f32_e32 v68, 0x2f800000, v68
	v_fmamk_f32 v68, v68, 0x3a800000, v172
	v_rsq_f32_e32 v68, v68
	v_lshl_add_u64 v[64:65], s[26:27], 0, v[64:65]
	v_lshl_add_u64 v[64:65], v[64:65], 0, v[66:67]
	v_lshl_add_u64 v[70:71], v[64:65], 0, v[136:137]
	v_pk_mul_f32 v[66:67], v[30:31], v[68:69] op_sel_hi:[1,0]
	v_pk_mul_f32 v[64:65], v[28:29], v[68:69] op_sel_hi:[1,0]
	v_pk_mul_f32 v[72:73], v[26:27], v[68:69] op_sel_hi:[1,0]
	v_pk_mul_f32 v[68:69], v[24:25], v[68:69] op_sel_hi:[1,0]
	v_cvt_pk_bf16_f32 v64, v64, v65
	v_cvt_pk_bf16_f32 v65, v66, v67
	v_cvt_pk_bf16_f32 v66, v68, v69
	v_cvt_pk_bf16_f32 v67, v72, v73
	global_store_dwordx4 v[70:71], v[64:67], off sc1
	global_load_dwordx2 v[64:65], v[154:155], off offset:1152
	v_lshlrev_b32_e32 v68, 7, v174
	v_ashrrev_i32_e32 v66, 11, v174
	v_and_or_b32 v70, v174, 31, v168
	v_and_b32_e32 v71, -2, v66
	v_and_b32_e32 v66, 0x7e000, v68
	v_lshlrev_b32_e32 v68, 4, v70
	v_add_u32_e32 v70, v71, v80
	v_mov_b32_e32 v67, v137
	v_mov_b32_e32 v69, v137
	s_waitcnt vmcnt(0)
	v_ffbh_u32_e32 v71, v65
	v_min_u32_e32 v72, 32, v71
	v_lshlrev_b64 v[64:65], v72, v[64:65]
	v_min_u32_e32 v64, 1, v64
	v_or_b32_e32 v64, v65, v64
	v_cvt_f32_u32_e32 v73, v64
	v_ashrrev_i32_e32 v71, 31, v70
	v_lshlrev_b64 v[64:65], 19, v[70:71]
	v_sub_u32_e32 v70, 32, v72
	v_ldexp_f32 v70, v73, v70
	v_mul_f32_e32 v70, 0x2f800000, v70
	v_fmamk_f32 v70, v70, 0x3a800000, v172
	v_rsq_f32_e32 v70, v70
	v_lshl_add_u64 v[64:65], s[26:27], 0, v[64:65]
	v_lshl_add_u64 v[64:65], v[64:65], 0, v[66:67]
	v_lshl_add_u64 v[68:69], v[64:65], 0, v[68:69]
	v_pk_mul_f32 v[66:67], v[22:23], v[70:71] op_sel_hi:[1,0]
	v_pk_mul_f32 v[64:65], v[20:21], v[70:71] op_sel_hi:[1,0]
	v_pk_mul_f32 v[72:73], v[18:19], v[70:71] op_sel_hi:[1,0]
	v_pk_mul_f32 v[70:71], v[16:17], v[70:71] op_sel_hi:[1,0]
	v_cvt_pk_bf16_f32 v64, v64, v65
	v_cvt_pk_bf16_f32 v65, v66, v67
	v_cvt_pk_bf16_f32 v66, v70, v71
	v_cvt_pk_bf16_f32 v67, v72, v73
	global_store_dwordx4 v[68:69], v[64:67], off sc1
	global_load_dwordx2 v[64:65], v[154:155], off offset:1280
	v_lshlrev_b32_e32 v68, 7, v173
	v_ashrrev_i32_e32 v66, 11, v173
	v_and_b32_e32 v69, -2, v66
	v_and_b32_e32 v66, 0x7f000, v68
	v_add_u32_e32 v68, v69, v80
	v_mov_b32_e32 v67, v137
	s_waitcnt vmcnt(0)
	v_ffbh_u32_e32 v69, v65
	v_min_u32_e32 v70, 32, v69
	v_lshlrev_b64 v[64:65], v70, v[64:65]
	v_min_u32_e32 v64, 1, v64
	v_or_b32_e32 v64, v65, v64
	v_cvt_f32_u32_e32 v71, v64
	v_ashrrev_i32_e32 v69, 31, v68
	v_lshlrev_b64 v[64:65], 19, v[68:69]
	v_sub_u32_e32 v68, 32, v70
	v_ldexp_f32 v68, v71, v68
	v_mul_f32_e32 v68, 0x2f800000, v68
	v_fmamk_f32 v68, v68, 0x3a800000, v172
	v_rsq_f32_e32 v68, v68
	v_lshl_add_u64 v[64:65], s[26:27], 0, v[64:65]
	v_lshl_add_u64 v[64:65], v[64:65], 0, v[66:67]
	v_lshl_add_u64 v[70:71], v[64:65], 0, v[136:137]
	v_pk_mul_f32 v[66:67], v[14:15], v[68:69] op_sel_hi:[1,0]
	v_pk_mul_f32 v[64:65], v[12:13], v[68:69] op_sel_hi:[1,0]
	v_pk_mul_f32 v[72:73], v[10:11], v[68:69] op_sel_hi:[1,0]
	v_pk_mul_f32 v[68:69], v[8:9], v[68:69] op_sel_hi:[1,0]
	v_cvt_pk_bf16_f32 v64, v64, v65
	v_cvt_pk_bf16_f32 v65, v66, v67
	v_cvt_pk_bf16_f32 v66, v68, v69
	v_cvt_pk_bf16_f32 v67, v72, v73
	global_store_dwordx4 v[70:71], v[64:67], off sc1
	global_load_dwordx2 v[64:65], v[154:155], off offset:1408
	v_lshlrev_b32_e32 v68, 7, v157
	v_ashrrev_i32_e32 v66, 11, v157
	v_and_b32_e32 v66, -2, v66
	v_add_u32_e32 v66, v66, v80
	v_ashrrev_i32_e32 v67, 31, v66
	v_and_or_b32 v70, v157, 31, v168
	v_and_b32_e32 v136, 0x7f000, v68
	s_waitcnt vmcnt(0)
	v_ffbh_u32_e32 v69, v65
	v_min_u32_e32 v69, 32, v69
	v_lshlrev_b64 v[64:65], v69, v[64:65]
	v_min_u32_e32 v64, 1, v64
	v_or_b32_e32 v64, v65, v64
	v_cvt_f32_u32_e32 v71, v64
	v_lshlrev_b64 v[64:65], 19, v[66:67]
	v_sub_u32_e32 v66, 32, v69
	v_lshl_add_u64 v[64:65], s[26:27], 0, v[64:65]
	v_ldexp_f32 v66, v71, v66
	v_mul_f32_e32 v66, 0x2f800000, v66
	v_fmamk_f32 v66, v66, 0x3a800000, v172
	v_rsq_f32_e32 v66, v66
	v_lshl_add_u64 v[68:69], v[64:65], 0, v[136:137]
	v_lshlrev_b32_e32 v136, 4, v70
	v_lshl_add_u64 v[68:69], v[68:69], 0, v[136:137]
	v_pk_mul_f32 v[70:71], v[6:7], v[66:67] op_sel_hi:[1,0]
	v_pk_mul_f32 v[64:65], v[4:5], v[66:67] op_sel_hi:[1,0]
	v_pk_mul_f32 v[72:73], v[2:3], v[66:67] op_sel_hi:[1,0]
	v_pk_mul_f32 v[66:67], v[0:1], v[66:67] op_sel_hi:[1,0]
	v_cvt_pk_bf16_f32 v64, v64, v65
	v_cvt_pk_bf16_f32 v65, v70, v71
	v_cvt_pk_bf16_f32 v66, v66, v67
	v_cvt_pk_bf16_f32 v67, v72, v73
	global_store_dwordx4 v[68:69], v[64:67], off sc1

; __device__ __forceinline__ unsigned cvtpk(float lo, float hi) { f32x2v_ v = {lo, hi}; bf16x2v_ b = __builtin_convertvector(v, bf16x2v_); return __builtin_bit_cast(unsigned, b); }
;     __device__ __forceinline__ void operator()(const f32x4 (&acc)[2][2][4][2], const Unit& u, int wr, int wc, int fr, int fq) const {
;     ...
;                 for (int ai = 0; ai < 2; ++ai)
; #pragma unroll
;                     for (int m = 0; m < 4; ++m) { const int row = row0 + ai * HALF + m * 16; const float rs = ss ? row_rs(ss, row) : 1.0f;
;                         const f32x4 v0 = acc[ai][bj][m][0] * rs, v1 = acc[ai][bj][m][1] * rs;
;                         u32x4 w; w.x = cvtpk(v0[0], v0[1]); w.y = cvtpk(v0[2], v0[3]); w.z = cvtpk(v1[0], v1[1]); w.w = cvtpk(v1[2], v1[3]);
;                         *(u32x4*)(O + (size_t)row * ldc + c0) = w; }
.LBB0_436:
	s_ashr_i32 s53, s52, 31
	v_cvt_pk_bf16_f32 v64, v58, v59
	v_cvt_pk_bf16_f32 v65, v56, v57
	v_mov_b64_e32 v[58:59], s[20:21]
	v_lshl_add_u64 v[56:57], s[52:53], 0, v[138:139]
	v_cvt_pk_bf16_f32 v67, v60, v61
	v_mad_i64_i32 v[60:61], s[14:15], v156, s88, v[58:59]
	v_lshlrev_b64 v[56:57], 1, v[56:57]
	v_cvt_pk_bf16_f32 v66, v62, v63
	v_lshl_add_u64 v[60:61], v[60:61], 0, v[56:57]
	v_ashrrev_i32_e32 v125, 31, v124
	global_store_dwordx4 v[60:61], v[64:67], off offset:256 sc1
	v_lshl_add_u64 v[60:61], v[124:125], 3, s[24:25]
	global_load_dwordx2 v[60:61], v[60:61], off
	v_ashrrev_i32_e32 v123, 31, v122
	v_lshl_add_u64 v[64:65], v[122:123], 3, s[24:25]
	v_ashrrev_i32_e32 v121, 31, v120
	s_waitcnt vmcnt(0)
	v_ffbh_u32_e32 v62, v61
	v_min_u32_e32 v62, 32, v62
	v_lshlrev_b64 v[60:61], v62, v[60:61]
	v_min_u32_e32 v60, 1, v60
	v_or_b32_e32 v60, v61, v60
	v_cvt_f32_u32_e32 v60, v60
	v_sub_u32_e32 v61, 32, v62
	v_mad_i64_i32 v[62:63], s[14:15], v124, s88, v[58:59]
	v_ldexp_f32 v60, v60, v61
	v_mul_f32_e32 v60, 0x2f800000, v60
	v_fmamk_f32 v60, v60, 0x3a800000, v172
	v_rsq_f32_e32 v60, v60
	v_lshl_add_u64 v[62:63], v[62:63], 0, v[56:57]
	v_pk_mul_f32 v[54:55], v[54:55], v[60:61] op_sel_hi:[1,0]
	v_pk_mul_f32 v[52:53], v[52:53], v[60:61] op_sel_hi:[1,0]
	v_pk_mul_f32 v[66:67], v[50:51], v[60:61] op_sel_hi:[1,0]
	v_pk_mul_f32 v[50:51], v[48:49], v[60:61] op_sel_hi:[1,0]
	v_cvt_pk_bf16_f32 v48, v52, v53
	v_cvt_pk_bf16_f32 v49, v54, v55
	v_cvt_pk_bf16_f32 v50, v50, v51
	v_cvt_pk_bf16_f32 v51, v66, v67
	global_store_dwordx4 v[62:63], v[48:51], off offset:256 sc1
	global_load_dwordx2 v[48:49], v[64:65], off
	v_lshl_add_u64 v[52:53], v[120:121], 3, s[24:25]
	s_waitcnt vmcnt(0)
	v_ffbh_u32_e32 v50, v49
	v_min_u32_e32 v50, 32, v50
	v_lshlrev_b64 v[48:49], v50, v[48:49]
	v_min_u32_e32 v48, 1, v48
	v_or_b32_e32 v48, v49, v48
	v_cvt_f32_u32_e32 v48, v48
	v_sub_u32_e32 v49, 32, v50
	v_mad_i64_i32 v[50:51], s[14:15], v122, s88, v[58:59]
	v_ldexp_f32 v48, v48, v49
	v_mul_f32_e32 v48, 0x2f800000, v48
	v_fmamk_f32 v48, v48, 0x3a800000, v172
	v_rsq_f32_e32 v48, v48
	v_lshl_add_u64 v[50:51], v[50:51], 0, v[56:57]
	v_pk_mul_f32 v[46:47], v[46:47], v[48:49] op_sel_hi:[1,0]
	v_pk_mul_f32 v[44:45], v[44:45], v[48:49] op_sel_hi:[1,0]
	v_pk_mul_f32 v[54:55], v[42:43], v[48:49] op_sel_hi:[1,0]
	v_pk_mul_f32 v[42:43], v[40:41], v[48:49] op_sel_hi:[1,0]
	v_cvt_pk_bf16_f32 v40, v44, v45
	v_cvt_pk_bf16_f32 v41, v46, v47
	v_cvt_pk_bf16_f32 v42, v42, v43
	v_cvt_pk_bf16_f32 v43, v54, v55
	global_store_dwordx4 v[50:51], v[40:43], off offset:256 sc1
	global_load_dwordx2 v[40:41], v[52:53], off
	s_waitcnt vmcnt(0)
	v_ffbh_u32_e32 v42, v41
	v_min_u32_e32 v42, 32, v42
	v_lshlrev_b64 v[40:41], v42, v[40:41]
	v_min_u32_e32 v40, 1, v40
	v_or_b32_e32 v40, v41, v40
	v_cvt_f32_u32_e32 v40, v40
	v_sub_u32_e32 v41, 32, v42
	v_mad_i64_i32 v[42:43], s[14:15], v120, s88, v[58:59]
	v_ldexp_f32 v40, v40, v41
	v_mul_f32_e32 v40, 0x2f800000, v40
	v_fmamk_f32 v40, v40, 0x3a800000, v172
	v_rsq_f32_e32 v40, v40
	v_lshl_add_u64 v[42:43], v[42:43], 0, v[56:57]
	v_pk_mul_f32 v[38:39], v[38:39], v[40:41] op_sel_hi:[1,0]
	v_pk_mul_f32 v[36:37], v[36:37], v[40:41] op_sel_hi:[1,0]
	v_pk_mul_f32 v[44:45], v[34:35], v[40:41] op_sel_hi:[1,0]
	v_pk_mul_f32 v[34:35], v[32:33], v[40:41] op_sel_hi:[1,0]
	v_cvt_pk_bf16_f32 v32, v36, v37
	v_cvt_pk_bf16_f32 v33, v38, v39
	v_cvt_pk_bf16_f32 v34, v34, v35
	v_cvt_pk_bf16_f32 v35, v44, v45
	global_store_dwordx4 v[42:43], v[32:35], off offset:256 sc1
	global_load_dwordx2 v[32:33], v[154:155], off offset:1024
	s_waitcnt vmcnt(0)
; __device__ __forceinline__ unsigned cvtpk(float lo, float hi) { f32x2v_ v = {lo, hi}; bf16x2v_ b = __builtin_convertvector(v, bf16x2v_); return __builtin_bit_cast(unsigned, b); }
;     __device__ __forceinline__ void operator()(const f32x4 (&acc)[2][2][4][2], const Unit& u, int wr, int wc, int fr, int fq) const {
;     ...
;                     for (int m = 0; m < 4; ++m) { const int row = row0 + ai * HALF + m * 16; const float rs = ss ? row_rs(ss, row) : 1.0f;
;                         const f32x4 v0 = acc[ai][bj][m][0] * rs, v1 = acc[ai][bj][m][1] * rs;
;                         u32x4 w; w.x = cvtpk(v0[0], v0[1]); w.y = cvtpk(v0[2], v0[3]); w.z = cvtpk(v1[0], v1[1]); w.w = cvtpk(v1[2], v1[3]);
;                         *(u32x4*)(O + (size_t)row * ldc + c0) = w; }
	v_ffbh_u32_e32 v34, v33
	v_min_u32_e32 v34, 32, v34
	v_lshlrev_b64 v[32:33], v34, v[32:33]
	v_min_u32_e32 v32, 1, v32
	v_or_b32_e32 v32, v33, v32
	v_cvt_f32_u32_e32 v32, v32
	v_sub_u32_e32 v33, 32, v34
	v_mad_i64_i32 v[34:35], s[14:15], v175, s88, v[58:59]
	v_ldexp_f32 v32, v32, v33
	v_mul_f32_e32 v32, 0x2f800000, v32
	v_fmamk_f32 v32, v32, 0x3a800000, v172
	v_rsq_f32_e32 v32, v32
	v_lshl_add_u64 v[34:35], v[34:35], 0, v[56:57]
	v_pk_mul_f32 v[30:31], v[30:31], v[32:33] op_sel_hi:[1,0]
	v_pk_mul_f32 v[28:29], v[28:29], v[32:33] op_sel_hi:[1,0]
	v_pk_mul_f32 v[36:37], v[26:27], v[32:33] op_sel_hi:[1,0]
	v_pk_mul_f32 v[26:27], v[24:25], v[32:33] op_sel_hi:[1,0]
	v_cvt_pk_bf16_f32 v24, v28, v29
	v_cvt_pk_bf16_f32 v25, v30, v31
	v_cvt_pk_bf16_f32 v26, v26, v27
	v_cvt_pk_bf16_f32 v27, v36, v37
	global_store_dwordx4 v[34:35], v[24:27], off offset:256 sc1
	global_load_dwordx2 v[24:25], v[154:155], off offset:1152
	s_waitcnt vmcnt(0)
	v_ffbh_u32_e32 v26, v25
	v_min_u32_e32 v26, 32, v26
	v_lshlrev_b64 v[24:25], v26, v[24:25]
	v_min_u32_e32 v24, 1, v24
	v_or_b32_e32 v24, v25, v24
	v_cvt_f32_u32_e32 v24, v24
	v_sub_u32_e32 v25, 32, v26
	v_mad_i64_i32 v[26:27], s[14:15], v174, s88, v[58:59]
	v_ldexp_f32 v24, v24, v25
	v_mul_f32_e32 v24, 0x2f800000, v24
	v_fmamk_f32 v24, v24, 0x3a800000, v172
	v_rsq_f32_e32 v24, v24
	v_lshl_add_u64 v[26:27], v[26:27], 0, v[56:57]
	v_pk_mul_f32 v[22:23], v[22:23], v[24:25] op_sel_hi:[1,0]
	v_pk_mul_f32 v[20:21], v[20:21], v[24:25] op_sel_hi:[1,0]
	v_pk_mul_f32 v[28:29], v[18:19], v[24:25] op_sel_hi:[1,0]
	v_pk_mul_f32 v[18:19], v[16:17], v[24:25] op_sel_hi:[1,0]
	v_cvt_pk_bf16_f32 v16, v20, v21
	v_cvt_pk_bf16_f32 v17, v22, v23
	v_cvt_pk_bf16_f32 v18, v18, v19
	v_cvt_pk_bf16_f32 v19, v28, v29
	global_store_dwordx4 v[26:27], v[16:19], off offset:256 sc1
	global_load_dwordx2 v[16:17], v[154:155], off offset:1280
	s_waitcnt vmcnt(0)
	v_ffbh_u32_e32 v18, v17
	v_min_u32_e32 v18, 32, v18
	v_lshlrev_b64 v[16:17], v18, v[16:17]
	v_min_u32_e32 v16, 1, v16
	v_or_b32_e32 v16, v17, v16
	v_cvt_f32_u32_e32 v16, v16
	v_sub_u32_e32 v17, 32, v18
	v_mad_i64_i32 v[18:19], s[14:15], v173, s88, v[58:59]
	v_ldexp_f32 v16, v16, v17
	v_mul_f32_e32 v16, 0x2f800000, v16
	v_fmamk_f32 v16, v16, 0x3a800000, v172
	v_rsq_f32_e32 v16, v16
	v_lshl_add_u64 v[18:19], v[18:19], 0, v[56:57]
	v_pk_mul_f32 v[14:15], v[14:15], v[16:17] op_sel_hi:[1,0]
	v_pk_mul_f32 v[12:13], v[12:13], v[16:17] op_sel_hi:[1,0]
	v_pk_mul_f32 v[20:21], v[10:11], v[16:17] op_sel_hi:[1,0]
	v_pk_mul_f32 v[10:11], v[8:9], v[16:17] op_sel_hi:[1,0]
	v_cvt_pk_bf16_f32 v8, v12, v13
	v_cvt_pk_bf16_f32 v9, v14, v15
	v_cvt_pk_bf16_f32 v10, v10, v11
	v_cvt_pk_bf16_f32 v11, v20, v21
	global_store_dwordx4 v[18:19], v[8:11], off offset:256 sc1
	global_load_dwordx2 v[8:9], v[154:155], off offset:1408
	s_waitcnt vmcnt(0)
	v_ffbh_u32_e32 v10, v9
	v_min_u32_e32 v10, 32, v10
	v_lshlrev_b64 v[8:9], v10, v[8:9]
	v_min_u32_e32 v8, 1, v8
	v_or_b32_e32 v8, v9, v8
	v_cvt_f32_u32_e32 v8, v8
	v_sub_u32_e32 v9, 32, v10
	v_mad_i64_i32 v[10:11], s[14:15], v157, s88, v[58:59]
	v_ldexp_f32 v8, v8, v9
	v_mul_f32_e32 v8, 0x2f800000, v8
	v_fmamk_f32 v8, v8, 0x3a800000, v172
	v_rsq_f32_e32 v8, v8
	s_nop 0
	v_pk_mul_f32 v[6:7], v[6:7], v[8:9] op_sel_hi:[1,0]
	v_pk_mul_f32 v[4:5], v[4:5], v[8:9] op_sel_hi:[1,0]
	v_pk_mul_f32 v[12:13], v[2:3], v[8:9] op_sel_hi:[1,0]
	v_pk_mul_f32 v[2:3], v[0:1], v[8:9] op_sel_hi:[1,0]
	v_cvt_pk_bf16_f32 v0, v4, v5
	v_cvt_pk_bf16_f32 v1, v6, v7
	v_cvt_pk_bf16_f32 v2, v2, v3
	v_cvt_pk_bf16_f32 v3, v12, v13
	v_lshl_add_u64 v[4:5], v[10:11], 0, v[56:57]
	global_store_dwordx4 v[4:5], v[0:3], off offset:256 sc1
	s_andn2_b64 vcc, exec, s[6:7]
	s_mov_b64 s[6:7], -1
	s_cbranch_vccnz .LBB0_413

; __device__ __forceinline__ unsigned cvtpk(float lo, float hi) { f32x2v_ v = {lo, hi}; bf16x2v_ b = __builtin_convertvector(v, bf16x2v_); return __builtin_bit_cast(unsigned, b); }
;     __device__ __forceinline__ void operator()(const f32x4 (&acc)[2][2][4][2], const Unit& u, int wr, int wc, int fr, int fq) const {
;     ...
;                 const int c = c0 - kbeg, head = c >> dh_shift, d = c & (DH - 1);
;                 float cs[8];
; #pragma unroll
;                 for (int e = 0; e < 8; ++e) cs[e] = 0.f;
; #pragma unroll
;                 for (int ai = 0; ai < 2; ++ai)
; #pragma unroll
;                     for (int m = 0; m < 4; ++m) { const int row = row0 + ai * HALF + m * 16; const float rs = ss ? row_rs(ss, row) : 1.0f;
;                         const f32x4 v0 = acc[ai][bj][m][0] * rs, v1 = acc[ai][bj][m][1] * rs;
;                         const int b = row >> S_shift, pos = row & ((1 << S_shift) - 1);
;                         const size_t tile = ((size_t)(b * kvh + head) << (S_shift - 5)) + (pos >> 5);
;                         u32x4 w; w.x = cvtpk(v0[0], v0[1]); w.y = cvtpk(v0[2], v0[3]); w.z = cvtpk(v1[0], v1[1]); w.w = cvtpk(v1[2], v1[3]);
;                         *(u32x4*)(KP + tile * (size_t)(32 * DH) + ((d >> 3) * 32 + (pos & 31)) * 8) = w;
.LBB0_465:
	s_andn2_b64 vcc, exec, s[56:57]
	s_cbranch_vccnz .LBB0_467
	s_lshr_b32 s3, s14, 7
	v_ashrrev_i32_e32 v64, 6, v169
	v_and_or_b32 v64, v64, -4, s3
	v_ashrrev_i32_e32 v65, 31, v64
	v_lshlrev_b64 v[64:65], 16, v[64:65]
	v_lshl_add_u64 v[66:67], v[154:155], 0, v[64:65]
	global_store_dwordx4 v[66:67], v[124:127], off sc1
	global_store_dwordx4 v[66:67], v[116:119], off offset:256 sc1
	v_lshl_add_u64 v[66:67], v[156:157], 0, v[64:65]
	global_store_dwordx4 v[66:67], v[108:111], off sc1
	v_lshl_add_u64 v[64:65], v[158:159], 0, v[64:65]
	v_add_u32_e32 v66, 0x80, v169
	global_store_dwordx4 v[64:65], v[100:103], off sc1
	v_ashrrev_i32_e32 v64, 6, v66
	v_and_or_b32 v64, v64, -4, s3
	v_ashrrev_i32_e32 v65, 31, v64
	v_lshlrev_b64 v[64:65], 16, v[64:65]
	v_lshlrev_b32_e32 v66, 8, v66
	v_lshl_add_u64 v[64:65], s[24:25], 0, v[64:65]
	v_and_b32_e32 v136, 0xc000, v66
	v_lshl_add_u64 v[64:65], v[64:65], 0, v[136:137]
	v_lshlrev_b32_e32 v136, 1, v152
	v_lshl_add_u64 v[64:65], v[64:65], 0, v[136:137]
	v_add_u32_e32 v72, 0x90, v169
	global_store_dwordx4 v[64:65], v[92:95], off sc1
	v_ashrrev_i32_e32 v64, 6, v72
	v_and_or_b32 v64, v64, -4, s3
	v_ashrrev_i32_e32 v65, 31, v64
	v_lshlrev_b64 v[64:65], 16, v[64:65]
	v_lshlrev_b32_e32 v66, 8, v72
	v_lshl_add_u64 v[64:65], s[24:25], 0, v[64:65]
	v_and_b32_e32 v66, 0xc000, v66
	v_mov_b32_e32 v67, v137
	v_lshl_add_u64 v[64:65], v[64:65], 0, v[66:67]
	v_and_or_b32 v66, v72, 31, v143
	v_lshlrev_b32_e32 v66, 4, v66
	v_lshl_add_u64 v[64:65], v[64:65], 0, v[66:67]
	v_add_u32_e32 v66, 0xa0, v169
	global_store_dwordx4 v[64:65], v[84:87], off sc1
	v_ashrrev_i32_e32 v64, 6, v66
	v_and_or_b32 v64, v64, -4, s3
	v_ashrrev_i32_e32 v65, 31, v64
	v_lshlrev_b64 v[64:65], 16, v[64:65]
	v_lshlrev_b32_e32 v66, 8, v66
	v_lshl_add_u64 v[64:65], s[24:25], 0, v[64:65]
	v_and_b32_e32 v66, 0xe000, v66
	v_lshl_add_u64 v[64:65], v[64:65], 0, v[66:67]
	v_lshl_add_u64 v[64:65], v[64:65], 0, v[136:137]
	v_add_u32_e32 v66, 0xb0, v169
	global_store_dwordx4 v[64:65], v[76:79], off sc1
	v_ashrrev_i32_e32 v64, 6, v66
	v_and_or_b32 v64, v64, -4, s3
	v_ashrrev_i32_e32 v65, 31, v64
	v_lshlrev_b64 v[64:65], 16, v[64:65]
	v_lshlrev_b32_e32 v67, 8, v66
	v_lshl_add_u64 v[64:65], s[24:25], 0, v[64:65]
	v_and_b32_e32 v136, 0xe000, v67
	v_and_or_b32 v66, v66, 31, v143
	v_lshl_add_u64 v[64:65], v[64:65], 0, v[136:137]
	v_lshlrev_b32_e32 v136, 4, v66
	v_lshl_add_u64 v[64:65], v[64:65], 0, v[136:137]
	global_store_dwordx4 v[64:65], v[68:71], off sc1

; __device__ __forceinline__ unsigned cvtpk(float lo, float hi) { f32x2v_ v = {lo, hi}; bf16x2v_ b = __builtin_convertvector(v, bf16x2v_); return __builtin_bit_cast(unsigned, b); }
;     __device__ __forceinline__ void operator()(const f32x4 (&acc)[2][2][4][2], const Unit& u, int wr, int wc, int fr, int fq) const {
;     ...
;                 const int c = c0 - kbeg, head = c >> dh_shift, d = c & (DH - 1);
;                 float cs[8];
; #pragma unroll
;                 for (int e = 0; e < 8; ++e) cs[e] = 0.f;
; #pragma unroll
;                 for (int ai = 0; ai < 2; ++ai)
; #pragma unroll
;                     for (int m = 0; m < 4; ++m) { const int row = row0 + ai * HALF + m * 16; const float rs = ss ? row_rs(ss, row) : 1.0f;
;                         const f32x4 v0 = acc[ai][bj][m][0] * rs, v1 = acc[ai][bj][m][1] * rs;
;                         const int b = row >> S_shift, pos = row & ((1 << S_shift) - 1);
;                         const size_t tile = ((size_t)(b * kvh + head) << (S_shift - 5)) + (pos >> 5);
;                         u32x4 w; w.x = cvtpk(v0[0], v0[1]); w.y = cvtpk(v0[2], v0[3]); w.z = cvtpk(v1[0], v1[1]); w.w = cvtpk(v1[2], v1[3]);
;                         *(u32x4*)(KP + tile * (size_t)(32 * DH) + ((d >> 3) * 32 + (pos & 31)) * 8) = w;
.LBB0_470:
	s_andn2_b64 vcc, exec, s[54:55]
	s_cbranch_vccnz .LBB0_472
	v_or_b32_e32 v0, s14, v153
	v_lshrrev_b32_e32 v10, 7, v0
	v_and_or_b32 v0, v66, -4, v10
	v_ashrrev_i32_e32 v1, 31, v0
	v_lshlrev_b64 v[0:1], 16, v[0:1]
	v_lshl_add_u64 v[2:3], v[154:155], 0, v[0:1]
	global_store_dwordx4 v[2:3], v[60:63], off sc1
	global_store_dwordx4 v[2:3], v[52:55], off offset:256 sc1
	v_lshl_add_u64 v[2:3], v[156:157], 0, v[0:1]
	v_lshl_add_u64 v[0:1], v[158:159], 0, v[0:1]
	global_store_dwordx4 v[2:3], v[44:47], off sc1
	global_store_dwordx4 v[0:1], v[36:39], off sc1
	v_and_or_b32 v0, v33, -4, v10
	v_ashrrev_i32_e32 v1, 31, v0
	v_lshlrev_b64 v[0:1], 16, v[0:1]
	v_lshl_add_u64 v[0:1], s[24:25], 0, v[0:1]
	v_and_b32_e32 v136, 0xc000, v32
	v_lshl_add_u64 v[0:1], v[0:1], 0, v[136:137]
	v_lshlrev_b32_e32 v136, 1, v152
	v_lshl_add_u64 v[0:1], v[0:1], 0, v[136:137]
	global_store_dwordx4 v[0:1], v[28:31], off sc1
	v_and_or_b32 v0, v25, -4, v10
	v_ashrrev_i32_e32 v1, 31, v0
	v_lshlrev_b64 v[0:1], 16, v[0:1]
	v_lshl_add_u64 v[0:1], s[24:25], 0, v[0:1]
	v_and_b32_e32 v2, 0xc000, v24
	v_mov_b32_e32 v3, v137
	v_lshl_add_u64 v[0:1], v[0:1], 0, v[2:3]
	v_and_or_b32 v2, v65, 31, v143
	v_lshlrev_b32_e32 v2, 4, v2
	v_lshl_add_u64 v[0:1], v[0:1], 0, v[2:3]
	global_store_dwordx4 v[0:1], v[20:23], off sc1
	v_and_or_b32 v0, v17, -4, v10
	v_ashrrev_i32_e32 v1, 31, v0
	v_lshlrev_b64 v[0:1], 16, v[0:1]
	v_lshl_add_u64 v[0:1], s[24:25], 0, v[0:1]
	v_and_b32_e32 v2, 0xe000, v16
	v_lshl_add_u64 v[0:1], v[0:1], 0, v[2:3]
	v_lshl_add_u64 v[0:1], v[0:1], 0, v[136:137]
	global_store_dwordx4 v[0:1], v[12:15], off sc1
	v_and_or_b32 v0, v9, -4, v10
	v_ashrrev_i32_e32 v1, 31, v0
	v_lshlrev_b64 v[0:1], 16, v[0:1]
	v_lshl_add_u64 v[0:1], s[24:25], 0, v[0:1]
	v_and_b32_e32 v136, 0xe000, v8
	v_and_or_b32 v2, v64, 31, v143
	v_lshl_add_u64 v[0:1], v[0:1], 0, v[136:137]
	v_lshlrev_b32_e32 v136, 4, v2
	v_lshl_add_u64 v[0:1], v[0:1], 0, v[136:137]
	global_store_dwordx4 v[0:1], v[4:7], off sc1

; __device__ __forceinline__ unsigned cvtpk(float lo, float hi) { f32x2v_ v = {lo, hi}; bf16x2v_ b = __builtin_convertvector(v, bf16x2v_); return __builtin_bit_cast(unsigned, b); }
;     __device__ __forceinline__ void operator()(const f32x4 (&acc)[2][2][4][2], const Unit& u, int wr, int wc, int fr, int fq) const {
;     ...
;                 const int c = c0 - kbeg, head = c >> dh_shift, d = c & (DH - 1);
;                 float cs[8];
; #pragma unroll
;                 for (int e = 0; e < 8; ++e) cs[e] = 0.f;
; #pragma unroll
;                 for (int ai = 0; ai < 2; ++ai)
; #pragma unroll
;                     for (int m = 0; m < 4; ++m) { const int row = row0 + ai * HALF + m * 16; const float rs = ss ? row_rs(ss, row) : 1.0f;
;                         const f32x4 v0 = acc[ai][bj][m][0] * rs, v1 = acc[ai][bj][m][1] * rs;
;                         const int b = row >> S_shift, pos = row & ((1 << S_shift) - 1);
;                         const size_t tile = ((size_t)(b * kvh + head) << (S_shift - 5)) + (pos >> 5);
;                         u32x4 w; w.x = cvtpk(v0[0], v0[1]); w.y = cvtpk(v0[2], v0[3]); w.z = cvtpk(v1[0], v1[1]); w.w = cvtpk(v1[2], v1[3]);
;                         *(u32x4*)(KP + tile * (size_t)(32 * DH) + ((d >> 3) * 32 + (pos & 31)) * 8) = w;
.LBB0_501:
	s_andn2_b64 vcc, exec, s[56:57]
	s_cbranch_vccnz .LBB0_503
	s_lshr_b32 s3, s14, 7
	v_ashrrev_i32_e32 v64, 6, v169
	v_and_or_b32 v64, v64, -4, s3
	v_ashrrev_i32_e32 v65, 31, v64
	v_lshlrev_b64 v[64:65], 16, v[64:65]
	v_lshl_add_u64 v[66:67], v[154:155], 0, v[64:65]
	global_store_dwordx4 v[66:67], v[124:127], off sc1
	global_store_dwordx4 v[66:67], v[116:119], off offset:256 sc1
	v_lshl_add_u64 v[66:67], v[156:157], 0, v[64:65]
	global_store_dwordx4 v[66:67], v[108:111], off sc1
	v_lshl_add_u64 v[64:65], v[158:159], 0, v[64:65]
	v_add_u32_e32 v66, 0x80, v169
	global_store_dwordx4 v[64:65], v[100:103], off sc1
	v_ashrrev_i32_e32 v64, 6, v66
	v_and_or_b32 v64, v64, -4, s3
	v_ashrrev_i32_e32 v65, 31, v64
	v_lshlrev_b64 v[64:65], 16, v[64:65]
	v_lshlrev_b32_e32 v66, 8, v66
	v_lshl_add_u64 v[64:65], s[6:7], 0, v[64:65]
	v_and_b32_e32 v136, 0xc000, v66
	v_lshl_add_u64 v[64:65], v[64:65], 0, v[136:137]
	v_lshlrev_b32_e32 v136, 1, v152
	v_lshl_add_u64 v[64:65], v[64:65], 0, v[136:137]
	v_add_u32_e32 v72, 0x90, v169
	global_store_dwordx4 v[64:65], v[92:95], off sc1
	v_ashrrev_i32_e32 v64, 6, v72
	v_and_or_b32 v64, v64, -4, s3
	v_ashrrev_i32_e32 v65, 31, v64
	v_lshlrev_b64 v[64:65], 16, v[64:65]
	v_lshlrev_b32_e32 v66, 8, v72
	v_lshl_add_u64 v[64:65], s[6:7], 0, v[64:65]
	v_and_b32_e32 v66, 0xc000, v66
	v_mov_b32_e32 v67, v137
	v_lshl_add_u64 v[64:65], v[64:65], 0, v[66:67]
	v_and_or_b32 v66, v72, 31, v143
	v_lshlrev_b32_e32 v66, 4, v66
	v_lshl_add_u64 v[64:65], v[64:65], 0, v[66:67]
	v_add_u32_e32 v66, 0xa0, v169
	global_store_dwordx4 v[64:65], v[84:87], off sc1
	v_ashrrev_i32_e32 v64, 6, v66
	v_and_or_b32 v64, v64, -4, s3
	v_ashrrev_i32_e32 v65, 31, v64
	v_lshlrev_b64 v[64:65], 16, v[64:65]
	v_lshlrev_b32_e32 v66, 8, v66
	v_lshl_add_u64 v[64:65], s[6:7], 0, v[64:65]
	v_and_b32_e32 v66, 0xe000, v66
	v_lshl_add_u64 v[64:65], v[64:65], 0, v[66:67]
	v_lshl_add_u64 v[64:65], v[64:65], 0, v[136:137]
	v_add_u32_e32 v66, 0xb0, v169
	global_store_dwordx4 v[64:65], v[76:79], off sc1
	v_ashrrev_i32_e32 v64, 6, v66
	v_and_or_b32 v64, v64, -4, s3
	v_ashrrev_i32_e32 v65, 31, v64
	v_lshlrev_b64 v[64:65], 16, v[64:65]
	v_lshlrev_b32_e32 v67, 8, v66
	v_lshl_add_u64 v[64:65], s[6:7], 0, v[64:65]
	v_and_b32_e32 v136, 0xe000, v67
	v_and_or_b32 v66, v66, 31, v143
	v_lshl_add_u64 v[64:65], v[64:65], 0, v[136:137]
	v_lshlrev_b32_e32 v136, 4, v66
	v_lshl_add_u64 v[64:65], v[64:65], 0, v[136:137]
	global_store_dwordx4 v[64:65], v[68:71], off sc1

; __device__ __forceinline__ unsigned cvtpk(float lo, float hi) { f32x2v_ v = {lo, hi}; bf16x2v_ b = __builtin_convertvector(v, bf16x2v_); return __builtin_bit_cast(unsigned, b); }
;     __device__ __forceinline__ void operator()(const f32x4 (&acc)[2][2][4][2], const Unit& u, int wr, int wc, int fr, int fq) const {
;     ...
;                 const int c = c0 - kbeg, head = c >> dh_shift, d = c & (DH - 1);
;                 float cs[8];
; #pragma unroll
;                 for (int e = 0; e < 8; ++e) cs[e] = 0.f;
; #pragma unroll
;                 for (int ai = 0; ai < 2; ++ai)
; #pragma unroll
;                     for (int m = 0; m < 4; ++m) { const int row = row0 + ai * HALF + m * 16; const float rs = ss ? row_rs(ss, row) : 1.0f;
;                         const f32x4 v0 = acc[ai][bj][m][0] * rs, v1 = acc[ai][bj][m][1] * rs;
;                         const int b = row >> S_shift, pos = row & ((1 << S_shift) - 1);
;                         const size_t tile = ((size_t)(b * kvh + head) << (S_shift - 5)) + (pos >> 5);
;                         u32x4 w; w.x = cvtpk(v0[0], v0[1]); w.y = cvtpk(v0[2], v0[3]); w.z = cvtpk(v1[0], v1[1]); w.w = cvtpk(v1[2], v1[3]);
;                         *(u32x4*)(KP + tile * (size_t)(32 * DH) + ((d >> 3) * 32 + (pos & 31)) * 8) = w;
.LBB0_506:
	s_andn2_b64 vcc, exec, s[56:57]
	s_cbranch_vccnz .LBB0_508
	v_or_b32_e32 v0, s14, v153
	v_lshrrev_b32_e32 v10, 7, v0
	v_and_or_b32 v0, v66, -4, v10
	v_ashrrev_i32_e32 v1, 31, v0
	v_lshlrev_b64 v[0:1], 16, v[0:1]
	v_lshl_add_u64 v[2:3], v[154:155], 0, v[0:1]
	global_store_dwordx4 v[2:3], v[60:63], off sc1
	global_store_dwordx4 v[2:3], v[52:55], off offset:256 sc1
	v_lshl_add_u64 v[2:3], v[156:157], 0, v[0:1]
	v_lshl_add_u64 v[0:1], v[158:159], 0, v[0:1]
	global_store_dwordx4 v[2:3], v[44:47], off sc1
	global_store_dwordx4 v[0:1], v[36:39], off sc1
	v_and_or_b32 v0, v33, -4, v10
	v_ashrrev_i32_e32 v1, 31, v0
	v_lshlrev_b64 v[0:1], 16, v[0:1]
	v_lshl_add_u64 v[0:1], s[6:7], 0, v[0:1]
	v_and_b32_e32 v136, 0xc000, v32
	v_lshl_add_u64 v[0:1], v[0:1], 0, v[136:137]
	v_lshlrev_b32_e32 v136, 1, v152
	v_lshl_add_u64 v[0:1], v[0:1], 0, v[136:137]
	global_store_dwordx4 v[0:1], v[28:31], off sc1
	v_and_or_b32 v0, v25, -4, v10
	v_ashrrev_i32_e32 v1, 31, v0
	v_lshlrev_b64 v[0:1], 16, v[0:1]
	v_lshl_add_u64 v[0:1], s[6:7], 0, v[0:1]
	v_and_b32_e32 v2, 0xc000, v24
	v_mov_b32_e32 v3, v137
	v_lshl_add_u64 v[0:1], v[0:1], 0, v[2:3]
	v_and_or_b32 v2, v65, 31, v143
	v_lshlrev_b32_e32 v2, 4, v2
	v_lshl_add_u64 v[0:1], v[0:1], 0, v[2:3]
	global_store_dwordx4 v[0:1], v[20:23], off sc1
	v_and_or_b32 v0, v17, -4, v10
	v_ashrrev_i32_e32 v1, 31, v0
	v_lshlrev_b64 v[0:1], 16, v[0:1]
	v_lshl_add_u64 v[0:1], s[6:7], 0, v[0:1]
	v_and_b32_e32 v2, 0xe000, v16
	v_lshl_add_u64 v[0:1], v[0:1], 0, v[2:3]
	v_lshl_add_u64 v[0:1], v[0:1], 0, v[136:137]
	global_store_dwordx4 v[0:1], v[12:15], off sc1
	v_and_or_b32 v0, v9, -4, v10
	v_ashrrev_i32_e32 v1, 31, v0
	v_lshlrev_b64 v[0:1], 16, v[0:1]
	v_lshl_add_u64 v[0:1], s[6:7], 0, v[0:1]
	v_and_b32_e32 v136, 0xe000, v8
	v_and_or_b32 v2, v64, 31, v143
	v_lshl_add_u64 v[0:1], v[0:1], 0, v[136:137]
	v_lshlrev_b32_e32 v136, 4, v2
	v_lshl_add_u64 v[0:1], v[0:1], 0, v[136:137]
	global_store_dwordx4 v[0:1], v[4:7], off sc1

; __device__ __forceinline__ void fx_add(float* p, size_t idx, float s) { atomicAdd((unsigned long long*)p + idx, (unsigned long long)(long long)(s * 4294967296.0f)); }
; __device__ __forceinline__ unsigned cvtpk(float lo, float hi) { f32x2v_ v = {lo, hi}; bf16x2v_ b = __builtin_convertvector(v, bf16x2v_); return __builtin_bit_cast(unsigned, b); }
;     __device__ __forceinline__ void operator()(const f32x4 (&acc)[2][2][4][2], const Unit& u, int wr, int wc, int fr, int fq) const {
;     ...
;             for (int m = 0; m < 4; ++m) { const int row = row0 + ai * HALF + m * 16; const size_t off = (size_t)row * 1024 + col0; float s = 0.f;
; #pragma unroll
;                 for (int bj = 0; bj < 2; ++bj) { f32x4 a0, a1;
;                     if (xin32) { const float* p = xin32 + off + bj * HALF; a0 = *(const f32x4*)p; a1 = *(const f32x4*)(p + 4); }
;                     else { const u32x4 w = *(const u32x4*)(xb + off + bj * HALF);
;                         a0 = (f32x4){__uint_as_float(w.x << 16), __uint_as_float(w.x & 0xffff0000u), __uint_as_float(w.y << 16), __uint_as_float(w.y & 0xffff0000u)};
;                         a1 = (f32x4){__uint_as_float(w.z << 16), __uint_as_float(w.z & 0xffff0000u), __uint_as_float(w.w << 16), __uint_as_float(w.w & 0xffff0000u)}; }
;                     const f32x4 v0 = a0 + acc[ai][bj][m][0] * alpha, v1 = a1 + acc[ai][bj][m][1] * alpha;
;                     u32x4 w; w.x = cvtpk(v0[0], v0[1]); w.y = cvtpk(v0[2], v0[3]); w.z = cvtpk(v1[0], v1[1]); w.w = cvtpk(v1[2], v1[3]);
;                     *(u32x4*)(xb + off + bj * HALF) = w;
;                     s += (v0[0] * v0[0] + v0[1] * v0[1]) + (v0[2] * v0[2] + v0[3] * v0[3]) + (v1[0] * v1[0] + v1[1] * v1[1]) + (v1[2] * v1[2] + v1[3] * v1[3]); }
;                 s += __shfl_xor(s, 16); s += __shfl_xor(s, 32);
;                 if (fq == 0) fx_add(ssout, row, s); }
.LBB0_653:
	v_lshl_add_u32 v150, s58, 8, v129
	v_ashrrev_i32_e32 v151, 31, v150
	v_lshl_or_b32 v148, s56, 8, v154
	v_lshlrev_b64 v[160:161], 11, v[150:151]
	v_ashrrev_i32_e32 v149, 31, v148
	v_lshl_add_u64 v[160:161], s[22:23], 0, v[160:161]
	v_lshl_add_u64 v[170:171], v[148:149], 1, v[160:161]
	global_load_dwordx4 v[162:165], v[170:171], off
	global_load_dwordx4 v[166:169], v[170:171], off offset:256
	v_and_b32_e32 v160, 64, v158
	v_xor_b32_e32 v159, 16, v158
	v_add_u32_e32 v160, 64, v160
	v_xor_b32_e32 v161, 32, v158
	v_cmp_lt_i32_e32 vcc, v159, v160
	s_waitcnt vmcnt(0)
	v_lshlrev_b32_e32 v172, 16, v162
	v_cndmask_b32_e32 v159, v158, v159, vcc
	v_cmp_lt_i32_e32 vcc, v161, v160
	v_and_b32_e32 v173, 0xffff0000, v162
	v_lshlrev_b32_e32 v162, 16, v163
	v_and_b32_e32 v163, 0xffff0000, v163
	v_lshlrev_b32_e32 v176, 16, v166
	v_and_b32_e32 v177, 0xffff0000, v166
	v_lshlrev_b32_e32 v166, 16, v167
	v_and_b32_e32 v167, 0xffff0000, v167
	v_cndmask_b32_e32 v161, v158, v161, vcc
	v_lshlrev_b32_e32 v174, 16, v164
	v_and_b32_e32 v175, 0xffff0000, v164
	v_lshlrev_b32_e32 v164, 16, v165
	v_and_b32_e32 v165, 0xffff0000, v165
	v_lshlrev_b32_e32 v178, 16, v168
	v_and_b32_e32 v179, 0xffff0000, v168
	v_lshlrev_b32_e32 v168, 16, v169
	v_and_b32_e32 v169, 0xffff0000, v169
	v_pk_add_f32 v[126:127], v[126:127], v[162:163]
	v_pk_add_f32 v[124:125], v[124:125], v[172:173]
	v_pk_add_f32 v[118:119], v[118:119], v[166:167]
	v_pk_add_f32 v[116:117], v[116:117], v[176:177]
	v_lshlrev_b32_e32 v160, 2, v159
	v_lshlrev_b32_e32 v159, 2, v161
	v_pk_add_f32 v[122:123], v[122:123], v[164:165]
	v_pk_add_f32 v[120:121], v[120:121], v[174:175]
	v_pk_add_f32 v[162:163], v[114:115], v[168:169]
	v_pk_add_f32 v[164:165], v[112:113], v[178:179]
	v_mul_f32_e32 v114, v125, v125
	v_mul_f32_e32 v115, v127, v127
	v_mul_f32_e32 v161, v117, v117
	v_mul_f32_e32 v166, v119, v119
	v_cvt_pk_bf16_f32 v112, v124, v125
	v_mul_f32_e32 v125, v121, v121
	v_mul_f32_e32 v167, v165, v165
	v_fmac_f32_e32 v114, v124, v124
	v_fmac_f32_e32 v115, v126, v126
	v_fmac_f32_e32 v161, v116, v116
	v_fmac_f32_e32 v166, v118, v118
	v_cvt_pk_bf16_f32 v113, v126, v127
	v_mul_f32_e32 v127, v123, v123
	v_mul_f32_e32 v168, v163, v163
	v_fmac_f32_e32 v125, v120, v120
	v_fmac_f32_e32 v167, v164, v164
	v_add_f32_e32 v114, v114, v115
	v_add_f32_e32 v115, v161, v166
	v_fmac_f32_e32 v127, v122, v122
	v_fmac_f32_e32 v168, v162, v162
	v_add_f32_e32 v114, v125, v114
	v_add_f32_e32 v115, v167, v115
	v_add_f32_e32 v114, v127, v114
	v_add_f32_e32 v115, v168, v115
	v_add_f32_e32 v124, v114, v115
	v_mov_b32_e32 v125, v124
	s_nop 1
	v_permlane16_swap_b32_e32 v125, v124
	v_cvt_pk_bf16_f32 v114, v120, v121
	v_cvt_pk_bf16_f32 v115, v122, v123
	global_store_dwordx4 v[170:171], v[112:115], off sc1
	s_waitcnt lgkmcnt(0)
	s_nop 0
	v_add_f32_e32 v112, v124, v125
	v_mov_b32_e32 v113, v112
	s_nop 1
	v_permlane32_swap_b32_e32 v113, v112
	v_cvt_pk_bf16_f32 v114, v116, v117
	v_cvt_pk_bf16_f32 v115, v118, v119
	v_cvt_pk_bf16_f32 v116, v164, v165
	v_cvt_pk_bf16_f32 v117, v162, v163
	global_store_dwordx4 v[170:171], v[114:117], off offset:256 sc1
	s_and_saveexec_b64 s[56:57], s[6:7]
	s_cbranch_execz .LBB0_655
	s_waitcnt lgkmcnt(0)
	v_add_f32_e32 v112, v112, v113
	v_mul_f32_e32 v112, 0x4f800000, v112
	v_trunc_f32_e32 v112, v112
	v_mul_f32_e64 v113, |v112|, s87
	v_floor_f32_e32 v113, v113
	v_fma_f32 v114, v113, s88, |v112|
	v_cvt_u32_f32_e32 v112, v114
	v_cvt_u32_f32_e32 v113, v113
	v_lshl_add_u64 v[114:115], v[150:151], 3, s[10:11]
	global_atomic_add_x2 v[114:115], v[112:113], off
.LBB0_655:
	s_or_b64 exec, exec, s[56:57]
	v_or_b32_e32 v112, 16, v150
	s_waitcnt lgkmcnt(0)
	v_ashrrev_i32_e32 v113, 31, v112
	v_lshlrev_b64 v[114:115], 11, v[112:113]
	v_lshl_add_u64 v[114:115], s[22:23], 0, v[114:115]
	v_lshl_add_u64 v[122:123], v[148:149], 1, v[114:115]
	global_load_dwordx4 v[114:117], v[122:123], off
	global_load_dwordx4 v[118:121], v[122:123], off offset:256
	s_waitcnt vmcnt(1)
	v_lshlrev_b32_e32 v124, 16, v114
	v_and_b32_e32 v125, 0xffff0000, v114
	v_lshlrev_b32_e32 v114, 16, v115
	v_and_b32_e32 v115, 0xffff0000, v115
	s_waitcnt vmcnt(0)
	v_lshlrev_b32_e32 v162, 16, v118
	v_and_b32_e32 v163, 0xffff0000, v118
	v_lshlrev_b32_e32 v118, 16, v119
	v_and_b32_e32 v119, 0xffff0000, v119
	v_lshlrev_b32_e32 v126, 16, v116
	v_and_b32_e32 v127, 0xffff0000, v116
	v_lshlrev_b32_e32 v116, 16, v117
	v_and_b32_e32 v117, 0xffff0000, v117
	v_lshlrev_b32_e32 v164, 16, v120
	v_and_b32_e32 v165, 0xffff0000, v120
	v_lshlrev_b32_e32 v120, 16, v121
	v_and_b32_e32 v121, 0xffff0000, v121
	v_pk_add_f32 v[110:111], v[110:111], v[114:115]
	v_pk_add_f32 v[108:109], v[108:109], v[124:125]
	v_pk_add_f32 v[102:103], v[102:103], v[118:119]
	v_pk_add_f32 v[100:101], v[100:101], v[162:163]
	v_pk_add_f32 v[106:107], v[106:107], v[116:117]
	v_pk_add_f32 v[104:105], v[104:105], v[126:127]
	v_pk_add_f32 v[114:115], v[98:99], v[120:121]
	v_pk_add_f32 v[116:117], v[96:97], v[164:165]
	v_mul_f32_e32 v98, v109, v109
	v_mul_f32_e32 v99, v111, v111
	v_mul_f32_e32 v118, v101, v101
	v_mul_f32_e32 v119, v103, v103
	v_cvt_pk_bf16_f32 v96, v108, v109
	v_mul_f32_e32 v109, v105, v105
	v_mul_f32_e32 v120, v117, v117
	v_fmac_f32_e32 v98, v108, v108
	v_fmac_f32_e32 v99, v110, v110
	v_fmac_f32_e32 v118, v100, v100
	v_fmac_f32_e32 v119, v102, v102
	v_cvt_pk_bf16_f32 v97, v110, v111
	v_mul_f32_e32 v111, v107, v107
	v_mul_f32_e32 v121, v115, v115
	v_fmac_f32_e32 v109, v104, v104
	v_fmac_f32_e32 v120, v116, v116
	v_add_f32_e32 v98, v98, v99
	v_add_f32_e32 v99, v118, v119
	v_fmac_f32_e32 v111, v106, v106
	v_fmac_f32_e32 v121, v114, v114
	v_add_f32_e32 v98, v109, v98
	v_add_f32_e32 v99, v120, v99
	v_add_f32_e32 v98, v111, v98
	v_add_f32_e32 v99, v121, v99
	v_add_f32_e32 v108, v98, v99
	v_mov_b32_e32 v109, v108
	s_nop 1
	v_permlane16_swap_b32_e32 v109, v108
	v_cvt_pk_bf16_f32 v98, v104, v105
	v_cvt_pk_bf16_f32 v99, v106, v107
	global_store_dwordx4 v[122:123], v[96:99], off sc1
	s_waitcnt lgkmcnt(0)
	s_nop 0
	v_add_f32_e32 v96, v108, v109
	v_mov_b32_e32 v97, v96
	s_nop 1
	v_permlane32_swap_b32_e32 v97, v96
	v_cvt_pk_bf16_f32 v98, v100, v101
	v_cvt_pk_bf16_f32 v99, v102, v103
	v_cvt_pk_bf16_f32 v100, v116, v117
	v_cvt_pk_bf16_f32 v101, v114, v115
	global_store_dwordx4 v[122:123], v[98:101], off offset:256 sc1
	s_and_saveexec_b64 s[56:57], s[6:7]
	s_cbranch_execz .LBB0_657
	s_waitcnt lgkmcnt(0)
	v_add_f32_e32 v96, v96, v97
	v_mul_f32_e32 v96, 0x4f800000, v96
	v_trunc_f32_e32 v96, v96
	v_mul_f32_e64 v97, |v96|, s87
	v_floor_f32_e32 v97, v97
	v_fma_f32 v98, v97, s88, |v96|
	v_cvt_u32_f32_e32 v96, v98
	v_cvt_u32_f32_e32 v97, v97
	v_lshl_add_u64 v[98:99], v[112:113], 3, s[10:11]
	global_atomic_add_x2 v[98:99], v[96:97], off
; __device__ __forceinline__ void fx_add(float* p, size_t idx, float s) { atomicAdd((unsigned long long*)p + idx, (unsigned long long)(long long)(s * 4294967296.0f)); }
; __device__ __forceinline__ unsigned cvtpk(float lo, float hi) { f32x2v_ v = {lo, hi}; bf16x2v_ b = __builtin_convertvector(v, bf16x2v_); return __builtin_bit_cast(unsigned, b); }
;     __device__ __forceinline__ void operator()(const f32x4 (&acc)[2][2][4][2], const Unit& u, int wr, int wc, int fr, int fq) const {
;     ...
;             for (int m = 0; m < 4; ++m) { const int row = row0 + ai * HALF + m * 16; const size_t off = (size_t)row * 1024 + col0; float s = 0.f;
; #pragma unroll
;                 for (int bj = 0; bj < 2; ++bj) { f32x4 a0, a1;
;                     if (xin32) { const float* p = xin32 + off + bj * HALF; a0 = *(const f32x4*)p; a1 = *(const f32x4*)(p + 4); }
;                     else { const u32x4 w = *(const u32x4*)(xb + off + bj * HALF);
;                         a0 = (f32x4){__uint_as_float(w.x << 16), __uint_as_float(w.x & 0xffff0000u), __uint_as_float(w.y << 16), __uint_as_float(w.y & 0xffff0000u)};
;                         a1 = (f32x4){__uint_as_float(w.z << 16), __uint_as_float(w.z & 0xffff0000u), __uint_as_float(w.w << 16), __uint_as_float(w.w & 0xffff0000u)}; }
;                     const f32x4 v0 = a0 + acc[ai][bj][m][0] * alpha, v1 = a1 + acc[ai][bj][m][1] * alpha;
;                     u32x4 w; w.x = cvtpk(v0[0], v0[1]); w.y = cvtpk(v0[2], v0[3]); w.z = cvtpk(v1[0], v1[1]); w.w = cvtpk(v1[2], v1[3]);
;                     *(u32x4*)(xb + off + bj * HALF) = w;
;                     s += (v0[0] * v0[0] + v0[1] * v0[1]) + (v0[2] * v0[2] + v0[3] * v0[3]) + (v1[0] * v1[0] + v1[1] * v1[1]) + (v1[2] * v1[2] + v1[3] * v1[3]); }
;                 s += __shfl_xor(s, 16); s += __shfl_xor(s, 32);
;                 if (fq == 0) fx_add(ssout, row, s); }
.LBB0_657:
	s_or_b64 exec, exec, s[56:57]
	v_or_b32_e32 v96, 32, v150
	s_waitcnt lgkmcnt(0)
	v_ashrrev_i32_e32 v97, 31, v96
	v_lshlrev_b64 v[98:99], 11, v[96:97]
	v_lshl_add_u64 v[98:99], s[22:23], 0, v[98:99]
	v_lshl_add_u64 v[106:107], v[148:149], 1, v[98:99]
	global_load_dwordx4 v[98:101], v[106:107], off
	global_load_dwordx4 v[102:105], v[106:107], off offset:256
	s_waitcnt vmcnt(1)
	v_lshlrev_b32_e32 v108, 16, v98
	v_and_b32_e32 v109, 0xffff0000, v98
	v_lshlrev_b32_e32 v98, 16, v99
	v_and_b32_e32 v99, 0xffff0000, v99
	s_waitcnt vmcnt(0)
	v_lshlrev_b32_e32 v112, 16, v102
	v_and_b32_e32 v113, 0xffff0000, v102
	v_lshlrev_b32_e32 v102, 16, v103
	v_and_b32_e32 v103, 0xffff0000, v103
	v_lshlrev_b32_e32 v110, 16, v100
	v_and_b32_e32 v111, 0xffff0000, v100
	v_lshlrev_b32_e32 v100, 16, v101
	v_and_b32_e32 v101, 0xffff0000, v101
	v_lshlrev_b32_e32 v114, 16, v104
	v_and_b32_e32 v115, 0xffff0000, v104
	v_lshlrev_b32_e32 v104, 16, v105
	v_and_b32_e32 v105, 0xffff0000, v105
	v_pk_add_f32 v[94:95], v[94:95], v[98:99]
	v_pk_add_f32 v[92:93], v[92:93], v[108:109]
	v_pk_add_f32 v[86:87], v[86:87], v[102:103]
	v_pk_add_f32 v[84:85], v[84:85], v[112:113]
	v_pk_add_f32 v[90:91], v[90:91], v[100:101]
	v_pk_add_f32 v[88:89], v[88:89], v[110:111]
	v_pk_add_f32 v[98:99], v[82:83], v[104:105]
	v_pk_add_f32 v[100:101], v[80:81], v[114:115]
	v_mul_f32_e32 v82, v93, v93
	v_mul_f32_e32 v83, v95, v95
	v_mul_f32_e32 v102, v85, v85
	v_mul_f32_e32 v103, v87, v87
	v_cvt_pk_bf16_f32 v80, v92, v93
	v_mul_f32_e32 v93, v89, v89
	v_mul_f32_e32 v104, v101, v101
	v_fmac_f32_e32 v82, v92, v92
	v_fmac_f32_e32 v83, v94, v94
	v_fmac_f32_e32 v102, v84, v84
	v_fmac_f32_e32 v103, v86, v86
	v_cvt_pk_bf16_f32 v81, v94, v95
	v_mul_f32_e32 v95, v91, v91
	v_mul_f32_e32 v105, v99, v99
	v_fmac_f32_e32 v93, v88, v88
	v_fmac_f32_e32 v104, v100, v100
	v_add_f32_e32 v82, v82, v83
	v_add_f32_e32 v83, v102, v103
	v_fmac_f32_e32 v95, v90, v90
	v_fmac_f32_e32 v105, v98, v98
	v_add_f32_e32 v82, v93, v82
	v_add_f32_e32 v83, v104, v83
	v_add_f32_e32 v82, v95, v82
	v_add_f32_e32 v83, v105, v83
	v_add_f32_e32 v92, v82, v83
	v_mov_b32_e32 v93, v92
	s_nop 1
	v_permlane16_swap_b32_e32 v93, v92
	v_cvt_pk_bf16_f32 v82, v88, v89
	v_cvt_pk_bf16_f32 v83, v90, v91
	global_store_dwordx4 v[106:107], v[80:83], off sc1
	s_waitcnt lgkmcnt(0)
	s_nop 0
	v_add_f32_e32 v80, v92, v93
	v_mov_b32_e32 v81, v80
	s_nop 1
	v_permlane32_swap_b32_e32 v81, v80
	v_cvt_pk_bf16_f32 v82, v84, v85
	v_cvt_pk_bf16_f32 v83, v86, v87
	v_cvt_pk_bf16_f32 v84, v100, v101
	v_cvt_pk_bf16_f32 v85, v98, v99
	global_store_dwordx4 v[106:107], v[82:85], off offset:256 sc1
	s_and_saveexec_b64 s[56:57], s[6:7]
	s_cbranch_execz .LBB0_659
	s_waitcnt lgkmcnt(0)
	v_add_f32_e32 v80, v80, v81
	v_mul_f32_e32 v80, 0x4f800000, v80
	v_trunc_f32_e32 v80, v80
	v_mul_f32_e64 v81, |v80|, s87
	v_floor_f32_e32 v81, v81
	v_fma_f32 v82, v81, s88, |v80|
	v_cvt_u32_f32_e32 v80, v82
	v_cvt_u32_f32_e32 v81, v81
	v_lshl_add_u64 v[82:83], v[96:97], 3, s[10:11]
	global_atomic_add_x2 v[82:83], v[80:81], off
.LBB0_659:
	s_or_b64 exec, exec, s[56:57]
	v_or_b32_e32 v80, 48, v150
	s_waitcnt lgkmcnt(0)
	v_ashrrev_i32_e32 v81, 31, v80
	v_lshlrev_b64 v[82:83], 11, v[80:81]
	v_lshl_add_u64 v[82:83], s[22:23], 0, v[82:83]
	v_lshl_add_u64 v[90:91], v[148:149], 1, v[82:83]
	global_load_dwordx4 v[82:85], v[90:91], off
	global_load_dwordx4 v[86:89], v[90:91], off offset:256
	s_waitcnt vmcnt(1)
	v_lshlrev_b32_e32 v92, 16, v82
	v_and_b32_e32 v93, 0xffff0000, v82
	v_lshlrev_b32_e32 v82, 16, v83
	v_and_b32_e32 v83, 0xffff0000, v83
	s_waitcnt vmcnt(0)
	v_lshlrev_b32_e32 v96, 16, v86
	v_and_b32_e32 v97, 0xffff0000, v86
	v_lshlrev_b32_e32 v86, 16, v87
	v_and_b32_e32 v87, 0xffff0000, v87
	v_lshlrev_b32_e32 v94, 16, v84
	v_and_b32_e32 v95, 0xffff0000, v84
	v_lshlrev_b32_e32 v84, 16, v85
	v_and_b32_e32 v85, 0xffff0000, v85
	v_lshlrev_b32_e32 v98, 16, v88
	v_and_b32_e32 v99, 0xffff0000, v88
	v_lshlrev_b32_e32 v88, 16, v89
	v_and_b32_e32 v89, 0xffff0000, v89
	v_pk_add_f32 v[78:79], v[78:79], v[82:83]
	v_pk_add_f32 v[76:77], v[76:77], v[92:93]
	v_pk_add_f32 v[70:71], v[70:71], v[86:87]
	v_pk_add_f32 v[68:69], v[68:69], v[96:97]
	v_pk_add_f32 v[74:75], v[74:75], v[84:85]
	v_pk_add_f32 v[72:73], v[72:73], v[94:95]
	v_pk_add_f32 v[82:83], v[66:67], v[88:89]
	v_pk_add_f32 v[84:85], v[64:65], v[98:99]
	v_mul_f32_e32 v66, v77, v77
	v_mul_f32_e32 v67, v79, v79
	v_mul_f32_e32 v86, v69, v69
	v_mul_f32_e32 v87, v71, v71
	v_cvt_pk_bf16_f32 v64, v76, v77
	v_mul_f32_e32 v77, v73, v73
	v_mul_f32_e32 v88, v85, v85
	v_fmac_f32_e32 v66, v76, v76
	v_fmac_f32_e32 v67, v78, v78
	v_fmac_f32_e32 v86, v68, v68
	v_fmac_f32_e32 v87, v70, v70
	v_cvt_pk_bf16_f32 v65, v78, v79
	v_mul_f32_e32 v79, v75, v75
	v_mul_f32_e32 v89, v83, v83
	v_fmac_f32_e32 v77, v72, v72
	v_fmac_f32_e32 v88, v84, v84
	v_add_f32_e32 v66, v66, v67
	v_add_f32_e32 v67, v86, v87
	v_fmac_f32_e32 v79, v74, v74
	v_fmac_f32_e32 v89, v82, v82
	v_add_f32_e32 v66, v77, v66
	v_add_f32_e32 v67, v88, v67
	v_add_f32_e32 v66, v79, v66
	v_add_f32_e32 v67, v89, v67
	v_add_f32_e32 v76, v66, v67
	v_mov_b32_e32 v77, v76
	s_nop 1
	v_permlane16_swap_b32_e32 v77, v76
	v_cvt_pk_bf16_f32 v66, v72, v73
	v_cvt_pk_bf16_f32 v67, v74, v75
	global_store_dwordx4 v[90:91], v[64:67], off sc1
	s_waitcnt lgkmcnt(0)
	s_nop 0
	v_add_f32_e32 v64, v76, v77
	v_mov_b32_e32 v65, v64
	s_nop 1
	v_permlane32_swap_b32_e32 v65, v64
	v_cvt_pk_bf16_f32 v66, v68, v69
	v_cvt_pk_bf16_f32 v67, v70, v71
	v_cvt_pk_bf16_f32 v68, v84, v85
	v_cvt_pk_bf16_f32 v69, v82, v83
	global_store_dwordx4 v[90:91], v[66:69], off offset:256 sc1
	s_and_saveexec_b64 s[56:57], s[6:7]
	s_cbranch_execz .LBB0_661
	s_waitcnt lgkmcnt(0)
	v_add_f32_e32 v64, v64, v65
	v_mul_f32_e32 v64, 0x4f800000, v64
	v_trunc_f32_e32 v64, v64
	v_mul_f32_e64 v65, |v64|, s87
	v_floor_f32_e32 v65, v65
	v_fma_f32 v66, v65, s88, |v64|
	v_cvt_u32_f32_e32 v64, v66
	v_cvt_u32_f32_e32 v65, v65
	v_lshl_add_u64 v[66:67], v[80:81], 3, s[10:11]
	global_atomic_add_x2 v[66:67], v[64:65], off
; __device__ __forceinline__ void fx_add(float* p, size_t idx, float s) { atomicAdd((unsigned long long*)p + idx, (unsigned long long)(long long)(s * 4294967296.0f)); }
; __device__ __forceinline__ unsigned cvtpk(float lo, float hi) { f32x2v_ v = {lo, hi}; bf16x2v_ b = __builtin_convertvector(v, bf16x2v_); return __builtin_bit_cast(unsigned, b); }
;     __device__ __forceinline__ void operator()(const f32x4 (&acc)[2][2][4][2], const Unit& u, int wr, int wc, int fr, int fq) const {
;     ...
;             for (int m = 0; m < 4; ++m) { const int row = row0 + ai * HALF + m * 16; const size_t off = (size_t)row * 1024 + col0; float s = 0.f;
; #pragma unroll
;                 for (int bj = 0; bj < 2; ++bj) { f32x4 a0, a1;
;                     if (xin32) { const float* p = xin32 + off + bj * HALF; a0 = *(const f32x4*)p; a1 = *(const f32x4*)(p + 4); }
;                     else { const u32x4 w = *(const u32x4*)(xb + off + bj * HALF);
;                         a0 = (f32x4){__uint_as_float(w.x << 16), __uint_as_float(w.x & 0xffff0000u), __uint_as_float(w.y << 16), __uint_as_float(w.y & 0xffff0000u)};
;                         a1 = (f32x4){__uint_as_float(w.z << 16), __uint_as_float(w.z & 0xffff0000u), __uint_as_float(w.w << 16), __uint_as_float(w.w & 0xffff0000u)}; }
;                     const f32x4 v0 = a0 + acc[ai][bj][m][0] * alpha, v1 = a1 + acc[ai][bj][m][1] * alpha;
;                     u32x4 w; w.x = cvtpk(v0[0], v0[1]); w.y = cvtpk(v0[2], v0[3]); w.z = cvtpk(v1[0], v1[1]); w.w = cvtpk(v1[2], v1[3]);
;                     *(u32x4*)(xb + off + bj * HALF) = w;
;                     s += (v0[0] * v0[0] + v0[1] * v0[1]) + (v0[2] * v0[2] + v0[3] * v0[3]) + (v1[0] * v1[0] + v1[1] * v1[1]) + (v1[2] * v1[2] + v1[3] * v1[3]); }
;                 s += __shfl_xor(s, 16); s += __shfl_xor(s, 32);
;                 if (fq == 0) fx_add(ssout, row, s); }
.LBB0_661:
	s_or_b64 exec, exec, s[56:57]
	v_add_u32_e32 v64, 0x80, v150
	s_waitcnt lgkmcnt(0)
	v_ashrrev_i32_e32 v65, 31, v64
	v_lshlrev_b64 v[66:67], 11, v[64:65]
	v_lshl_add_u64 v[66:67], s[22:23], 0, v[66:67]
	v_lshl_add_u64 v[74:75], v[148:149], 1, v[66:67]
	global_load_dwordx4 v[66:69], v[74:75], off
	global_load_dwordx4 v[70:73], v[74:75], off offset:256
	s_waitcnt vmcnt(1)
	v_lshlrev_b32_e32 v76, 16, v66
	v_and_b32_e32 v77, 0xffff0000, v66
	v_lshlrev_b32_e32 v66, 16, v67
	v_and_b32_e32 v67, 0xffff0000, v67
	s_waitcnt vmcnt(0)
	v_lshlrev_b32_e32 v80, 16, v70
	v_and_b32_e32 v81, 0xffff0000, v70
	v_lshlrev_b32_e32 v70, 16, v71
	v_and_b32_e32 v71, 0xffff0000, v71
	v_lshlrev_b32_e32 v78, 16, v68
	v_and_b32_e32 v79, 0xffff0000, v68
	v_lshlrev_b32_e32 v68, 16, v69
	v_and_b32_e32 v69, 0xffff0000, v69
	v_lshlrev_b32_e32 v82, 16, v72
	v_and_b32_e32 v83, 0xffff0000, v72
	v_lshlrev_b32_e32 v72, 16, v73
	v_and_b32_e32 v73, 0xffff0000, v73
	v_pk_add_f32 v[62:63], v[62:63], v[66:67]
	v_pk_add_f32 v[60:61], v[60:61], v[76:77]
	v_pk_add_f32 v[54:55], v[54:55], v[70:71]
	v_pk_add_f32 v[52:53], v[52:53], v[80:81]
	v_pk_add_f32 v[58:59], v[58:59], v[68:69]
	v_pk_add_f32 v[56:57], v[56:57], v[78:79]
	v_pk_add_f32 v[66:67], v[50:51], v[72:73]
	v_pk_add_f32 v[68:69], v[48:49], v[82:83]
	v_mul_f32_e32 v50, v61, v61
	v_mul_f32_e32 v51, v63, v63
	v_mul_f32_e32 v70, v53, v53
	v_mul_f32_e32 v71, v55, v55
	v_cvt_pk_bf16_f32 v48, v60, v61
	v_mul_f32_e32 v61, v57, v57
	v_mul_f32_e32 v72, v69, v69
	v_fmac_f32_e32 v50, v60, v60
	v_fmac_f32_e32 v51, v62, v62
	v_fmac_f32_e32 v70, v52, v52
	v_fmac_f32_e32 v71, v54, v54
	v_cvt_pk_bf16_f32 v49, v62, v63
	v_mul_f32_e32 v63, v59, v59
	v_mul_f32_e32 v73, v67, v67
	v_fmac_f32_e32 v61, v56, v56
	v_fmac_f32_e32 v72, v68, v68
	v_add_f32_e32 v50, v50, v51
	v_add_f32_e32 v51, v70, v71
	v_fmac_f32_e32 v63, v58, v58
	v_fmac_f32_e32 v73, v66, v66
	v_add_f32_e32 v50, v61, v50
	v_add_f32_e32 v51, v72, v51
	v_add_f32_e32 v50, v63, v50
	v_add_f32_e32 v51, v73, v51
	v_add_f32_e32 v60, v50, v51
	v_mov_b32_e32 v61, v60
	s_nop 1
	v_permlane16_swap_b32_e32 v61, v60
	v_cvt_pk_bf16_f32 v50, v56, v57
	v_cvt_pk_bf16_f32 v51, v58, v59
	global_store_dwordx4 v[74:75], v[48:51], off sc1
	s_waitcnt lgkmcnt(0)
	s_nop 0
	v_add_f32_e32 v48, v60, v61
	v_mov_b32_e32 v49, v48
	s_nop 1
	v_permlane32_swap_b32_e32 v49, v48
	v_cvt_pk_bf16_f32 v50, v52, v53
	v_cvt_pk_bf16_f32 v51, v54, v55
	v_cvt_pk_bf16_f32 v52, v68, v69
	v_cvt_pk_bf16_f32 v53, v66, v67
	global_store_dwordx4 v[74:75], v[50:53], off offset:256 sc1
	s_and_saveexec_b64 s[56:57], s[6:7]
	s_cbranch_execz .LBB0_663
	s_waitcnt lgkmcnt(0)
	v_add_f32_e32 v48, v48, v49
	v_mul_f32_e32 v48, 0x4f800000, v48
	v_trunc_f32_e32 v48, v48
	v_mul_f32_e64 v49, |v48|, s87
	v_floor_f32_e32 v49, v49
	v_fma_f32 v50, v49, s88, |v48|
	v_cvt_u32_f32_e32 v48, v50
	v_cvt_u32_f32_e32 v49, v49
	v_lshl_add_u64 v[50:51], v[64:65], 3, s[10:11]
	global_atomic_add_x2 v[50:51], v[48:49], off
.LBB0_663:
	s_or_b64 exec, exec, s[56:57]
	v_add_u32_e32 v48, 0x90, v150
	s_waitcnt lgkmcnt(0)
	v_ashrrev_i32_e32 v49, 31, v48
	v_lshlrev_b64 v[50:51], 11, v[48:49]
	v_lshl_add_u64 v[50:51], s[22:23], 0, v[50:51]
	v_lshl_add_u64 v[58:59], v[148:149], 1, v[50:51]
	global_load_dwordx4 v[50:53], v[58:59], off
	global_load_dwordx4 v[54:57], v[58:59], off offset:256
	s_waitcnt vmcnt(1)
	v_lshlrev_b32_e32 v60, 16, v50
	v_and_b32_e32 v61, 0xffff0000, v50
	v_lshlrev_b32_e32 v50, 16, v51
	v_and_b32_e32 v51, 0xffff0000, v51
	s_waitcnt vmcnt(0)
	v_lshlrev_b32_e32 v64, 16, v54
	v_and_b32_e32 v65, 0xffff0000, v54
	v_lshlrev_b32_e32 v54, 16, v55
	v_and_b32_e32 v55, 0xffff0000, v55
	v_lshlrev_b32_e32 v62, 16, v52
	v_and_b32_e32 v63, 0xffff0000, v52
	v_lshlrev_b32_e32 v52, 16, v53
	v_and_b32_e32 v53, 0xffff0000, v53
	v_lshlrev_b32_e32 v66, 16, v56
	v_and_b32_e32 v67, 0xffff0000, v56
	v_lshlrev_b32_e32 v56, 16, v57
	v_and_b32_e32 v57, 0xffff0000, v57
	v_pk_add_f32 v[46:47], v[46:47], v[50:51]
	v_pk_add_f32 v[44:45], v[44:45], v[60:61]
	v_pk_add_f32 v[38:39], v[38:39], v[54:55]
	v_pk_add_f32 v[36:37], v[36:37], v[64:65]
	v_pk_add_f32 v[42:43], v[42:43], v[52:53]
	v_pk_add_f32 v[40:41], v[40:41], v[62:63]
	v_pk_add_f32 v[50:51], v[34:35], v[56:57]
	v_pk_add_f32 v[52:53], v[32:33], v[66:67]
	v_mul_f32_e32 v34, v45, v45
	v_mul_f32_e32 v35, v47, v47
	v_mul_f32_e32 v54, v37, v37
	v_mul_f32_e32 v55, v39, v39
	v_cvt_pk_bf16_f32 v32, v44, v45
	v_mul_f32_e32 v45, v41, v41
	v_mul_f32_e32 v56, v53, v53
	v_fmac_f32_e32 v34, v44, v44
	v_fmac_f32_e32 v35, v46, v46
	v_fmac_f32_e32 v54, v36, v36
	v_fmac_f32_e32 v55, v38, v38
	v_cvt_pk_bf16_f32 v33, v46, v47
	v_mul_f32_e32 v47, v43, v43
	v_mul_f32_e32 v57, v51, v51
	v_fmac_f32_e32 v45, v40, v40
	v_fmac_f32_e32 v56, v52, v52
	v_add_f32_e32 v34, v34, v35
	v_add_f32_e32 v35, v54, v55
	v_fmac_f32_e32 v47, v42, v42
	v_fmac_f32_e32 v57, v50, v50
	v_add_f32_e32 v34, v45, v34
	v_add_f32_e32 v35, v56, v35
	v_add_f32_e32 v34, v47, v34
	v_add_f32_e32 v35, v57, v35
	v_add_f32_e32 v44, v34, v35
	v_mov_b32_e32 v45, v44
	s_nop 1
	v_permlane16_swap_b32_e32 v45, v44
	v_cvt_pk_bf16_f32 v34, v40, v41
	v_cvt_pk_bf16_f32 v35, v42, v43
	global_store_dwordx4 v[58:59], v[32:35], off sc1
	s_waitcnt lgkmcnt(0)
	s_nop 0
	v_add_f32_e32 v32, v44, v45
	v_mov_b32_e32 v33, v32
	s_nop 1
	v_permlane32_swap_b32_e32 v33, v32
	v_cvt_pk_bf16_f32 v34, v36, v37
	v_cvt_pk_bf16_f32 v35, v38, v39
	v_cvt_pk_bf16_f32 v36, v52, v53
	v_cvt_pk_bf16_f32 v37, v50, v51
	global_store_dwordx4 v[58:59], v[34:37], off offset:256 sc1
	s_and_saveexec_b64 s[56:57], s[6:7]
	s_cbranch_execz .LBB0_665
	s_waitcnt lgkmcnt(0)
	v_add_f32_e32 v32, v32, v33
	v_mul_f32_e32 v32, 0x4f800000, v32
	v_trunc_f32_e32 v32, v32
	v_mul_f32_e64 v33, |v32|, s87
	v_floor_f32_e32 v33, v33
	v_fma_f32 v34, v33, s88, |v32|
	v_cvt_u32_f32_e32 v32, v34
	v_cvt_u32_f32_e32 v33, v33
	v_lshl_add_u64 v[34:35], v[48:49], 3, s[10:11]
	global_atomic_add_x2 v[34:35], v[32:33], off
; __device__ __forceinline__ void fx_add(float* p, size_t idx, float s) { atomicAdd((unsigned long long*)p + idx, (unsigned long long)(long long)(s * 4294967296.0f)); }
; __device__ __forceinline__ unsigned cvtpk(float lo, float hi) { f32x2v_ v = {lo, hi}; bf16x2v_ b = __builtin_convertvector(v, bf16x2v_); return __builtin_bit_cast(unsigned, b); }
;     __device__ __forceinline__ void operator()(const f32x4 (&acc)[2][2][4][2], const Unit& u, int wr, int wc, int fr, int fq) const {
;     ...
;             for (int m = 0; m < 4; ++m) { const int row = row0 + ai * HALF + m * 16; const size_t off = (size_t)row * 1024 + col0; float s = 0.f;
; #pragma unroll
;                 for (int bj = 0; bj < 2; ++bj) { f32x4 a0, a1;
;                     if (xin32) { const float* p = xin32 + off + bj * HALF; a0 = *(const f32x4*)p; a1 = *(const f32x4*)(p + 4); }
;                     else { const u32x4 w = *(const u32x4*)(xb + off + bj * HALF);
;                         a0 = (f32x4){__uint_as_float(w.x << 16), __uint_as_float(w.x & 0xffff0000u), __uint_as_float(w.y << 16), __uint_as_float(w.y & 0xffff0000u)};
;                         a1 = (f32x4){__uint_as_float(w.z << 16), __uint_as_float(w.z & 0xffff0000u), __uint_as_float(w.w << 16), __uint_as_float(w.w & 0xffff0000u)}; }
;                     const f32x4 v0 = a0 + acc[ai][bj][m][0] * alpha, v1 = a1 + acc[ai][bj][m][1] * alpha;
;                     u32x4 w; w.x = cvtpk(v0[0], v0[1]); w.y = cvtpk(v0[2], v0[3]); w.z = cvtpk(v1[0], v1[1]); w.w = cvtpk(v1[2], v1[3]);
;                     *(u32x4*)(xb + off + bj * HALF) = w;
;                     s += (v0[0] * v0[0] + v0[1] * v0[1]) + (v0[2] * v0[2] + v0[3] * v0[3]) + (v1[0] * v1[0] + v1[1] * v1[1]) + (v1[2] * v1[2] + v1[3] * v1[3]); }
;                 s += __shfl_xor(s, 16); s += __shfl_xor(s, 32);
;                 if (fq == 0) fx_add(ssout, row, s); }
.LBB0_665:
	s_or_b64 exec, exec, s[56:57]
	v_add_u32_e32 v32, 0xa0, v150
	s_waitcnt lgkmcnt(0)
	v_ashrrev_i32_e32 v33, 31, v32
	v_lshlrev_b64 v[34:35], 11, v[32:33]
	v_lshl_add_u64 v[34:35], s[22:23], 0, v[34:35]
	v_lshl_add_u64 v[42:43], v[148:149], 1, v[34:35]
	global_load_dwordx4 v[34:37], v[42:43], off
	global_load_dwordx4 v[38:41], v[42:43], off offset:256
	s_waitcnt vmcnt(1)
	v_lshlrev_b32_e32 v44, 16, v34
	v_and_b32_e32 v45, 0xffff0000, v34
	v_lshlrev_b32_e32 v34, 16, v35
	v_and_b32_e32 v35, 0xffff0000, v35
	s_waitcnt vmcnt(0)
	v_lshlrev_b32_e32 v48, 16, v38
	v_and_b32_e32 v49, 0xffff0000, v38
	v_lshlrev_b32_e32 v38, 16, v39
	v_and_b32_e32 v39, 0xffff0000, v39
	v_lshlrev_b32_e32 v46, 16, v36
	v_and_b32_e32 v47, 0xffff0000, v36
	v_lshlrev_b32_e32 v36, 16, v37
	v_and_b32_e32 v37, 0xffff0000, v37
	v_lshlrev_b32_e32 v50, 16, v40
	v_and_b32_e32 v51, 0xffff0000, v40
	v_lshlrev_b32_e32 v40, 16, v41
	v_and_b32_e32 v41, 0xffff0000, v41
	v_pk_add_f32 v[30:31], v[30:31], v[34:35]
	v_pk_add_f32 v[28:29], v[28:29], v[44:45]
	v_pk_add_f32 v[22:23], v[22:23], v[38:39]
	v_pk_add_f32 v[20:21], v[20:21], v[48:49]
	v_pk_add_f32 v[26:27], v[26:27], v[36:37]
	v_pk_add_f32 v[24:25], v[24:25], v[46:47]
	v_pk_add_f32 v[34:35], v[18:19], v[40:41]
	v_pk_add_f32 v[36:37], v[16:17], v[50:51]
	v_mul_f32_e32 v18, v29, v29
	v_mul_f32_e32 v19, v31, v31
	v_mul_f32_e32 v38, v21, v21
	v_mul_f32_e32 v39, v23, v23
	v_cvt_pk_bf16_f32 v16, v28, v29
	v_mul_f32_e32 v29, v25, v25
	v_mul_f32_e32 v40, v37, v37
	v_fmac_f32_e32 v18, v28, v28
	v_fmac_f32_e32 v19, v30, v30
	v_fmac_f32_e32 v38, v20, v20
	v_fmac_f32_e32 v39, v22, v22
	v_cvt_pk_bf16_f32 v17, v30, v31
	v_mul_f32_e32 v31, v27, v27
	v_mul_f32_e32 v41, v35, v35
	v_fmac_f32_e32 v29, v24, v24
	v_fmac_f32_e32 v40, v36, v36
	v_add_f32_e32 v18, v18, v19
	v_add_f32_e32 v19, v38, v39
	v_fmac_f32_e32 v31, v26, v26
	v_fmac_f32_e32 v41, v34, v34
	v_add_f32_e32 v18, v29, v18
	v_add_f32_e32 v19, v40, v19
	v_add_f32_e32 v18, v31, v18
	v_add_f32_e32 v19, v41, v19
	v_add_f32_e32 v28, v18, v19
	v_mov_b32_e32 v29, v28
	s_nop 1
	v_permlane16_swap_b32_e32 v29, v28
	v_cvt_pk_bf16_f32 v18, v24, v25
	v_cvt_pk_bf16_f32 v19, v26, v27
	global_store_dwordx4 v[42:43], v[16:19], off sc1
	s_waitcnt lgkmcnt(0)
	s_nop 0
	v_add_f32_e32 v16, v28, v29
	v_mov_b32_e32 v17, v16
	s_nop 1
	v_permlane32_swap_b32_e32 v17, v16
	v_cvt_pk_bf16_f32 v18, v20, v21
	v_cvt_pk_bf16_f32 v19, v22, v23
	v_cvt_pk_bf16_f32 v20, v36, v37
	v_cvt_pk_bf16_f32 v21, v34, v35
	global_store_dwordx4 v[42:43], v[18:21], off offset:256 sc1
	s_and_saveexec_b64 s[56:57], s[6:7]
	s_cbranch_execz .LBB0_667
	s_waitcnt lgkmcnt(0)
	v_add_f32_e32 v16, v16, v17
	v_mul_f32_e32 v16, 0x4f800000, v16
	v_trunc_f32_e32 v16, v16
	v_mul_f32_e64 v17, |v16|, s87
	v_floor_f32_e32 v17, v17
	v_fma_f32 v18, v17, s88, |v16|
	v_cvt_u32_f32_e32 v16, v18
	v_cvt_u32_f32_e32 v17, v17
	v_lshl_add_u64 v[18:19], v[32:33], 3, s[10:11]
	global_atomic_add_x2 v[18:19], v[16:17], off
.LBB0_667:
	s_or_b64 exec, exec, s[56:57]
	v_add_u32_e32 v16, 0xb0, v150
	s_waitcnt lgkmcnt(0)
	v_ashrrev_i32_e32 v17, 31, v16
	v_lshlrev_b64 v[18:19], 11, v[16:17]
	v_lshl_add_u64 v[18:19], s[22:23], 0, v[18:19]
	v_lshl_add_u64 v[26:27], v[148:149], 1, v[18:19]
	global_load_dwordx4 v[18:21], v[26:27], off
	global_load_dwordx4 v[22:25], v[26:27], off offset:256
	s_waitcnt vmcnt(1)
	v_lshlrev_b32_e32 v28, 16, v18
	v_and_b32_e32 v29, 0xffff0000, v18
	v_lshlrev_b32_e32 v18, 16, v19
	v_and_b32_e32 v19, 0xffff0000, v19
	s_waitcnt vmcnt(0)
	v_lshlrev_b32_e32 v32, 16, v22
	v_and_b32_e32 v33, 0xffff0000, v22
	v_lshlrev_b32_e32 v22, 16, v23
	v_and_b32_e32 v23, 0xffff0000, v23
	v_lshlrev_b32_e32 v30, 16, v20
	v_and_b32_e32 v31, 0xffff0000, v20
	v_lshlrev_b32_e32 v20, 16, v21
	v_and_b32_e32 v21, 0xffff0000, v21
	v_lshlrev_b32_e32 v34, 16, v24
	v_and_b32_e32 v35, 0xffff0000, v24
	v_lshlrev_b32_e32 v24, 16, v25
	v_and_b32_e32 v25, 0xffff0000, v25
	v_pk_add_f32 v[14:15], v[14:15], v[18:19]
	v_pk_add_f32 v[12:13], v[12:13], v[28:29]
	v_pk_add_f32 v[6:7], v[6:7], v[22:23]
	v_pk_add_f32 v[4:5], v[4:5], v[32:33]
	v_pk_add_f32 v[10:11], v[10:11], v[20:21]
	v_pk_add_f32 v[8:9], v[8:9], v[30:31]
	v_pk_add_f32 v[18:19], v[2:3], v[24:25]
	v_pk_add_f32 v[20:21], v[0:1], v[34:35]
	v_mul_f32_e32 v2, v13, v13
	v_mul_f32_e32 v3, v15, v15
	v_mul_f32_e32 v22, v5, v5
	v_mul_f32_e32 v23, v7, v7
	v_cvt_pk_bf16_f32 v0, v12, v13
	v_mul_f32_e32 v13, v9, v9
	v_mul_f32_e32 v24, v21, v21
	v_fmac_f32_e32 v2, v12, v12
	v_fmac_f32_e32 v3, v14, v14
	v_fmac_f32_e32 v22, v4, v4
	v_fmac_f32_e32 v23, v6, v6
	v_cvt_pk_bf16_f32 v1, v14, v15
	v_mul_f32_e32 v15, v11, v11
	v_mul_f32_e32 v25, v19, v19
	v_fmac_f32_e32 v13, v8, v8
	v_fmac_f32_e32 v24, v20, v20
	v_add_f32_e32 v2, v2, v3
	v_add_f32_e32 v3, v22, v23
	v_fmac_f32_e32 v15, v10, v10
	v_fmac_f32_e32 v25, v18, v18
	v_add_f32_e32 v2, v13, v2
	v_add_f32_e32 v3, v24, v3
	v_add_f32_e32 v2, v15, v2
	v_add_f32_e32 v3, v25, v3
	v_add_f32_e32 v12, v2, v3
	v_mov_b32_e32 v13, v12
	s_nop 1
	v_permlane16_swap_b32_e32 v13, v12
	v_cvt_pk_bf16_f32 v2, v8, v9
	v_cvt_pk_bf16_f32 v3, v10, v11
	global_store_dwordx4 v[26:27], v[0:3], off sc1
	s_waitcnt lgkmcnt(0)
	s_nop 0
	v_add_f32_e32 v0, v12, v13
	v_mov_b32_e32 v1, v0
	s_nop 1
	v_permlane32_swap_b32_e32 v1, v0
	v_cvt_pk_bf16_f32 v2, v4, v5
	v_cvt_pk_bf16_f32 v3, v6, v7
	v_cvt_pk_bf16_f32 v4, v20, v21
	v_cvt_pk_bf16_f32 v5, v18, v19
	global_store_dwordx4 v[26:27], v[2:5], off offset:256 sc1
	s_and_saveexec_b64 s[56:57], s[6:7]
	s_cbranch_execz .LBB0_669
	s_waitcnt lgkmcnt(0)
	v_add_f32_e32 v0, v0, v1
	v_mul_f32_e32 v0, 0x4f800000, v0
	v_trunc_f32_e32 v0, v0
	v_mul_f32_e64 v1, |v0|, s87
	v_floor_f32_e32 v1, v1
	v_fma_f32 v2, v1, s88, |v0|
	v_cvt_u32_f32_e32 v0, v2
	v_cvt_u32_f32_e32 v1, v1
	v_lshl_add_u64 v[2:3], v[16:17], 3, s[10:11]
	global_atomic_add_x2 v[2:3], v[0:1], off

; __device__ __forceinline__ unsigned cvtpk(float lo, float hi) { f32x2v_ v = {lo, hi}; bf16x2v_ b = __builtin_convertvector(v, bf16x2v_); return __builtin_bit_cast(unsigned, b); }
;     __device__ __forceinline__ void operator()(const f32x4 (&acc)[2][2][4][2], const Unit& u, int wr, int wc, int fr, int fq) const {
;     ...
;             for (int m = 0; m < 4; ++m) { const int row = row0 + ai * HALF + m * 16; const float rs = ss ? row_rs(ss, row) : 1.0f;
; #pragma unroll
;                 for (int bj = 0; bj < 2; ++bj) { const f32x4 v0 = acc[ai][bj][m][0] * rs, v1 = acc[ai][bj][m][1] * rs;
;                     u32x4 w; w.x = cvtpk(v0[0], v0[1]); w.y = cvtpk(v0[2], v0[3]); w.z = cvtpk(v1[0], v1[1]); w.w = cvtpk(v1[2], v1[3]);
;                     *(u32x4*)(O + (size_t)row * ldc + col0 + bj * HALF) = w; } }
.LBB0_741:
	v_lshl_add_u32 v160, s0, 8, v129
	v_ashrrev_i32_e32 v161, 31, v160
	v_lshl_add_u64 v[150:151], v[160:161], 3, s[10:11]
	global_load_dwordx2 v[148:149], v[150:151], off
	v_lshl_or_b32 v162, s1, 8, v154
	v_ashrrev_i32_e32 v163, 31, v162
	v_lshlrev_b64 v[166:167], 10, v[160:161]
	v_or_b32_e32 v164, 16, v160
	v_lshlrev_b64 v[162:163], 1, v[162:163]
	v_ashrrev_i32_e32 v165, 31, v164
	s_mov_b32 s3, 0x20000
	s_mov_b64 s[0:1], 0x20000
	s_waitcnt vmcnt(0)
	v_ffbh_u32_e32 v159, v149
	v_min_u32_e32 v159, 32, v159
	v_lshlrev_b64 v[148:149], v159, v[148:149]
	v_min_u32_e32 v148, 1, v148
	v_or_b32_e32 v148, v149, v148
	v_cvt_f32_u32_e32 v148, v148
	v_sub_u32_e32 v149, 32, v159
	v_ldexp_f32 v148, v148, v149
	v_mul_f32_e32 v148, 0x2f800000, v148
	v_fmamk_f32 v148, v148, 0x3a800000, v158
	v_rsq_f32_e32 v168, v148
	v_lshl_add_u64 v[148:149], s[20:21], 0, v[166:167]
	v_lshl_add_u64 v[148:149], v[148:149], 0, v[162:163]
	v_lshl_add_u64 v[166:167], v[164:165], 3, s[10:11]
	v_pk_mul_f32 v[126:127], v[126:127], v[168:169] op_sel_hi:[1,0]
	v_pk_mul_f32 v[124:125], v[124:125], v[168:169] op_sel_hi:[1,0]
	v_pk_mul_f32 v[122:123], v[122:123], v[168:169] op_sel_hi:[1,0]
	v_pk_mul_f32 v[120:121], v[120:121], v[168:169] op_sel_hi:[1,0]
	v_pk_mul_f32 v[118:119], v[118:119], v[168:169] op_sel_hi:[1,0]
	v_pk_mul_f32 v[116:117], v[116:117], v[168:169] op_sel_hi:[1,0]
	v_pk_mul_f32 v[170:171], v[114:115], v[168:169] op_sel_hi:[1,0]
	v_pk_mul_f32 v[168:169], v[112:113], v[168:169] op_sel_hi:[1,0]
	v_cvt_pk_bf16_f32 v112, v124, v125
	v_cvt_pk_bf16_f32 v113, v126, v127
	v_cvt_pk_bf16_f32 v114, v120, v121
	v_cvt_pk_bf16_f32 v115, v122, v123
	v_cvt_pk_bf16_f32 v116, v116, v117
	v_cvt_pk_bf16_f32 v117, v118, v119
	v_cvt_pk_bf16_f32 v118, v168, v169
	v_cvt_pk_bf16_f32 v119, v170, v171
	global_store_dwordx4 v[148:149], v[112:115], off sc1
	global_store_dwordx4 v[148:149], v[116:119], off offset:256 sc1
	global_load_dwordx2 v[112:113], v[166:167], off
	v_or_b32_e32 v114, 32, v160
	s_waitcnt vmcnt(0)
	v_ffbh_u32_e32 v115, v113
	v_min_u32_e32 v116, 32, v115
	v_lshlrev_b64 v[112:113], v116, v[112:113]
	v_min_u32_e32 v112, 1, v112
	v_or_b32_e32 v112, v113, v112
	v_cvt_f32_u32_e32 v117, v112
	v_sub_u32_e32 v116, 32, v116
	v_lshlrev_b64 v[112:113], 10, v[164:165]
	v_lshl_add_u64 v[112:113], s[20:21], 0, v[112:113]
	v_ldexp_f32 v116, v117, v116
	v_mul_f32_e32 v116, 0x2f800000, v116
	v_fmamk_f32 v116, v116, 0x3a800000, v158
	v_rsq_f32_e32 v116, v116
	v_ashrrev_i32_e32 v115, 31, v114
	v_lshl_add_u64 v[112:113], v[112:113], 0, v[162:163]
	v_lshl_add_u64 v[118:119], v[114:115], 3, s[10:11]
	v_pk_mul_f32 v[110:111], v[110:111], v[116:117] op_sel_hi:[1,0]
	v_pk_mul_f32 v[108:109], v[108:109], v[116:117] op_sel_hi:[1,0]
	v_pk_mul_f32 v[106:107], v[106:107], v[116:117] op_sel_hi:[1,0]
	v_pk_mul_f32 v[104:105], v[104:105], v[116:117] op_sel_hi:[1,0]
	v_pk_mul_f32 v[102:103], v[102:103], v[116:117] op_sel_hi:[1,0]
	v_pk_mul_f32 v[100:101], v[100:101], v[116:117] op_sel_hi:[1,0]
	v_pk_mul_f32 v[120:121], v[98:99], v[116:117] op_sel_hi:[1,0]
	v_pk_mul_f32 v[116:117], v[96:97], v[116:117] op_sel_hi:[1,0]
	v_cvt_pk_bf16_f32 v96, v108, v109
	v_cvt_pk_bf16_f32 v97, v110, v111
	v_cvt_pk_bf16_f32 v98, v104, v105
	v_cvt_pk_bf16_f32 v99, v106, v107
	v_cvt_pk_bf16_f32 v100, v100, v101
	v_cvt_pk_bf16_f32 v101, v102, v103
	v_cvt_pk_bf16_f32 v102, v116, v117
	v_cvt_pk_bf16_f32 v103, v120, v121
	global_store_dwordx4 v[112:113], v[96:99], off sc1
	global_store_dwordx4 v[112:113], v[100:103], off offset:256 sc1
	global_load_dwordx2 v[96:97], v[118:119], off
	v_or_b32_e32 v98, 48, v160
	s_waitcnt vmcnt(0)
	v_ffbh_u32_e32 v99, v97
	v_min_u32_e32 v100, 32, v99
	v_lshlrev_b64 v[96:97], v100, v[96:97]
	v_min_u32_e32 v96, 1, v96
	v_or_b32_e32 v96, v97, v96
	v_cvt_f32_u32_e32 v101, v96
	v_sub_u32_e32 v100, 32, v100
	v_lshlrev_b64 v[96:97], 10, v[114:115]
	v_lshl_add_u64 v[96:97], s[20:21], 0, v[96:97]
	v_ldexp_f32 v100, v101, v100
	v_mul_f32_e32 v100, 0x2f800000, v100
	v_fmamk_f32 v100, v100, 0x3a800000, v158
	v_rsq_f32_e32 v100, v100
	v_ashrrev_i32_e32 v99, 31, v98
	v_lshl_add_u64 v[96:97], v[96:97], 0, v[162:163]
	v_lshl_add_u64 v[102:103], v[98:99], 3, s[10:11]
	v_pk_mul_f32 v[94:95], v[94:95], v[100:101] op_sel_hi:[1,0]
	v_pk_mul_f32 v[92:93], v[92:93], v[100:101] op_sel_hi:[1,0]
	v_pk_mul_f32 v[90:91], v[90:91], v[100:101] op_sel_hi:[1,0]
	v_pk_mul_f32 v[88:89], v[88:89], v[100:101] op_sel_hi:[1,0]
	v_pk_mul_f32 v[86:87], v[86:87], v[100:101] op_sel_hi:[1,0]
	v_pk_mul_f32 v[84:85], v[84:85], v[100:101] op_sel_hi:[1,0]
	v_pk_mul_f32 v[104:105], v[82:83], v[100:101] op_sel_hi:[1,0]
	v_pk_mul_f32 v[100:101], v[80:81], v[100:101] op_sel_hi:[1,0]
	v_cvt_pk_bf16_f32 v80, v92, v93
	v_cvt_pk_bf16_f32 v81, v94, v95
	v_cvt_pk_bf16_f32 v82, v88, v89
	v_cvt_pk_bf16_f32 v83, v90, v91
	v_cvt_pk_bf16_f32 v84, v84, v85
	v_cvt_pk_bf16_f32 v85, v86, v87
	v_cvt_pk_bf16_f32 v86, v100, v101
	v_cvt_pk_bf16_f32 v87, v104, v105
	global_store_dwordx4 v[96:97], v[80:83], off sc1
	global_store_dwordx4 v[96:97], v[84:87], off offset:256 sc1
	global_load_dwordx2 v[80:81], v[102:103], off
	s_waitcnt vmcnt(0)
; __device__ __forceinline__ unsigned cvtpk(float lo, float hi) { f32x2v_ v = {lo, hi}; bf16x2v_ b = __builtin_convertvector(v, bf16x2v_); return __builtin_bit_cast(unsigned, b); }
;     __device__ __forceinline__ void operator()(const f32x4 (&acc)[2][2][4][2], const Unit& u, int wr, int wc, int fr, int fq) const {
;     ...
;             for (int m = 0; m < 4; ++m) { const int row = row0 + ai * HALF + m * 16; const float rs = ss ? row_rs(ss, row) : 1.0f;
; #pragma unroll
;                 for (int bj = 0; bj < 2; ++bj) { const f32x4 v0 = acc[ai][bj][m][0] * rs, v1 = acc[ai][bj][m][1] * rs;
;                     u32x4 w; w.x = cvtpk(v0[0], v0[1]); w.y = cvtpk(v0[2], v0[3]); w.z = cvtpk(v1[0], v1[1]); w.w = cvtpk(v1[2], v1[3]);
;                     *(u32x4*)(O + (size_t)row * ldc + col0 + bj * HALF) = w; } }
	v_ffbh_u32_e32 v82, v81
	v_min_u32_e32 v82, 32, v82
	v_lshlrev_b64 v[80:81], v82, v[80:81]
	v_min_u32_e32 v80, 1, v80
	v_or_b32_e32 v80, v81, v80
	v_cvt_f32_u32_e32 v80, v80
	v_sub_u32_e32 v81, 32, v82
	v_lshlrev_b64 v[82:83], 10, v[98:99]
	v_lshl_add_u64 v[82:83], s[20:21], 0, v[82:83]
	v_ldexp_f32 v80, v80, v81
	v_mul_f32_e32 v80, 0x2f800000, v80
	v_fmamk_f32 v80, v80, 0x3a800000, v158
	v_rsq_f32_e32 v80, v80
	v_lshl_add_u64 v[82:83], v[82:83], 0, v[162:163]
	v_pk_mul_f32 v[78:79], v[78:79], v[80:81] op_sel_hi:[1,0]
	v_pk_mul_f32 v[76:77], v[76:77], v[80:81] op_sel_hi:[1,0]
	v_pk_mul_f32 v[74:75], v[74:75], v[80:81] op_sel_hi:[1,0]
	v_pk_mul_f32 v[72:73], v[72:73], v[80:81] op_sel_hi:[1,0]
	v_pk_mul_f32 v[70:71], v[70:71], v[80:81] op_sel_hi:[1,0]
	v_pk_mul_f32 v[68:69], v[68:69], v[80:81] op_sel_hi:[1,0]
	v_pk_mul_f32 v[84:85], v[66:67], v[80:81] op_sel_hi:[1,0]
	v_pk_mul_f32 v[80:81], v[64:65], v[80:81] op_sel_hi:[1,0]
	v_cvt_pk_bf16_f32 v64, v76, v77
	v_cvt_pk_bf16_f32 v65, v78, v79
	v_cvt_pk_bf16_f32 v66, v72, v73
	v_cvt_pk_bf16_f32 v67, v74, v75
	v_cvt_pk_bf16_f32 v68, v68, v69
	v_cvt_pk_bf16_f32 v69, v70, v71
	v_cvt_pk_bf16_f32 v70, v80, v81
	v_cvt_pk_bf16_f32 v71, v84, v85
	global_store_dwordx4 v[82:83], v[64:67], off sc1
	global_store_dwordx4 v[82:83], v[68:71], off offset:256 sc1
	global_load_dwordx2 v[64:65], v[150:151], off offset:1024
	s_waitcnt vmcnt(0)
	v_ffbh_u32_e32 v66, v65
	v_min_u32_e32 v66, 32, v66
	v_lshlrev_b64 v[64:65], v66, v[64:65]
	v_min_u32_e32 v64, 1, v64
	v_or_b32_e32 v64, v65, v64
	v_cvt_f32_u32_e32 v67, v64
	v_sub_u32_e32 v66, 32, v66
	v_add_co_u32_e32 v68, vcc, s3, v148
	v_ldexp_f32 v66, v67, v66
	v_mul_f32_e32 v66, 0x2f800000, v66
	v_fmamk_f32 v66, v66, 0x3a800000, v158
	v_rsq_f32_e32 v66, v66
	v_addc_co_u32_e32 v69, vcc, 0, v149, vcc
	v_lshl_add_u64 v[64:65], v[148:149], 0, s[0:1]
	v_pk_mul_f32 v[62:63], v[62:63], v[66:67] op_sel_hi:[1,0]
	v_pk_mul_f32 v[60:61], v[60:61], v[66:67] op_sel_hi:[1,0]
	v_pk_mul_f32 v[58:59], v[58:59], v[66:67] op_sel_hi:[1,0]
	v_pk_mul_f32 v[56:57], v[56:57], v[66:67] op_sel_hi:[1,0]
	v_pk_mul_f32 v[54:55], v[54:55], v[66:67] op_sel_hi:[1,0]
	v_pk_mul_f32 v[52:53], v[52:53], v[66:67] op_sel_hi:[1,0]
	v_pk_mul_f32 v[70:71], v[50:51], v[66:67] op_sel_hi:[1,0]
	v_pk_mul_f32 v[66:67], v[48:49], v[66:67] op_sel_hi:[1,0]
	v_cvt_pk_bf16_f32 v48, v60, v61
	v_cvt_pk_bf16_f32 v49, v62, v63
	v_cvt_pk_bf16_f32 v50, v56, v57
	v_cvt_pk_bf16_f32 v51, v58, v59
	v_cvt_pk_bf16_f32 v52, v52, v53
	v_cvt_pk_bf16_f32 v53, v54, v55
	v_cvt_pk_bf16_f32 v54, v66, v67
	v_cvt_pk_bf16_f32 v55, v70, v71
	global_store_dwordx4 v[68:69], v[48:51], off sc1
	global_store_dwordx4 v[64:65], v[52:55], off offset:256 sc1
	global_load_dwordx2 v[48:49], v[150:151], off offset:1152
	s_mov_b32 s3, 0x24000
	v_add_co_u32_e32 v52, vcc, s3, v148
	s_mov_b64 s[0:1], 0x24000
	s_nop 0
	v_addc_co_u32_e32 v53, vcc, 0, v149, vcc
	s_mov_b32 s3, 0x28000
	s_waitcnt vmcnt(0)
; __device__ __forceinline__ unsigned cvtpk(float lo, float hi) { f32x2v_ v = {lo, hi}; bf16x2v_ b = __builtin_convertvector(v, bf16x2v_); return __builtin_bit_cast(unsigned, b); }
; #define PG8_BAR __builtin_amdgcn_s_barrier()
;     __device__ __forceinline__ void operator()(const f32x4 (&acc)[2][2][4][2], const Unit& u, int wr, int wc, int fr, int fq) const {
;     ...
;             for (int m = 0; m < 4; ++m) { const int row = row0 + ai * HALF + m * 16; const float rs = ss ? row_rs(ss, row) : 1.0f;
; #pragma unroll
;                 for (int bj = 0; bj < 2; ++bj) { const f32x4 v0 = acc[ai][bj][m][0] * rs, v1 = acc[ai][bj][m][1] * rs;
;                     u32x4 w; w.x = cvtpk(v0[0], v0[1]); w.y = cvtpk(v0[2], v0[3]); w.z = cvtpk(v1[0], v1[1]); w.w = cvtpk(v1[2], v1[3]);
;                     *(u32x4*)(O + (size_t)row * ldc + col0 + bj * HALF) = w; } }
; template <class Epi, class Sched, bool ALIGN_EPI = false, bool SP2 = false>
; __device__ __forceinline__ void gemm_phase(PG8_LAS unsigned char* lds, const Gemm g, const Sched& S, const Epi& E) {
;     ...
;         if constexpr (!Epi::AFTER_DRAIN) { E(acc, cur, wr, wc, fr, fq); S.done(cur); }
;         if (!has_next) break;
; #pragma unroll
;         for (int a = 0; a < 2; ++a)
; #pragma unroll
;             for (int b = 0; b < 2; ++b)
; #pragma unroll
;                 for (int m = 0; m < 4; ++m)
; #pragma unroll
;                     for (int n = 0; n < 2; ++n) acc[a][b][m][n] = (f32x4){0.f, 0.f, 0.f, 0.f};
;         cur = nxt; cA = nA; cB = nB; ++ui;
;         if constexpr (ALIGN_EPI) { if (wr == 1) PG8_BAR; }
	v_ffbh_u32_e32 v50, v49
	v_min_u32_e32 v50, 32, v50
	v_lshlrev_b64 v[48:49], v50, v[48:49]
	v_min_u32_e32 v48, 1, v48
	v_or_b32_e32 v48, v49, v48
	v_cvt_f32_u32_e32 v51, v48
	v_sub_u32_e32 v50, 32, v50
	v_lshl_add_u64 v[48:49], v[148:149], 0, s[0:1]
	s_mov_b64 s[0:1], 0x28000
	v_ldexp_f32 v50, v51, v50
	v_mul_f32_e32 v50, 0x2f800000, v50
	v_fmamk_f32 v50, v50, 0x3a800000, v158
	v_rsq_f32_e32 v50, v50
	s_nop 0
	v_pk_mul_f32 v[46:47], v[46:47], v[50:51] op_sel_hi:[1,0]
	v_pk_mul_f32 v[44:45], v[44:45], v[50:51] op_sel_hi:[1,0]
	v_pk_mul_f32 v[42:43], v[42:43], v[50:51] op_sel_hi:[1,0]
	v_pk_mul_f32 v[40:41], v[40:41], v[50:51] op_sel_hi:[1,0]
	v_pk_mul_f32 v[38:39], v[38:39], v[50:51] op_sel_hi:[1,0]
	v_pk_mul_f32 v[36:37], v[36:37], v[50:51] op_sel_hi:[1,0]
	v_pk_mul_f32 v[54:55], v[34:35], v[50:51] op_sel_hi:[1,0]
	v_pk_mul_f32 v[50:51], v[32:33], v[50:51] op_sel_hi:[1,0]
	v_cvt_pk_bf16_f32 v32, v44, v45
	v_cvt_pk_bf16_f32 v33, v46, v47
	v_cvt_pk_bf16_f32 v34, v40, v41
	v_cvt_pk_bf16_f32 v35, v42, v43
	v_cvt_pk_bf16_f32 v36, v36, v37
	v_cvt_pk_bf16_f32 v37, v38, v39
	v_cvt_pk_bf16_f32 v38, v50, v51
	v_cvt_pk_bf16_f32 v39, v54, v55
	global_store_dwordx4 v[52:53], v[32:35], off sc1
	global_store_dwordx4 v[48:49], v[36:39], off offset:256 sc1
	global_load_dwordx2 v[32:33], v[150:151], off offset:1280
	s_waitcnt vmcnt(0)
	v_ffbh_u32_e32 v34, v33
	v_min_u32_e32 v34, 32, v34
	v_lshlrev_b64 v[32:33], v34, v[32:33]
	v_min_u32_e32 v32, 1, v32
	v_or_b32_e32 v32, v33, v32
	v_cvt_f32_u32_e32 v35, v32
	v_sub_u32_e32 v34, 32, v34
	v_add_co_u32_e32 v36, vcc, s3, v148
	v_ldexp_f32 v34, v35, v34
	v_mul_f32_e32 v34, 0x2f800000, v34
	v_fmamk_f32 v34, v34, 0x3a800000, v158
	v_rsq_f32_e32 v34, v34
	v_addc_co_u32_e32 v37, vcc, 0, v149, vcc
	v_lshl_add_u64 v[32:33], v[148:149], 0, s[0:1]
	v_pk_mul_f32 v[30:31], v[30:31], v[34:35] op_sel_hi:[1,0]
	v_pk_mul_f32 v[28:29], v[28:29], v[34:35] op_sel_hi:[1,0]
	v_pk_mul_f32 v[26:27], v[26:27], v[34:35] op_sel_hi:[1,0]
	v_pk_mul_f32 v[24:25], v[24:25], v[34:35] op_sel_hi:[1,0]
	v_pk_mul_f32 v[22:23], v[22:23], v[34:35] op_sel_hi:[1,0]
	v_pk_mul_f32 v[20:21], v[20:21], v[34:35] op_sel_hi:[1,0]
	v_pk_mul_f32 v[38:39], v[18:19], v[34:35] op_sel_hi:[1,0]
	v_pk_mul_f32 v[34:35], v[16:17], v[34:35] op_sel_hi:[1,0]
	v_cvt_pk_bf16_f32 v16, v28, v29
	v_cvt_pk_bf16_f32 v17, v30, v31
	v_cvt_pk_bf16_f32 v18, v24, v25
	v_cvt_pk_bf16_f32 v19, v26, v27
	v_cvt_pk_bf16_f32 v20, v20, v21
	v_cvt_pk_bf16_f32 v21, v22, v23
	v_cvt_pk_bf16_f32 v22, v34, v35
	v_cvt_pk_bf16_f32 v23, v38, v39
	global_store_dwordx4 v[36:37], v[16:19], off sc1
	global_store_dwordx4 v[32:33], v[20:23], off offset:256 sc1
	global_load_dwordx2 v[16:17], v[150:151], off offset:1408
	s_mov_b64 s[0:1], 0x2c000
	s_mov_b32 s3, 0x2c000
	s_andn2_b64 vcc, exec, s[8:9]
	s_waitcnt vmcnt(0)
	v_ffbh_u32_e32 v18, v17
	v_min_u32_e32 v18, 32, v18
	v_lshlrev_b64 v[16:17], v18, v[16:17]
	v_min_u32_e32 v16, 1, v16
	v_or_b32_e32 v16, v17, v16
	v_cvt_f32_u32_e32 v19, v16
	v_sub_u32_e32 v18, 32, v18
	v_lshl_add_u64 v[16:17], v[148:149], 0, s[0:1]
	v_add_co_u32_e64 v20, s[0:1], s3, v148
	v_ldexp_f32 v18, v19, v18
	v_mul_f32_e32 v18, 0x2f800000, v18
	v_fmamk_f32 v18, v18, 0x3a800000, v158
	v_rsq_f32_e32 v18, v18
	v_addc_co_u32_e64 v21, s[0:1], 0, v149, s[0:1]
	s_mov_b64 s[0:1], -1
	v_pk_mul_f32 v[14:15], v[14:15], v[18:19] op_sel_hi:[1,0]
	v_pk_mul_f32 v[12:13], v[12:13], v[18:19] op_sel_hi:[1,0]
	v_pk_mul_f32 v[10:11], v[10:11], v[18:19] op_sel_hi:[1,0]
	v_pk_mul_f32 v[8:9], v[8:9], v[18:19] op_sel_hi:[1,0]
	v_pk_mul_f32 v[6:7], v[6:7], v[18:19] op_sel_hi:[1,0]
	v_pk_mul_f32 v[4:5], v[4:5], v[18:19] op_sel_hi:[1,0]
	v_pk_mul_f32 v[22:23], v[2:3], v[18:19] op_sel_hi:[1,0]
	v_pk_mul_f32 v[18:19], v[0:1], v[18:19] op_sel_hi:[1,0]
	v_cvt_pk_bf16_f32 v0, v12, v13
	v_cvt_pk_bf16_f32 v1, v14, v15
	v_cvt_pk_bf16_f32 v2, v8, v9
	v_cvt_pk_bf16_f32 v3, v10, v11
	v_cvt_pk_bf16_f32 v4, v4, v5
	v_cvt_pk_bf16_f32 v5, v6, v7
	v_cvt_pk_bf16_f32 v6, v18, v19
	v_cvt_pk_bf16_f32 v7, v22, v23
	global_store_dwordx4 v[20:21], v[0:3], off sc1
	global_store_dwordx4 v[16:17], v[4:7], off offset:256 sc1
	s_cbranch_vccnz .LBB0_730
	s_andn2_b64 vcc, exec, s[36:37]
	s_cbranch_vccnz .LBB0_729
	s_barrier
	s_branch .LBB0_729

; __device__ __forceinline__ void fx_add(float* p, size_t idx, float s) { atomicAdd((unsigned long long*)p + idx, (unsigned long long)(long long)(s * 4294967296.0f)); }
; __device__ __forceinline__ unsigned cvtpk(float lo, float hi) { f32x2v_ v = {lo, hi}; bf16x2v_ b = __builtin_convertvector(v, bf16x2v_); return __builtin_bit_cast(unsigned, b); }
;     __device__ __forceinline__ void operator()(const f32x4 (&acc)[2][2][4][2], const Unit& u, int wr, int wc, int fr, int fq) const {
;     ...
;             for (int m = 0; m < 4; ++m) { const int row = row0 + ai * HALF + m * 16; const size_t off = (size_t)row * 1024 + col0; float s = 0.f;
; #pragma unroll
;                 for (int bj = 0; bj < 2; ++bj) { f32x4 a0, a1;
;                     if (xin32) { const float* p = xin32 + off + bj * HALF; a0 = *(const f32x4*)p; a1 = *(const f32x4*)(p + 4); }
;                     else { const u32x4 w = *(const u32x4*)(xb + off + bj * HALF);
;                         a0 = (f32x4){__uint_as_float(w.x << 16), __uint_as_float(w.x & 0xffff0000u), __uint_as_float(w.y << 16), __uint_as_float(w.y & 0xffff0000u)};
;                         a1 = (f32x4){__uint_as_float(w.z << 16), __uint_as_float(w.z & 0xffff0000u), __uint_as_float(w.w << 16), __uint_as_float(w.w & 0xffff0000u)}; }
;                     const f32x4 v0 = a0 + acc[ai][bj][m][0] * alpha, v1 = a1 + acc[ai][bj][m][1] * alpha;
;                     u32x4 w; w.x = cvtpk(v0[0], v0[1]); w.y = cvtpk(v0[2], v0[3]); w.z = cvtpk(v1[0], v1[1]); w.w = cvtpk(v1[2], v1[3]);
;                     *(u32x4*)(xb + off + bj * HALF) = w;
;                     s += (v0[0] * v0[0] + v0[1] * v0[1]) + (v0[2] * v0[2] + v0[3] * v0[3]) + (v1[0] * v1[0] + v1[1] * v1[1]) + (v1[2] * v1[2] + v1[3] * v1[3]); }
;                 s += __shfl_xor(s, 16); s += __shfl_xor(s, 32);
;                 if (fq == 0) fx_add(ssout, row, s); }
.LBB0_876:
	v_lshl_add_u32 v146, s56, 8, v148
	v_ashrrev_i32_e32 v147, 31, v146
	v_lshl_or_b32 v144, s54, 8, v150
	v_lshlrev_b64 v[156:157], 11, v[146:147]
	v_ashrrev_i32_e32 v145, 31, v144
	v_lshl_add_u64 v[156:157], s[22:23], 0, v[156:157]
	v_lshl_add_u64 v[166:167], v[144:145], 1, v[156:157]
	global_load_dwordx4 v[158:161], v[166:167], off
	global_load_dwordx4 v[162:165], v[166:167], off offset:256
	v_and_b32_e32 v156, 64, v154
	v_xor_b32_e32 v155, 16, v154
	v_add_u32_e32 v156, 64, v156
	v_xor_b32_e32 v157, 32, v154
	v_cmp_lt_i32_e32 vcc, v155, v156
	s_waitcnt vmcnt(0)
	v_lshlrev_b32_e32 v168, 16, v158
	v_cndmask_b32_e32 v155, v154, v155, vcc
	v_cmp_lt_i32_e32 vcc, v157, v156
	v_and_b32_e32 v169, 0xffff0000, v158
	v_lshlrev_b32_e32 v158, 16, v159
	v_and_b32_e32 v159, 0xffff0000, v159
	v_lshlrev_b32_e32 v172, 16, v162
	v_and_b32_e32 v173, 0xffff0000, v162
	v_lshlrev_b32_e32 v162, 16, v163
	v_and_b32_e32 v163, 0xffff0000, v163
	v_cndmask_b32_e32 v157, v154, v157, vcc
	v_lshlrev_b32_e32 v170, 16, v160
	v_and_b32_e32 v171, 0xffff0000, v160
	v_lshlrev_b32_e32 v160, 16, v161
	v_and_b32_e32 v161, 0xffff0000, v161
	v_lshlrev_b32_e32 v174, 16, v164
	v_and_b32_e32 v175, 0xffff0000, v164
	v_lshlrev_b32_e32 v164, 16, v165
	v_and_b32_e32 v165, 0xffff0000, v165
	v_pk_add_f32 v[126:127], v[126:127], v[158:159]
	v_pk_add_f32 v[124:125], v[124:125], v[168:169]
	v_pk_add_f32 v[118:119], v[118:119], v[162:163]
	v_pk_add_f32 v[116:117], v[116:117], v[172:173]
	v_lshlrev_b32_e32 v156, 2, v155
	v_lshlrev_b32_e32 v155, 2, v157
	v_pk_add_f32 v[122:123], v[122:123], v[160:161]
	v_pk_add_f32 v[120:121], v[120:121], v[170:171]
	v_pk_add_f32 v[158:159], v[114:115], v[164:165]
	v_pk_add_f32 v[160:161], v[112:113], v[174:175]
	v_mul_f32_e32 v114, v125, v125
	v_mul_f32_e32 v115, v127, v127
	v_mul_f32_e32 v157, v117, v117
	v_mul_f32_e32 v162, v119, v119
	v_cvt_pk_bf16_f32 v112, v124, v125
	v_mul_f32_e32 v125, v121, v121
	v_mul_f32_e32 v163, v161, v161
	v_fmac_f32_e32 v114, v124, v124
	v_fmac_f32_e32 v115, v126, v126
	v_fmac_f32_e32 v157, v116, v116
	v_fmac_f32_e32 v162, v118, v118
	v_cvt_pk_bf16_f32 v113, v126, v127
	v_mul_f32_e32 v127, v123, v123
	v_mul_f32_e32 v164, v159, v159
	v_fmac_f32_e32 v125, v120, v120
	v_fmac_f32_e32 v163, v160, v160
	v_add_f32_e32 v114, v114, v115
	v_add_f32_e32 v115, v157, v162
	v_fmac_f32_e32 v127, v122, v122
	v_fmac_f32_e32 v164, v158, v158
	v_add_f32_e32 v114, v125, v114
	v_add_f32_e32 v115, v163, v115
	v_add_f32_e32 v114, v127, v114
	v_add_f32_e32 v115, v164, v115
	v_add_f32_e32 v124, v114, v115
	v_mov_b32_e32 v125, v124
	s_nop 1
	v_permlane16_swap_b32_e32 v125, v124
	v_cvt_pk_bf16_f32 v114, v120, v121
	v_cvt_pk_bf16_f32 v115, v122, v123
	global_store_dwordx4 v[166:167], v[112:115], off sc1
	s_waitcnt lgkmcnt(0)
	s_nop 0
	v_add_f32_e32 v112, v124, v125
	v_mov_b32_e32 v113, v112
	s_nop 1
	v_permlane32_swap_b32_e32 v113, v112
	v_cvt_pk_bf16_f32 v114, v116, v117
	v_cvt_pk_bf16_f32 v115, v118, v119
	v_cvt_pk_bf16_f32 v116, v160, v161
	v_cvt_pk_bf16_f32 v117, v158, v159
	global_store_dwordx4 v[166:167], v[114:117], off offset:256 sc1
	s_and_saveexec_b64 s[54:55], s[8:9]
	s_cbranch_execz .LBB0_878
	s_waitcnt lgkmcnt(0)
	v_add_f32_e32 v112, v112, v113
	v_mul_f32_e32 v112, 0x4f800000, v112
	v_trunc_f32_e32 v112, v112
	v_mul_f32_e64 v113, |v112|, s82
	v_floor_f32_e32 v113, v113
	v_fma_f32 v114, v113, s83, |v112|
	v_cvt_u32_f32_e32 v112, v114
	v_cvt_u32_f32_e32 v113, v113
	v_lshl_add_u64 v[114:115], v[146:147], 3, s[0:1]
	global_atomic_add_x2 v[114:115], v[112:113], off
.LBB0_878:
	s_or_b64 exec, exec, s[54:55]
	v_or_b32_e32 v112, 16, v146
	s_waitcnt lgkmcnt(0)
	v_ashrrev_i32_e32 v113, 31, v112
	v_lshlrev_b64 v[114:115], 11, v[112:113]
	v_lshl_add_u64 v[114:115], s[22:23], 0, v[114:115]
	v_lshl_add_u64 v[122:123], v[144:145], 1, v[114:115]
	global_load_dwordx4 v[114:117], v[122:123], off
	global_load_dwordx4 v[118:121], v[122:123], off offset:256
	s_waitcnt vmcnt(1)
	v_lshlrev_b32_e32 v124, 16, v114
	v_and_b32_e32 v125, 0xffff0000, v114
	v_lshlrev_b32_e32 v114, 16, v115
	v_and_b32_e32 v115, 0xffff0000, v115
	s_waitcnt vmcnt(0)
	v_lshlrev_b32_e32 v158, 16, v118
	v_and_b32_e32 v159, 0xffff0000, v118
	v_lshlrev_b32_e32 v118, 16, v119
	v_and_b32_e32 v119, 0xffff0000, v119
	v_lshlrev_b32_e32 v126, 16, v116
	v_and_b32_e32 v127, 0xffff0000, v116
	v_lshlrev_b32_e32 v116, 16, v117
	v_and_b32_e32 v117, 0xffff0000, v117
	v_lshlrev_b32_e32 v160, 16, v120
	v_and_b32_e32 v161, 0xffff0000, v120
	v_lshlrev_b32_e32 v120, 16, v121
	v_and_b32_e32 v121, 0xffff0000, v121
	v_pk_add_f32 v[110:111], v[110:111], v[114:115]
	v_pk_add_f32 v[108:109], v[108:109], v[124:125]
	v_pk_add_f32 v[102:103], v[102:103], v[118:119]
	v_pk_add_f32 v[100:101], v[100:101], v[158:159]
	v_pk_add_f32 v[106:107], v[106:107], v[116:117]
	v_pk_add_f32 v[104:105], v[104:105], v[126:127]
	v_pk_add_f32 v[114:115], v[98:99], v[120:121]
	v_pk_add_f32 v[116:117], v[96:97], v[160:161]
	v_mul_f32_e32 v98, v109, v109
	v_mul_f32_e32 v99, v111, v111
	v_mul_f32_e32 v118, v101, v101
	v_mul_f32_e32 v119, v103, v103
	v_cvt_pk_bf16_f32 v96, v108, v109
	v_mul_f32_e32 v109, v105, v105
	v_mul_f32_e32 v120, v117, v117
	v_fmac_f32_e32 v98, v108, v108
	v_fmac_f32_e32 v99, v110, v110
	v_fmac_f32_e32 v118, v100, v100
	v_fmac_f32_e32 v119, v102, v102
	v_cvt_pk_bf16_f32 v97, v110, v111
	v_mul_f32_e32 v111, v107, v107
	v_mul_f32_e32 v121, v115, v115
	v_fmac_f32_e32 v109, v104, v104
	v_fmac_f32_e32 v120, v116, v116
	v_add_f32_e32 v98, v98, v99
	v_add_f32_e32 v99, v118, v119
	v_fmac_f32_e32 v111, v106, v106
	v_fmac_f32_e32 v121, v114, v114
	v_add_f32_e32 v98, v109, v98
	v_add_f32_e32 v99, v120, v99
	v_add_f32_e32 v98, v111, v98
	v_add_f32_e32 v99, v121, v99
	v_add_f32_e32 v108, v98, v99
	v_mov_b32_e32 v109, v108
	s_nop 1
	v_permlane16_swap_b32_e32 v109, v108
	v_cvt_pk_bf16_f32 v98, v104, v105
	v_cvt_pk_bf16_f32 v99, v106, v107
	global_store_dwordx4 v[122:123], v[96:99], off sc1
	s_waitcnt lgkmcnt(0)
	s_nop 0
	v_add_f32_e32 v96, v108, v109
	v_mov_b32_e32 v97, v96
	s_nop 1
	v_permlane32_swap_b32_e32 v97, v96
	v_cvt_pk_bf16_f32 v98, v100, v101
	v_cvt_pk_bf16_f32 v99, v102, v103
	v_cvt_pk_bf16_f32 v100, v116, v117
	v_cvt_pk_bf16_f32 v101, v114, v115
	global_store_dwordx4 v[122:123], v[98:101], off offset:256 sc1
	s_and_saveexec_b64 s[54:55], s[8:9]
	s_cbranch_execz .LBB0_880
	s_waitcnt lgkmcnt(0)
	v_add_f32_e32 v96, v96, v97
	v_mul_f32_e32 v96, 0x4f800000, v96
	v_trunc_f32_e32 v96, v96
	v_mul_f32_e64 v97, |v96|, s82
	v_floor_f32_e32 v97, v97
	v_fma_f32 v98, v97, s83, |v96|
	v_cvt_u32_f32_e32 v96, v98
	v_cvt_u32_f32_e32 v97, v97
	v_lshl_add_u64 v[98:99], v[112:113], 3, s[0:1]
	global_atomic_add_x2 v[98:99], v[96:97], off
; __device__ __forceinline__ void fx_add(float* p, size_t idx, float s) { atomicAdd((unsigned long long*)p + idx, (unsigned long long)(long long)(s * 4294967296.0f)); }
; __device__ __forceinline__ unsigned cvtpk(float lo, float hi) { f32x2v_ v = {lo, hi}; bf16x2v_ b = __builtin_convertvector(v, bf16x2v_); return __builtin_bit_cast(unsigned, b); }
;     __device__ __forceinline__ void operator()(const f32x4 (&acc)[2][2][4][2], const Unit& u, int wr, int wc, int fr, int fq) const {
;     ...
;             for (int m = 0; m < 4; ++m) { const int row = row0 + ai * HALF + m * 16; const size_t off = (size_t)row * 1024 + col0; float s = 0.f;
; #pragma unroll
;                 for (int bj = 0; bj < 2; ++bj) { f32x4 a0, a1;
;                     if (xin32) { const float* p = xin32 + off + bj * HALF; a0 = *(const f32x4*)p; a1 = *(const f32x4*)(p + 4); }
;                     else { const u32x4 w = *(const u32x4*)(xb + off + bj * HALF);
;                         a0 = (f32x4){__uint_as_float(w.x << 16), __uint_as_float(w.x & 0xffff0000u), __uint_as_float(w.y << 16), __uint_as_float(w.y & 0xffff0000u)};
;                         a1 = (f32x4){__uint_as_float(w.z << 16), __uint_as_float(w.z & 0xffff0000u), __uint_as_float(w.w << 16), __uint_as_float(w.w & 0xffff0000u)}; }
;                     const f32x4 v0 = a0 + acc[ai][bj][m][0] * alpha, v1 = a1 + acc[ai][bj][m][1] * alpha;
;                     u32x4 w; w.x = cvtpk(v0[0], v0[1]); w.y = cvtpk(v0[2], v0[3]); w.z = cvtpk(v1[0], v1[1]); w.w = cvtpk(v1[2], v1[3]);
;                     *(u32x4*)(xb + off + bj * HALF) = w;
;                     s += (v0[0] * v0[0] + v0[1] * v0[1]) + (v0[2] * v0[2] + v0[3] * v0[3]) + (v1[0] * v1[0] + v1[1] * v1[1]) + (v1[2] * v1[2] + v1[3] * v1[3]); }
;                 s += __shfl_xor(s, 16); s += __shfl_xor(s, 32);
;                 if (fq == 0) fx_add(ssout, row, s); }
.LBB0_880:
	s_or_b64 exec, exec, s[54:55]
	v_or_b32_e32 v96, 32, v146
	s_waitcnt lgkmcnt(0)
	v_ashrrev_i32_e32 v97, 31, v96
	v_lshlrev_b64 v[98:99], 11, v[96:97]
	v_lshl_add_u64 v[98:99], s[22:23], 0, v[98:99]
	v_lshl_add_u64 v[106:107], v[144:145], 1, v[98:99]
	global_load_dwordx4 v[98:101], v[106:107], off
	global_load_dwordx4 v[102:105], v[106:107], off offset:256
	s_waitcnt vmcnt(1)
	v_lshlrev_b32_e32 v108, 16, v98
	v_and_b32_e32 v109, 0xffff0000, v98
	v_lshlrev_b32_e32 v98, 16, v99
	v_and_b32_e32 v99, 0xffff0000, v99
	s_waitcnt vmcnt(0)
	v_lshlrev_b32_e32 v112, 16, v102
	v_and_b32_e32 v113, 0xffff0000, v102
	v_lshlrev_b32_e32 v102, 16, v103
	v_and_b32_e32 v103, 0xffff0000, v103
	v_lshlrev_b32_e32 v110, 16, v100
	v_and_b32_e32 v111, 0xffff0000, v100
	v_lshlrev_b32_e32 v100, 16, v101
	v_and_b32_e32 v101, 0xffff0000, v101
	v_lshlrev_b32_e32 v114, 16, v104
	v_and_b32_e32 v115, 0xffff0000, v104
	v_lshlrev_b32_e32 v104, 16, v105
	v_and_b32_e32 v105, 0xffff0000, v105
	v_pk_add_f32 v[94:95], v[94:95], v[98:99]
	v_pk_add_f32 v[92:93], v[92:93], v[108:109]
	v_pk_add_f32 v[86:87], v[86:87], v[102:103]
	v_pk_add_f32 v[84:85], v[84:85], v[112:113]
	v_pk_add_f32 v[90:91], v[90:91], v[100:101]
	v_pk_add_f32 v[88:89], v[88:89], v[110:111]
	v_pk_add_f32 v[98:99], v[82:83], v[104:105]
	v_pk_add_f32 v[100:101], v[80:81], v[114:115]
	v_mul_f32_e32 v82, v93, v93
	v_mul_f32_e32 v83, v95, v95
	v_mul_f32_e32 v102, v85, v85
	v_mul_f32_e32 v103, v87, v87
	v_cvt_pk_bf16_f32 v80, v92, v93
	v_mul_f32_e32 v93, v89, v89
	v_mul_f32_e32 v104, v101, v101
	v_fmac_f32_e32 v82, v92, v92
	v_fmac_f32_e32 v83, v94, v94
	v_fmac_f32_e32 v102, v84, v84
	v_fmac_f32_e32 v103, v86, v86
	v_cvt_pk_bf16_f32 v81, v94, v95
	v_mul_f32_e32 v95, v91, v91
	v_mul_f32_e32 v105, v99, v99
	v_fmac_f32_e32 v93, v88, v88
	v_fmac_f32_e32 v104, v100, v100
	v_add_f32_e32 v82, v82, v83
	v_add_f32_e32 v83, v102, v103
	v_fmac_f32_e32 v95, v90, v90
	v_fmac_f32_e32 v105, v98, v98
	v_add_f32_e32 v82, v93, v82
	v_add_f32_e32 v83, v104, v83
	v_add_f32_e32 v82, v95, v82
	v_add_f32_e32 v83, v105, v83
	v_add_f32_e32 v92, v82, v83
	v_mov_b32_e32 v93, v92
	s_nop 1
	v_permlane16_swap_b32_e32 v93, v92
	v_cvt_pk_bf16_f32 v82, v88, v89
	v_cvt_pk_bf16_f32 v83, v90, v91
	global_store_dwordx4 v[106:107], v[80:83], off sc1
	s_waitcnt lgkmcnt(0)
	s_nop 0
	v_add_f32_e32 v80, v92, v93
	v_mov_b32_e32 v81, v80
	s_nop 1
	v_permlane32_swap_b32_e32 v81, v80
	v_cvt_pk_bf16_f32 v82, v84, v85
	v_cvt_pk_bf16_f32 v83, v86, v87
	v_cvt_pk_bf16_f32 v84, v100, v101
	v_cvt_pk_bf16_f32 v85, v98, v99
	global_store_dwordx4 v[106:107], v[82:85], off offset:256 sc1
	s_and_saveexec_b64 s[54:55], s[8:9]
	s_cbranch_execz .LBB0_882
	s_waitcnt lgkmcnt(0)
	v_add_f32_e32 v80, v80, v81
	v_mul_f32_e32 v80, 0x4f800000, v80
	v_trunc_f32_e32 v80, v80
	v_mul_f32_e64 v81, |v80|, s82
	v_floor_f32_e32 v81, v81
	v_fma_f32 v82, v81, s83, |v80|
	v_cvt_u32_f32_e32 v80, v82
	v_cvt_u32_f32_e32 v81, v81
	v_lshl_add_u64 v[82:83], v[96:97], 3, s[0:1]
	global_atomic_add_x2 v[82:83], v[80:81], off
.LBB0_882:
	s_or_b64 exec, exec, s[54:55]
	v_or_b32_e32 v80, 48, v146
	s_waitcnt lgkmcnt(0)
	v_ashrrev_i32_e32 v81, 31, v80
	v_lshlrev_b64 v[82:83], 11, v[80:81]
	v_lshl_add_u64 v[82:83], s[22:23], 0, v[82:83]
	v_lshl_add_u64 v[90:91], v[144:145], 1, v[82:83]
	global_load_dwordx4 v[82:85], v[90:91], off
	global_load_dwordx4 v[86:89], v[90:91], off offset:256
	s_waitcnt vmcnt(1)
	v_lshlrev_b32_e32 v92, 16, v82
	v_and_b32_e32 v93, 0xffff0000, v82
	v_lshlrev_b32_e32 v82, 16, v83
	v_and_b32_e32 v83, 0xffff0000, v83
	s_waitcnt vmcnt(0)
	v_lshlrev_b32_e32 v96, 16, v86
	v_and_b32_e32 v97, 0xffff0000, v86
	v_lshlrev_b32_e32 v86, 16, v87
	v_and_b32_e32 v87, 0xffff0000, v87
	v_lshlrev_b32_e32 v94, 16, v84
	v_and_b32_e32 v95, 0xffff0000, v84
	v_lshlrev_b32_e32 v84, 16, v85
	v_and_b32_e32 v85, 0xffff0000, v85
	v_lshlrev_b32_e32 v98, 16, v88
	v_and_b32_e32 v99, 0xffff0000, v88
	v_lshlrev_b32_e32 v88, 16, v89
	v_and_b32_e32 v89, 0xffff0000, v89
	v_pk_add_f32 v[78:79], v[78:79], v[82:83]
	v_pk_add_f32 v[76:77], v[76:77], v[92:93]
	v_pk_add_f32 v[70:71], v[70:71], v[86:87]
	v_pk_add_f32 v[68:69], v[68:69], v[96:97]
	v_pk_add_f32 v[74:75], v[74:75], v[84:85]
	v_pk_add_f32 v[72:73], v[72:73], v[94:95]
	v_pk_add_f32 v[82:83], v[66:67], v[88:89]
	v_pk_add_f32 v[84:85], v[64:65], v[98:99]
	v_mul_f32_e32 v66, v77, v77
	v_mul_f32_e32 v67, v79, v79
	v_mul_f32_e32 v86, v69, v69
	v_mul_f32_e32 v87, v71, v71
	v_cvt_pk_bf16_f32 v64, v76, v77
	v_mul_f32_e32 v77, v73, v73
	v_mul_f32_e32 v88, v85, v85
	v_fmac_f32_e32 v66, v76, v76
	v_fmac_f32_e32 v67, v78, v78
	v_fmac_f32_e32 v86, v68, v68
	v_fmac_f32_e32 v87, v70, v70
	v_cvt_pk_bf16_f32 v65, v78, v79
	v_mul_f32_e32 v79, v75, v75
	v_mul_f32_e32 v89, v83, v83
	v_fmac_f32_e32 v77, v72, v72
	v_fmac_f32_e32 v88, v84, v84
	v_add_f32_e32 v66, v66, v67
	v_add_f32_e32 v67, v86, v87
	v_fmac_f32_e32 v79, v74, v74
	v_fmac_f32_e32 v89, v82, v82
	v_add_f32_e32 v66, v77, v66
	v_add_f32_e32 v67, v88, v67
	v_add_f32_e32 v66, v79, v66
	v_add_f32_e32 v67, v89, v67
	v_add_f32_e32 v76, v66, v67
	v_mov_b32_e32 v77, v76
	s_nop 1
	v_permlane16_swap_b32_e32 v77, v76
	v_cvt_pk_bf16_f32 v66, v72, v73
	v_cvt_pk_bf16_f32 v67, v74, v75
	global_store_dwordx4 v[90:91], v[64:67], off sc1
	s_waitcnt lgkmcnt(0)
	s_nop 0
	v_add_f32_e32 v64, v76, v77
	v_mov_b32_e32 v65, v64
	s_nop 1
	v_permlane32_swap_b32_e32 v65, v64
	v_cvt_pk_bf16_f32 v66, v68, v69
	v_cvt_pk_bf16_f32 v67, v70, v71
	v_cvt_pk_bf16_f32 v68, v84, v85
	v_cvt_pk_bf16_f32 v69, v82, v83
	global_store_dwordx4 v[90:91], v[66:69], off offset:256 sc1
	s_and_saveexec_b64 s[54:55], s[8:9]
	s_cbranch_execz .LBB0_884
	s_waitcnt lgkmcnt(0)
	v_add_f32_e32 v64, v64, v65
	v_mul_f32_e32 v64, 0x4f800000, v64
	v_trunc_f32_e32 v64, v64
	v_mul_f32_e64 v65, |v64|, s82
	v_floor_f32_e32 v65, v65
	v_fma_f32 v66, v65, s83, |v64|
	v_cvt_u32_f32_e32 v64, v66
	v_cvt_u32_f32_e32 v65, v65
	v_lshl_add_u64 v[66:67], v[80:81], 3, s[0:1]
	global_atomic_add_x2 v[66:67], v[64:65], off
; __device__ __forceinline__ void fx_add(float* p, size_t idx, float s) { atomicAdd((unsigned long long*)p + idx, (unsigned long long)(long long)(s * 4294967296.0f)); }
; __device__ __forceinline__ unsigned cvtpk(float lo, float hi) { f32x2v_ v = {lo, hi}; bf16x2v_ b = __builtin_convertvector(v, bf16x2v_); return __builtin_bit_cast(unsigned, b); }
;     __device__ __forceinline__ void operator()(const f32x4 (&acc)[2][2][4][2], const Unit& u, int wr, int wc, int fr, int fq) const {
;     ...
;             for (int m = 0; m < 4; ++m) { const int row = row0 + ai * HALF + m * 16; const size_t off = (size_t)row * 1024 + col0; float s = 0.f;
; #pragma unroll
;                 for (int bj = 0; bj < 2; ++bj) { f32x4 a0, a1;
;                     if (xin32) { const float* p = xin32 + off + bj * HALF; a0 = *(const f32x4*)p; a1 = *(const f32x4*)(p + 4); }
;                     else { const u32x4 w = *(const u32x4*)(xb + off + bj * HALF);
;                         a0 = (f32x4){__uint_as_float(w.x << 16), __uint_as_float(w.x & 0xffff0000u), __uint_as_float(w.y << 16), __uint_as_float(w.y & 0xffff0000u)};
;                         a1 = (f32x4){__uint_as_float(w.z << 16), __uint_as_float(w.z & 0xffff0000u), __uint_as_float(w.w << 16), __uint_as_float(w.w & 0xffff0000u)}; }
;                     const f32x4 v0 = a0 + acc[ai][bj][m][0] * alpha, v1 = a1 + acc[ai][bj][m][1] * alpha;
;                     u32x4 w; w.x = cvtpk(v0[0], v0[1]); w.y = cvtpk(v0[2], v0[3]); w.z = cvtpk(v1[0], v1[1]); w.w = cvtpk(v1[2], v1[3]);
;                     *(u32x4*)(xb + off + bj * HALF) = w;
;                     s += (v0[0] * v0[0] + v0[1] * v0[1]) + (v0[2] * v0[2] + v0[3] * v0[3]) + (v1[0] * v1[0] + v1[1] * v1[1]) + (v1[2] * v1[2] + v1[3] * v1[3]); }
;                 s += __shfl_xor(s, 16); s += __shfl_xor(s, 32);
;                 if (fq == 0) fx_add(ssout, row, s); }
.LBB0_884:
	s_or_b64 exec, exec, s[54:55]
	v_add_u32_e32 v64, 0x80, v146
	s_waitcnt lgkmcnt(0)
	v_ashrrev_i32_e32 v65, 31, v64
	v_lshlrev_b64 v[66:67], 11, v[64:65]
	v_lshl_add_u64 v[66:67], s[22:23], 0, v[66:67]
	v_lshl_add_u64 v[74:75], v[144:145], 1, v[66:67]
	global_load_dwordx4 v[66:69], v[74:75], off
	global_load_dwordx4 v[70:73], v[74:75], off offset:256
	s_waitcnt vmcnt(1)
	v_lshlrev_b32_e32 v76, 16, v66
	v_and_b32_e32 v77, 0xffff0000, v66
	v_lshlrev_b32_e32 v66, 16, v67
	v_and_b32_e32 v67, 0xffff0000, v67
	s_waitcnt vmcnt(0)
	v_lshlrev_b32_e32 v80, 16, v70
	v_and_b32_e32 v81, 0xffff0000, v70
	v_lshlrev_b32_e32 v70, 16, v71
	v_and_b32_e32 v71, 0xffff0000, v71
	v_lshlrev_b32_e32 v78, 16, v68
	v_and_b32_e32 v79, 0xffff0000, v68
	v_lshlrev_b32_e32 v68, 16, v69
	v_and_b32_e32 v69, 0xffff0000, v69
	v_lshlrev_b32_e32 v82, 16, v72
	v_and_b32_e32 v83, 0xffff0000, v72
	v_lshlrev_b32_e32 v72, 16, v73
	v_and_b32_e32 v73, 0xffff0000, v73
	v_pk_add_f32 v[62:63], v[62:63], v[66:67]
	v_pk_add_f32 v[60:61], v[60:61], v[76:77]
	v_pk_add_f32 v[54:55], v[54:55], v[70:71]
	v_pk_add_f32 v[52:53], v[52:53], v[80:81]
	v_pk_add_f32 v[58:59], v[58:59], v[68:69]
	v_pk_add_f32 v[56:57], v[56:57], v[78:79]
	v_pk_add_f32 v[66:67], v[50:51], v[72:73]
	v_pk_add_f32 v[68:69], v[48:49], v[82:83]
	v_mul_f32_e32 v50, v61, v61
	v_mul_f32_e32 v51, v63, v63
	v_mul_f32_e32 v70, v53, v53
	v_mul_f32_e32 v71, v55, v55
	v_cvt_pk_bf16_f32 v48, v60, v61
	v_mul_f32_e32 v61, v57, v57
	v_mul_f32_e32 v72, v69, v69
	v_fmac_f32_e32 v50, v60, v60
	v_fmac_f32_e32 v51, v62, v62
	v_fmac_f32_e32 v70, v52, v52
	v_fmac_f32_e32 v71, v54, v54
	v_cvt_pk_bf16_f32 v49, v62, v63
	v_mul_f32_e32 v63, v59, v59
	v_mul_f32_e32 v73, v67, v67
	v_fmac_f32_e32 v61, v56, v56
	v_fmac_f32_e32 v72, v68, v68
	v_add_f32_e32 v50, v50, v51
	v_add_f32_e32 v51, v70, v71
	v_fmac_f32_e32 v63, v58, v58
	v_fmac_f32_e32 v73, v66, v66
	v_add_f32_e32 v50, v61, v50
	v_add_f32_e32 v51, v72, v51
	v_add_f32_e32 v50, v63, v50
	v_add_f32_e32 v51, v73, v51
	v_add_f32_e32 v60, v50, v51
	v_mov_b32_e32 v61, v60
	s_nop 1
	v_permlane16_swap_b32_e32 v61, v60
	v_cvt_pk_bf16_f32 v50, v56, v57
	v_cvt_pk_bf16_f32 v51, v58, v59
	global_store_dwordx4 v[74:75], v[48:51], off sc1
	s_waitcnt lgkmcnt(0)
	s_nop 0
	v_add_f32_e32 v48, v60, v61
	v_mov_b32_e32 v49, v48
	s_nop 1
	v_permlane32_swap_b32_e32 v49, v48
	v_cvt_pk_bf16_f32 v50, v52, v53
	v_cvt_pk_bf16_f32 v51, v54, v55
	v_cvt_pk_bf16_f32 v52, v68, v69
	v_cvt_pk_bf16_f32 v53, v66, v67
	global_store_dwordx4 v[74:75], v[50:53], off offset:256 sc1
	s_and_saveexec_b64 s[54:55], s[8:9]
	s_cbranch_execz .LBB0_886
	s_waitcnt lgkmcnt(0)
	v_add_f32_e32 v48, v48, v49
	v_mul_f32_e32 v48, 0x4f800000, v48
	v_trunc_f32_e32 v48, v48
	v_mul_f32_e64 v49, |v48|, s82
	v_floor_f32_e32 v49, v49
	v_fma_f32 v50, v49, s83, |v48|
	v_cvt_u32_f32_e32 v48, v50
	v_cvt_u32_f32_e32 v49, v49
	v_lshl_add_u64 v[50:51], v[64:65], 3, s[0:1]
	global_atomic_add_x2 v[50:51], v[48:49], off
.LBB0_886:
	s_or_b64 exec, exec, s[54:55]
	v_add_u32_e32 v48, 0x90, v146
	s_waitcnt lgkmcnt(0)
	v_ashrrev_i32_e32 v49, 31, v48
	v_lshlrev_b64 v[50:51], 11, v[48:49]
	v_lshl_add_u64 v[50:51], s[22:23], 0, v[50:51]
	v_lshl_add_u64 v[58:59], v[144:145], 1, v[50:51]
	global_load_dwordx4 v[50:53], v[58:59], off
	global_load_dwordx4 v[54:57], v[58:59], off offset:256
	s_waitcnt vmcnt(1)
	v_lshlrev_b32_e32 v60, 16, v50
	v_and_b32_e32 v61, 0xffff0000, v50
	v_lshlrev_b32_e32 v50, 16, v51
	v_and_b32_e32 v51, 0xffff0000, v51
	s_waitcnt vmcnt(0)
	v_lshlrev_b32_e32 v64, 16, v54
	v_and_b32_e32 v65, 0xffff0000, v54
	v_lshlrev_b32_e32 v54, 16, v55
	v_and_b32_e32 v55, 0xffff0000, v55
	v_lshlrev_b32_e32 v62, 16, v52
	v_and_b32_e32 v63, 0xffff0000, v52
	v_lshlrev_b32_e32 v52, 16, v53
	v_and_b32_e32 v53, 0xffff0000, v53
	v_lshlrev_b32_e32 v66, 16, v56
	v_and_b32_e32 v67, 0xffff0000, v56
	v_lshlrev_b32_e32 v56, 16, v57
	v_and_b32_e32 v57, 0xffff0000, v57
	v_pk_add_f32 v[46:47], v[46:47], v[50:51]
	v_pk_add_f32 v[44:45], v[44:45], v[60:61]
	v_pk_add_f32 v[38:39], v[38:39], v[54:55]
	v_pk_add_f32 v[36:37], v[36:37], v[64:65]
	v_pk_add_f32 v[42:43], v[42:43], v[52:53]
	v_pk_add_f32 v[40:41], v[40:41], v[62:63]
	v_pk_add_f32 v[50:51], v[34:35], v[56:57]
	v_pk_add_f32 v[52:53], v[32:33], v[66:67]
	v_mul_f32_e32 v34, v45, v45
	v_mul_f32_e32 v35, v47, v47
	v_mul_f32_e32 v54, v37, v37
	v_mul_f32_e32 v55, v39, v39
	v_cvt_pk_bf16_f32 v32, v44, v45
	v_mul_f32_e32 v45, v41, v41
	v_mul_f32_e32 v56, v53, v53
	v_fmac_f32_e32 v34, v44, v44
	v_fmac_f32_e32 v35, v46, v46
	v_fmac_f32_e32 v54, v36, v36
	v_fmac_f32_e32 v55, v38, v38
	v_cvt_pk_bf16_f32 v33, v46, v47
	v_mul_f32_e32 v47, v43, v43
	v_mul_f32_e32 v57, v51, v51
	v_fmac_f32_e32 v45, v40, v40
	v_fmac_f32_e32 v56, v52, v52
	v_add_f32_e32 v34, v34, v35
	v_add_f32_e32 v35, v54, v55
	v_fmac_f32_e32 v47, v42, v42
	v_fmac_f32_e32 v57, v50, v50
	v_add_f32_e32 v34, v45, v34
	v_add_f32_e32 v35, v56, v35
	v_add_f32_e32 v34, v47, v34
	v_add_f32_e32 v35, v57, v35
	v_add_f32_e32 v44, v34, v35
	v_mov_b32_e32 v45, v44
	s_nop 1
	v_permlane16_swap_b32_e32 v45, v44
	v_cvt_pk_bf16_f32 v34, v40, v41
	v_cvt_pk_bf16_f32 v35, v42, v43
	global_store_dwordx4 v[58:59], v[32:35], off sc1
	s_waitcnt lgkmcnt(0)
	s_nop 0
	v_add_f32_e32 v32, v44, v45
	v_mov_b32_e32 v33, v32
	s_nop 1
	v_permlane32_swap_b32_e32 v33, v32
	v_cvt_pk_bf16_f32 v34, v36, v37
	v_cvt_pk_bf16_f32 v35, v38, v39
	v_cvt_pk_bf16_f32 v36, v52, v53
	v_cvt_pk_bf16_f32 v37, v50, v51
	global_store_dwordx4 v[58:59], v[34:37], off offset:256 sc1
	s_and_saveexec_b64 s[54:55], s[8:9]
	s_cbranch_execz .LBB0_888
	s_waitcnt lgkmcnt(0)
	v_add_f32_e32 v32, v32, v33
	v_mul_f32_e32 v32, 0x4f800000, v32
	v_trunc_f32_e32 v32, v32
	v_mul_f32_e64 v33, |v32|, s82
	v_floor_f32_e32 v33, v33
	v_fma_f32 v34, v33, s83, |v32|
	v_cvt_u32_f32_e32 v32, v34
	v_cvt_u32_f32_e32 v33, v33
	v_lshl_add_u64 v[34:35], v[48:49], 3, s[0:1]
	global_atomic_add_x2 v[34:35], v[32:33], off
; __device__ __forceinline__ void fx_add(float* p, size_t idx, float s) { atomicAdd((unsigned long long*)p + idx, (unsigned long long)(long long)(s * 4294967296.0f)); }
; __device__ __forceinline__ unsigned cvtpk(float lo, float hi) { f32x2v_ v = {lo, hi}; bf16x2v_ b = __builtin_convertvector(v, bf16x2v_); return __builtin_bit_cast(unsigned, b); }
;     __device__ __forceinline__ void operator()(const f32x4 (&acc)[2][2][4][2], const Unit& u, int wr, int wc, int fr, int fq) const {
;     ...
;             for (int m = 0; m < 4; ++m) { const int row = row0 + ai * HALF + m * 16; const size_t off = (size_t)row * 1024 + col0; float s = 0.f;
; #pragma unroll
;                 for (int bj = 0; bj < 2; ++bj) { f32x4 a0, a1;
;                     if (xin32) { const float* p = xin32 + off + bj * HALF; a0 = *(const f32x4*)p; a1 = *(const f32x4*)(p + 4); }
;                     else { const u32x4 w = *(const u32x4*)(xb + off + bj * HALF);
;                         a0 = (f32x4){__uint_as_float(w.x << 16), __uint_as_float(w.x & 0xffff0000u), __uint_as_float(w.y << 16), __uint_as_float(w.y & 0xffff0000u)};
;                         a1 = (f32x4){__uint_as_float(w.z << 16), __uint_as_float(w.z & 0xffff0000u), __uint_as_float(w.w << 16), __uint_as_float(w.w & 0xffff0000u)}; }
;                     const f32x4 v0 = a0 + acc[ai][bj][m][0] * alpha, v1 = a1 + acc[ai][bj][m][1] * alpha;
;                     u32x4 w; w.x = cvtpk(v0[0], v0[1]); w.y = cvtpk(v0[2], v0[3]); w.z = cvtpk(v1[0], v1[1]); w.w = cvtpk(v1[2], v1[3]);
;                     *(u32x4*)(xb + off + bj * HALF) = w;
;                     s += (v0[0] * v0[0] + v0[1] * v0[1]) + (v0[2] * v0[2] + v0[3] * v0[3]) + (v1[0] * v1[0] + v1[1] * v1[1]) + (v1[2] * v1[2] + v1[3] * v1[3]); }
;                 s += __shfl_xor(s, 16); s += __shfl_xor(s, 32);
;                 if (fq == 0) fx_add(ssout, row, s); }
.LBB0_888:
	s_or_b64 exec, exec, s[54:55]
	v_add_u32_e32 v32, 0xa0, v146
	s_waitcnt lgkmcnt(0)
	v_ashrrev_i32_e32 v33, 31, v32
	v_lshlrev_b64 v[34:35], 11, v[32:33]
	v_lshl_add_u64 v[34:35], s[22:23], 0, v[34:35]
	v_lshl_add_u64 v[42:43], v[144:145], 1, v[34:35]
	global_load_dwordx4 v[34:37], v[42:43], off
	global_load_dwordx4 v[38:41], v[42:43], off offset:256
	s_waitcnt vmcnt(1)
	v_lshlrev_b32_e32 v44, 16, v34
	v_and_b32_e32 v45, 0xffff0000, v34
	v_lshlrev_b32_e32 v34, 16, v35
	v_and_b32_e32 v35, 0xffff0000, v35
	s_waitcnt vmcnt(0)
	v_lshlrev_b32_e32 v48, 16, v38
	v_and_b32_e32 v49, 0xffff0000, v38
	v_lshlrev_b32_e32 v38, 16, v39
	v_and_b32_e32 v39, 0xffff0000, v39
	v_lshlrev_b32_e32 v46, 16, v36
	v_and_b32_e32 v47, 0xffff0000, v36
	v_lshlrev_b32_e32 v36, 16, v37
	v_and_b32_e32 v37, 0xffff0000, v37
	v_lshlrev_b32_e32 v50, 16, v40
	v_and_b32_e32 v51, 0xffff0000, v40
	v_lshlrev_b32_e32 v40, 16, v41
	v_and_b32_e32 v41, 0xffff0000, v41
	v_pk_add_f32 v[30:31], v[30:31], v[34:35]
	v_pk_add_f32 v[28:29], v[28:29], v[44:45]
	v_pk_add_f32 v[22:23], v[22:23], v[38:39]
	v_pk_add_f32 v[20:21], v[20:21], v[48:49]
	v_pk_add_f32 v[26:27], v[26:27], v[36:37]
	v_pk_add_f32 v[24:25], v[24:25], v[46:47]
	v_pk_add_f32 v[34:35], v[18:19], v[40:41]
	v_pk_add_f32 v[36:37], v[16:17], v[50:51]
	v_mul_f32_e32 v18, v29, v29
	v_mul_f32_e32 v19, v31, v31
	v_mul_f32_e32 v38, v21, v21
	v_mul_f32_e32 v39, v23, v23
	v_cvt_pk_bf16_f32 v16, v28, v29
	v_mul_f32_e32 v29, v25, v25
	v_mul_f32_e32 v40, v37, v37
	v_fmac_f32_e32 v18, v28, v28
	v_fmac_f32_e32 v19, v30, v30
	v_fmac_f32_e32 v38, v20, v20
	v_fmac_f32_e32 v39, v22, v22
	v_cvt_pk_bf16_f32 v17, v30, v31
	v_mul_f32_e32 v31, v27, v27
	v_mul_f32_e32 v41, v35, v35
	v_fmac_f32_e32 v29, v24, v24
	v_fmac_f32_e32 v40, v36, v36
	v_add_f32_e32 v18, v18, v19
	v_add_f32_e32 v19, v38, v39
	v_fmac_f32_e32 v31, v26, v26
	v_fmac_f32_e32 v41, v34, v34
	v_add_f32_e32 v18, v29, v18
	v_add_f32_e32 v19, v40, v19
	v_add_f32_e32 v18, v31, v18
	v_add_f32_e32 v19, v41, v19
	v_add_f32_e32 v28, v18, v19
	v_mov_b32_e32 v29, v28
	s_nop 1
	v_permlane16_swap_b32_e32 v29, v28
	v_cvt_pk_bf16_f32 v18, v24, v25
	v_cvt_pk_bf16_f32 v19, v26, v27
	global_store_dwordx4 v[42:43], v[16:19], off sc1
	s_waitcnt lgkmcnt(0)
	s_nop 0
	v_add_f32_e32 v16, v28, v29
	v_mov_b32_e32 v17, v16
	s_nop 1
	v_permlane32_swap_b32_e32 v17, v16
	v_cvt_pk_bf16_f32 v18, v20, v21
	v_cvt_pk_bf16_f32 v19, v22, v23
	v_cvt_pk_bf16_f32 v20, v36, v37
	v_cvt_pk_bf16_f32 v21, v34, v35
	global_store_dwordx4 v[42:43], v[18:21], off offset:256 sc1
	s_and_saveexec_b64 s[54:55], s[8:9]
	s_cbranch_execz .LBB0_890
	s_waitcnt lgkmcnt(0)
	v_add_f32_e32 v16, v16, v17
	v_mul_f32_e32 v16, 0x4f800000, v16
	v_trunc_f32_e32 v16, v16
	v_mul_f32_e64 v17, |v16|, s82
	v_floor_f32_e32 v17, v17
	v_fma_f32 v18, v17, s83, |v16|
	v_cvt_u32_f32_e32 v16, v18
	v_cvt_u32_f32_e32 v17, v17
	v_lshl_add_u64 v[18:19], v[32:33], 3, s[0:1]
	global_atomic_add_x2 v[18:19], v[16:17], off
.LBB0_890:
	s_or_b64 exec, exec, s[54:55]
	v_add_u32_e32 v16, 0xb0, v146
	s_waitcnt lgkmcnt(0)
	v_ashrrev_i32_e32 v17, 31, v16
	v_lshlrev_b64 v[18:19], 11, v[16:17]
	v_lshl_add_u64 v[18:19], s[22:23], 0, v[18:19]
	v_lshl_add_u64 v[26:27], v[144:145], 1, v[18:19]
	global_load_dwordx4 v[18:21], v[26:27], off
	global_load_dwordx4 v[22:25], v[26:27], off offset:256
	s_waitcnt vmcnt(1)
	v_lshlrev_b32_e32 v28, 16, v18
	v_and_b32_e32 v29, 0xffff0000, v18
	v_lshlrev_b32_e32 v18, 16, v19
	v_and_b32_e32 v19, 0xffff0000, v19
	s_waitcnt vmcnt(0)
	v_lshlrev_b32_e32 v32, 16, v22
	v_and_b32_e32 v33, 0xffff0000, v22
	v_lshlrev_b32_e32 v22, 16, v23
	v_and_b32_e32 v23, 0xffff0000, v23
	v_lshlrev_b32_e32 v30, 16, v20
	v_and_b32_e32 v31, 0xffff0000, v20
	v_lshlrev_b32_e32 v20, 16, v21
	v_and_b32_e32 v21, 0xffff0000, v21
	v_lshlrev_b32_e32 v34, 16, v24
	v_and_b32_e32 v35, 0xffff0000, v24
	v_lshlrev_b32_e32 v24, 16, v25
	v_and_b32_e32 v25, 0xffff0000, v25
	v_pk_add_f32 v[14:15], v[14:15], v[18:19]
	v_pk_add_f32 v[12:13], v[12:13], v[28:29]
	v_pk_add_f32 v[6:7], v[6:7], v[22:23]
	v_pk_add_f32 v[4:5], v[4:5], v[32:33]
	v_pk_add_f32 v[10:11], v[10:11], v[20:21]
	v_pk_add_f32 v[8:9], v[8:9], v[30:31]
	v_pk_add_f32 v[18:19], v[2:3], v[24:25]
	v_pk_add_f32 v[20:21], v[0:1], v[34:35]
	v_mul_f32_e32 v2, v13, v13
	v_mul_f32_e32 v3, v15, v15
	v_mul_f32_e32 v22, v5, v5
	v_mul_f32_e32 v23, v7, v7
	v_cvt_pk_bf16_f32 v0, v12, v13
	v_mul_f32_e32 v13, v9, v9
	v_mul_f32_e32 v24, v21, v21
	v_fmac_f32_e32 v2, v12, v12
	v_fmac_f32_e32 v3, v14, v14
	v_fmac_f32_e32 v22, v4, v4
	v_fmac_f32_e32 v23, v6, v6
	v_cvt_pk_bf16_f32 v1, v14, v15
	v_mul_f32_e32 v15, v11, v11
	v_mul_f32_e32 v25, v19, v19
	v_fmac_f32_e32 v13, v8, v8
	v_fmac_f32_e32 v24, v20, v20
	v_add_f32_e32 v2, v2, v3
	v_add_f32_e32 v3, v22, v23
	v_fmac_f32_e32 v15, v10, v10
	v_fmac_f32_e32 v25, v18, v18
	v_add_f32_e32 v2, v13, v2
	v_add_f32_e32 v3, v24, v3
	v_add_f32_e32 v2, v15, v2
	v_add_f32_e32 v3, v25, v3
	v_add_f32_e32 v12, v2, v3
	v_mov_b32_e32 v13, v12
	s_nop 1
	v_permlane16_swap_b32_e32 v13, v12
	v_cvt_pk_bf16_f32 v2, v8, v9
	v_cvt_pk_bf16_f32 v3, v10, v11
	global_store_dwordx4 v[26:27], v[0:3], off sc1
	s_waitcnt lgkmcnt(0)
	s_nop 0
	v_add_f32_e32 v0, v12, v13
	v_mov_b32_e32 v1, v0
	s_nop 1
	v_permlane32_swap_b32_e32 v1, v0
	v_cvt_pk_bf16_f32 v2, v4, v5
	v_cvt_pk_bf16_f32 v3, v6, v7
	v_cvt_pk_bf16_f32 v4, v20, v21
	v_cvt_pk_bf16_f32 v5, v18, v19
	global_store_dwordx4 v[26:27], v[2:5], off offset:256 sc1
	s_and_saveexec_b64 s[54:55], s[8:9]
	s_cbranch_execz .LBB0_892
	s_waitcnt lgkmcnt(0)
	v_add_f32_e32 v0, v0, v1
	v_mul_f32_e32 v0, 0x4f800000, v0
	v_trunc_f32_e32 v0, v0
	v_mul_f32_e64 v1, |v0|, s82
	v_floor_f32_e32 v1, v1
	v_fma_f32 v2, v1, s83, |v0|
	v_cvt_u32_f32_e32 v0, v2
	v_cvt_u32_f32_e32 v1, v1
	v_lshl_add_u64 v[2:3], v[16:17], 3, s[0:1]
	global_atomic_add_x2 v[2:3], v[0:1], off

; __device__ __forceinline__ unsigned cvtpk(float lo, float hi) { f32x2v_ v = {lo, hi}; bf16x2v_ b = __builtin_convertvector(v, bf16x2v_); return __builtin_bit_cast(unsigned, b); }
;     __device__ __forceinline__ void operator()(const f32x4 (&acc)[2][2][4][2], const Unit& u, int wr, int wc, int fr, int fq) const {
;     ...
;             for (int m = 0; m < 4; ++m) { const int row = row0 + ai * HALF + m * 16; const float rs = row_rs(ss, row);
;                 float hv[8];
; #pragma unroll
;                 for (int n = 0; n < 2; ++n)
; #pragma unroll
;                     for (int i = 0; i < 4; ++i) { const float g = acc[ai][0][m][n][i] * rs, uu = acc[ai][1][m][n][i] * rs;
;                         hv[n * 4 + i] = g * __builtin_amdgcn_rcpf(1.0f + __expf(-g)) * uu; }
;                 u32x4 w; w.x = cvtpk(hv[0], hv[1]); w.y = cvtpk(hv[2], hv[3]); w.z = cvtpk(hv[4], hv[5]); w.w = cvtpk(hv[6], hv[7]);
;                 *(u32x4*)(H + (size_t)row * ldh + col0) = w; }
.LBB0_960:
	v_lshl_or_b32 v160, s74, 7, v154
	v_ashrrev_i32_e32 v161, 31, v160
	v_or_b32_e32 v164, 16, v144
	v_ashrrev_i32_e32 v165, 31, v164
	v_lshl_add_u64 v[166:167], v[164:165], 3, s[0:1]
	v_mov_b64_e32 v[146:147], s[20:21]
	v_mad_i64_i32 v[162:163], s[54:55], v144, s67, v[146:147]
	s_andn2_b64 vcc, exec, s[10:11]
	s_mov_b64 s[10:11], -1
	s_waitcnt vmcnt(7)
	v_cvt_f32_u32_e32 v159, v183
	v_cvt_f32_u32_e32 v145, v182
	v_lshlrev_b64 v[148:149], 1, v[160:161]
	v_lshl_add_u64 v[162:163], v[162:163], 0, v[148:149]
	v_fmamk_f32 v145, v145, 0x2f800000, v159
	v_fmamk_f32 v145, v145, 0x3a800000, v158
	v_rsq_f32_e32 v160, v145
	s_nop 0
	v_mul_f32_e32 v182, 0xbfb8aa3b, v160
	v_mul_f32_e32 v183, v160, v160
	v_pk_mul_f32 v[160:161], v[124:125], v[182:183] op_sel_hi:[1,0]
	v_pk_mul_f32 v[168:169], v[126:127], v[182:183] op_sel_hi:[1,0]
	v_pk_mul_f32 v[170:171], v[120:121], v[182:183] op_sel_hi:[1,0]
	v_pk_mul_f32 v[172:173], v[122:123], v[182:183] op_sel_hi:[1,0]
	v_pk_mul_f32 v[116:117], v[116:117], v[124:125]
	v_pk_mul_f32 v[118:119], v[118:119], v[126:127]
	v_pk_mul_f32 v[120:121], v[112:113], v[120:121]
	v_pk_mul_f32 v[122:123], v[114:115], v[122:123]
	v_exp_f32_e32 v160, v160
	v_exp_f32_e32 v161, v161
	v_exp_f32_e32 v168, v168
	v_exp_f32_e32 v169, v169
	v_exp_f32_e32 v170, v170
	v_exp_f32_e32 v171, v171
	v_exp_f32_e32 v172, v172
	v_exp_f32_e32 v173, v173
	v_pk_mul_f32 v[116:117], v[116:117], v[182:183] op_sel:[0,1] op_sel_hi:[1,1]
	v_pk_mul_f32 v[118:119], v[118:119], v[182:183] op_sel:[0,1] op_sel_hi:[1,1]
	v_pk_mul_f32 v[120:121], v[120:121], v[182:183] op_sel:[0,1] op_sel_hi:[1,1]
	v_pk_mul_f32 v[122:123], v[122:123], v[182:183] op_sel:[0,1] op_sel_hi:[1,1]
	v_pk_add_f32 v[160:161], v[160:161], 1.0 op_sel_hi:[1,0]
	v_pk_add_f32 v[168:169], v[168:169], 1.0 op_sel_hi:[1,0]
	v_pk_add_f32 v[170:171], v[170:171], 1.0 op_sel_hi:[1,0]
	v_pk_add_f32 v[172:173], v[172:173], 1.0 op_sel_hi:[1,0]
	v_rcp_f32_e32 v160, v160
	v_rcp_f32_e32 v161, v161
	v_rcp_f32_e32 v168, v168
	v_rcp_f32_e32 v169, v169
	v_rcp_f32_e32 v170, v170
	v_rcp_f32_e32 v171, v171
	v_rcp_f32_e32 v172, v172
	v_rcp_f32_e32 v173, v173
	v_pk_mul_f32 v[116:117], v[116:117], v[160:161]
	v_pk_mul_f32 v[118:119], v[118:119], v[168:169]
	v_pk_mul_f32 v[120:121], v[120:121], v[170:171]
	v_pk_mul_f32 v[122:123], v[122:123], v[172:173]
	v_cvt_pk_bf16_f32 v112, v116, v117
	v_cvt_pk_bf16_f32 v113, v118, v119
	v_cvt_pk_bf16_f32 v114, v120, v121
	v_cvt_pk_bf16_f32 v115, v122, v123
	global_store_dwordx4 v[162:163], v[112:115], off sc1
	s_nop 0
	s_nop 0
	v_or_b32_e32 v114, 32, v144
	s_waitcnt vmcnt(7)
	v_cvt_f32_u32_e32 v116, v185
	v_cvt_f32_u32_e32 v115, v184
	v_mad_i64_i32 v[112:113], s[54:55], v164, s67, v[146:147]
	v_fmamk_f32 v115, v115, 0x2f800000, v116
	v_fmamk_f32 v115, v115, 0x3a800000, v158
	v_rsq_f32_e32 v116, v115
	v_ashrrev_i32_e32 v115, 31, v114
	v_lshl_add_u64 v[118:119], v[114:115], 3, s[0:1]
	v_lshl_add_u64 v[112:113], v[112:113], 0, v[148:149]
	v_mul_f32_e32 v184, 0xbfb8aa3b, v116
	v_mul_f32_e32 v185, v116, v116
	v_pk_mul_f32 v[116:117], v[108:109], v[184:185] op_sel_hi:[1,0]
	v_pk_mul_f32 v[120:121], v[110:111], v[184:185] op_sel_hi:[1,0]
	v_pk_mul_f32 v[122:123], v[104:105], v[184:185] op_sel_hi:[1,0]
	v_pk_mul_f32 v[124:125], v[106:107], v[184:185] op_sel_hi:[1,0]
	v_pk_mul_f32 v[100:101], v[100:101], v[108:109]
	v_pk_mul_f32 v[102:103], v[102:103], v[110:111]
	v_pk_mul_f32 v[104:105], v[96:97], v[104:105]
	v_pk_mul_f32 v[106:107], v[98:99], v[106:107]
	v_exp_f32_e32 v116, v116
	v_exp_f32_e32 v117, v117
	v_exp_f32_e32 v120, v120
	v_exp_f32_e32 v121, v121
	v_exp_f32_e32 v122, v122
	v_exp_f32_e32 v123, v123
	v_exp_f32_e32 v124, v124
	v_exp_f32_e32 v125, v125
	v_pk_mul_f32 v[100:101], v[100:101], v[184:185] op_sel:[0,1] op_sel_hi:[1,1]
	v_pk_mul_f32 v[102:103], v[102:103], v[184:185] op_sel:[0,1] op_sel_hi:[1,1]
	v_pk_mul_f32 v[104:105], v[104:105], v[184:185] op_sel:[0,1] op_sel_hi:[1,1]
	v_pk_mul_f32 v[106:107], v[106:107], v[184:185] op_sel:[0,1] op_sel_hi:[1,1]
	v_pk_add_f32 v[116:117], v[116:117], 1.0 op_sel_hi:[1,0]
	v_pk_add_f32 v[120:121], v[120:121], 1.0 op_sel_hi:[1,0]
	v_pk_add_f32 v[122:123], v[122:123], 1.0 op_sel_hi:[1,0]
	v_pk_add_f32 v[124:125], v[124:125], 1.0 op_sel_hi:[1,0]
	v_rcp_f32_e32 v116, v116
	v_rcp_f32_e32 v117, v117
	v_rcp_f32_e32 v120, v120
	v_rcp_f32_e32 v121, v121
	v_rcp_f32_e32 v122, v122
	v_rcp_f32_e32 v123, v123
	v_rcp_f32_e32 v124, v124
	v_rcp_f32_e32 v125, v125
	v_pk_mul_f32 v[100:101], v[100:101], v[116:117]
	v_pk_mul_f32 v[102:103], v[102:103], v[120:121]
	v_pk_mul_f32 v[104:105], v[104:105], v[122:123]
	v_pk_mul_f32 v[106:107], v[106:107], v[124:125]
	v_cvt_pk_bf16_f32 v96, v100, v101
	v_cvt_pk_bf16_f32 v97, v102, v103
	v_cvt_pk_bf16_f32 v98, v104, v105
	v_cvt_pk_bf16_f32 v99, v106, v107
	global_store_dwordx4 v[112:113], v[96:99], off sc1
	s_nop 0
	s_nop 0
	v_or_b32_e32 v98, 48, v144
	s_waitcnt vmcnt(7)
; __device__ __forceinline__ unsigned cvtpk(float lo, float hi) { f32x2v_ v = {lo, hi}; bf16x2v_ b = __builtin_convertvector(v, bf16x2v_); return __builtin_bit_cast(unsigned, b); }
;     __device__ __forceinline__ void operator()(const f32x4 (&acc)[2][2][4][2], const Unit& u, int wr, int wc, int fr, int fq) const {
;     ...
;             for (int m = 0; m < 4; ++m) { const int row = row0 + ai * HALF + m * 16; const float rs = row_rs(ss, row);
;                 float hv[8];
; #pragma unroll
;                 for (int n = 0; n < 2; ++n)
; #pragma unroll
;                     for (int i = 0; i < 4; ++i) { const float g = acc[ai][0][m][n][i] * rs, uu = acc[ai][1][m][n][i] * rs;
;                         hv[n * 4 + i] = g * __builtin_amdgcn_rcpf(1.0f + __expf(-g)) * uu; }
;                 u32x4 w; w.x = cvtpk(hv[0], hv[1]); w.y = cvtpk(hv[2], hv[3]); w.z = cvtpk(hv[4], hv[5]); w.w = cvtpk(hv[6], hv[7]);
;                 *(u32x4*)(H + (size_t)row * ldh + col0) = w; }
	v_cvt_f32_u32_e32 v100, v187
	v_cvt_f32_u32_e32 v99, v186
	v_mad_i64_i32 v[96:97], s[54:55], v114, s67, v[146:147]
	v_fmamk_f32 v99, v99, 0x2f800000, v100
	v_fmamk_f32 v99, v99, 0x3a800000, v158
	v_rsq_f32_e32 v100, v99
	v_ashrrev_i32_e32 v99, 31, v98
	v_lshl_add_u64 v[102:103], v[98:99], 3, s[0:1]
	v_lshl_add_u64 v[96:97], v[96:97], 0, v[148:149]
	v_mul_f32_e32 v186, 0xbfb8aa3b, v100
	v_mul_f32_e32 v187, v100, v100
	v_pk_mul_f32 v[100:101], v[92:93], v[186:187] op_sel_hi:[1,0]
	v_pk_mul_f32 v[104:105], v[94:95], v[186:187] op_sel_hi:[1,0]
	v_pk_mul_f32 v[106:107], v[88:89], v[186:187] op_sel_hi:[1,0]
	v_pk_mul_f32 v[108:109], v[90:91], v[186:187] op_sel_hi:[1,0]
	v_pk_mul_f32 v[84:85], v[84:85], v[92:93]
	v_pk_mul_f32 v[86:87], v[86:87], v[94:95]
	v_pk_mul_f32 v[88:89], v[80:81], v[88:89]
	v_pk_mul_f32 v[90:91], v[82:83], v[90:91]
	v_exp_f32_e32 v100, v100
	v_exp_f32_e32 v101, v101
	v_exp_f32_e32 v104, v104
	v_exp_f32_e32 v105, v105
	v_exp_f32_e32 v106, v106
	v_exp_f32_e32 v107, v107
	v_exp_f32_e32 v108, v108
	v_exp_f32_e32 v109, v109
	v_pk_mul_f32 v[84:85], v[84:85], v[186:187] op_sel:[0,1] op_sel_hi:[1,1]
	v_pk_mul_f32 v[86:87], v[86:87], v[186:187] op_sel:[0,1] op_sel_hi:[1,1]
	v_pk_mul_f32 v[88:89], v[88:89], v[186:187] op_sel:[0,1] op_sel_hi:[1,1]
	v_pk_mul_f32 v[90:91], v[90:91], v[186:187] op_sel:[0,1] op_sel_hi:[1,1]
	v_pk_add_f32 v[100:101], v[100:101], 1.0 op_sel_hi:[1,0]
	v_pk_add_f32 v[104:105], v[104:105], 1.0 op_sel_hi:[1,0]
	v_pk_add_f32 v[106:107], v[106:107], 1.0 op_sel_hi:[1,0]
	v_pk_add_f32 v[108:109], v[108:109], 1.0 op_sel_hi:[1,0]
	v_rcp_f32_e32 v100, v100
	v_rcp_f32_e32 v101, v101
	v_rcp_f32_e32 v104, v104
	v_rcp_f32_e32 v105, v105
	v_rcp_f32_e32 v106, v106
	v_rcp_f32_e32 v107, v107
	v_rcp_f32_e32 v108, v108
	v_rcp_f32_e32 v109, v109
	v_pk_mul_f32 v[84:85], v[84:85], v[100:101]
	v_pk_mul_f32 v[86:87], v[86:87], v[104:105]
	v_pk_mul_f32 v[88:89], v[88:89], v[106:107]
	v_pk_mul_f32 v[90:91], v[90:91], v[108:109]
	v_cvt_pk_bf16_f32 v80, v84, v85
	v_cvt_pk_bf16_f32 v81, v86, v87
	v_cvt_pk_bf16_f32 v82, v88, v89
	v_cvt_pk_bf16_f32 v83, v90, v91
	global_store_dwordx4 v[96:97], v[80:83], off sc1
	s_nop 0
	s_waitcnt vmcnt(7)
	v_cvt_f32_u32_e32 v80, v189
	v_cvt_f32_u32_e32 v81, v188
	v_mad_i64_i32 v[82:83], s[54:55], v98, s67, v[146:147]
	v_fmamk_f32 v80, v81, 0x2f800000, v80
	v_fmamk_f32 v80, v80, 0x3a800000, v158
	v_rsq_f32_e32 v80, v80
	v_lshl_add_u64 v[82:83], v[82:83], 0, v[148:149]
	v_mul_f32_e32 v188, 0xbfb8aa3b, v80
	v_mul_f32_e32 v189, v80, v80
	v_pk_mul_f32 v[80:81], v[76:77], v[188:189] op_sel_hi:[1,0]
	v_pk_mul_f32 v[84:85], v[78:79], v[188:189] op_sel_hi:[1,0]
	v_pk_mul_f32 v[86:87], v[72:73], v[188:189] op_sel_hi:[1,0]
	v_pk_mul_f32 v[88:89], v[74:75], v[188:189] op_sel_hi:[1,0]
	v_pk_mul_f32 v[68:69], v[68:69], v[76:77]
	v_pk_mul_f32 v[70:71], v[70:71], v[78:79]
	v_pk_mul_f32 v[72:73], v[64:65], v[72:73]
	v_pk_mul_f32 v[74:75], v[66:67], v[74:75]
	v_exp_f32_e32 v80, v80
	v_exp_f32_e32 v81, v81
	v_exp_f32_e32 v84, v84
	v_exp_f32_e32 v85, v85
	v_exp_f32_e32 v86, v86
	v_exp_f32_e32 v87, v87
	v_exp_f32_e32 v88, v88
	v_exp_f32_e32 v89, v89
	v_pk_mul_f32 v[68:69], v[68:69], v[188:189] op_sel:[0,1] op_sel_hi:[1,1]
	v_pk_mul_f32 v[70:71], v[70:71], v[188:189] op_sel:[0,1] op_sel_hi:[1,1]
	v_pk_mul_f32 v[72:73], v[72:73], v[188:189] op_sel:[0,1] op_sel_hi:[1,1]
	v_pk_mul_f32 v[74:75], v[74:75], v[188:189] op_sel:[0,1] op_sel_hi:[1,1]
	v_pk_add_f32 v[80:81], v[80:81], 1.0 op_sel_hi:[1,0]
	v_pk_add_f32 v[84:85], v[84:85], 1.0 op_sel_hi:[1,0]
	v_pk_add_f32 v[86:87], v[86:87], 1.0 op_sel_hi:[1,0]
	v_pk_add_f32 v[88:89], v[88:89], 1.0 op_sel_hi:[1,0]
	v_rcp_f32_e32 v80, v80
	v_rcp_f32_e32 v81, v81
	v_rcp_f32_e32 v84, v84
	v_rcp_f32_e32 v85, v85
	v_rcp_f32_e32 v86, v86
	v_rcp_f32_e32 v87, v87
	v_rcp_f32_e32 v88, v88
	v_rcp_f32_e32 v89, v89
	v_pk_mul_f32 v[68:69], v[68:69], v[80:81]
	v_pk_mul_f32 v[70:71], v[70:71], v[84:85]
	v_pk_mul_f32 v[72:73], v[72:73], v[86:87]
	v_pk_mul_f32 v[74:75], v[74:75], v[88:89]
	v_cvt_pk_bf16_f32 v64, v68, v69
	v_cvt_pk_bf16_f32 v65, v70, v71
	v_cvt_pk_bf16_f32 v66, v72, v73
	v_cvt_pk_bf16_f32 v67, v74, v75
	global_store_dwordx4 v[82:83], v[64:67], off sc1
	s_nop 0
	s_waitcnt vmcnt(7)
	v_cvt_f32_u32_e32 v64, v191
	v_cvt_f32_u32_e32 v66, v190
	v_add_u32_e32 v65, 0x80, v144
	v_fmamk_f32 v64, v66, 0x2f800000, v64
	v_fmamk_f32 v64, v64, 0x3a800000, v158
	v_rsq_f32_e32 v64, v64
	v_mad_i64_i32 v[66:67], s[54:55], v65, s67, v[146:147]
	v_lshl_add_u64 v[66:67], v[66:67], 0, v[148:149]
	v_mul_f32_e32 v190, 0xbfb8aa3b, v64
	v_mul_f32_e32 v191, v64, v64
	v_pk_mul_f32 v[64:65], v[60:61], v[190:191] op_sel_hi:[1,0]
	v_pk_mul_f32 v[68:69], v[62:63], v[190:191] op_sel_hi:[1,0]
	v_pk_mul_f32 v[70:71], v[56:57], v[190:191] op_sel_hi:[1,0]
	v_pk_mul_f32 v[72:73], v[58:59], v[190:191] op_sel_hi:[1,0]
	v_pk_mul_f32 v[52:53], v[52:53], v[60:61]
	v_pk_mul_f32 v[54:55], v[54:55], v[62:63]
	v_pk_mul_f32 v[56:57], v[48:49], v[56:57]
	v_pk_mul_f32 v[58:59], v[50:51], v[58:59]
	v_exp_f32_e32 v64, v64
	v_exp_f32_e32 v65, v65
	v_exp_f32_e32 v68, v68
	v_exp_f32_e32 v69, v69
	v_exp_f32_e32 v70, v70
	v_exp_f32_e32 v71, v71
	v_exp_f32_e32 v72, v72
	v_exp_f32_e32 v73, v73
	v_pk_mul_f32 v[52:53], v[52:53], v[190:191] op_sel:[0,1] op_sel_hi:[1,1]
	v_pk_mul_f32 v[54:55], v[54:55], v[190:191] op_sel:[0,1] op_sel_hi:[1,1]
	v_pk_mul_f32 v[56:57], v[56:57], v[190:191] op_sel:[0,1] op_sel_hi:[1,1]
	v_pk_mul_f32 v[58:59], v[58:59], v[190:191] op_sel:[0,1] op_sel_hi:[1,1]
	v_pk_add_f32 v[64:65], v[64:65], 1.0 op_sel_hi:[1,0]
	v_pk_add_f32 v[68:69], v[68:69], 1.0 op_sel_hi:[1,0]
	v_pk_add_f32 v[70:71], v[70:71], 1.0 op_sel_hi:[1,0]
	v_pk_add_f32 v[72:73], v[72:73], 1.0 op_sel_hi:[1,0]
	v_rcp_f32_e32 v64, v64
	v_rcp_f32_e32 v65, v65
	v_rcp_f32_e32 v68, v68
	v_rcp_f32_e32 v69, v69
	v_rcp_f32_e32 v70, v70
	v_rcp_f32_e32 v71, v71
	v_rcp_f32_e32 v72, v72
	v_rcp_f32_e32 v73, v73
	v_pk_mul_f32 v[52:53], v[52:53], v[64:65]
	v_pk_mul_f32 v[54:55], v[54:55], v[68:69]
	v_pk_mul_f32 v[56:57], v[56:57], v[70:71]
	v_pk_mul_f32 v[58:59], v[58:59], v[72:73]
	v_cvt_pk_bf16_f32 v48, v52, v53
	v_cvt_pk_bf16_f32 v49, v54, v55
	v_cvt_pk_bf16_f32 v50, v56, v57
	v_cvt_pk_bf16_f32 v51, v58, v59
	global_store_dwordx4 v[66:67], v[48:51], off sc1
	s_nop 0
	s_waitcnt vmcnt(7)
; __device__ __forceinline__ unsigned cvtpk(float lo, float hi) { f32x2v_ v = {lo, hi}; bf16x2v_ b = __builtin_convertvector(v, bf16x2v_); return __builtin_bit_cast(unsigned, b); }
;     __device__ __forceinline__ void operator()(const f32x4 (&acc)[2][2][4][2], const Unit& u, int wr, int wc, int fr, int fq) const {
;     ...
;             for (int m = 0; m < 4; ++m) { const int row = row0 + ai * HALF + m * 16; const float rs = row_rs(ss, row);
;                 float hv[8];
; #pragma unroll
;                 for (int n = 0; n < 2; ++n)
; #pragma unroll
;                     for (int i = 0; i < 4; ++i) { const float g = acc[ai][0][m][n][i] * rs, uu = acc[ai][1][m][n][i] * rs;
;                         hv[n * 4 + i] = g * __builtin_amdgcn_rcpf(1.0f + __expf(-g)) * uu; }
;                 u32x4 w; w.x = cvtpk(hv[0], hv[1]); w.y = cvtpk(hv[2], hv[3]); w.z = cvtpk(hv[4], hv[5]); w.w = cvtpk(hv[6], hv[7]);
;                 *(u32x4*)(H + (size_t)row * ldh + col0) = w; }
	v_cvt_f32_u32_e32 v48, v193
	v_cvt_f32_u32_e32 v50, v192
	v_add_u32_e32 v49, 0x90, v144
	v_fmamk_f32 v48, v50, 0x2f800000, v48
	v_fmamk_f32 v48, v48, 0x3a800000, v158
	v_rsq_f32_e32 v48, v48
	v_mad_i64_i32 v[50:51], s[54:55], v49, s67, v[146:147]
	v_lshl_add_u64 v[50:51], v[50:51], 0, v[148:149]
	v_mul_f32_e32 v192, 0xbfb8aa3b, v48
	v_mul_f32_e32 v193, v48, v48
	v_pk_mul_f32 v[48:49], v[44:45], v[192:193] op_sel_hi:[1,0]
	v_pk_mul_f32 v[52:53], v[46:47], v[192:193] op_sel_hi:[1,0]
	v_pk_mul_f32 v[54:55], v[40:41], v[192:193] op_sel_hi:[1,0]
	v_pk_mul_f32 v[56:57], v[42:43], v[192:193] op_sel_hi:[1,0]
	v_pk_mul_f32 v[36:37], v[36:37], v[44:45]
	v_pk_mul_f32 v[38:39], v[38:39], v[46:47]
	v_pk_mul_f32 v[40:41], v[32:33], v[40:41]
	v_pk_mul_f32 v[42:43], v[34:35], v[42:43]
	v_exp_f32_e32 v48, v48
	v_exp_f32_e32 v49, v49
	v_exp_f32_e32 v52, v52
	v_exp_f32_e32 v53, v53
	v_exp_f32_e32 v54, v54
	v_exp_f32_e32 v55, v55
	v_exp_f32_e32 v56, v56
	v_exp_f32_e32 v57, v57
	v_pk_mul_f32 v[36:37], v[36:37], v[192:193] op_sel:[0,1] op_sel_hi:[1,1]
	v_pk_mul_f32 v[38:39], v[38:39], v[192:193] op_sel:[0,1] op_sel_hi:[1,1]
	v_pk_mul_f32 v[40:41], v[40:41], v[192:193] op_sel:[0,1] op_sel_hi:[1,1]
	v_pk_mul_f32 v[42:43], v[42:43], v[192:193] op_sel:[0,1] op_sel_hi:[1,1]
	v_pk_add_f32 v[48:49], v[48:49], 1.0 op_sel_hi:[1,0]
	v_pk_add_f32 v[52:53], v[52:53], 1.0 op_sel_hi:[1,0]
	v_pk_add_f32 v[54:55], v[54:55], 1.0 op_sel_hi:[1,0]
	v_pk_add_f32 v[56:57], v[56:57], 1.0 op_sel_hi:[1,0]
	v_rcp_f32_e32 v48, v48
	v_rcp_f32_e32 v49, v49
	v_rcp_f32_e32 v52, v52
	v_rcp_f32_e32 v53, v53
	v_rcp_f32_e32 v54, v54
	v_rcp_f32_e32 v55, v55
	v_rcp_f32_e32 v56, v56
	v_rcp_f32_e32 v57, v57
	v_pk_mul_f32 v[36:37], v[36:37], v[48:49]
	v_pk_mul_f32 v[38:39], v[38:39], v[52:53]
	v_pk_mul_f32 v[40:41], v[40:41], v[54:55]
	v_pk_mul_f32 v[42:43], v[42:43], v[56:57]
	v_cvt_pk_bf16_f32 v32, v36, v37
	v_cvt_pk_bf16_f32 v33, v38, v39
	v_cvt_pk_bf16_f32 v34, v40, v41
	v_cvt_pk_bf16_f32 v35, v42, v43
	global_store_dwordx4 v[50:51], v[32:35], off sc1
	s_nop 0
	s_waitcnt vmcnt(7)
	v_cvt_f32_u32_e32 v32, v195
	v_cvt_f32_u32_e32 v34, v194
	v_add_u32_e32 v33, 0xa0, v144
	v_fmamk_f32 v32, v34, 0x2f800000, v32
	v_fmamk_f32 v32, v32, 0x3a800000, v158
	v_rsq_f32_e32 v32, v32
	v_mad_i64_i32 v[34:35], s[54:55], v33, s67, v[146:147]
	v_lshl_add_u64 v[34:35], v[34:35], 0, v[148:149]
	v_mul_f32_e32 v194, 0xbfb8aa3b, v32
	v_mul_f32_e32 v195, v32, v32
	v_pk_mul_f32 v[32:33], v[28:29], v[194:195] op_sel_hi:[1,0]
	v_pk_mul_f32 v[36:37], v[30:31], v[194:195] op_sel_hi:[1,0]
	v_pk_mul_f32 v[38:39], v[24:25], v[194:195] op_sel_hi:[1,0]
	v_pk_mul_f32 v[40:41], v[26:27], v[194:195] op_sel_hi:[1,0]
	v_pk_mul_f32 v[20:21], v[20:21], v[28:29]
	v_pk_mul_f32 v[22:23], v[22:23], v[30:31]
	v_pk_mul_f32 v[24:25], v[16:17], v[24:25]
	v_pk_mul_f32 v[26:27], v[18:19], v[26:27]
	v_exp_f32_e32 v32, v32
	v_exp_f32_e32 v33, v33
	v_exp_f32_e32 v36, v36
	v_exp_f32_e32 v37, v37
	v_exp_f32_e32 v38, v38
	v_exp_f32_e32 v39, v39
	v_exp_f32_e32 v40, v40
	v_exp_f32_e32 v41, v41
	v_pk_mul_f32 v[20:21], v[20:21], v[194:195] op_sel:[0,1] op_sel_hi:[1,1]
	v_pk_mul_f32 v[22:23], v[22:23], v[194:195] op_sel:[0,1] op_sel_hi:[1,1]
	v_pk_mul_f32 v[24:25], v[24:25], v[194:195] op_sel:[0,1] op_sel_hi:[1,1]
	v_pk_mul_f32 v[26:27], v[26:27], v[194:195] op_sel:[0,1] op_sel_hi:[1,1]
	v_pk_add_f32 v[32:33], v[32:33], 1.0 op_sel_hi:[1,0]
	v_pk_add_f32 v[36:37], v[36:37], 1.0 op_sel_hi:[1,0]
	v_pk_add_f32 v[38:39], v[38:39], 1.0 op_sel_hi:[1,0]
	v_pk_add_f32 v[40:41], v[40:41], 1.0 op_sel_hi:[1,0]
	v_rcp_f32_e32 v32, v32
	v_rcp_f32_e32 v33, v33
	v_rcp_f32_e32 v36, v36
	v_rcp_f32_e32 v37, v37
	v_rcp_f32_e32 v38, v38
	v_rcp_f32_e32 v39, v39
	v_rcp_f32_e32 v40, v40
	v_rcp_f32_e32 v41, v41
	v_pk_mul_f32 v[20:21], v[20:21], v[32:33]
	v_pk_mul_f32 v[22:23], v[22:23], v[36:37]
	v_pk_mul_f32 v[24:25], v[24:25], v[38:39]
	v_pk_mul_f32 v[26:27], v[26:27], v[40:41]
	v_cvt_pk_bf16_f32 v16, v20, v21
	v_cvt_pk_bf16_f32 v17, v22, v23
	v_cvt_pk_bf16_f32 v18, v24, v25
	v_cvt_pk_bf16_f32 v19, v26, v27
	global_store_dwordx4 v[34:35], v[16:19], off sc1
	s_nop 0
	s_waitcnt vmcnt(7)
	v_cvt_f32_u32_e32 v16, v197
	v_cvt_f32_u32_e32 v18, v196
	v_add_u32_e32 v17, 0xb0, v144
	v_fmamk_f32 v16, v18, 0x2f800000, v16
	v_fmamk_f32 v16, v16, 0x3a800000, v158
	v_rsq_f32_e32 v16, v16
	v_mad_i64_i32 v[18:19], s[54:55], v17, s67, v[146:147]
	v_lshl_add_u64 v[18:19], v[18:19], 0, v[148:149]
	v_mul_f32_e32 v196, 0xbfb8aa3b, v16
	v_mul_f32_e32 v197, v16, v16
	v_pk_mul_f32 v[16:17], v[12:13], v[196:197] op_sel_hi:[1,0]
	v_pk_mul_f32 v[20:21], v[14:15], v[196:197] op_sel_hi:[1,0]
	v_pk_mul_f32 v[22:23], v[8:9], v[196:197] op_sel_hi:[1,0]
	v_pk_mul_f32 v[24:25], v[10:11], v[196:197] op_sel_hi:[1,0]
	v_pk_mul_f32 v[4:5], v[4:5], v[12:13]
	v_pk_mul_f32 v[6:7], v[6:7], v[14:15]
	v_pk_mul_f32 v[8:9], v[0:1], v[8:9]
	v_pk_mul_f32 v[10:11], v[2:3], v[10:11]
	v_exp_f32_e32 v16, v16
	v_exp_f32_e32 v17, v17
	v_exp_f32_e32 v20, v20
	v_exp_f32_e32 v21, v21
	v_exp_f32_e32 v22, v22
	v_exp_f32_e32 v23, v23
	v_exp_f32_e32 v24, v24
	v_exp_f32_e32 v25, v25
	v_pk_mul_f32 v[4:5], v[4:5], v[196:197] op_sel:[0,1] op_sel_hi:[1,1]
	v_pk_mul_f32 v[6:7], v[6:7], v[196:197] op_sel:[0,1] op_sel_hi:[1,1]
	v_pk_mul_f32 v[8:9], v[8:9], v[196:197] op_sel:[0,1] op_sel_hi:[1,1]
	v_pk_mul_f32 v[10:11], v[10:11], v[196:197] op_sel:[0,1] op_sel_hi:[1,1]
	v_pk_add_f32 v[16:17], v[16:17], 1.0 op_sel_hi:[1,0]
	v_pk_add_f32 v[20:21], v[20:21], 1.0 op_sel_hi:[1,0]
	v_pk_add_f32 v[22:23], v[22:23], 1.0 op_sel_hi:[1,0]
	v_pk_add_f32 v[24:25], v[24:25], 1.0 op_sel_hi:[1,0]
	v_rcp_f32_e32 v16, v16
	v_rcp_f32_e32 v17, v17
	v_rcp_f32_e32 v20, v20
	v_rcp_f32_e32 v21, v21
	v_rcp_f32_e32 v22, v22
	v_rcp_f32_e32 v23, v23
	v_rcp_f32_e32 v24, v24
	v_rcp_f32_e32 v25, v25
	v_pk_mul_f32 v[4:5], v[4:5], v[16:17]
	v_pk_mul_f32 v[6:7], v[6:7], v[20:21]
	v_pk_mul_f32 v[8:9], v[8:9], v[22:23]
	v_pk_mul_f32 v[10:11], v[10:11], v[24:25]
	v_cvt_pk_bf16_f32 v0, v4, v5
	v_cvt_pk_bf16_f32 v1, v6, v7
	v_cvt_pk_bf16_f32 v2, v8, v9
	v_cvt_pk_bf16_f32 v3, v10, v11
	global_store_dwordx4 v[18:19], v[0:3], off sc1
	s_cbranch_vccnz .LBB0_953
	s_andn2_b64 vcc, exec, s[12:13]
	s_cbranch_vccnz .LBB0_952
	s_barrier
	s_branch .LBB0_952

; __device__ __forceinline__ void fx_add(float* p, size_t idx, float s) { atomicAdd((unsigned long long*)p + idx, (unsigned long long)(long long)(s * 4294967296.0f)); }
; __device__ __forceinline__ unsigned cvtpk(float lo, float hi) { f32x2v_ v = {lo, hi}; bf16x2v_ b = __builtin_convertvector(v, bf16x2v_); return __builtin_bit_cast(unsigned, b); }
;     __device__ __forceinline__ void operator()(const f32x4 (&acc)[2][2][4][2], const Unit& u, int wr, int wc, int fr, int fq) const {
;     ...
;             for (int m = 0; m < 4; ++m) { const int row = row0 + ai * HALF + m * 16; const size_t off = (size_t)row * 1024 + col0; float s = 0.f;
; #pragma unroll
;                 for (int bj = 0; bj < 2; ++bj) { f32x4 a0, a1;
;                     if (xin32) { const float* p = xin32 + off + bj * HALF; a0 = *(const f32x4*)p; a1 = *(const f32x4*)(p + 4); }
;                     else { const u32x4 w = *(const u32x4*)(xb + off + bj * HALF);
;                         a0 = (f32x4){__uint_as_float(w.x << 16), __uint_as_float(w.x & 0xffff0000u), __uint_as_float(w.y << 16), __uint_as_float(w.y & 0xffff0000u)};
;                         a1 = (f32x4){__uint_as_float(w.z << 16), __uint_as_float(w.z & 0xffff0000u), __uint_as_float(w.w << 16), __uint_as_float(w.w & 0xffff0000u)}; }
;                     const f32x4 v0 = a0 + acc[ai][bj][m][0] * alpha, v1 = a1 + acc[ai][bj][m][1] * alpha;
;                     u32x4 w; w.x = cvtpk(v0[0], v0[1]); w.y = cvtpk(v0[2], v0[3]); w.z = cvtpk(v1[0], v1[1]); w.w = cvtpk(v1[2], v1[3]);
;                     *(u32x4*)(xb + off + bj * HALF) = w;
;                     s += (v0[0] * v0[0] + v0[1] * v0[1]) + (v0[2] * v0[2] + v0[3] * v0[3]) + (v1[0] * v1[0] + v1[1] * v1[1]) + (v1[2] * v1[2] + v1[3] * v1[3]); }
;                 s += __shfl_xor(s, 16); s += __shfl_xor(s, 32);
;                 if (fq == 0) fx_add(ssout, row, s); }
.LBB0_1038:
	v_lshl_add_u32 v146, s74, 8, v148
	v_ashrrev_i32_e32 v147, 31, v146
	v_lshl_or_b32 v144, s67, 8, v150
	v_lshlrev_b64 v[156:157], 11, v[146:147]
	v_ashrrev_i32_e32 v145, 31, v144
	v_lshl_add_u64 v[156:157], s[22:23], 0, v[156:157]
	v_lshl_add_u64 v[166:167], v[144:145], 1, v[156:157]
	global_load_dwordx4 v[158:161], v[166:167], off
	global_load_dwordx4 v[162:165], v[166:167], off offset:256
	v_and_b32_e32 v156, 64, v154
	v_xor_b32_e32 v155, 16, v154
	v_add_u32_e32 v156, 64, v156
	v_xor_b32_e32 v157, 32, v154
	v_cmp_lt_i32_e32 vcc, v155, v156
	s_waitcnt vmcnt(0)
	v_lshlrev_b32_e32 v168, 16, v158
	v_cndmask_b32_e32 v155, v154, v155, vcc
	v_cmp_lt_i32_e32 vcc, v157, v156
	v_and_b32_e32 v169, 0xffff0000, v158
	v_lshlrev_b32_e32 v158, 16, v159
	v_and_b32_e32 v159, 0xffff0000, v159
	v_lshlrev_b32_e32 v172, 16, v162
	v_and_b32_e32 v173, 0xffff0000, v162
	v_lshlrev_b32_e32 v162, 16, v163
	v_and_b32_e32 v163, 0xffff0000, v163
	v_cndmask_b32_e32 v157, v154, v157, vcc
	v_lshlrev_b32_e32 v170, 16, v160
	v_and_b32_e32 v171, 0xffff0000, v160
	v_lshlrev_b32_e32 v160, 16, v161
	v_and_b32_e32 v161, 0xffff0000, v161
	v_lshlrev_b32_e32 v174, 16, v164
	v_and_b32_e32 v175, 0xffff0000, v164
	v_lshlrev_b32_e32 v164, 16, v165
	v_and_b32_e32 v165, 0xffff0000, v165
	v_pk_fma_f32 v[126:127], v[126:127], 0.5, v[158:159] op_sel_hi:[1,0,1]
	v_pk_fma_f32 v[124:125], v[124:125], 0.5, v[168:169] op_sel_hi:[1,0,1]
	v_pk_fma_f32 v[118:119], v[118:119], 0.5, v[162:163] op_sel_hi:[1,0,1]
	v_pk_fma_f32 v[116:117], v[116:117], 0.5, v[172:173] op_sel_hi:[1,0,1]
	v_lshlrev_b32_e32 v156, 2, v155
	v_lshlrev_b32_e32 v155, 2, v157
	v_pk_fma_f32 v[122:123], v[122:123], 0.5, v[160:161] op_sel_hi:[1,0,1]
	v_pk_fma_f32 v[120:121], v[120:121], 0.5, v[170:171] op_sel_hi:[1,0,1]
	v_pk_fma_f32 v[158:159], v[114:115], 0.5, v[164:165] op_sel_hi:[1,0,1]
	v_pk_fma_f32 v[160:161], v[112:113], 0.5, v[174:175] op_sel_hi:[1,0,1]
	v_mul_f32_e32 v114, v125, v125
	v_mul_f32_e32 v115, v127, v127
	v_mul_f32_e32 v157, v117, v117
	v_mul_f32_e32 v162, v119, v119
	v_cvt_pk_bf16_f32 v112, v124, v125
	v_mul_f32_e32 v125, v121, v121
	v_mul_f32_e32 v163, v161, v161
	v_fmac_f32_e32 v114, v124, v124
	v_fmac_f32_e32 v115, v126, v126
	v_fmac_f32_e32 v157, v116, v116
	v_fmac_f32_e32 v162, v118, v118
	v_cvt_pk_bf16_f32 v113, v126, v127
	v_mul_f32_e32 v127, v123, v123
	v_mul_f32_e32 v164, v159, v159
	v_fmac_f32_e32 v125, v120, v120
	v_fmac_f32_e32 v163, v160, v160
	v_add_f32_e32 v114, v114, v115
	v_add_f32_e32 v115, v157, v162
	v_fmac_f32_e32 v127, v122, v122
	v_fmac_f32_e32 v164, v158, v158
	v_add_f32_e32 v114, v125, v114
	v_add_f32_e32 v115, v163, v115
	v_add_f32_e32 v114, v127, v114
	v_add_f32_e32 v115, v164, v115
	v_add_f32_e32 v124, v114, v115
	v_mov_b32_e32 v125, v124
	s_nop 1
	v_permlane16_swap_b32_e32 v125, v124
	v_cvt_pk_bf16_f32 v114, v120, v121
	v_cvt_pk_bf16_f32 v115, v122, v123
	global_store_dwordx4 v[166:167], v[112:115], off sc1
	s_waitcnt lgkmcnt(0)
	s_nop 0
	v_add_f32_e32 v112, v124, v125
	v_mov_b32_e32 v113, v112
	s_nop 1
	v_permlane32_swap_b32_e32 v113, v112
	v_cvt_pk_bf16_f32 v114, v116, v117
	v_cvt_pk_bf16_f32 v115, v118, v119
	v_cvt_pk_bf16_f32 v116, v160, v161
	v_cvt_pk_bf16_f32 v117, v158, v159
	global_store_dwordx4 v[166:167], v[114:117], off offset:256 sc1
	s_and_saveexec_b64 s[50:51], s[10:11]
	s_cbranch_execz .LBB0_1040
	s_waitcnt lgkmcnt(0)
	v_add_f32_e32 v112, v112, v113
	v_mul_f32_e32 v112, 0x4f800000, v112
	v_trunc_f32_e32 v112, v112
	v_mul_f32_e64 v113, |v112|, s63
	v_floor_f32_e32 v113, v113
	v_fma_f32 v114, v113, s64, |v112|
	v_cvt_u32_f32_e32 v112, v114
	v_cvt_u32_f32_e32 v113, v113
	v_lshl_add_u64 v[114:115], v[146:147], 3, s[36:37]
	global_atomic_add_x2 v[114:115], v[112:113], off
.LBB0_1040:
	s_or_b64 exec, exec, s[50:51]
	v_or_b32_e32 v112, 16, v146
	s_waitcnt lgkmcnt(0)
	v_ashrrev_i32_e32 v113, 31, v112
	v_lshlrev_b64 v[114:115], 11, v[112:113]
	v_lshl_add_u64 v[114:115], s[22:23], 0, v[114:115]
	v_lshl_add_u64 v[122:123], v[144:145], 1, v[114:115]
	global_load_dwordx4 v[114:117], v[122:123], off
	global_load_dwordx4 v[118:121], v[122:123], off offset:256
	s_waitcnt vmcnt(1)
	v_lshlrev_b32_e32 v124, 16, v114
	v_and_b32_e32 v125, 0xffff0000, v114
	v_lshlrev_b32_e32 v114, 16, v115
	v_and_b32_e32 v115, 0xffff0000, v115
	s_waitcnt vmcnt(0)
	v_lshlrev_b32_e32 v158, 16, v118
	v_and_b32_e32 v159, 0xffff0000, v118
	v_lshlrev_b32_e32 v118, 16, v119
	v_and_b32_e32 v119, 0xffff0000, v119
	v_lshlrev_b32_e32 v126, 16, v116
	v_and_b32_e32 v127, 0xffff0000, v116
	v_lshlrev_b32_e32 v116, 16, v117
	v_and_b32_e32 v117, 0xffff0000, v117
	v_lshlrev_b32_e32 v160, 16, v120
	v_and_b32_e32 v161, 0xffff0000, v120
	v_lshlrev_b32_e32 v120, 16, v121
	v_and_b32_e32 v121, 0xffff0000, v121
	v_pk_fma_f32 v[110:111], v[110:111], 0.5, v[114:115] op_sel_hi:[1,0,1]
	v_pk_fma_f32 v[108:109], v[108:109], 0.5, v[124:125] op_sel_hi:[1,0,1]
	v_pk_fma_f32 v[102:103], v[102:103], 0.5, v[118:119] op_sel_hi:[1,0,1]
	v_pk_fma_f32 v[100:101], v[100:101], 0.5, v[158:159] op_sel_hi:[1,0,1]
	v_pk_fma_f32 v[106:107], v[106:107], 0.5, v[116:117] op_sel_hi:[1,0,1]
	v_pk_fma_f32 v[104:105], v[104:105], 0.5, v[126:127] op_sel_hi:[1,0,1]
	v_pk_fma_f32 v[114:115], v[98:99], 0.5, v[120:121] op_sel_hi:[1,0,1]
	v_pk_fma_f32 v[116:117], v[96:97], 0.5, v[160:161] op_sel_hi:[1,0,1]
	v_mul_f32_e32 v98, v109, v109
	v_mul_f32_e32 v99, v111, v111
	v_mul_f32_e32 v118, v101, v101
	v_mul_f32_e32 v119, v103, v103
	v_cvt_pk_bf16_f32 v96, v108, v109
	v_mul_f32_e32 v109, v105, v105
	v_mul_f32_e32 v120, v117, v117
	v_fmac_f32_e32 v98, v108, v108
	v_fmac_f32_e32 v99, v110, v110
	v_fmac_f32_e32 v118, v100, v100
	v_fmac_f32_e32 v119, v102, v102
	v_cvt_pk_bf16_f32 v97, v110, v111
	v_mul_f32_e32 v111, v107, v107
	v_mul_f32_e32 v121, v115, v115
	v_fmac_f32_e32 v109, v104, v104
	v_fmac_f32_e32 v120, v116, v116
	v_add_f32_e32 v98, v98, v99
	v_add_f32_e32 v99, v118, v119
	v_fmac_f32_e32 v111, v106, v106
	v_fmac_f32_e32 v121, v114, v114
	v_add_f32_e32 v98, v109, v98
	v_add_f32_e32 v99, v120, v99
	v_add_f32_e32 v98, v111, v98
	v_add_f32_e32 v99, v121, v99
	v_add_f32_e32 v108, v98, v99
	v_mov_b32_e32 v109, v108
	s_nop 1
	v_permlane16_swap_b32_e32 v109, v108
	v_cvt_pk_bf16_f32 v98, v104, v105
	v_cvt_pk_bf16_f32 v99, v106, v107
	global_store_dwordx4 v[122:123], v[96:99], off sc1
	s_waitcnt lgkmcnt(0)
	s_nop 0
	v_add_f32_e32 v96, v108, v109
	v_mov_b32_e32 v97, v96
	s_nop 1
	v_permlane32_swap_b32_e32 v97, v96
	v_cvt_pk_bf16_f32 v98, v100, v101
	v_cvt_pk_bf16_f32 v99, v102, v103
	v_cvt_pk_bf16_f32 v100, v116, v117
	v_cvt_pk_bf16_f32 v101, v114, v115
	global_store_dwordx4 v[122:123], v[98:101], off offset:256 sc1
	s_and_saveexec_b64 s[50:51], s[10:11]
	s_cbranch_execz .LBB0_1042
	s_waitcnt lgkmcnt(0)
	v_add_f32_e32 v96, v96, v97
	v_mul_f32_e32 v96, 0x4f800000, v96
	v_trunc_f32_e32 v96, v96
	v_mul_f32_e64 v97, |v96|, s63
	v_floor_f32_e32 v97, v97
	v_fma_f32 v98, v97, s64, |v96|
	v_cvt_u32_f32_e32 v96, v98
	v_cvt_u32_f32_e32 v97, v97
	v_lshl_add_u64 v[98:99], v[112:113], 3, s[36:37]
	global_atomic_add_x2 v[98:99], v[96:97], off
; __device__ __forceinline__ void fx_add(float* p, size_t idx, float s) { atomicAdd((unsigned long long*)p + idx, (unsigned long long)(long long)(s * 4294967296.0f)); }
; __device__ __forceinline__ unsigned cvtpk(float lo, float hi) { f32x2v_ v = {lo, hi}; bf16x2v_ b = __builtin_convertvector(v, bf16x2v_); return __builtin_bit_cast(unsigned, b); }
;     __device__ __forceinline__ void operator()(const f32x4 (&acc)[2][2][4][2], const Unit& u, int wr, int wc, int fr, int fq) const {
;     ...
;             for (int m = 0; m < 4; ++m) { const int row = row0 + ai * HALF + m * 16; const size_t off = (size_t)row * 1024 + col0; float s = 0.f;
; #pragma unroll
;                 for (int bj = 0; bj < 2; ++bj) { f32x4 a0, a1;
;                     if (xin32) { const float* p = xin32 + off + bj * HALF; a0 = *(const f32x4*)p; a1 = *(const f32x4*)(p + 4); }
;                     else { const u32x4 w = *(const u32x4*)(xb + off + bj * HALF);
;                         a0 = (f32x4){__uint_as_float(w.x << 16), __uint_as_float(w.x & 0xffff0000u), __uint_as_float(w.y << 16), __uint_as_float(w.y & 0xffff0000u)};
;                         a1 = (f32x4){__uint_as_float(w.z << 16), __uint_as_float(w.z & 0xffff0000u), __uint_as_float(w.w << 16), __uint_as_float(w.w & 0xffff0000u)}; }
;                     const f32x4 v0 = a0 + acc[ai][bj][m][0] * alpha, v1 = a1 + acc[ai][bj][m][1] * alpha;
;                     u32x4 w; w.x = cvtpk(v0[0], v0[1]); w.y = cvtpk(v0[2], v0[3]); w.z = cvtpk(v1[0], v1[1]); w.w = cvtpk(v1[2], v1[3]);
;                     *(u32x4*)(xb + off + bj * HALF) = w;
;                     s += (v0[0] * v0[0] + v0[1] * v0[1]) + (v0[2] * v0[2] + v0[3] * v0[3]) + (v1[0] * v1[0] + v1[1] * v1[1]) + (v1[2] * v1[2] + v1[3] * v1[3]); }
;                 s += __shfl_xor(s, 16); s += __shfl_xor(s, 32);
;                 if (fq == 0) fx_add(ssout, row, s); }
.LBB0_1042:
	s_or_b64 exec, exec, s[50:51]
	v_or_b32_e32 v96, 32, v146
	s_waitcnt lgkmcnt(0)
	v_ashrrev_i32_e32 v97, 31, v96
	v_lshlrev_b64 v[98:99], 11, v[96:97]
	v_lshl_add_u64 v[98:99], s[22:23], 0, v[98:99]
	v_lshl_add_u64 v[106:107], v[144:145], 1, v[98:99]
	global_load_dwordx4 v[98:101], v[106:107], off
	global_load_dwordx4 v[102:105], v[106:107], off offset:256
	s_waitcnt vmcnt(1)
	v_lshlrev_b32_e32 v108, 16, v98
	v_and_b32_e32 v109, 0xffff0000, v98
	v_lshlrev_b32_e32 v98, 16, v99
	v_and_b32_e32 v99, 0xffff0000, v99
	s_waitcnt vmcnt(0)
	v_lshlrev_b32_e32 v112, 16, v102
	v_and_b32_e32 v113, 0xffff0000, v102
	v_lshlrev_b32_e32 v102, 16, v103
	v_and_b32_e32 v103, 0xffff0000, v103
	v_lshlrev_b32_e32 v110, 16, v100
	v_and_b32_e32 v111, 0xffff0000, v100
	v_lshlrev_b32_e32 v100, 16, v101
	v_and_b32_e32 v101, 0xffff0000, v101
	v_lshlrev_b32_e32 v114, 16, v104
	v_and_b32_e32 v115, 0xffff0000, v104
	v_lshlrev_b32_e32 v104, 16, v105
	v_and_b32_e32 v105, 0xffff0000, v105
	v_pk_fma_f32 v[94:95], v[94:95], 0.5, v[98:99] op_sel_hi:[1,0,1]
	v_pk_fma_f32 v[92:93], v[92:93], 0.5, v[108:109] op_sel_hi:[1,0,1]
	v_pk_fma_f32 v[86:87], v[86:87], 0.5, v[102:103] op_sel_hi:[1,0,1]
	v_pk_fma_f32 v[84:85], v[84:85], 0.5, v[112:113] op_sel_hi:[1,0,1]
	v_pk_fma_f32 v[90:91], v[90:91], 0.5, v[100:101] op_sel_hi:[1,0,1]
	v_pk_fma_f32 v[88:89], v[88:89], 0.5, v[110:111] op_sel_hi:[1,0,1]
	v_pk_fma_f32 v[98:99], v[82:83], 0.5, v[104:105] op_sel_hi:[1,0,1]
	v_pk_fma_f32 v[100:101], v[80:81], 0.5, v[114:115] op_sel_hi:[1,0,1]
	v_mul_f32_e32 v82, v93, v93
	v_mul_f32_e32 v83, v95, v95
	v_mul_f32_e32 v102, v85, v85
	v_mul_f32_e32 v103, v87, v87
	v_cvt_pk_bf16_f32 v80, v92, v93
	v_mul_f32_e32 v93, v89, v89
	v_mul_f32_e32 v104, v101, v101
	v_fmac_f32_e32 v82, v92, v92
	v_fmac_f32_e32 v83, v94, v94
	v_fmac_f32_e32 v102, v84, v84
	v_fmac_f32_e32 v103, v86, v86
	v_cvt_pk_bf16_f32 v81, v94, v95
	v_mul_f32_e32 v95, v91, v91
	v_mul_f32_e32 v105, v99, v99
	v_fmac_f32_e32 v93, v88, v88
	v_fmac_f32_e32 v104, v100, v100
	v_add_f32_e32 v82, v82, v83
	v_add_f32_e32 v83, v102, v103
	v_fmac_f32_e32 v95, v90, v90
	v_fmac_f32_e32 v105, v98, v98
	v_add_f32_e32 v82, v93, v82
	v_add_f32_e32 v83, v104, v83
	v_add_f32_e32 v82, v95, v82
	v_add_f32_e32 v83, v105, v83
	v_add_f32_e32 v92, v82, v83
	v_mov_b32_e32 v93, v92
	s_nop 1
	v_permlane16_swap_b32_e32 v93, v92
	v_cvt_pk_bf16_f32 v82, v88, v89
	v_cvt_pk_bf16_f32 v83, v90, v91
	global_store_dwordx4 v[106:107], v[80:83], off sc1
	s_waitcnt lgkmcnt(0)
	s_nop 0
	v_add_f32_e32 v80, v92, v93
	v_mov_b32_e32 v81, v80
	s_nop 1
	v_permlane32_swap_b32_e32 v81, v80
	v_cvt_pk_bf16_f32 v82, v84, v85
	v_cvt_pk_bf16_f32 v83, v86, v87
	v_cvt_pk_bf16_f32 v84, v100, v101
	v_cvt_pk_bf16_f32 v85, v98, v99
	global_store_dwordx4 v[106:107], v[82:85], off offset:256 sc1
	s_and_saveexec_b64 s[50:51], s[10:11]
	s_cbranch_execz .LBB0_1044
	s_waitcnt lgkmcnt(0)
	v_add_f32_e32 v80, v80, v81
	v_mul_f32_e32 v80, 0x4f800000, v80
	v_trunc_f32_e32 v80, v80
	v_mul_f32_e64 v81, |v80|, s63
	v_floor_f32_e32 v81, v81
	v_fma_f32 v82, v81, s64, |v80|
	v_cvt_u32_f32_e32 v80, v82
	v_cvt_u32_f32_e32 v81, v81
	v_lshl_add_u64 v[82:83], v[96:97], 3, s[36:37]
	global_atomic_add_x2 v[82:83], v[80:81], off
.LBB0_1044:
	s_or_b64 exec, exec, s[50:51]
	v_or_b32_e32 v80, 48, v146
	s_waitcnt lgkmcnt(0)
	v_ashrrev_i32_e32 v81, 31, v80
	v_lshlrev_b64 v[82:83], 11, v[80:81]
	v_lshl_add_u64 v[82:83], s[22:23], 0, v[82:83]
	v_lshl_add_u64 v[90:91], v[144:145], 1, v[82:83]
	global_load_dwordx4 v[82:85], v[90:91], off
	global_load_dwordx4 v[86:89], v[90:91], off offset:256
	s_waitcnt vmcnt(1)
	v_lshlrev_b32_e32 v92, 16, v82
	v_and_b32_e32 v93, 0xffff0000, v82
	v_lshlrev_b32_e32 v82, 16, v83
	v_and_b32_e32 v83, 0xffff0000, v83
	s_waitcnt vmcnt(0)
	v_lshlrev_b32_e32 v96, 16, v86
	v_and_b32_e32 v97, 0xffff0000, v86
	v_lshlrev_b32_e32 v86, 16, v87
	v_and_b32_e32 v87, 0xffff0000, v87
	v_lshlrev_b32_e32 v94, 16, v84
	v_and_b32_e32 v95, 0xffff0000, v84
	v_lshlrev_b32_e32 v84, 16, v85
	v_and_b32_e32 v85, 0xffff0000, v85
	v_lshlrev_b32_e32 v98, 16, v88
	v_and_b32_e32 v99, 0xffff0000, v88
	v_lshlrev_b32_e32 v88, 16, v89
	v_and_b32_e32 v89, 0xffff0000, v89
	v_pk_fma_f32 v[78:79], v[78:79], 0.5, v[82:83] op_sel_hi:[1,0,1]
	v_pk_fma_f32 v[76:77], v[76:77], 0.5, v[92:93] op_sel_hi:[1,0,1]
	v_pk_fma_f32 v[70:71], v[70:71], 0.5, v[86:87] op_sel_hi:[1,0,1]
	v_pk_fma_f32 v[68:69], v[68:69], 0.5, v[96:97] op_sel_hi:[1,0,1]
	v_pk_fma_f32 v[74:75], v[74:75], 0.5, v[84:85] op_sel_hi:[1,0,1]
	v_pk_fma_f32 v[72:73], v[72:73], 0.5, v[94:95] op_sel_hi:[1,0,1]
	v_pk_fma_f32 v[82:83], v[66:67], 0.5, v[88:89] op_sel_hi:[1,0,1]
	v_pk_fma_f32 v[84:85], v[64:65], 0.5, v[98:99] op_sel_hi:[1,0,1]
	v_mul_f32_e32 v66, v77, v77
	v_mul_f32_e32 v67, v79, v79
	v_mul_f32_e32 v86, v69, v69
	v_mul_f32_e32 v87, v71, v71
	v_cvt_pk_bf16_f32 v64, v76, v77
	v_mul_f32_e32 v77, v73, v73
	v_mul_f32_e32 v88, v85, v85
	v_fmac_f32_e32 v66, v76, v76
	v_fmac_f32_e32 v67, v78, v78
	v_fmac_f32_e32 v86, v68, v68
	v_fmac_f32_e32 v87, v70, v70
	v_cvt_pk_bf16_f32 v65, v78, v79
	v_mul_f32_e32 v79, v75, v75
	v_mul_f32_e32 v89, v83, v83
	v_fmac_f32_e32 v77, v72, v72
	v_fmac_f32_e32 v88, v84, v84
	v_add_f32_e32 v66, v66, v67
	v_add_f32_e32 v67, v86, v87
	v_fmac_f32_e32 v79, v74, v74
	v_fmac_f32_e32 v89, v82, v82
	v_add_f32_e32 v66, v77, v66
	v_add_f32_e32 v67, v88, v67
	v_add_f32_e32 v66, v79, v66
	v_add_f32_e32 v67, v89, v67
	v_add_f32_e32 v76, v66, v67
	v_mov_b32_e32 v77, v76
	s_nop 1
	v_permlane16_swap_b32_e32 v77, v76
	v_cvt_pk_bf16_f32 v66, v72, v73
	v_cvt_pk_bf16_f32 v67, v74, v75
	global_store_dwordx4 v[90:91], v[64:67], off sc1
	s_waitcnt lgkmcnt(0)
	s_nop 0
	v_add_f32_e32 v64, v76, v77
	v_mov_b32_e32 v65, v64
	s_nop 1
	v_permlane32_swap_b32_e32 v65, v64
	v_cvt_pk_bf16_f32 v66, v68, v69
	v_cvt_pk_bf16_f32 v67, v70, v71
	v_cvt_pk_bf16_f32 v68, v84, v85
	v_cvt_pk_bf16_f32 v69, v82, v83
	global_store_dwordx4 v[90:91], v[66:69], off offset:256 sc1
	s_and_saveexec_b64 s[50:51], s[10:11]
	s_cbranch_execz .LBB0_1046
	s_waitcnt lgkmcnt(0)
	v_add_f32_e32 v64, v64, v65
	v_mul_f32_e32 v64, 0x4f800000, v64
	v_trunc_f32_e32 v64, v64
	v_mul_f32_e64 v65, |v64|, s63
	v_floor_f32_e32 v65, v65
	v_fma_f32 v66, v65, s64, |v64|
	v_cvt_u32_f32_e32 v64, v66
	v_cvt_u32_f32_e32 v65, v65
	v_lshl_add_u64 v[66:67], v[80:81], 3, s[36:37]
	global_atomic_add_x2 v[66:67], v[64:65], off
; __device__ __forceinline__ void fx_add(float* p, size_t idx, float s) { atomicAdd((unsigned long long*)p + idx, (unsigned long long)(long long)(s * 4294967296.0f)); }
; __device__ __forceinline__ unsigned cvtpk(float lo, float hi) { f32x2v_ v = {lo, hi}; bf16x2v_ b = __builtin_convertvector(v, bf16x2v_); return __builtin_bit_cast(unsigned, b); }
;     __device__ __forceinline__ void operator()(const f32x4 (&acc)[2][2][4][2], const Unit& u, int wr, int wc, int fr, int fq) const {
;     ...
;             for (int m = 0; m < 4; ++m) { const int row = row0 + ai * HALF + m * 16; const size_t off = (size_t)row * 1024 + col0; float s = 0.f;
; #pragma unroll
;                 for (int bj = 0; bj < 2; ++bj) { f32x4 a0, a1;
;                     if (xin32) { const float* p = xin32 + off + bj * HALF; a0 = *(const f32x4*)p; a1 = *(const f32x4*)(p + 4); }
;                     else { const u32x4 w = *(const u32x4*)(xb + off + bj * HALF);
;                         a0 = (f32x4){__uint_as_float(w.x << 16), __uint_as_float(w.x & 0xffff0000u), __uint_as_float(w.y << 16), __uint_as_float(w.y & 0xffff0000u)};
;                         a1 = (f32x4){__uint_as_float(w.z << 16), __uint_as_float(w.z & 0xffff0000u), __uint_as_float(w.w << 16), __uint_as_float(w.w & 0xffff0000u)}; }
;                     const f32x4 v0 = a0 + acc[ai][bj][m][0] * alpha, v1 = a1 + acc[ai][bj][m][1] * alpha;
;                     u32x4 w; w.x = cvtpk(v0[0], v0[1]); w.y = cvtpk(v0[2], v0[3]); w.z = cvtpk(v1[0], v1[1]); w.w = cvtpk(v1[2], v1[3]);
;                     *(u32x4*)(xb + off + bj * HALF) = w;
;                     s += (v0[0] * v0[0] + v0[1] * v0[1]) + (v0[2] * v0[2] + v0[3] * v0[3]) + (v1[0] * v1[0] + v1[1] * v1[1]) + (v1[2] * v1[2] + v1[3] * v1[3]); }
;                 s += __shfl_xor(s, 16); s += __shfl_xor(s, 32);
;                 if (fq == 0) fx_add(ssout, row, s); }
.LBB0_1046:
	s_or_b64 exec, exec, s[50:51]
	v_add_u32_e32 v64, 0x80, v146
	s_waitcnt lgkmcnt(0)
	v_ashrrev_i32_e32 v65, 31, v64
	v_lshlrev_b64 v[66:67], 11, v[64:65]
	v_lshl_add_u64 v[66:67], s[22:23], 0, v[66:67]
	v_lshl_add_u64 v[74:75], v[144:145], 1, v[66:67]
	global_load_dwordx4 v[66:69], v[74:75], off
	global_load_dwordx4 v[70:73], v[74:75], off offset:256
	s_waitcnt vmcnt(1)
	v_lshlrev_b32_e32 v76, 16, v66
	v_and_b32_e32 v77, 0xffff0000, v66
	v_lshlrev_b32_e32 v66, 16, v67
	v_and_b32_e32 v67, 0xffff0000, v67
	s_waitcnt vmcnt(0)
	v_lshlrev_b32_e32 v80, 16, v70
	v_and_b32_e32 v81, 0xffff0000, v70
	v_lshlrev_b32_e32 v70, 16, v71
	v_and_b32_e32 v71, 0xffff0000, v71
	v_lshlrev_b32_e32 v78, 16, v68
	v_and_b32_e32 v79, 0xffff0000, v68
	v_lshlrev_b32_e32 v68, 16, v69
	v_and_b32_e32 v69, 0xffff0000, v69
	v_lshlrev_b32_e32 v82, 16, v72
	v_and_b32_e32 v83, 0xffff0000, v72
	v_lshlrev_b32_e32 v72, 16, v73
	v_and_b32_e32 v73, 0xffff0000, v73
	v_pk_fma_f32 v[62:63], v[62:63], 0.5, v[66:67] op_sel_hi:[1,0,1]
	v_pk_fma_f32 v[60:61], v[60:61], 0.5, v[76:77] op_sel_hi:[1,0,1]
	v_pk_fma_f32 v[54:55], v[54:55], 0.5, v[70:71] op_sel_hi:[1,0,1]
	v_pk_fma_f32 v[52:53], v[52:53], 0.5, v[80:81] op_sel_hi:[1,0,1]
	v_pk_fma_f32 v[58:59], v[58:59], 0.5, v[68:69] op_sel_hi:[1,0,1]
	v_pk_fma_f32 v[56:57], v[56:57], 0.5, v[78:79] op_sel_hi:[1,0,1]
	v_pk_fma_f32 v[66:67], v[50:51], 0.5, v[72:73] op_sel_hi:[1,0,1]
	v_pk_fma_f32 v[68:69], v[48:49], 0.5, v[82:83] op_sel_hi:[1,0,1]
	v_mul_f32_e32 v50, v61, v61
	v_mul_f32_e32 v51, v63, v63
	v_mul_f32_e32 v70, v53, v53
	v_mul_f32_e32 v71, v55, v55
	v_cvt_pk_bf16_f32 v48, v60, v61
	v_mul_f32_e32 v61, v57, v57
	v_mul_f32_e32 v72, v69, v69
	v_fmac_f32_e32 v50, v60, v60
	v_fmac_f32_e32 v51, v62, v62
	v_fmac_f32_e32 v70, v52, v52
	v_fmac_f32_e32 v71, v54, v54
	v_cvt_pk_bf16_f32 v49, v62, v63
	v_mul_f32_e32 v63, v59, v59
	v_mul_f32_e32 v73, v67, v67
	v_fmac_f32_e32 v61, v56, v56
	v_fmac_f32_e32 v72, v68, v68
	v_add_f32_e32 v50, v50, v51
	v_add_f32_e32 v51, v70, v71
	v_fmac_f32_e32 v63, v58, v58
	v_fmac_f32_e32 v73, v66, v66
	v_add_f32_e32 v50, v61, v50
	v_add_f32_e32 v51, v72, v51
	v_add_f32_e32 v50, v63, v50
	v_add_f32_e32 v51, v73, v51
	v_add_f32_e32 v60, v50, v51
	v_mov_b32_e32 v61, v60
	s_nop 1
	v_permlane16_swap_b32_e32 v61, v60
	v_cvt_pk_bf16_f32 v50, v56, v57
	v_cvt_pk_bf16_f32 v51, v58, v59
	global_store_dwordx4 v[74:75], v[48:51], off sc1
	s_waitcnt lgkmcnt(0)
	s_nop 0
	v_add_f32_e32 v48, v60, v61
	v_mov_b32_e32 v49, v48
	s_nop 1
	v_permlane32_swap_b32_e32 v49, v48
	v_cvt_pk_bf16_f32 v50, v52, v53
	v_cvt_pk_bf16_f32 v51, v54, v55
	v_cvt_pk_bf16_f32 v52, v68, v69
	v_cvt_pk_bf16_f32 v53, v66, v67
	global_store_dwordx4 v[74:75], v[50:53], off offset:256 sc1
	s_and_saveexec_b64 s[50:51], s[10:11]
	s_cbranch_execz .LBB0_1048
	s_waitcnt lgkmcnt(0)
	v_add_f32_e32 v48, v48, v49
	v_mul_f32_e32 v48, 0x4f800000, v48
	v_trunc_f32_e32 v48, v48
	v_mul_f32_e64 v49, |v48|, s63
	v_floor_f32_e32 v49, v49
	v_fma_f32 v50, v49, s64, |v48|
	v_cvt_u32_f32_e32 v48, v50
	v_cvt_u32_f32_e32 v49, v49
	v_lshl_add_u64 v[50:51], v[64:65], 3, s[36:37]
	global_atomic_add_x2 v[50:51], v[48:49], off
.LBB0_1048:
	s_or_b64 exec, exec, s[50:51]
	v_add_u32_e32 v48, 0x90, v146
	s_waitcnt lgkmcnt(0)
	v_ashrrev_i32_e32 v49, 31, v48
	v_lshlrev_b64 v[50:51], 11, v[48:49]
	v_lshl_add_u64 v[50:51], s[22:23], 0, v[50:51]
	v_lshl_add_u64 v[58:59], v[144:145], 1, v[50:51]
	global_load_dwordx4 v[50:53], v[58:59], off
	global_load_dwordx4 v[54:57], v[58:59], off offset:256
	s_waitcnt vmcnt(1)
	v_lshlrev_b32_e32 v60, 16, v50
	v_and_b32_e32 v61, 0xffff0000, v50
	v_lshlrev_b32_e32 v50, 16, v51
	v_and_b32_e32 v51, 0xffff0000, v51
	s_waitcnt vmcnt(0)
	v_lshlrev_b32_e32 v64, 16, v54
	v_and_b32_e32 v65, 0xffff0000, v54
	v_lshlrev_b32_e32 v54, 16, v55
	v_and_b32_e32 v55, 0xffff0000, v55
	v_lshlrev_b32_e32 v62, 16, v52
	v_and_b32_e32 v63, 0xffff0000, v52
	v_lshlrev_b32_e32 v52, 16, v53
	v_and_b32_e32 v53, 0xffff0000, v53
	v_lshlrev_b32_e32 v66, 16, v56
	v_and_b32_e32 v67, 0xffff0000, v56
	v_lshlrev_b32_e32 v56, 16, v57
	v_and_b32_e32 v57, 0xffff0000, v57
	v_pk_fma_f32 v[46:47], v[46:47], 0.5, v[50:51] op_sel_hi:[1,0,1]
	v_pk_fma_f32 v[44:45], v[44:45], 0.5, v[60:61] op_sel_hi:[1,0,1]
	v_pk_fma_f32 v[38:39], v[38:39], 0.5, v[54:55] op_sel_hi:[1,0,1]
	v_pk_fma_f32 v[36:37], v[36:37], 0.5, v[64:65] op_sel_hi:[1,0,1]
	v_pk_fma_f32 v[42:43], v[42:43], 0.5, v[52:53] op_sel_hi:[1,0,1]
	v_pk_fma_f32 v[40:41], v[40:41], 0.5, v[62:63] op_sel_hi:[1,0,1]
	v_pk_fma_f32 v[50:51], v[34:35], 0.5, v[56:57] op_sel_hi:[1,0,1]
	v_pk_fma_f32 v[52:53], v[32:33], 0.5, v[66:67] op_sel_hi:[1,0,1]
	v_mul_f32_e32 v34, v45, v45
	v_mul_f32_e32 v35, v47, v47
	v_mul_f32_e32 v54, v37, v37
	v_mul_f32_e32 v55, v39, v39
	v_cvt_pk_bf16_f32 v32, v44, v45
	v_mul_f32_e32 v45, v41, v41
	v_mul_f32_e32 v56, v53, v53
	v_fmac_f32_e32 v34, v44, v44
	v_fmac_f32_e32 v35, v46, v46
	v_fmac_f32_e32 v54, v36, v36
	v_fmac_f32_e32 v55, v38, v38
	v_cvt_pk_bf16_f32 v33, v46, v47
	v_mul_f32_e32 v47, v43, v43
	v_mul_f32_e32 v57, v51, v51
	v_fmac_f32_e32 v45, v40, v40
	v_fmac_f32_e32 v56, v52, v52
	v_add_f32_e32 v34, v34, v35
	v_add_f32_e32 v35, v54, v55
	v_fmac_f32_e32 v47, v42, v42
	v_fmac_f32_e32 v57, v50, v50
	v_add_f32_e32 v34, v45, v34
	v_add_f32_e32 v35, v56, v35
	v_add_f32_e32 v34, v47, v34
	v_add_f32_e32 v35, v57, v35
	v_add_f32_e32 v44, v34, v35
	v_mov_b32_e32 v45, v44
	s_nop 1
	v_permlane16_swap_b32_e32 v45, v44
	v_cvt_pk_bf16_f32 v34, v40, v41
	v_cvt_pk_bf16_f32 v35, v42, v43
	global_store_dwordx4 v[58:59], v[32:35], off sc1
	s_waitcnt lgkmcnt(0)
	s_nop 0
	v_add_f32_e32 v32, v44, v45
	v_mov_b32_e32 v33, v32
	s_nop 1
	v_permlane32_swap_b32_e32 v33, v32
	v_cvt_pk_bf16_f32 v34, v36, v37
	v_cvt_pk_bf16_f32 v35, v38, v39
	v_cvt_pk_bf16_f32 v36, v52, v53
	v_cvt_pk_bf16_f32 v37, v50, v51
	global_store_dwordx4 v[58:59], v[34:37], off offset:256 sc1
	s_and_saveexec_b64 s[50:51], s[10:11]
	s_cbranch_execz .LBB0_1050
	s_waitcnt lgkmcnt(0)
	v_add_f32_e32 v32, v32, v33
	v_mul_f32_e32 v32, 0x4f800000, v32
	v_trunc_f32_e32 v32, v32
	v_mul_f32_e64 v33, |v32|, s63
	v_floor_f32_e32 v33, v33
	v_fma_f32 v34, v33, s64, |v32|
	v_cvt_u32_f32_e32 v32, v34
	v_cvt_u32_f32_e32 v33, v33
	v_lshl_add_u64 v[34:35], v[48:49], 3, s[36:37]
	global_atomic_add_x2 v[34:35], v[32:33], off
; __device__ __forceinline__ void fx_add(float* p, size_t idx, float s) { atomicAdd((unsigned long long*)p + idx, (unsigned long long)(long long)(s * 4294967296.0f)); }
; __device__ __forceinline__ unsigned cvtpk(float lo, float hi) { f32x2v_ v = {lo, hi}; bf16x2v_ b = __builtin_convertvector(v, bf16x2v_); return __builtin_bit_cast(unsigned, b); }
;     __device__ __forceinline__ void operator()(const f32x4 (&acc)[2][2][4][2], const Unit& u, int wr, int wc, int fr, int fq) const {
;     ...
;             for (int m = 0; m < 4; ++m) { const int row = row0 + ai * HALF + m * 16; const size_t off = (size_t)row * 1024 + col0; float s = 0.f;
; #pragma unroll
;                 for (int bj = 0; bj < 2; ++bj) { f32x4 a0, a1;
;                     if (xin32) { const float* p = xin32 + off + bj * HALF; a0 = *(const f32x4*)p; a1 = *(const f32x4*)(p + 4); }
;                     else { const u32x4 w = *(const u32x4*)(xb + off + bj * HALF);
;                         a0 = (f32x4){__uint_as_float(w.x << 16), __uint_as_float(w.x & 0xffff0000u), __uint_as_float(w.y << 16), __uint_as_float(w.y & 0xffff0000u)};
;                         a1 = (f32x4){__uint_as_float(w.z << 16), __uint_as_float(w.z & 0xffff0000u), __uint_as_float(w.w << 16), __uint_as_float(w.w & 0xffff0000u)}; }
;                     const f32x4 v0 = a0 + acc[ai][bj][m][0] * alpha, v1 = a1 + acc[ai][bj][m][1] * alpha;
;                     u32x4 w; w.x = cvtpk(v0[0], v0[1]); w.y = cvtpk(v0[2], v0[3]); w.z = cvtpk(v1[0], v1[1]); w.w = cvtpk(v1[2], v1[3]);
;                     *(u32x4*)(xb + off + bj * HALF) = w;
;                     s += (v0[0] * v0[0] + v0[1] * v0[1]) + (v0[2] * v0[2] + v0[3] * v0[3]) + (v1[0] * v1[0] + v1[1] * v1[1]) + (v1[2] * v1[2] + v1[3] * v1[3]); }
;                 s += __shfl_xor(s, 16); s += __shfl_xor(s, 32);
;                 if (fq == 0) fx_add(ssout, row, s); }
.LBB0_1050:
	s_or_b64 exec, exec, s[50:51]
	v_add_u32_e32 v32, 0xa0, v146
	s_waitcnt lgkmcnt(0)
	v_ashrrev_i32_e32 v33, 31, v32
	v_lshlrev_b64 v[34:35], 11, v[32:33]
	v_lshl_add_u64 v[34:35], s[22:23], 0, v[34:35]
	v_lshl_add_u64 v[42:43], v[144:145], 1, v[34:35]
	global_load_dwordx4 v[34:37], v[42:43], off
	global_load_dwordx4 v[38:41], v[42:43], off offset:256
	s_waitcnt vmcnt(1)
	v_lshlrev_b32_e32 v44, 16, v34
	v_and_b32_e32 v45, 0xffff0000, v34
	v_lshlrev_b32_e32 v34, 16, v35
	v_and_b32_e32 v35, 0xffff0000, v35
	s_waitcnt vmcnt(0)
	v_lshlrev_b32_e32 v48, 16, v38
	v_and_b32_e32 v49, 0xffff0000, v38
	v_lshlrev_b32_e32 v38, 16, v39
	v_and_b32_e32 v39, 0xffff0000, v39
	v_lshlrev_b32_e32 v46, 16, v36
	v_and_b32_e32 v47, 0xffff0000, v36
	v_lshlrev_b32_e32 v36, 16, v37
	v_and_b32_e32 v37, 0xffff0000, v37
	v_lshlrev_b32_e32 v50, 16, v40
	v_and_b32_e32 v51, 0xffff0000, v40
	v_lshlrev_b32_e32 v40, 16, v41
	v_and_b32_e32 v41, 0xffff0000, v41
	v_pk_fma_f32 v[30:31], v[30:31], 0.5, v[34:35] op_sel_hi:[1,0,1]
	v_pk_fma_f32 v[28:29], v[28:29], 0.5, v[44:45] op_sel_hi:[1,0,1]
	v_pk_fma_f32 v[22:23], v[22:23], 0.5, v[38:39] op_sel_hi:[1,0,1]
	v_pk_fma_f32 v[20:21], v[20:21], 0.5, v[48:49] op_sel_hi:[1,0,1]
	v_pk_fma_f32 v[26:27], v[26:27], 0.5, v[36:37] op_sel_hi:[1,0,1]
	v_pk_fma_f32 v[24:25], v[24:25], 0.5, v[46:47] op_sel_hi:[1,0,1]
	v_pk_fma_f32 v[34:35], v[18:19], 0.5, v[40:41] op_sel_hi:[1,0,1]
	v_pk_fma_f32 v[36:37], v[16:17], 0.5, v[50:51] op_sel_hi:[1,0,1]
	v_mul_f32_e32 v18, v29, v29
	v_mul_f32_e32 v19, v31, v31
	v_mul_f32_e32 v38, v21, v21
	v_mul_f32_e32 v39, v23, v23
	v_cvt_pk_bf16_f32 v16, v28, v29
	v_mul_f32_e32 v29, v25, v25
	v_mul_f32_e32 v40, v37, v37
	v_fmac_f32_e32 v18, v28, v28
	v_fmac_f32_e32 v19, v30, v30
	v_fmac_f32_e32 v38, v20, v20
	v_fmac_f32_e32 v39, v22, v22
	v_cvt_pk_bf16_f32 v17, v30, v31
	v_mul_f32_e32 v31, v27, v27
	v_mul_f32_e32 v41, v35, v35
	v_fmac_f32_e32 v29, v24, v24
	v_fmac_f32_e32 v40, v36, v36
	v_add_f32_e32 v18, v18, v19
	v_add_f32_e32 v19, v38, v39
	v_fmac_f32_e32 v31, v26, v26
	v_fmac_f32_e32 v41, v34, v34
	v_add_f32_e32 v18, v29, v18
	v_add_f32_e32 v19, v40, v19
	v_add_f32_e32 v18, v31, v18
	v_add_f32_e32 v19, v41, v19
	v_add_f32_e32 v28, v18, v19
	v_mov_b32_e32 v29, v28
	s_nop 1
	v_permlane16_swap_b32_e32 v29, v28
	v_cvt_pk_bf16_f32 v18, v24, v25
	v_cvt_pk_bf16_f32 v19, v26, v27
	global_store_dwordx4 v[42:43], v[16:19], off sc1
	s_waitcnt lgkmcnt(0)
	s_nop 0
	v_add_f32_e32 v16, v28, v29
	v_mov_b32_e32 v17, v16
	s_nop 1
	v_permlane32_swap_b32_e32 v17, v16
	v_cvt_pk_bf16_f32 v18, v20, v21
	v_cvt_pk_bf16_f32 v19, v22, v23
	v_cvt_pk_bf16_f32 v20, v36, v37
	v_cvt_pk_bf16_f32 v21, v34, v35
	global_store_dwordx4 v[42:43], v[18:21], off offset:256 sc1
	s_and_saveexec_b64 s[50:51], s[10:11]
	s_cbranch_execz .LBB0_1052
	s_waitcnt lgkmcnt(0)
	v_add_f32_e32 v16, v16, v17
	v_mul_f32_e32 v16, 0x4f800000, v16
	v_trunc_f32_e32 v16, v16
	v_mul_f32_e64 v17, |v16|, s63
	v_floor_f32_e32 v17, v17
	v_fma_f32 v18, v17, s64, |v16|
	v_cvt_u32_f32_e32 v16, v18
	v_cvt_u32_f32_e32 v17, v17
	v_lshl_add_u64 v[18:19], v[32:33], 3, s[36:37]
	global_atomic_add_x2 v[18:19], v[16:17], off
.LBB0_1052:
	s_or_b64 exec, exec, s[50:51]
	v_add_u32_e32 v16, 0xb0, v146
	s_waitcnt lgkmcnt(0)
	v_ashrrev_i32_e32 v17, 31, v16
	v_lshlrev_b64 v[18:19], 11, v[16:17]
	v_lshl_add_u64 v[18:19], s[22:23], 0, v[18:19]
	v_lshl_add_u64 v[26:27], v[144:145], 1, v[18:19]
	global_load_dwordx4 v[18:21], v[26:27], off
	global_load_dwordx4 v[22:25], v[26:27], off offset:256
	s_waitcnt vmcnt(1)
	v_lshlrev_b32_e32 v28, 16, v18
	v_and_b32_e32 v29, 0xffff0000, v18
	v_lshlrev_b32_e32 v18, 16, v19
	v_and_b32_e32 v19, 0xffff0000, v19
	s_waitcnt vmcnt(0)
	v_lshlrev_b32_e32 v32, 16, v22
	v_and_b32_e32 v33, 0xffff0000, v22
	v_lshlrev_b32_e32 v22, 16, v23
	v_and_b32_e32 v23, 0xffff0000, v23
	v_lshlrev_b32_e32 v30, 16, v20
	v_and_b32_e32 v31, 0xffff0000, v20
	v_lshlrev_b32_e32 v20, 16, v21
	v_and_b32_e32 v21, 0xffff0000, v21
	v_lshlrev_b32_e32 v34, 16, v24
	v_and_b32_e32 v35, 0xffff0000, v24
	v_lshlrev_b32_e32 v24, 16, v25
	v_and_b32_e32 v25, 0xffff0000, v25
	v_pk_fma_f32 v[14:15], v[14:15], 0.5, v[18:19] op_sel_hi:[1,0,1]
	v_pk_fma_f32 v[12:13], v[12:13], 0.5, v[28:29] op_sel_hi:[1,0,1]
	v_pk_fma_f32 v[6:7], v[6:7], 0.5, v[22:23] op_sel_hi:[1,0,1]
	v_pk_fma_f32 v[4:5], v[4:5], 0.5, v[32:33] op_sel_hi:[1,0,1]
	v_pk_fma_f32 v[10:11], v[10:11], 0.5, v[20:21] op_sel_hi:[1,0,1]
	v_pk_fma_f32 v[8:9], v[8:9], 0.5, v[30:31] op_sel_hi:[1,0,1]
	v_pk_fma_f32 v[18:19], v[2:3], 0.5, v[24:25] op_sel_hi:[1,0,1]
	v_pk_fma_f32 v[20:21], v[0:1], 0.5, v[34:35] op_sel_hi:[1,0,1]
	v_mul_f32_e32 v2, v13, v13
	v_mul_f32_e32 v3, v15, v15
	v_mul_f32_e32 v22, v5, v5
	v_mul_f32_e32 v23, v7, v7
	v_cvt_pk_bf16_f32 v0, v12, v13
	v_mul_f32_e32 v13, v9, v9
	v_mul_f32_e32 v24, v21, v21
	v_fmac_f32_e32 v2, v12, v12
	v_fmac_f32_e32 v3, v14, v14
	v_fmac_f32_e32 v22, v4, v4
	v_fmac_f32_e32 v23, v6, v6
	v_cvt_pk_bf16_f32 v1, v14, v15
	v_mul_f32_e32 v15, v11, v11
	v_mul_f32_e32 v25, v19, v19
	v_fmac_f32_e32 v13, v8, v8
	v_fmac_f32_e32 v24, v20, v20
	v_add_f32_e32 v2, v2, v3
	v_add_f32_e32 v3, v22, v23
	v_fmac_f32_e32 v15, v10, v10
	v_fmac_f32_e32 v25, v18, v18
	v_add_f32_e32 v2, v13, v2
	v_add_f32_e32 v3, v24, v3
	v_add_f32_e32 v2, v15, v2
	v_add_f32_e32 v3, v25, v3
	v_add_f32_e32 v12, v2, v3
	v_mov_b32_e32 v13, v12
	s_nop 1
	v_permlane16_swap_b32_e32 v13, v12
	v_cvt_pk_bf16_f32 v2, v8, v9
	v_cvt_pk_bf16_f32 v3, v10, v11
	global_store_dwordx4 v[26:27], v[0:3], off sc1
	s_waitcnt lgkmcnt(0)
	s_nop 0
	v_add_f32_e32 v0, v12, v13
	v_mov_b32_e32 v1, v0
	s_nop 1
	v_permlane32_swap_b32_e32 v1, v0
	v_cvt_pk_bf16_f32 v2, v4, v5
	v_cvt_pk_bf16_f32 v3, v6, v7
	v_cvt_pk_bf16_f32 v4, v20, v21
	v_cvt_pk_bf16_f32 v5, v18, v19
	global_store_dwordx4 v[26:27], v[2:5], off offset:256 sc1
	s_and_saveexec_b64 s[50:51], s[10:11]
	s_cbranch_execz .LBB0_1054
	s_waitcnt lgkmcnt(0)
	v_add_f32_e32 v0, v0, v1
	v_mul_f32_e32 v0, 0x4f800000, v0
	v_trunc_f32_e32 v0, v0
	v_mul_f32_e64 v1, |v0|, s63
	v_floor_f32_e32 v1, v1
	v_fma_f32 v2, v1, s64, |v0|
	v_cvt_u32_f32_e32 v0, v2
	v_cvt_u32_f32_e32 v1, v1
	v_lshl_add_u64 v[2:3], v[16:17], 3, s[36:37]
	global_atomic_add_x2 v[2:3], v[0:1], off

; __device__ __forceinline__ unsigned cvtpk(float lo, float hi) { f32x2v_ v = {lo, hi}; bf16x2v_ b = __builtin_convertvector(v, bf16x2v_); return __builtin_bit_cast(unsigned, b); }
;     __device__ __forceinline__ void operator()(const f32x4 (&acc)[2][2][4][2], const Unit& u, int wr, int wc, int fr, int fq) const {
;         const int row0 = u.pm * BM + wr * 64 + fr, col0 = u.pn * HALF + wc * 32 + 8 * fq;
; #pragma unroll
;         for (int ai = 0; ai < 2; ++ai)
; #pragma unroll
;             for (int m = 0; m < 4; ++m) { const int row = row0 + ai * HALF + m * 16; const float rs = row_rs(ss, row);
;                 float hv[8];
; #pragma unroll
;                 for (int n = 0; n < 2; ++n)
; #pragma unroll
;                     for (int i = 0; i < 4; ++i) { const float g = acc[ai][0][m][n][i] * rs, uu = acc[ai][1][m][n][i] * rs;
;                         hv[n * 4 + i] = g * __builtin_amdgcn_rcpf(1.0f + __expf(-g)) * uu; }
;                 u32x4 w; w.x = cvtpk(hv[0], hv[1]); w.y = cvtpk(hv[2], hv[3]); w.z = cvtpk(hv[4], hv[5]); w.w = cvtpk(hv[6], hv[7]);
;                 *(u32x4*)(H + (size_t)row * ldh + col0) = w; }
.LBB0_1122:
	v_lshl_or_b32 v160, s75, 7, v154
	v_ashrrev_i32_e32 v161, 31, v160
	v_or_b32_e32 v164, 16, v144
	v_ashrrev_i32_e32 v165, 31, v164
	v_lshl_add_u64 v[166:167], v[164:165], 3, s[36:37]
	v_mov_b64_e32 v[146:147], s[20:21]
	v_mad_i64_i32 v[162:163], s[54:55], v144, s74, v[146:147]
	s_andn2_b64 vcc, exec, s[10:11]
	s_mov_b64 s[10:11], -1
	s_waitcnt vmcnt(7)
	v_cvt_f32_u32_e32 v159, v183
	v_cvt_f32_u32_e32 v145, v182
	v_lshlrev_b64 v[148:149], 1, v[160:161]
	v_lshl_add_u64 v[162:163], v[162:163], 0, v[148:149]
	v_fmamk_f32 v145, v145, 0x2f800000, v159
	v_fmamk_f32 v145, v145, 0x3a800000, v158
	v_rsq_f32_e32 v160, v145
	s_nop 0
	v_mul_f32_e32 v182, 0xbfb8aa3b, v160
	v_mul_f32_e32 v183, v160, v160
	v_pk_mul_f32 v[160:161], v[124:125], v[182:183] op_sel_hi:[1,0]
	v_pk_mul_f32 v[168:169], v[126:127], v[182:183] op_sel_hi:[1,0]
	v_pk_mul_f32 v[170:171], v[120:121], v[182:183] op_sel_hi:[1,0]
	v_pk_mul_f32 v[172:173], v[122:123], v[182:183] op_sel_hi:[1,0]
	v_pk_mul_f32 v[116:117], v[116:117], v[124:125]
	v_pk_mul_f32 v[118:119], v[118:119], v[126:127]
	v_pk_mul_f32 v[120:121], v[112:113], v[120:121]
	v_pk_mul_f32 v[122:123], v[114:115], v[122:123]
	v_exp_f32_e32 v160, v160
	v_exp_f32_e32 v161, v161
	v_exp_f32_e32 v168, v168
	v_exp_f32_e32 v169, v169
	v_exp_f32_e32 v170, v170
	v_exp_f32_e32 v171, v171
	v_exp_f32_e32 v172, v172
	v_exp_f32_e32 v173, v173
	v_pk_mul_f32 v[116:117], v[116:117], v[182:183] op_sel:[0,1] op_sel_hi:[1,1]
	v_pk_mul_f32 v[118:119], v[118:119], v[182:183] op_sel:[0,1] op_sel_hi:[1,1]
	v_pk_mul_f32 v[120:121], v[120:121], v[182:183] op_sel:[0,1] op_sel_hi:[1,1]
	v_pk_mul_f32 v[122:123], v[122:123], v[182:183] op_sel:[0,1] op_sel_hi:[1,1]
	v_pk_add_f32 v[160:161], v[160:161], 1.0 op_sel_hi:[1,0]
	v_pk_add_f32 v[168:169], v[168:169], 1.0 op_sel_hi:[1,0]
	v_pk_add_f32 v[170:171], v[170:171], 1.0 op_sel_hi:[1,0]
	v_pk_add_f32 v[172:173], v[172:173], 1.0 op_sel_hi:[1,0]
	v_rcp_f32_e32 v160, v160
	v_rcp_f32_e32 v161, v161
	v_rcp_f32_e32 v168, v168
	v_rcp_f32_e32 v169, v169
	v_rcp_f32_e32 v170, v170
	v_rcp_f32_e32 v171, v171
	v_rcp_f32_e32 v172, v172
	v_rcp_f32_e32 v173, v173
	v_pk_mul_f32 v[116:117], v[116:117], v[160:161]
	v_pk_mul_f32 v[118:119], v[118:119], v[168:169]
	v_pk_mul_f32 v[120:121], v[120:121], v[170:171]
	v_pk_mul_f32 v[122:123], v[122:123], v[172:173]
	v_cvt_pk_bf16_f32 v112, v116, v117
	v_cvt_pk_bf16_f32 v113, v118, v119
	v_cvt_pk_bf16_f32 v114, v120, v121
	v_cvt_pk_bf16_f32 v115, v122, v123
	global_store_dwordx4 v[162:163], v[112:115], off sc1
	s_nop 0
	s_nop 0
	v_or_b32_e32 v114, 32, v144
	s_waitcnt vmcnt(7)
	v_cvt_f32_u32_e32 v116, v185
	v_cvt_f32_u32_e32 v115, v184
	v_mad_i64_i32 v[112:113], s[54:55], v164, s74, v[146:147]
	v_fmamk_f32 v115, v115, 0x2f800000, v116
	v_fmamk_f32 v115, v115, 0x3a800000, v158
	v_rsq_f32_e32 v116, v115
	v_ashrrev_i32_e32 v115, 31, v114
	v_lshl_add_u64 v[118:119], v[114:115], 3, s[36:37]
	v_lshl_add_u64 v[112:113], v[112:113], 0, v[148:149]
	v_mul_f32_e32 v184, 0xbfb8aa3b, v116
	v_mul_f32_e32 v185, v116, v116
	v_pk_mul_f32 v[116:117], v[108:109], v[184:185] op_sel_hi:[1,0]
	v_pk_mul_f32 v[120:121], v[110:111], v[184:185] op_sel_hi:[1,0]
	v_pk_mul_f32 v[122:123], v[104:105], v[184:185] op_sel_hi:[1,0]
	v_pk_mul_f32 v[124:125], v[106:107], v[184:185] op_sel_hi:[1,0]
	v_pk_mul_f32 v[100:101], v[100:101], v[108:109]
	v_pk_mul_f32 v[102:103], v[102:103], v[110:111]
	v_pk_mul_f32 v[104:105], v[96:97], v[104:105]
	v_pk_mul_f32 v[106:107], v[98:99], v[106:107]
	v_exp_f32_e32 v116, v116
	v_exp_f32_e32 v117, v117
	v_exp_f32_e32 v120, v120
	v_exp_f32_e32 v121, v121
	v_exp_f32_e32 v122, v122
	v_exp_f32_e32 v123, v123
	v_exp_f32_e32 v124, v124
	v_exp_f32_e32 v125, v125
	v_pk_mul_f32 v[100:101], v[100:101], v[184:185] op_sel:[0,1] op_sel_hi:[1,1]
	v_pk_mul_f32 v[102:103], v[102:103], v[184:185] op_sel:[0,1] op_sel_hi:[1,1]
	v_pk_mul_f32 v[104:105], v[104:105], v[184:185] op_sel:[0,1] op_sel_hi:[1,1]
	v_pk_mul_f32 v[106:107], v[106:107], v[184:185] op_sel:[0,1] op_sel_hi:[1,1]
	v_pk_add_f32 v[116:117], v[116:117], 1.0 op_sel_hi:[1,0]
	v_pk_add_f32 v[120:121], v[120:121], 1.0 op_sel_hi:[1,0]
	v_pk_add_f32 v[122:123], v[122:123], 1.0 op_sel_hi:[1,0]
	v_pk_add_f32 v[124:125], v[124:125], 1.0 op_sel_hi:[1,0]
	v_rcp_f32_e32 v116, v116
	v_rcp_f32_e32 v117, v117
	v_rcp_f32_e32 v120, v120
	v_rcp_f32_e32 v121, v121
	v_rcp_f32_e32 v122, v122
	v_rcp_f32_e32 v123, v123
	v_rcp_f32_e32 v124, v124
	v_rcp_f32_e32 v125, v125
	v_pk_mul_f32 v[100:101], v[100:101], v[116:117]
	v_pk_mul_f32 v[102:103], v[102:103], v[120:121]
	v_pk_mul_f32 v[104:105], v[104:105], v[122:123]
	v_pk_mul_f32 v[106:107], v[106:107], v[124:125]
	v_cvt_pk_bf16_f32 v96, v100, v101
	v_cvt_pk_bf16_f32 v97, v102, v103
	v_cvt_pk_bf16_f32 v98, v104, v105
	v_cvt_pk_bf16_f32 v99, v106, v107
	global_store_dwordx4 v[112:113], v[96:99], off sc1
	s_nop 0
	s_nop 0
	v_or_b32_e32 v98, 48, v144
	s_waitcnt vmcnt(7)
; __device__ __forceinline__ unsigned cvtpk(float lo, float hi) { f32x2v_ v = {lo, hi}; bf16x2v_ b = __builtin_convertvector(v, bf16x2v_); return __builtin_bit_cast(unsigned, b); }
;     __device__ __forceinline__ void operator()(const f32x4 (&acc)[2][2][4][2], const Unit& u, int wr, int wc, int fr, int fq) const {
;     ...
;             for (int m = 0; m < 4; ++m) { const int row = row0 + ai * HALF + m * 16; const float rs = row_rs(ss, row);
;                 float hv[8];
; #pragma unroll
;                 for (int n = 0; n < 2; ++n)
; #pragma unroll
;                     for (int i = 0; i < 4; ++i) { const float g = acc[ai][0][m][n][i] * rs, uu = acc[ai][1][m][n][i] * rs;
;                         hv[n * 4 + i] = g * __builtin_amdgcn_rcpf(1.0f + __expf(-g)) * uu; }
;                 u32x4 w; w.x = cvtpk(hv[0], hv[1]); w.y = cvtpk(hv[2], hv[3]); w.z = cvtpk(hv[4], hv[5]); w.w = cvtpk(hv[6], hv[7]);
;                 *(u32x4*)(H + (size_t)row * ldh + col0) = w; }
	v_cvt_f32_u32_e32 v100, v187
	v_cvt_f32_u32_e32 v99, v186
	v_mad_i64_i32 v[96:97], s[54:55], v114, s74, v[146:147]
	v_fmamk_f32 v99, v99, 0x2f800000, v100
	v_fmamk_f32 v99, v99, 0x3a800000, v158
	v_rsq_f32_e32 v100, v99
	v_ashrrev_i32_e32 v99, 31, v98
	v_lshl_add_u64 v[102:103], v[98:99], 3, s[36:37]
	v_lshl_add_u64 v[96:97], v[96:97], 0, v[148:149]
	v_mul_f32_e32 v186, 0xbfb8aa3b, v100
	v_mul_f32_e32 v187, v100, v100
	v_pk_mul_f32 v[100:101], v[92:93], v[186:187] op_sel_hi:[1,0]
	v_pk_mul_f32 v[104:105], v[94:95], v[186:187] op_sel_hi:[1,0]
	v_pk_mul_f32 v[106:107], v[88:89], v[186:187] op_sel_hi:[1,0]
	v_pk_mul_f32 v[108:109], v[90:91], v[186:187] op_sel_hi:[1,0]
	v_pk_mul_f32 v[84:85], v[84:85], v[92:93]
	v_pk_mul_f32 v[86:87], v[86:87], v[94:95]
	v_pk_mul_f32 v[88:89], v[80:81], v[88:89]
	v_pk_mul_f32 v[90:91], v[82:83], v[90:91]
	v_exp_f32_e32 v100, v100
	v_exp_f32_e32 v101, v101
	v_exp_f32_e32 v104, v104
	v_exp_f32_e32 v105, v105
	v_exp_f32_e32 v106, v106
	v_exp_f32_e32 v107, v107
	v_exp_f32_e32 v108, v108
	v_exp_f32_e32 v109, v109
	v_pk_mul_f32 v[84:85], v[84:85], v[186:187] op_sel:[0,1] op_sel_hi:[1,1]
	v_pk_mul_f32 v[86:87], v[86:87], v[186:187] op_sel:[0,1] op_sel_hi:[1,1]
	v_pk_mul_f32 v[88:89], v[88:89], v[186:187] op_sel:[0,1] op_sel_hi:[1,1]
	v_pk_mul_f32 v[90:91], v[90:91], v[186:187] op_sel:[0,1] op_sel_hi:[1,1]
	v_pk_add_f32 v[100:101], v[100:101], 1.0 op_sel_hi:[1,0]
	v_pk_add_f32 v[104:105], v[104:105], 1.0 op_sel_hi:[1,0]
	v_pk_add_f32 v[106:107], v[106:107], 1.0 op_sel_hi:[1,0]
	v_pk_add_f32 v[108:109], v[108:109], 1.0 op_sel_hi:[1,0]
	v_rcp_f32_e32 v100, v100
	v_rcp_f32_e32 v101, v101
	v_rcp_f32_e32 v104, v104
	v_rcp_f32_e32 v105, v105
	v_rcp_f32_e32 v106, v106
	v_rcp_f32_e32 v107, v107
	v_rcp_f32_e32 v108, v108
	v_rcp_f32_e32 v109, v109
	v_pk_mul_f32 v[84:85], v[84:85], v[100:101]
	v_pk_mul_f32 v[86:87], v[86:87], v[104:105]
	v_pk_mul_f32 v[88:89], v[88:89], v[106:107]
	v_pk_mul_f32 v[90:91], v[90:91], v[108:109]
	v_cvt_pk_bf16_f32 v80, v84, v85
	v_cvt_pk_bf16_f32 v81, v86, v87
	v_cvt_pk_bf16_f32 v82, v88, v89
	v_cvt_pk_bf16_f32 v83, v90, v91
	global_store_dwordx4 v[96:97], v[80:83], off sc1
	s_nop 0
	s_waitcnt vmcnt(7)
	v_cvt_f32_u32_e32 v80, v189
	v_cvt_f32_u32_e32 v81, v188
	v_mad_i64_i32 v[82:83], s[54:55], v98, s74, v[146:147]
	v_fmamk_f32 v80, v81, 0x2f800000, v80
	v_fmamk_f32 v80, v80, 0x3a800000, v158
	v_rsq_f32_e32 v80, v80
	v_lshl_add_u64 v[82:83], v[82:83], 0, v[148:149]
	v_mul_f32_e32 v188, 0xbfb8aa3b, v80
	v_mul_f32_e32 v189, v80, v80
	v_pk_mul_f32 v[80:81], v[76:77], v[188:189] op_sel_hi:[1,0]
	v_pk_mul_f32 v[84:85], v[78:79], v[188:189] op_sel_hi:[1,0]
	v_pk_mul_f32 v[86:87], v[72:73], v[188:189] op_sel_hi:[1,0]
	v_pk_mul_f32 v[88:89], v[74:75], v[188:189] op_sel_hi:[1,0]
	v_pk_mul_f32 v[68:69], v[68:69], v[76:77]
	v_pk_mul_f32 v[70:71], v[70:71], v[78:79]
	v_pk_mul_f32 v[72:73], v[64:65], v[72:73]
	v_pk_mul_f32 v[74:75], v[66:67], v[74:75]
	v_exp_f32_e32 v80, v80
	v_exp_f32_e32 v81, v81
	v_exp_f32_e32 v84, v84
	v_exp_f32_e32 v85, v85
	v_exp_f32_e32 v86, v86
	v_exp_f32_e32 v87, v87
	v_exp_f32_e32 v88, v88
	v_exp_f32_e32 v89, v89
	v_pk_mul_f32 v[68:69], v[68:69], v[188:189] op_sel:[0,1] op_sel_hi:[1,1]
	v_pk_mul_f32 v[70:71], v[70:71], v[188:189] op_sel:[0,1] op_sel_hi:[1,1]
	v_pk_mul_f32 v[72:73], v[72:73], v[188:189] op_sel:[0,1] op_sel_hi:[1,1]
	v_pk_mul_f32 v[74:75], v[74:75], v[188:189] op_sel:[0,1] op_sel_hi:[1,1]
	v_pk_add_f32 v[80:81], v[80:81], 1.0 op_sel_hi:[1,0]
	v_pk_add_f32 v[84:85], v[84:85], 1.0 op_sel_hi:[1,0]
	v_pk_add_f32 v[86:87], v[86:87], 1.0 op_sel_hi:[1,0]
	v_pk_add_f32 v[88:89], v[88:89], 1.0 op_sel_hi:[1,0]
	v_rcp_f32_e32 v80, v80
	v_rcp_f32_e32 v81, v81
	v_rcp_f32_e32 v84, v84
	v_rcp_f32_e32 v85, v85
	v_rcp_f32_e32 v86, v86
	v_rcp_f32_e32 v87, v87
	v_rcp_f32_e32 v88, v88
	v_rcp_f32_e32 v89, v89
	v_pk_mul_f32 v[68:69], v[68:69], v[80:81]
	v_pk_mul_f32 v[70:71], v[70:71], v[84:85]
	v_pk_mul_f32 v[72:73], v[72:73], v[86:87]
	v_pk_mul_f32 v[74:75], v[74:75], v[88:89]
	v_cvt_pk_bf16_f32 v64, v68, v69
	v_cvt_pk_bf16_f32 v65, v70, v71
	v_cvt_pk_bf16_f32 v66, v72, v73
	v_cvt_pk_bf16_f32 v67, v74, v75
	global_store_dwordx4 v[82:83], v[64:67], off sc1
	s_nop 0
	s_waitcnt vmcnt(7)
	v_cvt_f32_u32_e32 v64, v191
	v_cvt_f32_u32_e32 v66, v190
	v_add_u32_e32 v65, 0x80, v144
	v_fmamk_f32 v64, v66, 0x2f800000, v64
	v_fmamk_f32 v64, v64, 0x3a800000, v158
	v_rsq_f32_e32 v64, v64
	v_mad_i64_i32 v[66:67], s[54:55], v65, s74, v[146:147]
	v_lshl_add_u64 v[66:67], v[66:67], 0, v[148:149]
	v_mul_f32_e32 v190, 0xbfb8aa3b, v64
	v_mul_f32_e32 v191, v64, v64
	v_pk_mul_f32 v[64:65], v[60:61], v[190:191] op_sel_hi:[1,0]
	v_pk_mul_f32 v[68:69], v[62:63], v[190:191] op_sel_hi:[1,0]
	v_pk_mul_f32 v[70:71], v[56:57], v[190:191] op_sel_hi:[1,0]
	v_pk_mul_f32 v[72:73], v[58:59], v[190:191] op_sel_hi:[1,0]
	v_pk_mul_f32 v[52:53], v[52:53], v[60:61]
	v_pk_mul_f32 v[54:55], v[54:55], v[62:63]
	v_pk_mul_f32 v[56:57], v[48:49], v[56:57]
	v_pk_mul_f32 v[58:59], v[50:51], v[58:59]
	v_exp_f32_e32 v64, v64
	v_exp_f32_e32 v65, v65
	v_exp_f32_e32 v68, v68
	v_exp_f32_e32 v69, v69
	v_exp_f32_e32 v70, v70
	v_exp_f32_e32 v71, v71
	v_exp_f32_e32 v72, v72
	v_exp_f32_e32 v73, v73
	v_pk_mul_f32 v[52:53], v[52:53], v[190:191] op_sel:[0,1] op_sel_hi:[1,1]
	v_pk_mul_f32 v[54:55], v[54:55], v[190:191] op_sel:[0,1] op_sel_hi:[1,1]
	v_pk_mul_f32 v[56:57], v[56:57], v[190:191] op_sel:[0,1] op_sel_hi:[1,1]
	v_pk_mul_f32 v[58:59], v[58:59], v[190:191] op_sel:[0,1] op_sel_hi:[1,1]
	v_pk_add_f32 v[64:65], v[64:65], 1.0 op_sel_hi:[1,0]
	v_pk_add_f32 v[68:69], v[68:69], 1.0 op_sel_hi:[1,0]
	v_pk_add_f32 v[70:71], v[70:71], 1.0 op_sel_hi:[1,0]
	v_pk_add_f32 v[72:73], v[72:73], 1.0 op_sel_hi:[1,0]
	v_rcp_f32_e32 v64, v64
	v_rcp_f32_e32 v65, v65
	v_rcp_f32_e32 v68, v68
	v_rcp_f32_e32 v69, v69
	v_rcp_f32_e32 v70, v70
	v_rcp_f32_e32 v71, v71
	v_rcp_f32_e32 v72, v72
	v_rcp_f32_e32 v73, v73
	v_pk_mul_f32 v[52:53], v[52:53], v[64:65]
	v_pk_mul_f32 v[54:55], v[54:55], v[68:69]
	v_pk_mul_f32 v[56:57], v[56:57], v[70:71]
	v_pk_mul_f32 v[58:59], v[58:59], v[72:73]
	v_cvt_pk_bf16_f32 v48, v52, v53
	v_cvt_pk_bf16_f32 v49, v54, v55
	v_cvt_pk_bf16_f32 v50, v56, v57
	v_cvt_pk_bf16_f32 v51, v58, v59
	global_store_dwordx4 v[66:67], v[48:51], off sc1
	s_nop 0
	s_waitcnt vmcnt(7)
; __device__ __forceinline__ unsigned cvtpk(float lo, float hi) { f32x2v_ v = {lo, hi}; bf16x2v_ b = __builtin_convertvector(v, bf16x2v_); return __builtin_bit_cast(unsigned, b); }
;     __device__ __forceinline__ void operator()(const f32x4 (&acc)[2][2][4][2], const Unit& u, int wr, int wc, int fr, int fq) const {
;     ...
;             for (int m = 0; m < 4; ++m) { const int row = row0 + ai * HALF + m * 16; const float rs = row_rs(ss, row);
;                 float hv[8];
; #pragma unroll
;                 for (int n = 0; n < 2; ++n)
; #pragma unroll
;                     for (int i = 0; i < 4; ++i) { const float g = acc[ai][0][m][n][i] * rs, uu = acc[ai][1][m][n][i] * rs;
;                         hv[n * 4 + i] = g * __builtin_amdgcn_rcpf(1.0f + __expf(-g)) * uu; }
;                 u32x4 w; w.x = cvtpk(hv[0], hv[1]); w.y = cvtpk(hv[2], hv[3]); w.z = cvtpk(hv[4], hv[5]); w.w = cvtpk(hv[6], hv[7]);
;                 *(u32x4*)(H + (size_t)row * ldh + col0) = w; }
	v_cvt_f32_u32_e32 v48, v193
	v_cvt_f32_u32_e32 v50, v192
	v_add_u32_e32 v49, 0x90, v144
	v_fmamk_f32 v48, v50, 0x2f800000, v48
	v_fmamk_f32 v48, v48, 0x3a800000, v158
	v_rsq_f32_e32 v48, v48
	v_mad_i64_i32 v[50:51], s[54:55], v49, s74, v[146:147]
	v_lshl_add_u64 v[50:51], v[50:51], 0, v[148:149]
	v_mul_f32_e32 v192, 0xbfb8aa3b, v48
	v_mul_f32_e32 v193, v48, v48
	v_pk_mul_f32 v[48:49], v[44:45], v[192:193] op_sel_hi:[1,0]
	v_pk_mul_f32 v[52:53], v[46:47], v[192:193] op_sel_hi:[1,0]
	v_pk_mul_f32 v[54:55], v[40:41], v[192:193] op_sel_hi:[1,0]
	v_pk_mul_f32 v[56:57], v[42:43], v[192:193] op_sel_hi:[1,0]
	v_pk_mul_f32 v[36:37], v[36:37], v[44:45]
	v_pk_mul_f32 v[38:39], v[38:39], v[46:47]
	v_pk_mul_f32 v[40:41], v[32:33], v[40:41]
	v_pk_mul_f32 v[42:43], v[34:35], v[42:43]
	v_exp_f32_e32 v48, v48
	v_exp_f32_e32 v49, v49
	v_exp_f32_e32 v52, v52
	v_exp_f32_e32 v53, v53
	v_exp_f32_e32 v54, v54
	v_exp_f32_e32 v55, v55
	v_exp_f32_e32 v56, v56
	v_exp_f32_e32 v57, v57
	v_pk_mul_f32 v[36:37], v[36:37], v[192:193] op_sel:[0,1] op_sel_hi:[1,1]
	v_pk_mul_f32 v[38:39], v[38:39], v[192:193] op_sel:[0,1] op_sel_hi:[1,1]
	v_pk_mul_f32 v[40:41], v[40:41], v[192:193] op_sel:[0,1] op_sel_hi:[1,1]
	v_pk_mul_f32 v[42:43], v[42:43], v[192:193] op_sel:[0,1] op_sel_hi:[1,1]
	v_pk_add_f32 v[48:49], v[48:49], 1.0 op_sel_hi:[1,0]
	v_pk_add_f32 v[52:53], v[52:53], 1.0 op_sel_hi:[1,0]
	v_pk_add_f32 v[54:55], v[54:55], 1.0 op_sel_hi:[1,0]
	v_pk_add_f32 v[56:57], v[56:57], 1.0 op_sel_hi:[1,0]
	v_rcp_f32_e32 v48, v48
	v_rcp_f32_e32 v49, v49
	v_rcp_f32_e32 v52, v52
	v_rcp_f32_e32 v53, v53
	v_rcp_f32_e32 v54, v54
	v_rcp_f32_e32 v55, v55
	v_rcp_f32_e32 v56, v56
	v_rcp_f32_e32 v57, v57
	v_pk_mul_f32 v[36:37], v[36:37], v[48:49]
	v_pk_mul_f32 v[38:39], v[38:39], v[52:53]
	v_pk_mul_f32 v[40:41], v[40:41], v[54:55]
	v_pk_mul_f32 v[42:43], v[42:43], v[56:57]
	v_cvt_pk_bf16_f32 v32, v36, v37
	v_cvt_pk_bf16_f32 v33, v38, v39
	v_cvt_pk_bf16_f32 v34, v40, v41
	v_cvt_pk_bf16_f32 v35, v42, v43
	global_store_dwordx4 v[50:51], v[32:35], off sc1
	s_nop 0
	s_waitcnt vmcnt(7)
	v_cvt_f32_u32_e32 v32, v195
	v_cvt_f32_u32_e32 v34, v194
	v_add_u32_e32 v33, 0xa0, v144
	v_fmamk_f32 v32, v34, 0x2f800000, v32
	v_fmamk_f32 v32, v32, 0x3a800000, v158
	v_rsq_f32_e32 v32, v32
	v_mad_i64_i32 v[34:35], s[54:55], v33, s74, v[146:147]
	v_lshl_add_u64 v[34:35], v[34:35], 0, v[148:149]
	v_mul_f32_e32 v194, 0xbfb8aa3b, v32
	v_mul_f32_e32 v195, v32, v32
	v_pk_mul_f32 v[32:33], v[28:29], v[194:195] op_sel_hi:[1,0]
	v_pk_mul_f32 v[36:37], v[30:31], v[194:195] op_sel_hi:[1,0]
	v_pk_mul_f32 v[38:39], v[24:25], v[194:195] op_sel_hi:[1,0]
	v_pk_mul_f32 v[40:41], v[26:27], v[194:195] op_sel_hi:[1,0]
	v_pk_mul_f32 v[20:21], v[20:21], v[28:29]
	v_pk_mul_f32 v[22:23], v[22:23], v[30:31]
	v_pk_mul_f32 v[24:25], v[16:17], v[24:25]
	v_pk_mul_f32 v[26:27], v[18:19], v[26:27]
	v_exp_f32_e32 v32, v32
	v_exp_f32_e32 v33, v33
	v_exp_f32_e32 v36, v36
	v_exp_f32_e32 v37, v37
	v_exp_f32_e32 v38, v38
	v_exp_f32_e32 v39, v39
	v_exp_f32_e32 v40, v40
	v_exp_f32_e32 v41, v41
	v_pk_mul_f32 v[20:21], v[20:21], v[194:195] op_sel:[0,1] op_sel_hi:[1,1]
	v_pk_mul_f32 v[22:23], v[22:23], v[194:195] op_sel:[0,1] op_sel_hi:[1,1]
	v_pk_mul_f32 v[24:25], v[24:25], v[194:195] op_sel:[0,1] op_sel_hi:[1,1]
	v_pk_mul_f32 v[26:27], v[26:27], v[194:195] op_sel:[0,1] op_sel_hi:[1,1]
	v_pk_add_f32 v[32:33], v[32:33], 1.0 op_sel_hi:[1,0]
	v_pk_add_f32 v[36:37], v[36:37], 1.0 op_sel_hi:[1,0]
	v_pk_add_f32 v[38:39], v[38:39], 1.0 op_sel_hi:[1,0]
	v_pk_add_f32 v[40:41], v[40:41], 1.0 op_sel_hi:[1,0]
	v_rcp_f32_e32 v32, v32
	v_rcp_f32_e32 v33, v33
	v_rcp_f32_e32 v36, v36
	v_rcp_f32_e32 v37, v37
	v_rcp_f32_e32 v38, v38
	v_rcp_f32_e32 v39, v39
	v_rcp_f32_e32 v40, v40
	v_rcp_f32_e32 v41, v41
	v_pk_mul_f32 v[20:21], v[20:21], v[32:33]
	v_pk_mul_f32 v[22:23], v[22:23], v[36:37]
	v_pk_mul_f32 v[24:25], v[24:25], v[38:39]
	v_pk_mul_f32 v[26:27], v[26:27], v[40:41]
	v_cvt_pk_bf16_f32 v16, v20, v21
	v_cvt_pk_bf16_f32 v17, v22, v23
	v_cvt_pk_bf16_f32 v18, v24, v25
	v_cvt_pk_bf16_f32 v19, v26, v27
	global_store_dwordx4 v[34:35], v[16:19], off sc1
	s_nop 0
	s_waitcnt vmcnt(7)
	v_cvt_f32_u32_e32 v16, v197
	v_cvt_f32_u32_e32 v18, v196
	v_add_u32_e32 v17, 0xb0, v144
	v_fmamk_f32 v16, v18, 0x2f800000, v16
	v_fmamk_f32 v16, v16, 0x3a800000, v158
	v_rsq_f32_e32 v16, v16
	v_mad_i64_i32 v[18:19], s[54:55], v17, s74, v[146:147]
	v_lshl_add_u64 v[18:19], v[18:19], 0, v[148:149]
	v_mul_f32_e32 v196, 0xbfb8aa3b, v16
	v_mul_f32_e32 v197, v16, v16
	v_pk_mul_f32 v[16:17], v[12:13], v[196:197] op_sel_hi:[1,0]
	v_pk_mul_f32 v[20:21], v[14:15], v[196:197] op_sel_hi:[1,0]
	v_pk_mul_f32 v[22:23], v[8:9], v[196:197] op_sel_hi:[1,0]
	v_pk_mul_f32 v[24:25], v[10:11], v[196:197] op_sel_hi:[1,0]
	v_pk_mul_f32 v[4:5], v[4:5], v[12:13]
	v_pk_mul_f32 v[6:7], v[6:7], v[14:15]
	v_pk_mul_f32 v[8:9], v[0:1], v[8:9]
	v_pk_mul_f32 v[10:11], v[2:3], v[10:11]
	v_exp_f32_e32 v16, v16
	v_exp_f32_e32 v17, v17
	v_exp_f32_e32 v20, v20
	v_exp_f32_e32 v21, v21
	v_exp_f32_e32 v22, v22
	v_exp_f32_e32 v23, v23
	v_exp_f32_e32 v24, v24
	v_exp_f32_e32 v25, v25
	v_pk_mul_f32 v[4:5], v[4:5], v[196:197] op_sel:[0,1] op_sel_hi:[1,1]
	v_pk_mul_f32 v[6:7], v[6:7], v[196:197] op_sel:[0,1] op_sel_hi:[1,1]
	v_pk_mul_f32 v[8:9], v[8:9], v[196:197] op_sel:[0,1] op_sel_hi:[1,1]
	v_pk_mul_f32 v[10:11], v[10:11], v[196:197] op_sel:[0,1] op_sel_hi:[1,1]
	v_pk_add_f32 v[16:17], v[16:17], 1.0 op_sel_hi:[1,0]
	v_pk_add_f32 v[20:21], v[20:21], 1.0 op_sel_hi:[1,0]
	v_pk_add_f32 v[22:23], v[22:23], 1.0 op_sel_hi:[1,0]
	v_pk_add_f32 v[24:25], v[24:25], 1.0 op_sel_hi:[1,0]
	v_rcp_f32_e32 v16, v16
	v_rcp_f32_e32 v17, v17
	v_rcp_f32_e32 v20, v20
	v_rcp_f32_e32 v21, v21
	v_rcp_f32_e32 v22, v22
	v_rcp_f32_e32 v23, v23
	v_rcp_f32_e32 v24, v24
	v_rcp_f32_e32 v25, v25
	v_pk_mul_f32 v[4:5], v[4:5], v[16:17]
	v_pk_mul_f32 v[6:7], v[6:7], v[20:21]
	v_pk_mul_f32 v[8:9], v[8:9], v[22:23]
	v_pk_mul_f32 v[10:11], v[10:11], v[24:25]
	v_cvt_pk_bf16_f32 v0, v4, v5
	v_cvt_pk_bf16_f32 v1, v6, v7
	v_cvt_pk_bf16_f32 v2, v8, v9
	v_cvt_pk_bf16_f32 v3, v10, v11
	global_store_dwordx4 v[18:19], v[0:3], off sc1
	s_cbranch_vccnz .LBB0_1115
	s_andn2_b64 vcc, exec, s[0:1]
	s_cbranch_vccnz .LBB0_1114
	s_barrier
	s_branch .LBB0_1114

; __device__ __forceinline__ void fx_add(float* p, size_t idx, float s) { atomicAdd((unsigned long long*)p + idx, (unsigned long long)(long long)(s * 4294967296.0f)); }
; __device__ __forceinline__ unsigned cvtpk(float lo, float hi) { f32x2v_ v = {lo, hi}; bf16x2v_ b = __builtin_convertvector(v, bf16x2v_); return __builtin_bit_cast(unsigned, b); }
;     __device__ __forceinline__ void operator()(const f32x4 (&acc)[2][2][4][2], const Unit& u, int wr, int wc, int fr, int fq) const {
;     ...
;             for (int m = 0; m < 4; ++m) { const int row = row0 + ai * HALF + m * 16; const size_t off = (size_t)row * 1024 + col0; float s = 0.f;
; #pragma unroll
;                 for (int bj = 0; bj < 2; ++bj) { f32x4 a0, a1;
;                     if (xin32) { const float* p = xin32 + off + bj * HALF; a0 = *(const f32x4*)p; a1 = *(const f32x4*)(p + 4); }
;                     else { const u32x4 w = *(const u32x4*)(xb + off + bj * HALF);
;                         a0 = (f32x4){__uint_as_float(w.x << 16), __uint_as_float(w.x & 0xffff0000u), __uint_as_float(w.y << 16), __uint_as_float(w.y & 0xffff0000u)};
;                         a1 = (f32x4){__uint_as_float(w.z << 16), __uint_as_float(w.z & 0xffff0000u), __uint_as_float(w.w << 16), __uint_as_float(w.w & 0xffff0000u)}; }
;                     const f32x4 v0 = a0 + acc[ai][bj][m][0] * alpha, v1 = a1 + acc[ai][bj][m][1] * alpha;
;                     u32x4 w; w.x = cvtpk(v0[0], v0[1]); w.y = cvtpk(v0[2], v0[3]); w.z = cvtpk(v1[0], v1[1]); w.w = cvtpk(v1[2], v1[3]);
;                     *(u32x4*)(xb + off + bj * HALF) = w;
;                     s += (v0[0] * v0[0] + v0[1] * v0[1]) + (v0[2] * v0[2] + v0[3] * v0[3]) + (v1[0] * v1[0] + v1[1] * v1[1]) + (v1[2] * v1[2] + v1[3] * v1[3]); }
;                 s += __shfl_xor(s, 16); s += __shfl_xor(s, 32);
;                 if (fq == 0) fx_add(ssout, row, s); }
.LBB0_1200:
	v_lshl_add_u32 v146, s77, 8, v148
	v_ashrrev_i32_e32 v147, 31, v146
	v_lshl_or_b32 v144, s76, 8, v150
	v_lshlrev_b64 v[156:157], 11, v[146:147]
	v_ashrrev_i32_e32 v145, 31, v144
	v_lshl_add_u64 v[156:157], s[22:23], 0, v[156:157]
	v_lshl_add_u64 v[166:167], v[144:145], 1, v[156:157]
	global_load_dwordx4 v[158:161], v[166:167], off
	global_load_dwordx4 v[162:165], v[166:167], off offset:256
	v_and_b32_e32 v156, 64, v154
	v_xor_b32_e32 v155, 16, v154
	v_add_u32_e32 v156, 64, v156
	v_xor_b32_e32 v157, 32, v154
	v_cmp_lt_i32_e32 vcc, v155, v156
	s_waitcnt vmcnt(0)
	v_lshlrev_b32_e32 v168, 16, v158
	v_cndmask_b32_e32 v155, v154, v155, vcc
	v_cmp_lt_i32_e32 vcc, v157, v156
	v_and_b32_e32 v169, 0xffff0000, v158
	v_lshlrev_b32_e32 v158, 16, v159
	v_and_b32_e32 v159, 0xffff0000, v159
	v_lshlrev_b32_e32 v172, 16, v162
	v_and_b32_e32 v173, 0xffff0000, v162
	v_lshlrev_b32_e32 v162, 16, v163
	v_and_b32_e32 v163, 0xffff0000, v163
	v_cndmask_b32_e32 v157, v154, v157, vcc
	v_lshlrev_b32_e32 v170, 16, v160
	v_and_b32_e32 v171, 0xffff0000, v160
	v_lshlrev_b32_e32 v160, 16, v161
	v_and_b32_e32 v161, 0xffff0000, v161
	v_lshlrev_b32_e32 v174, 16, v164
	v_and_b32_e32 v175, 0xffff0000, v164
	v_lshlrev_b32_e32 v164, 16, v165
	v_and_b32_e32 v165, 0xffff0000, v165
	v_pk_fma_f32 v[126:127], v[126:127], 0.5, v[158:159] op_sel_hi:[1,0,1]
	v_pk_fma_f32 v[124:125], v[124:125], 0.5, v[168:169] op_sel_hi:[1,0,1]
	v_pk_fma_f32 v[118:119], v[118:119], 0.5, v[162:163] op_sel_hi:[1,0,1]
	v_pk_fma_f32 v[116:117], v[116:117], 0.5, v[172:173] op_sel_hi:[1,0,1]
	v_lshlrev_b32_e32 v156, 2, v155
	v_lshlrev_b32_e32 v155, 2, v157
	v_pk_fma_f32 v[122:123], v[122:123], 0.5, v[160:161] op_sel_hi:[1,0,1]
	v_pk_fma_f32 v[120:121], v[120:121], 0.5, v[170:171] op_sel_hi:[1,0,1]
	v_pk_fma_f32 v[158:159], v[114:115], 0.5, v[164:165] op_sel_hi:[1,0,1]
	v_pk_fma_f32 v[160:161], v[112:113], 0.5, v[174:175] op_sel_hi:[1,0,1]
	v_mul_f32_e32 v114, v125, v125
	v_mul_f32_e32 v115, v127, v127
	v_mul_f32_e32 v157, v117, v117
	v_mul_f32_e32 v162, v119, v119
	v_cvt_pk_bf16_f32 v112, v124, v125
	v_mul_f32_e32 v125, v121, v121
	v_mul_f32_e32 v163, v161, v161
	v_fmac_f32_e32 v114, v124, v124
	v_fmac_f32_e32 v115, v126, v126
	v_fmac_f32_e32 v157, v116, v116
	v_fmac_f32_e32 v162, v118, v118
	v_cvt_pk_bf16_f32 v113, v126, v127
	v_mul_f32_e32 v127, v123, v123
	v_mul_f32_e32 v164, v159, v159
	v_fmac_f32_e32 v125, v120, v120
	v_fmac_f32_e32 v163, v160, v160
	v_add_f32_e32 v114, v114, v115
	v_add_f32_e32 v115, v157, v162
	v_fmac_f32_e32 v127, v122, v122
	v_fmac_f32_e32 v164, v158, v158
	v_add_f32_e32 v114, v125, v114
	v_add_f32_e32 v115, v163, v115
	v_add_f32_e32 v114, v127, v114
	v_add_f32_e32 v115, v164, v115
	v_add_f32_e32 v124, v114, v115
	v_mov_b32_e32 v125, v124
	s_nop 1
	v_permlane16_swap_b32_e32 v125, v124
	v_cvt_pk_bf16_f32 v114, v120, v121
	v_cvt_pk_bf16_f32 v115, v122, v123
	global_store_dwordx4 v[166:167], v[112:115], off sc1
	s_waitcnt lgkmcnt(0)
	s_nop 0
	v_add_f32_e32 v112, v124, v125
	v_mov_b32_e32 v113, v112
	s_nop 1
	v_permlane32_swap_b32_e32 v113, v112
	v_cvt_pk_bf16_f32 v114, v116, v117
	v_cvt_pk_bf16_f32 v115, v118, v119
	v_cvt_pk_bf16_f32 v116, v160, v161
	v_cvt_pk_bf16_f32 v117, v158, v159
	global_store_dwordx4 v[166:167], v[114:117], off offset:256 sc1
	s_and_saveexec_b64 s[50:51], s[10:11]
	s_cbranch_execz .LBB0_1202
	s_waitcnt lgkmcnt(0)
	v_add_f32_e32 v112, v112, v113
	v_mul_f32_e32 v112, 0x4f800000, v112
	v_trunc_f32_e32 v112, v112
	v_mul_f32_e64 v113, |v112|, s66
	v_floor_f32_e32 v113, v113
	v_fma_f32 v114, v113, s67, |v112|
	v_cvt_u32_f32_e32 v112, v114
	v_cvt_u32_f32_e32 v113, v113
	v_lshl_add_u64 v[114:115], v[146:147], 3, s[36:37]
	global_atomic_add_x2 v[114:115], v[112:113], off
.LBB0_1202:
	s_or_b64 exec, exec, s[50:51]
	v_or_b32_e32 v112, 16, v146
	s_waitcnt lgkmcnt(0)
	v_ashrrev_i32_e32 v113, 31, v112
	v_lshlrev_b64 v[114:115], 11, v[112:113]
	v_lshl_add_u64 v[114:115], s[22:23], 0, v[114:115]
	v_lshl_add_u64 v[122:123], v[144:145], 1, v[114:115]
	global_load_dwordx4 v[114:117], v[122:123], off
	global_load_dwordx4 v[118:121], v[122:123], off offset:256
	s_waitcnt vmcnt(1)
	v_lshlrev_b32_e32 v124, 16, v114
	v_and_b32_e32 v125, 0xffff0000, v114
	v_lshlrev_b32_e32 v114, 16, v115
	v_and_b32_e32 v115, 0xffff0000, v115
	s_waitcnt vmcnt(0)
	v_lshlrev_b32_e32 v158, 16, v118
	v_and_b32_e32 v159, 0xffff0000, v118
	v_lshlrev_b32_e32 v118, 16, v119
	v_and_b32_e32 v119, 0xffff0000, v119
	v_lshlrev_b32_e32 v126, 16, v116
	v_and_b32_e32 v127, 0xffff0000, v116
	v_lshlrev_b32_e32 v116, 16, v117
	v_and_b32_e32 v117, 0xffff0000, v117
	v_lshlrev_b32_e32 v160, 16, v120
	v_and_b32_e32 v161, 0xffff0000, v120
	v_lshlrev_b32_e32 v120, 16, v121
	v_and_b32_e32 v121, 0xffff0000, v121
	v_pk_fma_f32 v[110:111], v[110:111], 0.5, v[114:115] op_sel_hi:[1,0,1]
	v_pk_fma_f32 v[108:109], v[108:109], 0.5, v[124:125] op_sel_hi:[1,0,1]
	v_pk_fma_f32 v[102:103], v[102:103], 0.5, v[118:119] op_sel_hi:[1,0,1]
	v_pk_fma_f32 v[100:101], v[100:101], 0.5, v[158:159] op_sel_hi:[1,0,1]
	v_pk_fma_f32 v[106:107], v[106:107], 0.5, v[116:117] op_sel_hi:[1,0,1]
	v_pk_fma_f32 v[104:105], v[104:105], 0.5, v[126:127] op_sel_hi:[1,0,1]
	v_pk_fma_f32 v[114:115], v[98:99], 0.5, v[120:121] op_sel_hi:[1,0,1]
	v_pk_fma_f32 v[116:117], v[96:97], 0.5, v[160:161] op_sel_hi:[1,0,1]
	v_mul_f32_e32 v98, v109, v109
	v_mul_f32_e32 v99, v111, v111
	v_mul_f32_e32 v118, v101, v101
	v_mul_f32_e32 v119, v103, v103
	v_cvt_pk_bf16_f32 v96, v108, v109
	v_mul_f32_e32 v109, v105, v105
	v_mul_f32_e32 v120, v117, v117
	v_fmac_f32_e32 v98, v108, v108
	v_fmac_f32_e32 v99, v110, v110
	v_fmac_f32_e32 v118, v100, v100
	v_fmac_f32_e32 v119, v102, v102
	v_cvt_pk_bf16_f32 v97, v110, v111
	v_mul_f32_e32 v111, v107, v107
	v_mul_f32_e32 v121, v115, v115
	v_fmac_f32_e32 v109, v104, v104
	v_fmac_f32_e32 v120, v116, v116
	v_add_f32_e32 v98, v98, v99
	v_add_f32_e32 v99, v118, v119
	v_fmac_f32_e32 v111, v106, v106
	v_fmac_f32_e32 v121, v114, v114
	v_add_f32_e32 v98, v109, v98
	v_add_f32_e32 v99, v120, v99
	v_add_f32_e32 v98, v111, v98
	v_add_f32_e32 v99, v121, v99
	v_add_f32_e32 v108, v98, v99
	v_mov_b32_e32 v109, v108
	s_nop 1
	v_permlane16_swap_b32_e32 v109, v108
	v_cvt_pk_bf16_f32 v98, v104, v105
	v_cvt_pk_bf16_f32 v99, v106, v107
	global_store_dwordx4 v[122:123], v[96:99], off sc1
	s_waitcnt lgkmcnt(0)
	s_nop 0
	v_add_f32_e32 v96, v108, v109
	v_mov_b32_e32 v97, v96
	s_nop 1
	v_permlane32_swap_b32_e32 v97, v96
	v_cvt_pk_bf16_f32 v98, v100, v101
	v_cvt_pk_bf16_f32 v99, v102, v103
	v_cvt_pk_bf16_f32 v100, v116, v117
	v_cvt_pk_bf16_f32 v101, v114, v115
	global_store_dwordx4 v[122:123], v[98:101], off offset:256 sc1
	s_and_saveexec_b64 s[50:51], s[10:11]
	s_cbranch_execz .LBB0_1204
	s_waitcnt lgkmcnt(0)
	v_add_f32_e32 v96, v96, v97
	v_mul_f32_e32 v96, 0x4f800000, v96
	v_trunc_f32_e32 v96, v96
	v_mul_f32_e64 v97, |v96|, s66
	v_floor_f32_e32 v97, v97
	v_fma_f32 v98, v97, s67, |v96|
	v_cvt_u32_f32_e32 v96, v98
	v_cvt_u32_f32_e32 v97, v97
	v_lshl_add_u64 v[98:99], v[112:113], 3, s[36:37]
	global_atomic_add_x2 v[98:99], v[96:97], off
; __device__ __forceinline__ void fx_add(float* p, size_t idx, float s) { atomicAdd((unsigned long long*)p + idx, (unsigned long long)(long long)(s * 4294967296.0f)); }
; __device__ __forceinline__ unsigned cvtpk(float lo, float hi) { f32x2v_ v = {lo, hi}; bf16x2v_ b = __builtin_convertvector(v, bf16x2v_); return __builtin_bit_cast(unsigned, b); }
;     __device__ __forceinline__ void operator()(const f32x4 (&acc)[2][2][4][2], const Unit& u, int wr, int wc, int fr, int fq) const {
;     ...
;             for (int m = 0; m < 4; ++m) { const int row = row0 + ai * HALF + m * 16; const size_t off = (size_t)row * 1024 + col0; float s = 0.f;
; #pragma unroll
;                 for (int bj = 0; bj < 2; ++bj) { f32x4 a0, a1;
;                     if (xin32) { const float* p = xin32 + off + bj * HALF; a0 = *(const f32x4*)p; a1 = *(const f32x4*)(p + 4); }
;                     else { const u32x4 w = *(const u32x4*)(xb + off + bj * HALF);
;                         a0 = (f32x4){__uint_as_float(w.x << 16), __uint_as_float(w.x & 0xffff0000u), __uint_as_float(w.y << 16), __uint_as_float(w.y & 0xffff0000u)};
;                         a1 = (f32x4){__uint_as_float(w.z << 16), __uint_as_float(w.z & 0xffff0000u), __uint_as_float(w.w << 16), __uint_as_float(w.w & 0xffff0000u)}; }
;                     const f32x4 v0 = a0 + acc[ai][bj][m][0] * alpha, v1 = a1 + acc[ai][bj][m][1] * alpha;
;                     u32x4 w; w.x = cvtpk(v0[0], v0[1]); w.y = cvtpk(v0[2], v0[3]); w.z = cvtpk(v1[0], v1[1]); w.w = cvtpk(v1[2], v1[3]);
;                     *(u32x4*)(xb + off + bj * HALF) = w;
;                     s += (v0[0] * v0[0] + v0[1] * v0[1]) + (v0[2] * v0[2] + v0[3] * v0[3]) + (v1[0] * v1[0] + v1[1] * v1[1]) + (v1[2] * v1[2] + v1[3] * v1[3]); }
;                 s += __shfl_xor(s, 16); s += __shfl_xor(s, 32);
;                 if (fq == 0) fx_add(ssout, row, s); }
.LBB0_1204:
	s_or_b64 exec, exec, s[50:51]
	v_or_b32_e32 v96, 32, v146
	s_waitcnt lgkmcnt(0)
	v_ashrrev_i32_e32 v97, 31, v96
	v_lshlrev_b64 v[98:99], 11, v[96:97]
	v_lshl_add_u64 v[98:99], s[22:23], 0, v[98:99]
	v_lshl_add_u64 v[106:107], v[144:145], 1, v[98:99]
	global_load_dwordx4 v[98:101], v[106:107], off
	global_load_dwordx4 v[102:105], v[106:107], off offset:256
	s_waitcnt vmcnt(1)
	v_lshlrev_b32_e32 v108, 16, v98
	v_and_b32_e32 v109, 0xffff0000, v98
	v_lshlrev_b32_e32 v98, 16, v99
	v_and_b32_e32 v99, 0xffff0000, v99
	s_waitcnt vmcnt(0)
	v_lshlrev_b32_e32 v112, 16, v102
	v_and_b32_e32 v113, 0xffff0000, v102
	v_lshlrev_b32_e32 v102, 16, v103
	v_and_b32_e32 v103, 0xffff0000, v103
	v_lshlrev_b32_e32 v110, 16, v100
	v_and_b32_e32 v111, 0xffff0000, v100
	v_lshlrev_b32_e32 v100, 16, v101
	v_and_b32_e32 v101, 0xffff0000, v101
	v_lshlrev_b32_e32 v114, 16, v104
	v_and_b32_e32 v115, 0xffff0000, v104
	v_lshlrev_b32_e32 v104, 16, v105
	v_and_b32_e32 v105, 0xffff0000, v105
	v_pk_fma_f32 v[94:95], v[94:95], 0.5, v[98:99] op_sel_hi:[1,0,1]
	v_pk_fma_f32 v[92:93], v[92:93], 0.5, v[108:109] op_sel_hi:[1,0,1]
	v_pk_fma_f32 v[86:87], v[86:87], 0.5, v[102:103] op_sel_hi:[1,0,1]
	v_pk_fma_f32 v[84:85], v[84:85], 0.5, v[112:113] op_sel_hi:[1,0,1]
	v_pk_fma_f32 v[90:91], v[90:91], 0.5, v[100:101] op_sel_hi:[1,0,1]
	v_pk_fma_f32 v[88:89], v[88:89], 0.5, v[110:111] op_sel_hi:[1,0,1]
	v_pk_fma_f32 v[98:99], v[82:83], 0.5, v[104:105] op_sel_hi:[1,0,1]
	v_pk_fma_f32 v[100:101], v[80:81], 0.5, v[114:115] op_sel_hi:[1,0,1]
	v_mul_f32_e32 v82, v93, v93
	v_mul_f32_e32 v83, v95, v95
	v_mul_f32_e32 v102, v85, v85
	v_mul_f32_e32 v103, v87, v87
	v_cvt_pk_bf16_f32 v80, v92, v93
	v_mul_f32_e32 v93, v89, v89
	v_mul_f32_e32 v104, v101, v101
	v_fmac_f32_e32 v82, v92, v92
	v_fmac_f32_e32 v83, v94, v94
	v_fmac_f32_e32 v102, v84, v84
	v_fmac_f32_e32 v103, v86, v86
	v_cvt_pk_bf16_f32 v81, v94, v95
	v_mul_f32_e32 v95, v91, v91
	v_mul_f32_e32 v105, v99, v99
	v_fmac_f32_e32 v93, v88, v88
	v_fmac_f32_e32 v104, v100, v100
	v_add_f32_e32 v82, v82, v83
	v_add_f32_e32 v83, v102, v103
	v_fmac_f32_e32 v95, v90, v90
	v_fmac_f32_e32 v105, v98, v98
	v_add_f32_e32 v82, v93, v82
	v_add_f32_e32 v83, v104, v83
	v_add_f32_e32 v82, v95, v82
	v_add_f32_e32 v83, v105, v83
	v_add_f32_e32 v92, v82, v83
	v_mov_b32_e32 v93, v92
	s_nop 1
	v_permlane16_swap_b32_e32 v93, v92
	v_cvt_pk_bf16_f32 v82, v88, v89
	v_cvt_pk_bf16_f32 v83, v90, v91
	global_store_dwordx4 v[106:107], v[80:83], off sc1
	s_waitcnt lgkmcnt(0)
	s_nop 0
	v_add_f32_e32 v80, v92, v93
	v_mov_b32_e32 v81, v80
	s_nop 1
	v_permlane32_swap_b32_e32 v81, v80
	v_cvt_pk_bf16_f32 v82, v84, v85
	v_cvt_pk_bf16_f32 v83, v86, v87
	v_cvt_pk_bf16_f32 v84, v100, v101
	v_cvt_pk_bf16_f32 v85, v98, v99
	global_store_dwordx4 v[106:107], v[82:85], off offset:256 sc1
	s_and_saveexec_b64 s[50:51], s[10:11]
	s_cbranch_execz .LBB0_1206
	s_waitcnt lgkmcnt(0)
	v_add_f32_e32 v80, v80, v81
	v_mul_f32_e32 v80, 0x4f800000, v80
	v_trunc_f32_e32 v80, v80
	v_mul_f32_e64 v81, |v80|, s66
	v_floor_f32_e32 v81, v81
	v_fma_f32 v82, v81, s67, |v80|
	v_cvt_u32_f32_e32 v80, v82
	v_cvt_u32_f32_e32 v81, v81
	v_lshl_add_u64 v[82:83], v[96:97], 3, s[36:37]
	global_atomic_add_x2 v[82:83], v[80:81], off
.LBB0_1206:
	s_or_b64 exec, exec, s[50:51]
	v_or_b32_e32 v80, 48, v146
	s_waitcnt lgkmcnt(0)
	v_ashrrev_i32_e32 v81, 31, v80
	v_lshlrev_b64 v[82:83], 11, v[80:81]
	v_lshl_add_u64 v[82:83], s[22:23], 0, v[82:83]
	v_lshl_add_u64 v[90:91], v[144:145], 1, v[82:83]
	global_load_dwordx4 v[82:85], v[90:91], off
	global_load_dwordx4 v[86:89], v[90:91], off offset:256
	s_waitcnt vmcnt(1)
	v_lshlrev_b32_e32 v92, 16, v82
	v_and_b32_e32 v93, 0xffff0000, v82
	v_lshlrev_b32_e32 v82, 16, v83
	v_and_b32_e32 v83, 0xffff0000, v83
	s_waitcnt vmcnt(0)
	v_lshlrev_b32_e32 v96, 16, v86
	v_and_b32_e32 v97, 0xffff0000, v86
	v_lshlrev_b32_e32 v86, 16, v87
	v_and_b32_e32 v87, 0xffff0000, v87
	v_lshlrev_b32_e32 v94, 16, v84
	v_and_b32_e32 v95, 0xffff0000, v84
	v_lshlrev_b32_e32 v84, 16, v85
	v_and_b32_e32 v85, 0xffff0000, v85
	v_lshlrev_b32_e32 v98, 16, v88
	v_and_b32_e32 v99, 0xffff0000, v88
	v_lshlrev_b32_e32 v88, 16, v89
	v_and_b32_e32 v89, 0xffff0000, v89
	v_pk_fma_f32 v[78:79], v[78:79], 0.5, v[82:83] op_sel_hi:[1,0,1]
	v_pk_fma_f32 v[76:77], v[76:77], 0.5, v[92:93] op_sel_hi:[1,0,1]
	v_pk_fma_f32 v[70:71], v[70:71], 0.5, v[86:87] op_sel_hi:[1,0,1]
	v_pk_fma_f32 v[68:69], v[68:69], 0.5, v[96:97] op_sel_hi:[1,0,1]
	v_pk_fma_f32 v[74:75], v[74:75], 0.5, v[84:85] op_sel_hi:[1,0,1]
	v_pk_fma_f32 v[72:73], v[72:73], 0.5, v[94:95] op_sel_hi:[1,0,1]
	v_pk_fma_f32 v[82:83], v[66:67], 0.5, v[88:89] op_sel_hi:[1,0,1]
	v_pk_fma_f32 v[84:85], v[64:65], 0.5, v[98:99] op_sel_hi:[1,0,1]
	v_mul_f32_e32 v66, v77, v77
	v_mul_f32_e32 v67, v79, v79
	v_mul_f32_e32 v86, v69, v69
	v_mul_f32_e32 v87, v71, v71
	v_cvt_pk_bf16_f32 v64, v76, v77
	v_mul_f32_e32 v77, v73, v73
	v_mul_f32_e32 v88, v85, v85
	v_fmac_f32_e32 v66, v76, v76
	v_fmac_f32_e32 v67, v78, v78
	v_fmac_f32_e32 v86, v68, v68
	v_fmac_f32_e32 v87, v70, v70
	v_cvt_pk_bf16_f32 v65, v78, v79
	v_mul_f32_e32 v79, v75, v75
	v_mul_f32_e32 v89, v83, v83
	v_fmac_f32_e32 v77, v72, v72
	v_fmac_f32_e32 v88, v84, v84
	v_add_f32_e32 v66, v66, v67
	v_add_f32_e32 v67, v86, v87
	v_fmac_f32_e32 v79, v74, v74
	v_fmac_f32_e32 v89, v82, v82
	v_add_f32_e32 v66, v77, v66
	v_add_f32_e32 v67, v88, v67
	v_add_f32_e32 v66, v79, v66
	v_add_f32_e32 v67, v89, v67
	v_add_f32_e32 v76, v66, v67
	v_mov_b32_e32 v77, v76
	s_nop 1
	v_permlane16_swap_b32_e32 v77, v76
	v_cvt_pk_bf16_f32 v66, v72, v73
	v_cvt_pk_bf16_f32 v67, v74, v75
	global_store_dwordx4 v[90:91], v[64:67], off sc1
	s_waitcnt lgkmcnt(0)
	s_nop 0
	v_add_f32_e32 v64, v76, v77
	v_mov_b32_e32 v65, v64
	s_nop 1
	v_permlane32_swap_b32_e32 v65, v64
	v_cvt_pk_bf16_f32 v66, v68, v69
	v_cvt_pk_bf16_f32 v67, v70, v71
	v_cvt_pk_bf16_f32 v68, v84, v85
	v_cvt_pk_bf16_f32 v69, v82, v83
	global_store_dwordx4 v[90:91], v[66:69], off offset:256 sc1
	s_and_saveexec_b64 s[50:51], s[10:11]
	s_cbranch_execz .LBB0_1208
	s_waitcnt lgkmcnt(0)
	v_add_f32_e32 v64, v64, v65
	v_mul_f32_e32 v64, 0x4f800000, v64
	v_trunc_f32_e32 v64, v64
	v_mul_f32_e64 v65, |v64|, s66
	v_floor_f32_e32 v65, v65
	v_fma_f32 v66, v65, s67, |v64|
	v_cvt_u32_f32_e32 v64, v66
	v_cvt_u32_f32_e32 v65, v65
	v_lshl_add_u64 v[66:67], v[80:81], 3, s[36:37]
	global_atomic_add_x2 v[66:67], v[64:65], off
; __device__ __forceinline__ void fx_add(float* p, size_t idx, float s) { atomicAdd((unsigned long long*)p + idx, (unsigned long long)(long long)(s * 4294967296.0f)); }
; __device__ __forceinline__ unsigned cvtpk(float lo, float hi) { f32x2v_ v = {lo, hi}; bf16x2v_ b = __builtin_convertvector(v, bf16x2v_); return __builtin_bit_cast(unsigned, b); }
;     __device__ __forceinline__ void operator()(const f32x4 (&acc)[2][2][4][2], const Unit& u, int wr, int wc, int fr, int fq) const {
;     ...
;             for (int m = 0; m < 4; ++m) { const int row = row0 + ai * HALF + m * 16; const size_t off = (size_t)row * 1024 + col0; float s = 0.f;
; #pragma unroll
;                 for (int bj = 0; bj < 2; ++bj) { f32x4 a0, a1;
;                     if (xin32) { const float* p = xin32 + off + bj * HALF; a0 = *(const f32x4*)p; a1 = *(const f32x4*)(p + 4); }
;                     else { const u32x4 w = *(const u32x4*)(xb + off + bj * HALF);
;                         a0 = (f32x4){__uint_as_float(w.x << 16), __uint_as_float(w.x & 0xffff0000u), __uint_as_float(w.y << 16), __uint_as_float(w.y & 0xffff0000u)};
;                         a1 = (f32x4){__uint_as_float(w.z << 16), __uint_as_float(w.z & 0xffff0000u), __uint_as_float(w.w << 16), __uint_as_float(w.w & 0xffff0000u)}; }
;                     const f32x4 v0 = a0 + acc[ai][bj][m][0] * alpha, v1 = a1 + acc[ai][bj][m][1] * alpha;
;                     u32x4 w; w.x = cvtpk(v0[0], v0[1]); w.y = cvtpk(v0[2], v0[3]); w.z = cvtpk(v1[0], v1[1]); w.w = cvtpk(v1[2], v1[3]);
;                     *(u32x4*)(xb + off + bj * HALF) = w;
;                     s += (v0[0] * v0[0] + v0[1] * v0[1]) + (v0[2] * v0[2] + v0[3] * v0[3]) + (v1[0] * v1[0] + v1[1] * v1[1]) + (v1[2] * v1[2] + v1[3] * v1[3]); }
;                 s += __shfl_xor(s, 16); s += __shfl_xor(s, 32);
;                 if (fq == 0) fx_add(ssout, row, s); }
.LBB0_1208:
	s_or_b64 exec, exec, s[50:51]
	v_add_u32_e32 v64, 0x80, v146
	s_waitcnt lgkmcnt(0)
	v_ashrrev_i32_e32 v65, 31, v64
	v_lshlrev_b64 v[66:67], 11, v[64:65]
	v_lshl_add_u64 v[66:67], s[22:23], 0, v[66:67]
	v_lshl_add_u64 v[74:75], v[144:145], 1, v[66:67]
	global_load_dwordx4 v[66:69], v[74:75], off
	global_load_dwordx4 v[70:73], v[74:75], off offset:256
	s_waitcnt vmcnt(1)
	v_lshlrev_b32_e32 v76, 16, v66
	v_and_b32_e32 v77, 0xffff0000, v66
	v_lshlrev_b32_e32 v66, 16, v67
	v_and_b32_e32 v67, 0xffff0000, v67
	s_waitcnt vmcnt(0)
	v_lshlrev_b32_e32 v80, 16, v70
	v_and_b32_e32 v81, 0xffff0000, v70
	v_lshlrev_b32_e32 v70, 16, v71
	v_and_b32_e32 v71, 0xffff0000, v71
	v_lshlrev_b32_e32 v78, 16, v68
	v_and_b32_e32 v79, 0xffff0000, v68
	v_lshlrev_b32_e32 v68, 16, v69
	v_and_b32_e32 v69, 0xffff0000, v69
	v_lshlrev_b32_e32 v82, 16, v72
	v_and_b32_e32 v83, 0xffff0000, v72
	v_lshlrev_b32_e32 v72, 16, v73
	v_and_b32_e32 v73, 0xffff0000, v73
	v_pk_fma_f32 v[62:63], v[62:63], 0.5, v[66:67] op_sel_hi:[1,0,1]
	v_pk_fma_f32 v[60:61], v[60:61], 0.5, v[76:77] op_sel_hi:[1,0,1]
	v_pk_fma_f32 v[54:55], v[54:55], 0.5, v[70:71] op_sel_hi:[1,0,1]
	v_pk_fma_f32 v[52:53], v[52:53], 0.5, v[80:81] op_sel_hi:[1,0,1]
	v_pk_fma_f32 v[58:59], v[58:59], 0.5, v[68:69] op_sel_hi:[1,0,1]
	v_pk_fma_f32 v[56:57], v[56:57], 0.5, v[78:79] op_sel_hi:[1,0,1]
	v_pk_fma_f32 v[66:67], v[50:51], 0.5, v[72:73] op_sel_hi:[1,0,1]
	v_pk_fma_f32 v[68:69], v[48:49], 0.5, v[82:83] op_sel_hi:[1,0,1]
	v_mul_f32_e32 v50, v61, v61
	v_mul_f32_e32 v51, v63, v63
	v_mul_f32_e32 v70, v53, v53
	v_mul_f32_e32 v71, v55, v55
	v_cvt_pk_bf16_f32 v48, v60, v61
	v_mul_f32_e32 v61, v57, v57
	v_mul_f32_e32 v72, v69, v69
	v_fmac_f32_e32 v50, v60, v60
	v_fmac_f32_e32 v51, v62, v62
	v_fmac_f32_e32 v70, v52, v52
	v_fmac_f32_e32 v71, v54, v54
	v_cvt_pk_bf16_f32 v49, v62, v63
	v_mul_f32_e32 v63, v59, v59
	v_mul_f32_e32 v73, v67, v67
	v_fmac_f32_e32 v61, v56, v56
	v_fmac_f32_e32 v72, v68, v68
	v_add_f32_e32 v50, v50, v51
	v_add_f32_e32 v51, v70, v71
	v_fmac_f32_e32 v63, v58, v58
	v_fmac_f32_e32 v73, v66, v66
	v_add_f32_e32 v50, v61, v50
	v_add_f32_e32 v51, v72, v51
	v_add_f32_e32 v50, v63, v50
	v_add_f32_e32 v51, v73, v51
	v_add_f32_e32 v60, v50, v51
	v_mov_b32_e32 v61, v60
	s_nop 1
	v_permlane16_swap_b32_e32 v61, v60
	v_cvt_pk_bf16_f32 v50, v56, v57
	v_cvt_pk_bf16_f32 v51, v58, v59
	global_store_dwordx4 v[74:75], v[48:51], off sc1
	s_waitcnt lgkmcnt(0)
	s_nop 0
	v_add_f32_e32 v48, v60, v61
	v_mov_b32_e32 v49, v48
	s_nop 1
	v_permlane32_swap_b32_e32 v49, v48
	v_cvt_pk_bf16_f32 v50, v52, v53
	v_cvt_pk_bf16_f32 v51, v54, v55
	v_cvt_pk_bf16_f32 v52, v68, v69
	v_cvt_pk_bf16_f32 v53, v66, v67
	global_store_dwordx4 v[74:75], v[50:53], off offset:256 sc1
	s_and_saveexec_b64 s[50:51], s[10:11]
	s_cbranch_execz .LBB0_1210
	s_waitcnt lgkmcnt(0)
	v_add_f32_e32 v48, v48, v49
	v_mul_f32_e32 v48, 0x4f800000, v48
	v_trunc_f32_e32 v48, v48
	v_mul_f32_e64 v49, |v48|, s66
	v_floor_f32_e32 v49, v49
	v_fma_f32 v50, v49, s67, |v48|
	v_cvt_u32_f32_e32 v48, v50
	v_cvt_u32_f32_e32 v49, v49
	v_lshl_add_u64 v[50:51], v[64:65], 3, s[36:37]
	global_atomic_add_x2 v[50:51], v[48:49], off
.LBB0_1210:
	s_or_b64 exec, exec, s[50:51]
	v_add_u32_e32 v48, 0x90, v146
	s_waitcnt lgkmcnt(0)
	v_ashrrev_i32_e32 v49, 31, v48
	v_lshlrev_b64 v[50:51], 11, v[48:49]
	v_lshl_add_u64 v[50:51], s[22:23], 0, v[50:51]
	v_lshl_add_u64 v[58:59], v[144:145], 1, v[50:51]
	global_load_dwordx4 v[50:53], v[58:59], off
	global_load_dwordx4 v[54:57], v[58:59], off offset:256
	s_waitcnt vmcnt(1)
	v_lshlrev_b32_e32 v60, 16, v50
	v_and_b32_e32 v61, 0xffff0000, v50
	v_lshlrev_b32_e32 v50, 16, v51
	v_and_b32_e32 v51, 0xffff0000, v51
	s_waitcnt vmcnt(0)
	v_lshlrev_b32_e32 v64, 16, v54
	v_and_b32_e32 v65, 0xffff0000, v54
	v_lshlrev_b32_e32 v54, 16, v55
	v_and_b32_e32 v55, 0xffff0000, v55
	v_lshlrev_b32_e32 v62, 16, v52
	v_and_b32_e32 v63, 0xffff0000, v52
	v_lshlrev_b32_e32 v52, 16, v53
	v_and_b32_e32 v53, 0xffff0000, v53
	v_lshlrev_b32_e32 v66, 16, v56
	v_and_b32_e32 v67, 0xffff0000, v56
	v_lshlrev_b32_e32 v56, 16, v57
	v_and_b32_e32 v57, 0xffff0000, v57
	v_pk_fma_f32 v[46:47], v[46:47], 0.5, v[50:51] op_sel_hi:[1,0,1]
	v_pk_fma_f32 v[44:45], v[44:45], 0.5, v[60:61] op_sel_hi:[1,0,1]
	v_pk_fma_f32 v[38:39], v[38:39], 0.5, v[54:55] op_sel_hi:[1,0,1]
	v_pk_fma_f32 v[36:37], v[36:37], 0.5, v[64:65] op_sel_hi:[1,0,1]
	v_pk_fma_f32 v[42:43], v[42:43], 0.5, v[52:53] op_sel_hi:[1,0,1]
	v_pk_fma_f32 v[40:41], v[40:41], 0.5, v[62:63] op_sel_hi:[1,0,1]
	v_pk_fma_f32 v[50:51], v[34:35], 0.5, v[56:57] op_sel_hi:[1,0,1]
	v_pk_fma_f32 v[52:53], v[32:33], 0.5, v[66:67] op_sel_hi:[1,0,1]
	v_mul_f32_e32 v34, v45, v45
	v_mul_f32_e32 v35, v47, v47
	v_mul_f32_e32 v54, v37, v37
	v_mul_f32_e32 v55, v39, v39
	v_cvt_pk_bf16_f32 v32, v44, v45
	v_mul_f32_e32 v45, v41, v41
	v_mul_f32_e32 v56, v53, v53
	v_fmac_f32_e32 v34, v44, v44
	v_fmac_f32_e32 v35, v46, v46
	v_fmac_f32_e32 v54, v36, v36
	v_fmac_f32_e32 v55, v38, v38
	v_cvt_pk_bf16_f32 v33, v46, v47
	v_mul_f32_e32 v47, v43, v43
	v_mul_f32_e32 v57, v51, v51
	v_fmac_f32_e32 v45, v40, v40
	v_fmac_f32_e32 v56, v52, v52
	v_add_f32_e32 v34, v34, v35
	v_add_f32_e32 v35, v54, v55
	v_fmac_f32_e32 v47, v42, v42
	v_fmac_f32_e32 v57, v50, v50
	v_add_f32_e32 v34, v45, v34
	v_add_f32_e32 v35, v56, v35
	v_add_f32_e32 v34, v47, v34
	v_add_f32_e32 v35, v57, v35
	v_add_f32_e32 v44, v34, v35
	v_mov_b32_e32 v45, v44
	s_nop 1
	v_permlane16_swap_b32_e32 v45, v44
	v_cvt_pk_bf16_f32 v34, v40, v41
	v_cvt_pk_bf16_f32 v35, v42, v43
	global_store_dwordx4 v[58:59], v[32:35], off sc1
	s_waitcnt lgkmcnt(0)
	s_nop 0
	v_add_f32_e32 v32, v44, v45
	v_mov_b32_e32 v33, v32
	s_nop 1
	v_permlane32_swap_b32_e32 v33, v32
	v_cvt_pk_bf16_f32 v34, v36, v37
	v_cvt_pk_bf16_f32 v35, v38, v39
	v_cvt_pk_bf16_f32 v36, v52, v53
	v_cvt_pk_bf16_f32 v37, v50, v51
	global_store_dwordx4 v[58:59], v[34:37], off offset:256 sc1
	s_and_saveexec_b64 s[50:51], s[10:11]
	s_cbranch_execz .LBB0_1212
	s_waitcnt lgkmcnt(0)
	v_add_f32_e32 v32, v32, v33
	v_mul_f32_e32 v32, 0x4f800000, v32
	v_trunc_f32_e32 v32, v32
	v_mul_f32_e64 v33, |v32|, s66
	v_floor_f32_e32 v33, v33
	v_fma_f32 v34, v33, s67, |v32|
	v_cvt_u32_f32_e32 v32, v34
	v_cvt_u32_f32_e32 v33, v33
	v_lshl_add_u64 v[34:35], v[48:49], 3, s[36:37]
	global_atomic_add_x2 v[34:35], v[32:33], off
; __device__ __forceinline__ void fx_add(float* p, size_t idx, float s) { atomicAdd((unsigned long long*)p + idx, (unsigned long long)(long long)(s * 4294967296.0f)); }
; __device__ __forceinline__ unsigned cvtpk(float lo, float hi) { f32x2v_ v = {lo, hi}; bf16x2v_ b = __builtin_convertvector(v, bf16x2v_); return __builtin_bit_cast(unsigned, b); }
;     __device__ __forceinline__ void operator()(const f32x4 (&acc)[2][2][4][2], const Unit& u, int wr, int wc, int fr, int fq) const {
;     ...
;             for (int m = 0; m < 4; ++m) { const int row = row0 + ai * HALF + m * 16; const size_t off = (size_t)row * 1024 + col0; float s = 0.f;
; #pragma unroll
;                 for (int bj = 0; bj < 2; ++bj) { f32x4 a0, a1;
;                     if (xin32) { const float* p = xin32 + off + bj * HALF; a0 = *(const f32x4*)p; a1 = *(const f32x4*)(p + 4); }
;                     else { const u32x4 w = *(const u32x4*)(xb + off + bj * HALF);
;                         a0 = (f32x4){__uint_as_float(w.x << 16), __uint_as_float(w.x & 0xffff0000u), __uint_as_float(w.y << 16), __uint_as_float(w.y & 0xffff0000u)};
;                         a1 = (f32x4){__uint_as_float(w.z << 16), __uint_as_float(w.z & 0xffff0000u), __uint_as_float(w.w << 16), __uint_as_float(w.w & 0xffff0000u)}; }
;                     const f32x4 v0 = a0 + acc[ai][bj][m][0] * alpha, v1 = a1 + acc[ai][bj][m][1] * alpha;
;                     u32x4 w; w.x = cvtpk(v0[0], v0[1]); w.y = cvtpk(v0[2], v0[3]); w.z = cvtpk(v1[0], v1[1]); w.w = cvtpk(v1[2], v1[3]);
;                     *(u32x4*)(xb + off + bj * HALF) = w;
;                     s += (v0[0] * v0[0] + v0[1] * v0[1]) + (v0[2] * v0[2] + v0[3] * v0[3]) + (v1[0] * v1[0] + v1[1] * v1[1]) + (v1[2] * v1[2] + v1[3] * v1[3]); }
;                 s += __shfl_xor(s, 16); s += __shfl_xor(s, 32);
;                 if (fq == 0) fx_add(ssout, row, s); }
.LBB0_1212:
	s_or_b64 exec, exec, s[50:51]
	v_add_u32_e32 v32, 0xa0, v146
	s_waitcnt lgkmcnt(0)
	v_ashrrev_i32_e32 v33, 31, v32
	v_lshlrev_b64 v[34:35], 11, v[32:33]
	v_lshl_add_u64 v[34:35], s[22:23], 0, v[34:35]
	v_lshl_add_u64 v[42:43], v[144:145], 1, v[34:35]
	global_load_dwordx4 v[34:37], v[42:43], off
	global_load_dwordx4 v[38:41], v[42:43], off offset:256
	s_waitcnt vmcnt(1)
	v_lshlrev_b32_e32 v44, 16, v34
	v_and_b32_e32 v45, 0xffff0000, v34
	v_lshlrev_b32_e32 v34, 16, v35
	v_and_b32_e32 v35, 0xffff0000, v35
	s_waitcnt vmcnt(0)
	v_lshlrev_b32_e32 v48, 16, v38
	v_and_b32_e32 v49, 0xffff0000, v38
	v_lshlrev_b32_e32 v38, 16, v39
	v_and_b32_e32 v39, 0xffff0000, v39
	v_lshlrev_b32_e32 v46, 16, v36
	v_and_b32_e32 v47, 0xffff0000, v36
	v_lshlrev_b32_e32 v36, 16, v37
	v_and_b32_e32 v37, 0xffff0000, v37
	v_lshlrev_b32_e32 v50, 16, v40
	v_and_b32_e32 v51, 0xffff0000, v40
	v_lshlrev_b32_e32 v40, 16, v41
	v_and_b32_e32 v41, 0xffff0000, v41
	v_pk_fma_f32 v[30:31], v[30:31], 0.5, v[34:35] op_sel_hi:[1,0,1]
	v_pk_fma_f32 v[28:29], v[28:29], 0.5, v[44:45] op_sel_hi:[1,0,1]
	v_pk_fma_f32 v[22:23], v[22:23], 0.5, v[38:39] op_sel_hi:[1,0,1]
	v_pk_fma_f32 v[20:21], v[20:21], 0.5, v[48:49] op_sel_hi:[1,0,1]
	v_pk_fma_f32 v[26:27], v[26:27], 0.5, v[36:37] op_sel_hi:[1,0,1]
	v_pk_fma_f32 v[24:25], v[24:25], 0.5, v[46:47] op_sel_hi:[1,0,1]
	v_pk_fma_f32 v[34:35], v[18:19], 0.5, v[40:41] op_sel_hi:[1,0,1]
	v_pk_fma_f32 v[36:37], v[16:17], 0.5, v[50:51] op_sel_hi:[1,0,1]
	v_mul_f32_e32 v18, v29, v29
	v_mul_f32_e32 v19, v31, v31
	v_mul_f32_e32 v38, v21, v21
	v_mul_f32_e32 v39, v23, v23
	v_cvt_pk_bf16_f32 v16, v28, v29
	v_mul_f32_e32 v29, v25, v25
	v_mul_f32_e32 v40, v37, v37
	v_fmac_f32_e32 v18, v28, v28
	v_fmac_f32_e32 v19, v30, v30
	v_fmac_f32_e32 v38, v20, v20
	v_fmac_f32_e32 v39, v22, v22
	v_cvt_pk_bf16_f32 v17, v30, v31
	v_mul_f32_e32 v31, v27, v27
	v_mul_f32_e32 v41, v35, v35
	v_fmac_f32_e32 v29, v24, v24
	v_fmac_f32_e32 v40, v36, v36
	v_add_f32_e32 v18, v18, v19
	v_add_f32_e32 v19, v38, v39
	v_fmac_f32_e32 v31, v26, v26
	v_fmac_f32_e32 v41, v34, v34
	v_add_f32_e32 v18, v29, v18
	v_add_f32_e32 v19, v40, v19
	v_add_f32_e32 v18, v31, v18
	v_add_f32_e32 v19, v41, v19
	v_add_f32_e32 v28, v18, v19
	v_mov_b32_e32 v29, v28
	s_nop 1
	v_permlane16_swap_b32_e32 v29, v28
	v_cvt_pk_bf16_f32 v18, v24, v25
	v_cvt_pk_bf16_f32 v19, v26, v27
	global_store_dwordx4 v[42:43], v[16:19], off sc1
	s_waitcnt lgkmcnt(0)
	s_nop 0
	v_add_f32_e32 v16, v28, v29
	v_mov_b32_e32 v17, v16
	s_nop 1
	v_permlane32_swap_b32_e32 v17, v16
	v_cvt_pk_bf16_f32 v18, v20, v21
	v_cvt_pk_bf16_f32 v19, v22, v23
	v_cvt_pk_bf16_f32 v20, v36, v37
	v_cvt_pk_bf16_f32 v21, v34, v35
	global_store_dwordx4 v[42:43], v[18:21], off offset:256 sc1
	s_and_saveexec_b64 s[50:51], s[10:11]
	s_cbranch_execz .LBB0_1214
	s_waitcnt lgkmcnt(0)
	v_add_f32_e32 v16, v16, v17
	v_mul_f32_e32 v16, 0x4f800000, v16
	v_trunc_f32_e32 v16, v16
	v_mul_f32_e64 v17, |v16|, s66
	v_floor_f32_e32 v17, v17
	v_fma_f32 v18, v17, s67, |v16|
	v_cvt_u32_f32_e32 v16, v18
	v_cvt_u32_f32_e32 v17, v17
	v_lshl_add_u64 v[18:19], v[32:33], 3, s[36:37]
	global_atomic_add_x2 v[18:19], v[16:17], off
.LBB0_1214:
	s_or_b64 exec, exec, s[50:51]
	v_add_u32_e32 v16, 0xb0, v146
	s_waitcnt lgkmcnt(0)
	v_ashrrev_i32_e32 v17, 31, v16
	v_lshlrev_b64 v[18:19], 11, v[16:17]
	v_lshl_add_u64 v[18:19], s[22:23], 0, v[18:19]
	v_lshl_add_u64 v[26:27], v[144:145], 1, v[18:19]
	global_load_dwordx4 v[18:21], v[26:27], off
	global_load_dwordx4 v[22:25], v[26:27], off offset:256
	s_waitcnt vmcnt(1)
	v_lshlrev_b32_e32 v28, 16, v18
	v_and_b32_e32 v29, 0xffff0000, v18
	v_lshlrev_b32_e32 v18, 16, v19
	v_and_b32_e32 v19, 0xffff0000, v19
	s_waitcnt vmcnt(0)
	v_lshlrev_b32_e32 v32, 16, v22
	v_and_b32_e32 v33, 0xffff0000, v22
	v_lshlrev_b32_e32 v22, 16, v23
	v_and_b32_e32 v23, 0xffff0000, v23
	v_lshlrev_b32_e32 v30, 16, v20
	v_and_b32_e32 v31, 0xffff0000, v20
	v_lshlrev_b32_e32 v20, 16, v21
	v_and_b32_e32 v21, 0xffff0000, v21
	v_lshlrev_b32_e32 v34, 16, v24
	v_and_b32_e32 v35, 0xffff0000, v24
	v_lshlrev_b32_e32 v24, 16, v25
	v_and_b32_e32 v25, 0xffff0000, v25
	v_pk_fma_f32 v[14:15], v[14:15], 0.5, v[18:19] op_sel_hi:[1,0,1]
	v_pk_fma_f32 v[12:13], v[12:13], 0.5, v[28:29] op_sel_hi:[1,0,1]
	v_pk_fma_f32 v[6:7], v[6:7], 0.5, v[22:23] op_sel_hi:[1,0,1]
	v_pk_fma_f32 v[4:5], v[4:5], 0.5, v[32:33] op_sel_hi:[1,0,1]
	v_pk_fma_f32 v[10:11], v[10:11], 0.5, v[20:21] op_sel_hi:[1,0,1]
	v_pk_fma_f32 v[8:9], v[8:9], 0.5, v[30:31] op_sel_hi:[1,0,1]
	v_pk_fma_f32 v[18:19], v[2:3], 0.5, v[24:25] op_sel_hi:[1,0,1]
	v_pk_fma_f32 v[20:21], v[0:1], 0.5, v[34:35] op_sel_hi:[1,0,1]
	v_mul_f32_e32 v2, v13, v13
	v_mul_f32_e32 v3, v15, v15
	v_mul_f32_e32 v22, v5, v5
	v_mul_f32_e32 v23, v7, v7
	v_cvt_pk_bf16_f32 v0, v12, v13
	v_mul_f32_e32 v13, v9, v9
	v_mul_f32_e32 v24, v21, v21
	v_fmac_f32_e32 v2, v12, v12
	v_fmac_f32_e32 v3, v14, v14
	v_fmac_f32_e32 v22, v4, v4
	v_fmac_f32_e32 v23, v6, v6
	v_cvt_pk_bf16_f32 v1, v14, v15
	v_mul_f32_e32 v15, v11, v11
	v_mul_f32_e32 v25, v19, v19
	v_fmac_f32_e32 v13, v8, v8
	v_fmac_f32_e32 v24, v20, v20
	v_add_f32_e32 v2, v2, v3
	v_add_f32_e32 v3, v22, v23
	v_fmac_f32_e32 v15, v10, v10
	v_fmac_f32_e32 v25, v18, v18
	v_add_f32_e32 v2, v13, v2
	v_add_f32_e32 v3, v24, v3
	v_add_f32_e32 v2, v15, v2
	v_add_f32_e32 v3, v25, v3
	v_add_f32_e32 v12, v2, v3
	v_mov_b32_e32 v13, v12
	s_nop 1
	v_permlane16_swap_b32_e32 v13, v12
	v_cvt_pk_bf16_f32 v2, v8, v9
	v_cvt_pk_bf16_f32 v3, v10, v11
	global_store_dwordx4 v[26:27], v[0:3], off sc1
	s_waitcnt lgkmcnt(0)
	s_nop 0
	v_add_f32_e32 v0, v12, v13
	v_mov_b32_e32 v1, v0
	s_nop 1
	v_permlane32_swap_b32_e32 v1, v0
	v_cvt_pk_bf16_f32 v2, v4, v5
	v_cvt_pk_bf16_f32 v3, v6, v7
	v_cvt_pk_bf16_f32 v4, v20, v21
	v_cvt_pk_bf16_f32 v5, v18, v19
	global_store_dwordx4 v[26:27], v[2:5], off offset:256 sc1
	s_and_saveexec_b64 s[50:51], s[10:11]
	s_cbranch_execz .LBB0_1216
	s_waitcnt lgkmcnt(0)
	v_add_f32_e32 v0, v0, v1
	v_mul_f32_e32 v0, 0x4f800000, v0
	v_trunc_f32_e32 v0, v0
	v_mul_f32_e64 v1, |v0|, s66
	v_floor_f32_e32 v1, v1
	v_fma_f32 v2, v1, s67, |v0|
	v_cvt_u32_f32_e32 v0, v2
	v_cvt_u32_f32_e32 v1, v1
	v_lshl_add_u64 v[2:3], v[16:17], 3, s[36:37]
	global_atomic_add_x2 v[2:3], v[0:1], off

; __device__ __forceinline__ unsigned cvtpk(float lo, float hi) { f32x2v_ v = {lo, hi}; bf16x2v_ b = __builtin_convertvector(v, bf16x2v_); return __builtin_bit_cast(unsigned, b); }
;     __device__ __forceinline__ void operator()(const f32x4 (&acc)[2][2][4][2], const Unit& u, int wr, int wc, int fr, int fq) const {
;     ...
;                     for (int m = 0; m < 4; ++m) { const int row = row0 + ai * HALF + m * 16; const float rs = ss ? row_rs(ss, row) : 1.0f;
;                         const f32x4 v0 = acc[ai][bj][m][0] * rs, v1 = acc[ai][bj][m][1] * rs;
;                         const int b = row >> S_shift, pos = row & ((1 << S_shift) - 1);
;                         const size_t tile = ((size_t)(b * kvh + head) << (S_shift - 5)) + (pos >> 5);
;                         u32x4 w; w.x = cvtpk(v0[0], v0[1]); w.y = cvtpk(v0[2], v0[3]); w.z = cvtpk(v1[0], v1[1]); w.w = cvtpk(v1[2], v1[3]);
;                         *(u32x4*)(KP + tile * (size_t)(32 * DH) + ((d >> 3) * 32 + (pos & 31)) * 8) = w;
; #pragma unroll
;                         for (int e = 0; e < 4; ++e) { cs[e] += v0[e]; cs[4 + e] += v1[e]; } }
.LBB0_1293:
	s_andn2_b64 vcc, exec, s[60:61]
	s_cbranch_vccnz .LBB0_1297
	s_add_i32 s49, s58, 0xfffffc00
	s_ashr_i32 s49, s49, 7
	v_add_u32_e32 v172, s49, v211
	v_ashrrev_i32_e32 v173, 31, v172
	v_lshlrev_b64 v[172:173], 20, v[172:173]
	v_lshlrev_b32_e32 v140, 8, v160
	v_lshl_add_u64 v[190:191], s[26:27], 0, v[172:173]
	v_and_b32_e32 v140, 0xfc000, v140
	v_lshl_add_u64 v[172:173], v[190:191], 0, v[140:141]
	v_lshlrev_b32_e32 v140, 1, v148
	v_lshl_add_u64 v[174:175], v[172:173], 0, v[140:141]
	global_store_dwordx4 v[174:175], v[128:131], off sc1
	v_or_b32_e32 v182, 32, v160
	v_ashrrev_i32_e32 v183, 31, v182
	v_or_b32_e32 v128, 16, v160
	v_ashrrev_i32_e32 v129, 31, v128
	v_lshl_add_u64 v[130:131], v[128:129], 3, s[36:37]
	global_load_dwordx2 v[130:131], v[130:131], off
	v_and_or_b32 v128, v128, 31, v149
	v_mov_b32_e32 v129, v141
	v_lshlrev_b32_e32 v128, 4, v128
	v_lshl_add_u64 v[186:187], v[172:173], 0, v[128:129]
	v_lshl_add_u64 v[184:185], v[182:183], 3, s[36:37]
	v_or_b32_e32 v192, 48, v160
	v_ashrrev_i32_e32 v193, 31, v192
	v_lshl_add_u64 v[194:195], v[192:193], 3, s[36:37]
	v_mov_b32_e32 v193, v141
	v_add_f32_e32 v170, 0, v170
	v_add_f32_e32 v167, 0, v167
	v_add_f32_e32 v168, 0, v168
	v_add_f32_e32 v169, 0, v169
	v_add_f32_e32 v171, 0, v171
	v_add_f32_e32 v166, 0, v166
	s_waitcnt vmcnt(0)
	v_ffbh_u32_e32 v174, v131
	v_min_u32_e32 v174, 32, v174
	v_lshlrev_b64 v[130:131], v174, v[130:131]
	v_min_u32_e32 v130, 1, v130
	v_or_b32_e32 v130, v131, v130
	v_cvt_f32_u32_e32 v130, v130
	v_sub_u32_e32 v131, 32, v174
	v_ldexp_f32 v130, v130, v131
	v_mul_f32_e32 v130, 0x2f800000, v130
	v_fmamk_f32 v130, v130, 0x3a800000, v209
	v_rsq_f32_e32 v174, v130
	s_nop 0
	v_pk_mul_f32 v[128:129], v[118:119], v[174:175] op_sel_hi:[1,0]
	v_pk_mul_f32 v[172:173], v[116:117], v[174:175] op_sel_hi:[1,0]
	v_pk_mul_f32 v[130:131], v[114:115], v[174:175] op_sel_hi:[1,0]
	v_pk_mul_f32 v[174:175], v[112:113], v[174:175] op_sel_hi:[1,0]
	v_cvt_pk_bf16_f32 v176, v172, v173
	v_cvt_pk_bf16_f32 v177, v128, v129
	v_cvt_pk_bf16_f32 v178, v174, v175
	v_cvt_pk_bf16_f32 v179, v130, v131
	global_store_dwordx4 v[186:187], v[176:179], off sc1
	global_load_dwordx2 v[176:177], v[184:185], off
	v_add_f32_e32 v131, v167, v131
	v_lshlrev_b32_e32 v178, 8, v182
	v_mov_b32_e32 v179, v141
	v_and_b32_e32 v178, 0xfe000, v178
	v_add_f32_e32 v130, v166, v130
	s_waitcnt vmcnt(0)
	v_ffbh_u32_e32 v182, v177
	v_min_u32_e32 v182, 32, v182
	v_lshlrev_b64 v[176:177], v182, v[176:177]
	v_min_u32_e32 v176, 1, v176
	v_or_b32_e32 v176, v177, v176
	v_cvt_f32_u32_e32 v176, v176
	v_sub_u32_e32 v177, 32, v182
	v_ldexp_f32 v176, v176, v177
	v_mul_f32_e32 v176, 0x2f800000, v176
	v_fmamk_f32 v176, v176, 0x3a800000, v209
	v_rsq_f32_e32 v184, v176
	v_lshl_add_u64 v[176:177], v[190:191], 0, v[178:179]
	v_lshl_add_u64 v[196:197], v[176:177], 0, v[140:141]
	v_pk_mul_f32 v[176:177], v[110:111], v[184:185] op_sel_hi:[1,0]
	v_pk_mul_f32 v[182:183], v[108:109], v[184:185] op_sel_hi:[1,0]
	v_pk_mul_f32 v[178:179], v[106:107], v[184:185] op_sel_hi:[1,0]
	v_pk_mul_f32 v[184:185], v[104:105], v[184:185] op_sel_hi:[1,0]
	v_cvt_pk_bf16_f32 v186, v182, v183
	v_cvt_pk_bf16_f32 v187, v176, v177
	v_cvt_pk_bf16_f32 v188, v184, v185
	v_cvt_pk_bf16_f32 v189, v178, v179
	global_store_dwordx4 v[196:197], v[186:189], off sc1
	global_load_dwordx2 v[186:187], v[194:195], off
	v_add_f32_e32 v130, v130, v178
	v_lshlrev_b32_e32 v188, 8, v192
	v_mov_b32_e32 v189, v141
	v_and_b32_e32 v188, 0xfe000, v188
	v_add_f32_e32 v131, v131, v179
	s_waitcnt vmcnt(0)
	v_ffbh_u32_e32 v194, v187
	v_min_u32_e32 v194, 32, v194
	v_lshlrev_b64 v[186:187], v194, v[186:187]
	v_min_u32_e32 v186, 1, v186
	v_or_b32_e32 v186, v187, v186
	v_cvt_f32_u32_e32 v186, v186
	v_and_or_b32 v187, v192, 31, v149
	v_sub_u32_e32 v192, 32, v194
	v_ldexp_f32 v186, v186, v192
	v_mul_f32_e32 v186, 0x2f800000, v186
	v_fmamk_f32 v186, v186, 0x3a800000, v209
	v_rsq_f32_e32 v194, v186
	v_lshlrev_b32_e32 v192, 4, v187
	v_lshl_add_u64 v[186:187], v[190:191], 0, v[188:189]
	v_lshl_add_u64 v[198:199], v[186:187], 0, v[192:193]
	v_pk_mul_f32 v[186:187], v[102:103], v[194:195] op_sel_hi:[1,0]
	v_pk_mul_f32 v[190:191], v[100:101], v[194:195] op_sel_hi:[1,0]
	v_pk_mul_f32 v[188:189], v[98:99], v[194:195] op_sel_hi:[1,0]
	v_pk_mul_f32 v[192:193], v[96:97], v[194:195] op_sel_hi:[1,0]
	v_cvt_pk_bf16_f32 v194, v190, v191
	v_cvt_pk_bf16_f32 v195, v186, v187
	v_cvt_pk_bf16_f32 v196, v192, v193
	v_cvt_pk_bf16_f32 v197, v188, v189
	global_store_dwordx4 v[198:199], v[194:197], off sc1
	global_load_dwordx2 v[194:195], v[162:163], off offset:1024
	v_add_f32_e32 v130, v130, v188
	v_add_u32_e32 v196, 0x80, v160
	v_ashrrev_i32_e32 v198, 10, v196
	v_and_b32_e32 v198, -4, v198
	v_add_u32_e32 v198, s49, v198
	v_lshlrev_b32_e32 v196, 8, v196
	v_mov_b32_e32 v197, v141
	v_and_b32_e32 v196, 0xfc000, v196
	v_add_f32_e32 v131, v131, v189
	s_waitcnt vmcnt(0)
	v_ffbh_u32_e32 v199, v195
	v_min_u32_e32 v200, 32, v199
	v_lshlrev_b64 v[194:195], v200, v[194:195]
	v_min_u32_e32 v194, 1, v194
	v_or_b32_e32 v194, v195, v194
	v_cvt_f32_u32_e32 v201, v194
	v_ashrrev_i32_e32 v199, 31, v198
	v_lshlrev_b64 v[194:195], 20, v[198:199]
	v_sub_u32_e32 v198, 32, v200
	v_ldexp_f32 v198, v201, v198
	v_mul_f32_e32 v198, 0x2f800000, v198
	v_fmamk_f32 v198, v198, 0x3a800000, v209
	v_rsq_f32_e32 v200, v198
	v_lshl_add_u64 v[194:195], s[26:27], 0, v[194:195]
	v_lshl_add_u64 v[194:195], v[194:195], 0, v[196:197]
	v_lshl_add_u64 v[216:217], v[194:195], 0, v[140:141]
	v_pk_mul_f32 v[194:195], v[94:95], v[200:201] op_sel_hi:[1,0]
	v_pk_mul_f32 v[198:199], v[92:93], v[200:201] op_sel_hi:[1,0]
	v_pk_mul_f32 v[196:197], v[90:91], v[200:201] op_sel_hi:[1,0]
	v_pk_mul_f32 v[200:201], v[88:89], v[200:201] op_sel_hi:[1,0]
	v_cvt_pk_bf16_f32 v212, v198, v199
	v_cvt_pk_bf16_f32 v213, v194, v195
	v_cvt_pk_bf16_f32 v214, v200, v201
	v_cvt_pk_bf16_f32 v215, v196, v197
	global_store_dwordx4 v[216:217], v[212:215], off sc1
	global_load_dwordx2 v[212:213], v[162:163], off offset:1152
	v_mov_b32_e32 v217, v141
	v_add_u32_e32 v214, 0x90, v160
	v_ashrrev_i32_e32 v216, 10, v214
	v_and_or_b32 v219, v214, 31, v149
	v_lshlrev_b32_e32 v218, 8, v214
	v_and_b32_e32 v220, -4, v216
	v_lshlrev_b32_e32 v216, 4, v219
	v_and_b32_e32 v214, 0xfc000, v218
	v_add_u32_e32 v218, s49, v220
	v_mov_b32_e32 v215, v141
	v_add_f32_e32 v130, v130, v196
	v_add_f32_e32 v131, v131, v197
	s_waitcnt vmcnt(0)
; __device__ __forceinline__ unsigned cvtpk(float lo, float hi) { f32x2v_ v = {lo, hi}; bf16x2v_ b = __builtin_convertvector(v, bf16x2v_); return __builtin_bit_cast(unsigned, b); }
;     __device__ __forceinline__ void operator()(const f32x4 (&acc)[2][2][4][2], const Unit& u, int wr, int wc, int fr, int fq) const {
;     ...
;                     for (int m = 0; m < 4; ++m) { const int row = row0 + ai * HALF + m * 16; const float rs = ss ? row_rs(ss, row) : 1.0f;
;                         const f32x4 v0 = acc[ai][bj][m][0] * rs, v1 = acc[ai][bj][m][1] * rs;
;                         const int b = row >> S_shift, pos = row & ((1 << S_shift) - 1);
;                         const size_t tile = ((size_t)(b * kvh + head) << (S_shift - 5)) + (pos >> 5);
;                         u32x4 w; w.x = cvtpk(v0[0], v0[1]); w.y = cvtpk(v0[2], v0[3]); w.z = cvtpk(v1[0], v1[1]); w.w = cvtpk(v1[2], v1[3]);
;                         *(u32x4*)(KP + tile * (size_t)(32 * DH) + ((d >> 3) * 32 + (pos & 31)) * 8) = w;
; #pragma unroll
;                         for (int e = 0; e < 4; ++e) { cs[e] += v0[e]; cs[4 + e] += v1[e]; } }
;                 if (ksum) {
; #pragma unroll
;                     for (int e = 0; e < 8; ++e) { float s = cs[e]; s += __shfl_xor(s, 1); s += __shfl_xor(s, 2); s += __shfl_xor(s, 4); s += __shfl_xor(s, 8); cs[e] = s; }
	v_ffbh_u32_e32 v219, v213
	v_min_u32_e32 v220, 32, v219
	v_lshlrev_b64 v[212:213], v220, v[212:213]
	v_min_u32_e32 v212, 1, v212
	v_or_b32_e32 v212, v213, v212
	v_cvt_f32_u32_e32 v221, v212
	v_ashrrev_i32_e32 v219, 31, v218
	v_lshlrev_b64 v[212:213], 20, v[218:219]
	v_sub_u32_e32 v218, 32, v220
	v_ldexp_f32 v218, v221, v218
	v_mul_f32_e32 v218, 0x2f800000, v218
	v_fmamk_f32 v218, v218, 0x3a800000, v209
	v_rsq_f32_e32 v218, v218
	v_lshl_add_u64 v[212:213], s[26:27], 0, v[212:213]
	v_lshl_add_u64 v[212:213], v[212:213], 0, v[214:215]
	v_lshl_add_u64 v[216:217], v[212:213], 0, v[216:217]
	v_pk_mul_f32 v[220:221], v[86:87], v[218:219] op_sel_hi:[1,0]
	v_pk_mul_f32 v[222:223], v[84:85], v[218:219] op_sel_hi:[1,0]
	v_pk_mul_f32 v[224:225], v[82:83], v[218:219] op_sel_hi:[1,0]
	v_pk_mul_f32 v[218:219], v[80:81], v[218:219] op_sel_hi:[1,0]
	v_cvt_pk_bf16_f32 v212, v222, v223
	v_cvt_pk_bf16_f32 v213, v220, v221
	v_cvt_pk_bf16_f32 v214, v218, v219
	v_cvt_pk_bf16_f32 v215, v224, v225
	global_store_dwordx4 v[216:217], v[212:215], off sc1
	global_load_dwordx2 v[212:213], v[162:163], off offset:1280
	v_add_f32_e32 v130, v130, v224
	v_add_u32_e32 v214, 0xa0, v160
	v_ashrrev_i32_e32 v216, 10, v214
	v_and_b32_e32 v216, -4, v216
	v_add_u32_e32 v216, s49, v216
	v_lshlrev_b32_e32 v214, 8, v214
	v_mov_b32_e32 v215, v141
	v_and_b32_e32 v214, 0xfe000, v214
	v_add_f32_e32 v131, v131, v225
	s_waitcnt vmcnt(0)
	v_ffbh_u32_e32 v217, v213
	v_min_u32_e32 v226, 32, v217
	v_lshlrev_b64 v[212:213], v226, v[212:213]
	v_min_u32_e32 v212, 1, v212
	v_or_b32_e32 v212, v213, v212
	v_cvt_f32_u32_e32 v227, v212
	v_ashrrev_i32_e32 v217, 31, v216
	v_lshlrev_b64 v[212:213], 20, v[216:217]
	v_sub_u32_e32 v216, 32, v226
	v_ldexp_f32 v216, v227, v216
	v_mul_f32_e32 v216, 0x2f800000, v216
	v_fmamk_f32 v216, v216, 0x3a800000, v209
	v_rsq_f32_e32 v216, v216
	v_lshl_add_u64 v[212:213], s[26:27], 0, v[212:213]
	v_lshl_add_u64 v[212:213], v[212:213], 0, v[214:215]
	v_lshl_add_u64 v[226:227], v[212:213], 0, v[140:141]
	v_pk_mul_f32 v[228:229], v[78:79], v[216:217] op_sel_hi:[1,0]
	v_pk_mul_f32 v[230:231], v[76:77], v[216:217] op_sel_hi:[1,0]
	v_pk_mul_f32 v[232:233], v[74:75], v[216:217] op_sel_hi:[1,0]
	v_pk_mul_f32 v[216:217], v[72:73], v[216:217] op_sel_hi:[1,0]
	v_cvt_pk_bf16_f32 v212, v230, v231
	v_cvt_pk_bf16_f32 v213, v228, v229
	v_cvt_pk_bf16_f32 v214, v216, v217
	v_cvt_pk_bf16_f32 v215, v232, v233
	global_store_dwordx4 v[226:227], v[212:215], off sc1
	global_load_dwordx2 v[162:163], v[162:163], off offset:1408
	v_xor_b32_e32 v140, 1, v210
	v_add_f32_e32 v214, 0, v164
	v_and_b32_e32 v164, 64, v210
	v_add_u32_e32 v164, 64, v164
	v_add_f32_e32 v215, 0, v165
	v_add_u32_e32 v226, 0xb0, v160
	v_xor_b32_e32 v165, 2, v210
	v_cmp_lt_i32_e32 vcc, v140, v164
	v_xor_b32_e32 v212, 4, v210
	v_ashrrev_i32_e32 v227, 10, v226
	v_cndmask_b32_e32 v140, v210, v140, vcc
	v_cmp_lt_i32_e32 vcc, v165, v164
	v_xor_b32_e32 v213, 8, v210
	v_and_b32_e32 v227, -4, v227
	v_cndmask_b32_e32 v165, v210, v165, vcc
	v_cmp_lt_i32_e32 vcc, v212, v164
	v_lshlrev_b32_e32 v235, 2, v165
	v_lshlrev_b32_e32 v234, 8, v226
	v_cndmask_b32_e32 v212, v210, v212, vcc
	v_cmp_lt_i32_e32 vcc, v213, v164
	v_add_u32_e32 v164, s49, v227
	v_ashrrev_i32_e32 v165, 31, v164
	v_lshlrev_b64 v[164:165], 20, v[164:165]
	v_cndmask_b32_e32 v213, v210, v213, vcc
	v_lshlrev_b32_e32 v227, 2, v140
	v_lshl_add_u64 v[164:165], s[26:27], 0, v[164:165]
	v_and_b32_e32 v140, 0xfe000, v234
	v_lshlrev_b32_e32 v236, 2, v212
	v_lshlrev_b32_e32 v237, 2, v213
	v_lshl_add_u64 v[212:213], v[164:165], 0, v[140:141]
	v_add_f32_e32 v164, v170, v174
	v_add_f32_e32 v128, v214, v128
	v_add_f32_e32 v164, v164, v184
	v_add_f32_e32 v128, v128, v176
	v_add_f32_e32 v129, v215, v129
	v_add_f32_e32 v164, v164, v192
	v_add_f32_e32 v128, v128, v186
	v_add_f32_e32 v129, v129, v177
	v_add_f32_e32 v164, v164, v200
	v_add_f32_e32 v128, v128, v194
	v_add_f32_e32 v129, v129, v187
	v_add_f32_e32 v164, v164, v218
	v_add_f32_e32 v167, v128, v220
	v_add_f32_e32 v140, v168, v172
	v_add_f32_e32 v165, v169, v173
	v_add_f32_e32 v168, v171, v175
	v_add_f32_e32 v129, v129, v195
	v_add_f32_e32 v169, v164, v216
	v_add_f32_e32 v166, v168, v185
	v_add_f32_e32 v168, v129, v221
	v_add_f32_e32 v140, v140, v182
	v_add_f32_e32 v165, v165, v183
	v_add_f32_e32 v140, v140, v190
	v_add_f32_e32 v165, v165, v191
	v_add_f32_e32 v166, v166, v193
	v_add_f32_e32 v140, v140, v198
	v_add_f32_e32 v165, v165, v199
	v_add_f32_e32 v166, v166, v201
	v_add_f32_e32 v140, v140, v222
	v_add_f32_e32 v165, v165, v223
	v_add_f32_e32 v166, v166, v219
	v_add_f32_e32 v140, v140, v230
	v_add_f32_e32 v170, v165, v231
	v_add_f32_e32 v166, v166, v217
	v_add_f32_e32 v167, v167, v228
	v_add_f32_e32 v171, v130, v232
	v_add_f32_e32 v168, v168, v229
	v_add_f32_e32 v172, v131, v233
	s_waitcnt vmcnt(0)
	v_ffbh_u32_e32 v128, v163
	v_min_u32_e32 v164, 32, v128
	v_lshlrev_b64 v[128:129], v164, v[162:163]
	v_min_u32_e32 v128, 1, v128
	v_or_b32_e32 v128, v129, v128
	v_cvt_f32_u32_e32 v128, v128
	v_sub_u32_e32 v129, 32, v164
	v_ldexp_f32 v128, v128, v129
	v_mul_f32_e32 v128, 0x2f800000, v128
	v_fmamk_f32 v128, v128, 0x3a800000, v209
	v_rsq_f32_e32 v128, v128
	s_nop 0
	v_pk_mul_f32 v[130:131], v[70:71], v[128:129] op_sel_hi:[1,0]
	v_pk_mul_f32 v[162:163], v[68:69], v[128:129] op_sel_hi:[1,0]
	v_pk_mul_f32 v[164:165], v[66:67], v[128:129] op_sel_hi:[1,0]
	v_pk_mul_f32 v[128:129], v[64:65], v[128:129] op_sel_hi:[1,0]
	v_cvt_pk_bf16_f32 v174, v162, v163
	v_cvt_pk_bf16_f32 v175, v130, v131
	v_cvt_pk_bf16_f32 v176, v128, v129
	v_cvt_pk_bf16_f32 v177, v164, v165
	v_add_f32_e32 v165, v172, v165
	v_add_f32_e32 v131, v168, v131
	v_add_f32_e32 v164, v171, v164
	v_add_f32_e32 v130, v167, v130
	v_add_f32_e32 v129, v166, v129
	v_add_f32_e32 v163, v170, v163
	v_add_f32_e32 v128, v169, v128
	v_add_f32_e32 v140, v140, v162
	ds_bpermute_b32 v162, v227, v140
	ds_bpermute_b32 v166, v227, v163
	ds_bpermute_b32 v167, v227, v130
	ds_bpermute_b32 v168, v227, v131
	ds_bpermute_b32 v169, v227, v128
	ds_bpermute_b32 v170, v227, v129
	ds_bpermute_b32 v171, v227, v164
	ds_bpermute_b32 v172, v227, v165
	s_waitcnt lgkmcnt(7)
; __device__ __forceinline__ void fx_add(float* p, size_t idx, float s) { atomicAdd((unsigned long long*)p + idx, (unsigned long long)(long long)(s * 4294967296.0f)); }
;     __device__ __forceinline__ void operator()(const f32x4 (&acc)[2][2][4][2], const Unit& u, int wr, int wc, int fr, int fq) const {
;     ...
;                 if (ksum) {
; #pragma unroll
;                     for (int e = 0; e < 8; ++e) { float s = cs[e]; s += __shfl_xor(s, 1); s += __shfl_xor(s, 2); s += __shfl_xor(s, 4); s += __shfl_xor(s, 8); cs[e] = s; }
;                     if (fr == 0) { const int rowb = u.pm * BM; const int b = rowb >> S_shift, blk = (rowb & ((1 << S_shift) - 1)) >> 8;
;                         const size_t kd = ((size_t)((b * kvh + head) << (S_shift - 8)) + blk) * DH + d;
; #pragma unroll
;                         for (int e = 0; e < 8; ++e) fx_add(ksum, kd + e, cs[e]); }
	v_add_f32_e32 v140, v140, v162
	s_waitcnt lgkmcnt(6)
	v_add_f32_e32 v162, v163, v166
	s_waitcnt lgkmcnt(5)
	v_add_f32_e32 v130, v130, v167
	s_waitcnt lgkmcnt(4)
	v_add_f32_e32 v131, v131, v168
	s_waitcnt lgkmcnt(3)
	v_add_f32_e32 v128, v128, v169
	s_waitcnt lgkmcnt(2)
	v_add_f32_e32 v129, v129, v170
	s_waitcnt lgkmcnt(1)
	v_add_f32_e32 v163, v164, v171
	s_waitcnt lgkmcnt(0)
	v_add_f32_e32 v164, v165, v172
	ds_bpermute_b32 v165, v235, v140
	ds_bpermute_b32 v166, v235, v162
	ds_bpermute_b32 v167, v235, v130
	ds_bpermute_b32 v168, v235, v131
	ds_bpermute_b32 v169, v235, v128
	ds_bpermute_b32 v170, v235, v129
	ds_bpermute_b32 v171, v235, v163
	ds_bpermute_b32 v172, v235, v164
	s_waitcnt lgkmcnt(7)
	v_add_f32_e32 v140, v140, v165
	s_waitcnt lgkmcnt(6)
	v_add_f32_e32 v162, v162, v166
	s_waitcnt lgkmcnt(5)
	v_add_f32_e32 v130, v130, v167
	s_waitcnt lgkmcnt(4)
	v_add_f32_e32 v131, v131, v168
	s_waitcnt lgkmcnt(3)
	v_add_f32_e32 v165, v128, v169
	s_waitcnt lgkmcnt(2)
	v_add_f32_e32 v166, v129, v170
	s_waitcnt lgkmcnt(1)
	v_add_f32_e32 v167, v163, v171
	s_waitcnt lgkmcnt(0)
	v_add_f32_e32 v164, v164, v172
	ds_bpermute_b32 v128, v236, v140
	ds_bpermute_b32 v129, v236, v162
	ds_bpermute_b32 v163, v236, v130
	ds_bpermute_b32 v168, v236, v131
	ds_bpermute_b32 v169, v236, v165
	ds_bpermute_b32 v170, v236, v166
	ds_bpermute_b32 v171, v236, v167
	ds_bpermute_b32 v172, v236, v164
	s_waitcnt lgkmcnt(7)
	v_add_f32_e32 v128, v140, v128
	s_waitcnt lgkmcnt(6)
	v_add_f32_e32 v129, v162, v129
	s_waitcnt lgkmcnt(5)
	v_add_f32_e32 v130, v130, v163
	s_waitcnt lgkmcnt(4)
	v_add_f32_e32 v131, v131, v168
	s_waitcnt lgkmcnt(3)
	v_add_f32_e32 v163, v165, v169
	s_waitcnt lgkmcnt(2)
	v_add_f32_e32 v165, v166, v170
	s_waitcnt lgkmcnt(1)
	v_add_f32_e32 v167, v167, v171
	s_waitcnt lgkmcnt(0)
	v_add_f32_e32 v169, v164, v172
	ds_bpermute_b32 v162, v237, v128
	ds_bpermute_b32 v164, v237, v129
	ds_bpermute_b32 v166, v237, v130
	ds_bpermute_b32 v168, v237, v131
	ds_bpermute_b32 v170, v237, v163
	ds_bpermute_b32 v171, v237, v165
	ds_bpermute_b32 v172, v237, v167
	ds_bpermute_b32 v173, v237, v169
	v_and_or_b32 v140, v226, 31, v149
	v_lshlrev_b32_e32 v140, 4, v140
	v_lshl_add_u64 v[178:179], v[212:213], 0, v[140:141]
	global_store_dwordx4 v[178:179], v[174:177], off sc1
	s_and_saveexec_b64 s[60:61], s[10:11]
	s_cbranch_execz .LBB0_1296
	s_waitcnt lgkmcnt(7)
	v_add_f32_e32 v128, v128, v162
	v_mul_f32_e32 v128, 0x4f800000, v128
	s_waitcnt lgkmcnt(5)
	v_add_f32_e32 v166, v130, v166
	v_trunc_f32_e32 v130, v128
	v_mul_f32_e64 v128, |v130|, s77
	v_floor_f32_e32 v128, v128
	v_add_f32_e32 v164, v129, v164
	v_fma_f32 v129, v128, s83, |v130|
	v_cvt_u32_f32_e32 v162, v129
	s_waitcnt lgkmcnt(0)
	v_add_f32_e32 v140, v169, v173
	v_add_f32_e32 v168, v131, v168
	v_cvt_u32_f32_e32 v131, v128
	v_ashrrev_i32_e32 v169, 31, v130
	v_xor_b32_e32 v130, v162, v169
	v_mul_f32_e32 v162, 0x4f800000, v164
	s_lshr_b32 s59, s56, 2
	v_trunc_f32_e32 v162, v162
	s_and_b32 s59, s59, 0xffffffc
	v_mul_f32_e64 v164, |v162|, s77
	s_add_i32 s59, s59, s49
	v_xor_b32_e32 v131, v131, v169
	v_sub_co_u32_e32 v130, vcc, v130, v169
	v_floor_f32_e32 v164, v164
	s_and_b32 s51, s56, 15
	s_lshl_b32 s49, s59, 4
	v_subb_co_u32_e32 v131, vcc, v131, v169, vcc
	v_fma_f32 v169, v164, s83, |v162|
	s_ashr_i32 s63, s49, 31
	s_or_b32 s62, s49, s51
	v_cvt_u32_f32_e32 v169, v169
	s_lshl_b64 s[62:63], s[62:63], 10
	v_cvt_u32_f32_e32 v164, v164
	v_lshl_add_u64 v[128:129], v[150:151], 0, s[62:63]
	global_atomic_add_x2 v[128:129], v[130:131], off
	v_ashrrev_i32_e32 v131, 31, v162
	v_xor_b32_e32 v130, v169, v131
	v_xor_b32_e32 v162, v164, v131
	v_sub_co_u32_e32 v130, vcc, v130, v131
	v_add_f32_e32 v163, v163, v170
	s_nop 0
	v_subb_co_u32_e32 v131, vcc, v162, v131, vcc
	v_mul_f32_e32 v162, 0x4f800000, v166
	v_trunc_f32_e32 v162, v162
	v_mul_f32_e64 v164, |v162|, s77
	v_floor_f32_e32 v164, v164
	v_fma_f32 v166, v164, s83, |v162|
	v_cvt_u32_f32_e32 v166, v166
	v_cvt_u32_f32_e32 v164, v164
	global_atomic_add_x2 v[128:129], v[130:131], off offset:8
	v_ashrrev_i32_e32 v131, 31, v162
	v_xor_b32_e32 v130, v166, v131
	v_xor_b32_e32 v162, v164, v131
	v_sub_co_u32_e32 v130, vcc, v130, v131
	v_add_f32_e32 v165, v165, v171
	s_nop 0
	v_subb_co_u32_e32 v131, vcc, v162, v131, vcc
	v_mul_f32_e32 v162, 0x4f800000, v168
	v_trunc_f32_e32 v162, v162
	v_mul_f32_e64 v164, |v162|, s77
	v_floor_f32_e32 v164, v164
	v_fma_f32 v166, v164, s83, |v162|
	v_cvt_u32_f32_e32 v166, v166
	v_cvt_u32_f32_e32 v164, v164
	global_atomic_add_x2 v[128:129], v[130:131], off offset:16
	v_ashrrev_i32_e32 v131, 31, v162
	v_xor_b32_e32 v130, v166, v131
	v_xor_b32_e32 v162, v164, v131
	v_sub_co_u32_e32 v130, vcc, v130, v131
	v_add_f32_e32 v167, v167, v172
	s_nop 0
	v_subb_co_u32_e32 v131, vcc, v162, v131, vcc
	v_mul_f32_e32 v162, 0x4f800000, v163
	v_trunc_f32_e32 v162, v162
	v_mul_f32_e64 v163, |v162|, s77
	v_floor_f32_e32 v163, v163
	v_fma_f32 v164, v163, s83, |v162|
	v_cvt_u32_f32_e32 v164, v164
	v_cvt_u32_f32_e32 v163, v163
	global_atomic_add_x2 v[128:129], v[130:131], off offset:24
	v_ashrrev_i32_e32 v131, 31, v162
	v_xor_b32_e32 v130, v164, v131
	v_xor_b32_e32 v162, v163, v131
	v_sub_co_u32_e32 v130, vcc, v130, v131
	v_mul_f32_e32 v140, 0x4f800000, v140
	s_nop 0
	v_subb_co_u32_e32 v131, vcc, v162, v131, vcc
	v_mul_f32_e32 v162, 0x4f800000, v165
	v_trunc_f32_e32 v162, v162
	v_mul_f32_e64 v163, |v162|, s77
	v_floor_f32_e32 v163, v163
	v_fma_f32 v164, v163, s83, |v162|
	v_cvt_u32_f32_e32 v164, v164
	v_cvt_u32_f32_e32 v163, v163
	global_atomic_add_x2 v[128:129], v[130:131], off offset:32
	v_ashrrev_i32_e32 v131, 31, v162
	v_xor_b32_e32 v130, v164, v131
	v_xor_b32_e32 v162, v163, v131
	v_sub_co_u32_e32 v130, vcc, v130, v131
	v_trunc_f32_e32 v140, v140
	s_nop 0
	v_subb_co_u32_e32 v131, vcc, v162, v131, vcc
	v_mul_f32_e32 v162, 0x4f800000, v167
	v_trunc_f32_e32 v162, v162
	v_mul_f32_e64 v163, |v162|, s77
	v_floor_f32_e32 v163, v163
	v_fma_f32 v164, v163, s83, |v162|
	v_cvt_u32_f32_e32 v164, v164
	v_cvt_u32_f32_e32 v163, v163
	global_atomic_add_x2 v[128:129], v[130:131], off offset:40
	v_ashrrev_i32_e32 v131, 31, v162
	v_xor_b32_e32 v130, v164, v131
	v_xor_b32_e32 v162, v163, v131
	v_sub_co_u32_e32 v130, vcc, v130, v131
	s_nop 1
	v_subb_co_u32_e32 v131, vcc, v162, v131, vcc
	v_mul_f32_e64 v162, |v140|, s77
	v_floor_f32_e32 v162, v162
	v_fma_f32 v163, v162, s83, |v140|
	v_cvt_u32_f32_e32 v163, v163
	v_cvt_u32_f32_e32 v162, v162
	global_atomic_add_x2 v[128:129], v[130:131], off offset:48
	v_ashrrev_i32_e32 v131, 31, v140
	v_xor_b32_e32 v130, v163, v131
	v_xor_b32_e32 v140, v162, v131
	v_sub_co_u32_e32 v130, vcc, v130, v131
	s_nop 1
	v_subb_co_u32_e32 v131, vcc, v140, v131, vcc
	global_atomic_add_x2 v[128:129], v[130:131], off offset:56

; __device__ __forceinline__ unsigned cvtpk(float lo, float hi) { f32x2v_ v = {lo, hi}; bf16x2v_ b = __builtin_convertvector(v, bf16x2v_); return __builtin_bit_cast(unsigned, b); }
;     __device__ __forceinline__ void operator()(const f32x4 (&acc)[2][2][4][2], const Unit& u, int wr, int wc, int fr, int fq) const {
;     ...
;                     for (int m = 0; m < 4; ++m) { const int row = row0 + ai * HALF + m * 16; const float rs = ss ? row_rs(ss, row) : 1.0f;
;                         const f32x4 v0 = acc[ai][bj][m][0] * rs, v1 = acc[ai][bj][m][1] * rs;
;                         u32x4 w; w.x = cvtpk(v0[0], v0[1]); w.y = cvtpk(v0[2], v0[3]); w.z = cvtpk(v1[0], v1[1]); w.w = cvtpk(v1[2], v1[3]);
;                         *(u32x4*)(O + (size_t)row * ldc + c0) = w; }
.LBB0_1302:
	v_lshl_add_u64 v[164:165], v[160:161], 3, s[36:37]
	global_load_dwordx2 v[166:167], v[164:165], off
	v_or_b32_e32 v168, s58, v142
	v_lshlrev_b64 v[170:171], 12, v[160:161]
	v_ashrrev_i32_e32 v169, 31, v168
	v_lshlrev_b64 v[168:169], 1, v[168:169]
	v_lshl_add_u64 v[172:173], v[162:163], 3, s[36:37]
	s_waitcnt vmcnt(0)
	v_ffbh_u32_e32 v140, v167
	v_min_u32_e32 v140, 32, v140
	v_lshlrev_b64 v[166:167], v140, v[166:167]
	v_min_u32_e32 v166, 1, v166
	v_or_b32_e32 v166, v167, v166
	v_cvt_f32_u32_e32 v166, v166
	v_sub_u32_e32 v140, 32, v140
	v_ldexp_f32 v140, v166, v140
	v_mul_f32_e32 v140, 0x2f800000, v140
	v_fmamk_f32 v140, v140, 0x3a800000, v209
	v_rsq_f32_e32 v140, v140
	v_lshl_add_u64 v[166:167], s[20:21], 0, v[170:171]
	v_lshl_add_u64 v[166:167], v[166:167], 0, v[168:169]
	v_pk_mul_f32 v[126:127], v[126:127], v[140:141] op_sel_hi:[1,0]
	v_pk_mul_f32 v[124:125], v[124:125], v[140:141] op_sel_hi:[1,0]
	v_pk_mul_f32 v[170:171], v[122:123], v[140:141] op_sel_hi:[1,0]
	v_pk_mul_f32 v[122:123], v[120:121], v[140:141] op_sel_hi:[1,0]
	v_cvt_pk_bf16_f32 v120, v124, v125
	v_cvt_pk_bf16_f32 v121, v126, v127
	v_cvt_pk_bf16_f32 v122, v122, v123
	v_cvt_pk_bf16_f32 v123, v170, v171
	global_store_dwordx4 v[166:167], v[120:123], off sc1
	global_load_dwordx2 v[120:121], v[172:173], off
	v_lshl_add_u64 v[124:125], v[130:131], 3, s[36:37]
	s_waitcnt vmcnt(0)
	v_ffbh_u32_e32 v122, v121
	v_min_u32_e32 v122, 32, v122
	v_lshlrev_b64 v[120:121], v122, v[120:121]
	v_min_u32_e32 v120, 1, v120
	v_or_b32_e32 v120, v121, v120
	v_cvt_f32_u32_e32 v123, v120
	v_sub_u32_e32 v122, 32, v122
	v_lshlrev_b64 v[120:121], 12, v[162:163]
	v_lshl_add_u64 v[120:121], s[20:21], 0, v[120:121]
	v_ldexp_f32 v122, v123, v122
	v_mul_f32_e32 v122, 0x2f800000, v122
	v_fmamk_f32 v122, v122, 0x3a800000, v209
	v_rsq_f32_e32 v122, v122
	v_lshl_add_u64 v[120:121], v[120:121], 0, v[168:169]
	v_pk_mul_f32 v[118:119], v[118:119], v[122:123] op_sel_hi:[1,0]
	v_pk_mul_f32 v[116:117], v[116:117], v[122:123] op_sel_hi:[1,0]
	v_pk_mul_f32 v[126:127], v[114:115], v[122:123] op_sel_hi:[1,0]
	v_pk_mul_f32 v[114:115], v[112:113], v[122:123] op_sel_hi:[1,0]
	v_cvt_pk_bf16_f32 v112, v116, v117
	v_cvt_pk_bf16_f32 v113, v118, v119
	v_cvt_pk_bf16_f32 v114, v114, v115
	v_cvt_pk_bf16_f32 v115, v126, v127
	global_store_dwordx4 v[120:121], v[112:115], off sc1
	global_load_dwordx2 v[112:113], v[124:125], off
	v_lshl_add_u64 v[116:117], v[128:129], 3, s[36:37]
	s_waitcnt vmcnt(0)
	v_ffbh_u32_e32 v114, v113
	v_min_u32_e32 v114, 32, v114
	v_lshlrev_b64 v[112:113], v114, v[112:113]
	v_min_u32_e32 v112, 1, v112
	v_or_b32_e32 v112, v113, v112
	v_cvt_f32_u32_e32 v115, v112
	v_sub_u32_e32 v114, 32, v114
	v_lshlrev_b64 v[112:113], 12, v[130:131]
	v_lshl_add_u64 v[112:113], s[20:21], 0, v[112:113]
	v_ldexp_f32 v114, v115, v114
	v_mul_f32_e32 v114, 0x2f800000, v114
	v_fmamk_f32 v114, v114, 0x3a800000, v209
	v_rsq_f32_e32 v114, v114
	v_lshl_add_u64 v[112:113], v[112:113], 0, v[168:169]
	v_pk_mul_f32 v[110:111], v[110:111], v[114:115] op_sel_hi:[1,0]
	v_pk_mul_f32 v[108:109], v[108:109], v[114:115] op_sel_hi:[1,0]
	v_pk_mul_f32 v[118:119], v[106:107], v[114:115] op_sel_hi:[1,0]
	v_pk_mul_f32 v[106:107], v[104:105], v[114:115] op_sel_hi:[1,0]
	v_cvt_pk_bf16_f32 v104, v108, v109
	v_cvt_pk_bf16_f32 v105, v110, v111
	v_cvt_pk_bf16_f32 v106, v106, v107
	v_cvt_pk_bf16_f32 v107, v118, v119
	global_store_dwordx4 v[112:113], v[104:107], off sc1
	global_load_dwordx2 v[104:105], v[116:117], off
	s_waitcnt vmcnt(0)
	v_ffbh_u32_e32 v106, v105
	v_min_u32_e32 v106, 32, v106
	v_lshlrev_b64 v[104:105], v106, v[104:105]
	v_min_u32_e32 v104, 1, v104
	v_or_b32_e32 v104, v105, v104
	v_cvt_f32_u32_e32 v104, v104
	v_sub_u32_e32 v105, 32, v106
	v_lshlrev_b64 v[106:107], 12, v[128:129]
	v_lshl_add_u64 v[106:107], s[20:21], 0, v[106:107]
	v_ldexp_f32 v104, v104, v105
	v_mul_f32_e32 v104, 0x2f800000, v104
	v_fmamk_f32 v104, v104, 0x3a800000, v209
	v_rsq_f32_e32 v104, v104
	v_lshl_add_u64 v[106:107], v[106:107], 0, v[168:169]
	v_pk_mul_f32 v[102:103], v[102:103], v[104:105] op_sel_hi:[1,0]
	v_pk_mul_f32 v[100:101], v[100:101], v[104:105] op_sel_hi:[1,0]
	v_pk_mul_f32 v[108:109], v[98:99], v[104:105] op_sel_hi:[1,0]
	v_pk_mul_f32 v[98:99], v[96:97], v[104:105] op_sel_hi:[1,0]
	v_cvt_pk_bf16_f32 v96, v100, v101
	v_cvt_pk_bf16_f32 v97, v102, v103
	v_cvt_pk_bf16_f32 v98, v98, v99
	v_cvt_pk_bf16_f32 v99, v108, v109
	global_store_dwordx4 v[106:107], v[96:99], off sc1
	global_load_dwordx2 v[96:97], v[164:165], off offset:1024
	s_waitcnt vmcnt(0)
; __device__ __forceinline__ unsigned cvtpk(float lo, float hi) { f32x2v_ v = {lo, hi}; bf16x2v_ b = __builtin_convertvector(v, bf16x2v_); return __builtin_bit_cast(unsigned, b); }
;     __device__ __forceinline__ void operator()(const f32x4 (&acc)[2][2][4][2], const Unit& u, int wr, int wc, int fr, int fq) const {
;     ...
;                     for (int m = 0; m < 4; ++m) { const int row = row0 + ai * HALF + m * 16; const float rs = ss ? row_rs(ss, row) : 1.0f;
;                         const f32x4 v0 = acc[ai][bj][m][0] * rs, v1 = acc[ai][bj][m][1] * rs;
;                         u32x4 w; w.x = cvtpk(v0[0], v0[1]); w.y = cvtpk(v0[2], v0[3]); w.z = cvtpk(v1[0], v1[1]); w.w = cvtpk(v1[2], v1[3]);
;                         *(u32x4*)(O + (size_t)row * ldc + c0) = w; }
	v_ffbh_u32_e32 v98, v97
	v_min_u32_e32 v98, 32, v98
	v_lshlrev_b64 v[96:97], v98, v[96:97]
	v_min_u32_e32 v96, 1, v96
	v_or_b32_e32 v96, v97, v96
	v_cvt_f32_u32_e32 v96, v96
	v_sub_u32_e32 v97, 32, v98
	v_add_co_u32_e32 v98, vcc, s84, v166
	v_ldexp_f32 v96, v96, v97
	v_mul_f32_e32 v96, 0x2f800000, v96
	v_fmamk_f32 v96, v96, 0x3a800000, v209
	v_rsq_f32_e32 v96, v96
	v_addc_co_u32_e32 v99, vcc, 0, v167, vcc
	v_pk_mul_f32 v[94:95], v[94:95], v[96:97] op_sel_hi:[1,0]
	v_pk_mul_f32 v[92:93], v[92:93], v[96:97] op_sel_hi:[1,0]
	v_pk_mul_f32 v[100:101], v[90:91], v[96:97] op_sel_hi:[1,0]
	v_pk_mul_f32 v[90:91], v[88:89], v[96:97] op_sel_hi:[1,0]
	v_cvt_pk_bf16_f32 v88, v92, v93
	v_cvt_pk_bf16_f32 v89, v94, v95
	v_cvt_pk_bf16_f32 v90, v90, v91
	v_cvt_pk_bf16_f32 v91, v100, v101
	global_store_dwordx4 v[98:99], v[88:91], off sc1
	global_load_dwordx2 v[88:89], v[164:165], off offset:1152
	s_waitcnt vmcnt(0)
	v_ffbh_u32_e32 v90, v89
	v_min_u32_e32 v90, 32, v90
	v_lshlrev_b64 v[88:89], v90, v[88:89]
	v_min_u32_e32 v88, 1, v88
	v_or_b32_e32 v88, v89, v88
	v_cvt_f32_u32_e32 v88, v88
	v_sub_u32_e32 v89, 32, v90
	v_add_co_u32_e32 v90, vcc, s85, v166
	v_ldexp_f32 v88, v88, v89
	v_mul_f32_e32 v88, 0x2f800000, v88
	v_fmamk_f32 v88, v88, 0x3a800000, v209
	v_rsq_f32_e32 v88, v88
	v_addc_co_u32_e32 v91, vcc, 0, v167, vcc
	v_pk_mul_f32 v[86:87], v[86:87], v[88:89] op_sel_hi:[1,0]
	v_pk_mul_f32 v[84:85], v[84:85], v[88:89] op_sel_hi:[1,0]
	v_pk_mul_f32 v[92:93], v[82:83], v[88:89] op_sel_hi:[1,0]
	v_pk_mul_f32 v[82:83], v[80:81], v[88:89] op_sel_hi:[1,0]
	v_cvt_pk_bf16_f32 v80, v84, v85
	v_cvt_pk_bf16_f32 v81, v86, v87
	v_cvt_pk_bf16_f32 v82, v82, v83
	v_cvt_pk_bf16_f32 v83, v92, v93
	global_store_dwordx4 v[90:91], v[80:83], off sc1
	global_load_dwordx2 v[80:81], v[164:165], off offset:1280
	s_waitcnt vmcnt(0)
	v_ffbh_u32_e32 v82, v81
	v_min_u32_e32 v82, 32, v82
	v_lshlrev_b64 v[80:81], v82, v[80:81]
	v_min_u32_e32 v80, 1, v80
	v_or_b32_e32 v80, v81, v80
	v_cvt_f32_u32_e32 v80, v80
	v_sub_u32_e32 v81, 32, v82
	v_add_co_u32_e32 v82, vcc, s86, v166
	v_ldexp_f32 v80, v80, v81
	v_mul_f32_e32 v80, 0x2f800000, v80
	v_fmamk_f32 v80, v80, 0x3a800000, v209
	v_rsq_f32_e32 v80, v80
	v_addc_co_u32_e32 v83, vcc, 0, v167, vcc
	v_pk_mul_f32 v[78:79], v[78:79], v[80:81] op_sel_hi:[1,0]
	v_pk_mul_f32 v[76:77], v[76:77], v[80:81] op_sel_hi:[1,0]
	v_pk_mul_f32 v[84:85], v[74:75], v[80:81] op_sel_hi:[1,0]
	v_pk_mul_f32 v[74:75], v[72:73], v[80:81] op_sel_hi:[1,0]
	v_cvt_pk_bf16_f32 v72, v76, v77
	v_cvt_pk_bf16_f32 v73, v78, v79
	v_cvt_pk_bf16_f32 v74, v74, v75
	v_cvt_pk_bf16_f32 v75, v84, v85
	global_store_dwordx4 v[82:83], v[72:75], off sc1
	global_load_dwordx2 v[72:73], v[164:165], off offset:1408
	s_waitcnt vmcnt(0)
	v_ffbh_u32_e32 v74, v73
	v_min_u32_e32 v74, 32, v74
	v_lshlrev_b64 v[72:73], v74, v[72:73]
	v_min_u32_e32 v72, 1, v72
	v_or_b32_e32 v72, v73, v72
	v_cvt_f32_u32_e32 v72, v72
	v_sub_u32_e32 v73, 32, v74
	v_add_co_u32_e32 v74, vcc, 0xb0000, v166
	v_ldexp_f32 v72, v72, v73
	v_mul_f32_e32 v72, 0x2f800000, v72
	v_fmamk_f32 v72, v72, 0x3a800000, v209
	v_rsq_f32_e32 v72, v72
	v_addc_co_u32_e32 v75, vcc, 0, v167, vcc
	v_pk_mul_f32 v[70:71], v[70:71], v[72:73] op_sel_hi:[1,0]
	v_pk_mul_f32 v[68:69], v[68:69], v[72:73] op_sel_hi:[1,0]
	v_pk_mul_f32 v[76:77], v[66:67], v[72:73] op_sel_hi:[1,0]
	v_pk_mul_f32 v[66:67], v[64:65], v[72:73] op_sel_hi:[1,0]
	v_cvt_pk_bf16_f32 v64, v68, v69
	v_cvt_pk_bf16_f32 v65, v70, v71
	v_cvt_pk_bf16_f32 v66, v66, v67
	v_cvt_pk_bf16_f32 v67, v76, v77
	global_store_dwordx4 v[74:75], v[64:67], off sc1
	s_or_b32 s49, s58, 0x80
	s_cmpk_lt_i32 s49, 0x400
	s_mov_b64 s[60:61], -1
	s_cbranch_scc1 .LBB0_1300

; __device__ __forceinline__ unsigned cvtpk(float lo, float hi) { f32x2v_ v = {lo, hi}; bf16x2v_ b = __builtin_convertvector(v, bf16x2v_); return __builtin_bit_cast(unsigned, b); }
;     __device__ __forceinline__ void operator()(const f32x4 (&acc)[2][2][4][2], const Unit& u, int wr, int wc, int fr, int fq) const {
;     ...
;                     for (int m = 0; m < 4; ++m) { const int row = row0 + ai * HALF + m * 16; const float rs = ss ? row_rs(ss, row) : 1.0f;
;                         const f32x4 v0 = acc[ai][bj][m][0] * rs, v1 = acc[ai][bj][m][1] * rs;
;                         const int b = row >> S_shift, pos = row & ((1 << S_shift) - 1);
;                         const size_t tile = ((size_t)(b * kvh + head) << (S_shift - 5)) + (pos >> 5);
;                         u32x4 w; w.x = cvtpk(v0[0], v0[1]); w.y = cvtpk(v0[2], v0[3]); w.z = cvtpk(v1[0], v1[1]); w.w = cvtpk(v1[2], v1[3]);
;                         *(u32x4*)(KP + tile * (size_t)(32 * DH) + ((d >> 3) * 32 + (pos & 31)) * 8) = w;
; #pragma unroll
;                         for (int e = 0; e < 4; ++e) { cs[e] += v0[e]; cs[4 + e] += v1[e]; } }
.LBB0_1305:
	s_andn2_b64 vcc, exec, s[60:61]
	s_cbranch_vccnz .LBB0_1309
	s_add_i32 s49, s58, 0xfffffc80
	s_lshr_b32 s49, s49, 7
	v_add_u32_e32 v78, s49, v211
	v_ashrrev_i32_e32 v79, 31, v78
	v_lshlrev_b64 v[78:79], 20, v[78:79]
	v_lshl_add_u64 v[96:97], s[26:27], 0, v[78:79]
	v_lshl_add_u64 v[78:79], v[96:97], 0, v[140:141]
	v_lshlrev_b32_e32 v140, 1, v148
	v_lshl_add_u64 v[80:81], v[78:79], 0, v[140:141]
	global_store_dwordx4 v[80:81], v[64:67], off sc1
	v_lshl_add_u64 v[88:89], v[130:131], 3, s[36:37]
	v_and_b32_e32 v82, 0xfe000, v82
	v_lshl_add_u64 v[64:65], v[162:163], 3, s[36:37]
	global_load_dwordx2 v[64:65], v[64:65], off
	v_and_or_b32 v67, v162, 31, v149
	v_lshl_add_u64 v[100:101], v[128:129], 3, s[36:37]
	v_and_b32_e32 v90, 0xfe000, v90
	v_mov_b32_e32 v91, v141
	v_lshl_add_u64 v[90:91], v[96:97], 0, v[90:91]
	v_and_b32_e32 v98, 0xfc000, v98
	v_and_or_b32 v111, v111, 31, v149
	v_and_b32_e32 v112, 0xfc000, v112
	v_add_f32_e32 v74, 0, v74
	v_add_f32_e32 v75, 0, v75
	v_add_f32_e32 v72, 0, v72
	v_add_f32_e32 v76, 0, v76
	v_add_f32_e32 v77, 0, v77
	v_add_f32_e32 v73, 0, v73
	s_waitcnt vmcnt(0)
	v_ffbh_u32_e32 v66, v65
	v_min_u32_e32 v66, 32, v66
	v_lshlrev_b64 v[64:65], v66, v[64:65]
	v_min_u32_e32 v64, 1, v64
	v_or_b32_e32 v64, v65, v64
	v_cvt_f32_u32_e32 v64, v64
	v_sub_u32_e32 v66, 32, v66
	v_mov_b32_e32 v65, v141
	v_ldexp_f32 v64, v64, v66
	v_mul_f32_e32 v64, 0x2f800000, v64
	v_fmamk_f32 v64, v64, 0x3a800000, v209
	v_rsq_f32_e32 v80, v64
	v_lshlrev_b32_e32 v64, 4, v67
	v_lshl_add_u64 v[92:93], v[78:79], 0, v[64:65]
	v_pk_mul_f32 v[64:65], v[54:55], v[80:81] op_sel_hi:[1,0]
	v_pk_mul_f32 v[78:79], v[52:53], v[80:81] op_sel_hi:[1,0]
	v_pk_mul_f32 v[66:67], v[50:51], v[80:81] op_sel_hi:[1,0]
	v_pk_mul_f32 v[80:81], v[48:49], v[80:81] op_sel_hi:[1,0]
	v_cvt_pk_bf16_f32 v84, v78, v79
	v_cvt_pk_bf16_f32 v85, v64, v65
	v_cvt_pk_bf16_f32 v86, v80, v81
	v_cvt_pk_bf16_f32 v87, v66, v67
	global_store_dwordx4 v[92:93], v[84:87], off sc1
	global_load_dwordx2 v[84:85], v[88:89], off
	v_add_f32_e32 v66, v72, v66
	v_add_f32_e32 v67, v73, v67
	s_waitcnt vmcnt(0)
	v_ffbh_u32_e32 v83, v85
	v_min_u32_e32 v86, 32, v83
	v_lshlrev_b64 v[84:85], v86, v[84:85]
	v_min_u32_e32 v83, 1, v84
	v_or_b32_e32 v83, v85, v83
	v_cvt_f32_u32_e32 v84, v83
	v_sub_u32_e32 v85, 32, v86
	v_mov_b32_e32 v83, v141
	v_lshl_add_u64 v[82:83], v[96:97], 0, v[82:83]
	v_ldexp_f32 v84, v84, v85
	v_mul_f32_e32 v84, 0x2f800000, v84
	v_fmamk_f32 v84, v84, 0x3a800000, v209
	v_rsq_f32_e32 v88, v84
	v_lshl_add_u64 v[102:103], v[82:83], 0, v[140:141]
	v_pk_mul_f32 v[82:83], v[46:47], v[88:89] op_sel_hi:[1,0]
	v_pk_mul_f32 v[86:87], v[44:45], v[88:89] op_sel_hi:[1,0]
	v_pk_mul_f32 v[84:85], v[42:43], v[88:89] op_sel_hi:[1,0]
	v_pk_mul_f32 v[88:89], v[40:41], v[88:89] op_sel_hi:[1,0]
	v_cvt_pk_bf16_f32 v92, v86, v87
	v_cvt_pk_bf16_f32 v93, v82, v83
	v_cvt_pk_bf16_f32 v94, v88, v89
	v_cvt_pk_bf16_f32 v95, v84, v85
	global_store_dwordx4 v[102:103], v[92:95], off sc1
	global_load_dwordx2 v[92:93], v[100:101], off
	v_add_f32_e32 v66, v66, v84
	v_and_or_b32 v95, v128, 31, v149
	v_add_f32_e32 v67, v67, v85
	v_and_or_b32 v84, v106, 31, v149
	s_waitcnt vmcnt(0)
	v_ffbh_u32_e32 v94, v93
	v_min_u32_e32 v94, 32, v94
	v_lshlrev_b64 v[92:93], v94, v[92:93]
	v_min_u32_e32 v92, 1, v92
	v_or_b32_e32 v92, v93, v92
	v_cvt_f32_u32_e32 v92, v92
	v_sub_u32_e32 v94, 32, v94
	v_mov_b32_e32 v93, v141
	v_ldexp_f32 v92, v92, v94
	v_mul_f32_e32 v92, 0x2f800000, v92
	v_fmamk_f32 v92, v92, 0x3a800000, v209
	v_rsq_f32_e32 v100, v92
	v_lshlrev_b32_e32 v92, 4, v95
	v_lshl_add_u64 v[104:105], v[90:91], 0, v[92:93]
	v_pk_mul_f32 v[90:91], v[38:39], v[100:101] op_sel_hi:[1,0]
	v_pk_mul_f32 v[94:95], v[36:37], v[100:101] op_sel_hi:[1,0]
	v_pk_mul_f32 v[92:93], v[34:35], v[100:101] op_sel_hi:[1,0]
	v_pk_mul_f32 v[96:97], v[32:33], v[100:101] op_sel_hi:[1,0]
	v_cvt_pk_bf16_f32 v100, v94, v95
	v_cvt_pk_bf16_f32 v101, v90, v91
	v_cvt_pk_bf16_f32 v102, v96, v97
	v_cvt_pk_bf16_f32 v103, v92, v93
	global_store_dwordx4 v[104:105], v[100:103], off sc1
	global_load_dwordx2 v[100:101], v[68:69], off offset:1024
	v_add_f32_e32 v66, v66, v92
	v_and_b32_e32 v102, -4, v99
	v_add_u32_e32 v102, s49, v102
	v_mov_b32_e32 v99, v141
	v_add_f32_e32 v67, v67, v93
	s_waitcnt vmcnt(0)
	v_ffbh_u32_e32 v103, v101
	v_min_u32_e32 v104, 32, v103
	v_lshlrev_b64 v[100:101], v104, v[100:101]
	v_min_u32_e32 v100, 1, v100
	v_or_b32_e32 v100, v101, v100
	v_cvt_f32_u32_e32 v105, v100
	v_ashrrev_i32_e32 v103, 31, v102
	v_lshlrev_b64 v[100:101], 20, v[102:103]
	v_sub_u32_e32 v102, 32, v104
	v_ldexp_f32 v102, v105, v102
	v_mul_f32_e32 v102, 0x2f800000, v102
	v_fmamk_f32 v102, v102, 0x3a800000, v209
	v_rsq_f32_e32 v104, v102
	v_lshl_add_u64 v[100:101], s[26:27], 0, v[100:101]
	v_lshl_add_u64 v[98:99], v[100:101], 0, v[98:99]
	v_lshl_add_u64 v[118:119], v[98:99], 0, v[140:141]
	v_pk_mul_f32 v[98:99], v[30:31], v[104:105] op_sel_hi:[1,0]
	v_pk_mul_f32 v[102:103], v[28:29], v[104:105] op_sel_hi:[1,0]
	v_pk_mul_f32 v[100:101], v[26:27], v[104:105] op_sel_hi:[1,0]
	v_pk_mul_f32 v[104:105], v[24:25], v[104:105] op_sel_hi:[1,0]
	v_cvt_pk_bf16_f32 v114, v102, v103
	v_cvt_pk_bf16_f32 v115, v98, v99
	v_cvt_pk_bf16_f32 v116, v104, v105
	v_cvt_pk_bf16_f32 v117, v100, v101
	global_store_dwordx4 v[118:119], v[114:117], off sc1
	global_load_dwordx2 v[114:115], v[68:69], off offset:1152
	v_and_b32_e32 v118, -4, v113
	v_lshlrev_b32_e32 v116, 4, v111
	v_add_u32_e32 v118, s49, v118
	v_ashrrev_i32_e32 v119, 31, v118
	v_mov_b32_e32 v113, v141
	v_mov_b32_e32 v117, v141
	v_add_f32_e32 v66, v66, v100
	v_add_f32_e32 v67, v67, v101
	s_waitcnt vmcnt(0)
; __device__ __forceinline__ unsigned cvtpk(float lo, float hi) { f32x2v_ v = {lo, hi}; bf16x2v_ b = __builtin_convertvector(v, bf16x2v_); return __builtin_bit_cast(unsigned, b); }
;     __device__ __forceinline__ void operator()(const f32x4 (&acc)[2][2][4][2], const Unit& u, int wr, int wc, int fr, int fq) const {
;     ...
;                     for (int m = 0; m < 4; ++m) { const int row = row0 + ai * HALF + m * 16; const float rs = ss ? row_rs(ss, row) : 1.0f;
;                         const f32x4 v0 = acc[ai][bj][m][0] * rs, v1 = acc[ai][bj][m][1] * rs;
;                         const int b = row >> S_shift, pos = row & ((1 << S_shift) - 1);
;                         const size_t tile = ((size_t)(b * kvh + head) << (S_shift - 5)) + (pos >> 5);
;                         u32x4 w; w.x = cvtpk(v0[0], v0[1]); w.y = cvtpk(v0[2], v0[3]); w.z = cvtpk(v1[0], v1[1]); w.w = cvtpk(v1[2], v1[3]);
;                         *(u32x4*)(KP + tile * (size_t)(32 * DH) + ((d >> 3) * 32 + (pos & 31)) * 8) = w;
; #pragma unroll
;                         for (int e = 0; e < 4; ++e) { cs[e] += v0[e]; cs[4 + e] += v1[e]; } }
;                 if (ksum) {
; #pragma unroll
;                     for (int e = 0; e < 8; ++e) { float s = cs[e]; s += __shfl_xor(s, 1); s += __shfl_xor(s, 2); s += __shfl_xor(s, 4); s += __shfl_xor(s, 8); cs[e] = s; }
	v_ffbh_u32_e32 v111, v115
	v_min_u32_e32 v111, 32, v111
	v_lshlrev_b64 v[114:115], v111, v[114:115]
	v_min_u32_e32 v114, 1, v114
	v_or_b32_e32 v114, v115, v114
	v_cvt_f32_u32_e32 v120, v114
	v_sub_u32_e32 v111, 32, v111
	v_lshlrev_b64 v[114:115], 20, v[118:119]
	v_lshl_add_u64 v[114:115], s[26:27], 0, v[114:115]
	v_ldexp_f32 v111, v120, v111
	v_mul_f32_e32 v111, 0x2f800000, v111
	v_fmamk_f32 v111, v111, 0x3a800000, v209
	v_rsq_f32_e32 v118, v111
	v_lshl_add_u64 v[112:113], v[114:115], 0, v[112:113]
	v_lshl_add_u64 v[116:117], v[112:113], 0, v[116:117]
	v_mov_b32_e32 v111, v141
	v_pk_mul_f32 v[120:121], v[22:23], v[118:119] op_sel_hi:[1,0]
	v_pk_mul_f32 v[122:123], v[20:21], v[118:119] op_sel_hi:[1,0]
	v_pk_mul_f32 v[124:125], v[18:19], v[118:119] op_sel_hi:[1,0]
	v_pk_mul_f32 v[118:119], v[16:17], v[118:119] op_sel_hi:[1,0]
	v_cvt_pk_bf16_f32 v112, v122, v123
	v_cvt_pk_bf16_f32 v113, v120, v121
	v_cvt_pk_bf16_f32 v114, v118, v119
	v_cvt_pk_bf16_f32 v115, v124, v125
	global_store_dwordx4 v[116:117], v[112:115], off sc1
	global_load_dwordx2 v[112:113], v[68:69], off offset:1280
	v_add_f32_e32 v66, v66, v124
	v_and_b32_e32 v114, -4, v110
	v_and_b32_e32 v110, 0xfe000, v109
	v_add_u32_e32 v114, s49, v114
	v_ashrrev_i32_e32 v115, 31, v114
	v_add_f32_e32 v67, v67, v125
	s_waitcnt vmcnt(0)
	v_ffbh_u32_e32 v109, v113
	v_min_u32_e32 v109, 32, v109
	v_lshlrev_b64 v[112:113], v109, v[112:113]
	v_min_u32_e32 v112, 1, v112
	v_or_b32_e32 v112, v113, v112
	v_cvt_f32_u32_e32 v116, v112
	v_sub_u32_e32 v109, 32, v109
	v_lshlrev_b64 v[112:113], 20, v[114:115]
	v_lshl_add_u64 v[112:113], s[26:27], 0, v[112:113]
	v_ldexp_f32 v109, v116, v109
	v_mul_f32_e32 v109, 0x2f800000, v109
	v_fmamk_f32 v109, v109, 0x3a800000, v209
	v_rsq_f32_e32 v114, v109
	v_lshl_add_u64 v[110:111], v[112:113], 0, v[110:111]
	v_lshl_add_u64 v[116:117], v[110:111], 0, v[140:141]
	v_xor_b32_e32 v109, 2, v210
	v_pk_mul_f32 v[126:127], v[14:15], v[114:115] op_sel_hi:[1,0]
	v_pk_mul_f32 v[164:165], v[12:13], v[114:115] op_sel_hi:[1,0]
	v_pk_mul_f32 v[166:167], v[10:11], v[114:115] op_sel_hi:[1,0]
	v_pk_mul_f32 v[114:115], v[8:9], v[114:115] op_sel_hi:[1,0]
	v_cvt_pk_bf16_f32 v110, v164, v165
	v_cvt_pk_bf16_f32 v111, v126, v127
	v_cvt_pk_bf16_f32 v112, v114, v115
	v_cvt_pk_bf16_f32 v113, v166, v167
	global_store_dwordx4 v[116:117], v[110:113], off sc1
	global_load_dwordx2 v[68:69], v[68:69], off offset:1408
	v_and_b32_e32 v140, 0xfe000, v107
	v_add_f32_e32 v110, 0, v70
	v_and_b32_e32 v70, -4, v108
	v_and_b32_e32 v108, 64, v210
	v_add_f32_e32 v111, 0, v71
	v_xor_b32_e32 v71, 1, v210
	v_add_u32_e32 v108, 64, v108
	v_cmp_lt_i32_e32 vcc, v71, v108
	v_xor_b32_e32 v112, 4, v210
	v_add_u32_e32 v70, s49, v70
	v_cndmask_b32_e32 v116, v210, v71, vcc
	v_cmp_lt_i32_e32 vcc, v109, v108
	v_xor_b32_e32 v113, 8, v210
	v_ashrrev_i32_e32 v71, 31, v70
	v_cndmask_b32_e32 v109, v210, v109, vcc
	v_cmp_lt_i32_e32 vcc, v112, v108
	v_lshlrev_b64 v[70:71], 20, v[70:71]
	v_lshl_add_u64 v[70:71], s[26:27], 0, v[70:71]
	v_cndmask_b32_e32 v112, v210, v112, vcc
	v_cmp_lt_i32_e32 vcc, v113, v108
	v_add_f32_e32 v64, v110, v64
	v_add_f32_e32 v64, v64, v82
	v_cndmask_b32_e32 v108, v210, v113, vcc
	v_lshlrev_b32_e32 v113, 2, v116
	v_lshlrev_b32_e32 v116, 2, v109
	v_lshlrev_b32_e32 v117, 2, v108
	v_lshl_add_u64 v[108:109], v[70:71], 0, v[140:141]
	v_add_f32_e32 v70, v74, v78
	v_add_f32_e32 v70, v70, v86
	v_add_f32_e32 v65, v111, v65
	v_add_f32_e32 v70, v70, v94
	v_add_f32_e32 v64, v64, v90
	v_add_f32_e32 v74, v75, v79
	v_add_f32_e32 v65, v65, v83
	v_add_f32_e32 v70, v70, v102
	v_add_f32_e32 v64, v64, v98
	v_add_f32_e32 v72, v74, v87
	v_add_f32_e32 v65, v65, v91
	v_add_f32_e32 v70, v70, v122
	v_add_f32_e32 v74, v64, v120
	v_add_f32_e32 v71, v76, v80
	v_add_f32_e32 v75, v77, v81
	v_add_f32_e32 v65, v65, v99
	v_add_f32_e32 v76, v70, v164
	v_add_f32_e32 v73, v75, v89
	v_add_f32_e32 v75, v65, v121
	v_add_f32_e32 v71, v71, v88
	v_add_f32_e32 v71, v71, v96
	v_add_f32_e32 v72, v72, v95
	v_add_f32_e32 v73, v73, v97
	v_add_f32_e32 v71, v71, v104
	v_add_f32_e32 v72, v72, v103
	v_add_f32_e32 v73, v73, v105
	v_add_f32_e32 v71, v71, v118
	v_add_f32_e32 v72, v72, v123
	v_add_f32_e32 v73, v73, v119
	v_add_f32_e32 v77, v71, v114
	v_add_f32_e32 v72, v72, v165
	v_add_f32_e32 v73, v73, v115
	v_add_f32_e32 v74, v74, v126
	v_add_f32_e32 v78, v66, v166
	v_add_f32_e32 v75, v75, v127
	v_add_f32_e32 v79, v67, v167
	v_lshlrev_b32_e32 v112, 2, v112
	v_lshlrev_b32_e32 v140, 4, v84
	v_lshl_add_u64 v[84:85], v[108:109], 0, v[140:141]
	s_waitcnt vmcnt(0)
	v_ffbh_u32_e32 v64, v69
	v_min_u32_e32 v70, 32, v64
	v_lshlrev_b64 v[64:65], v70, v[68:69]
	v_min_u32_e32 v64, 1, v64
	v_or_b32_e32 v64, v65, v64
	v_cvt_f32_u32_e32 v64, v64
	v_sub_u32_e32 v65, 32, v70
	v_ldexp_f32 v64, v64, v65
	v_mul_f32_e32 v64, 0x2f800000, v64
	v_fmamk_f32 v64, v64, 0x3a800000, v209
	v_rsq_f32_e32 v64, v64
	s_nop 0
	v_pk_mul_f32 v[66:67], v[6:7], v[64:65] op_sel_hi:[1,0]
	v_pk_mul_f32 v[68:69], v[4:5], v[64:65] op_sel_hi:[1,0]
	v_pk_mul_f32 v[70:71], v[2:3], v[64:65] op_sel_hi:[1,0]
	v_pk_mul_f32 v[64:65], v[0:1], v[64:65] op_sel_hi:[1,0]
	v_cvt_pk_bf16_f32 v80, v68, v69
	v_cvt_pk_bf16_f32 v81, v66, v67
	v_cvt_pk_bf16_f32 v82, v64, v65
	v_cvt_pk_bf16_f32 v83, v70, v71
	v_add_f32_e32 v71, v79, v71
	v_add_f32_e32 v67, v75, v67
	v_add_f32_e32 v70, v78, v70
	v_add_f32_e32 v66, v74, v66
	v_add_f32_e32 v65, v73, v65
	v_add_f32_e32 v69, v72, v69
	v_add_f32_e32 v64, v77, v64
	v_add_f32_e32 v68, v76, v68
	ds_bpermute_b32 v72, v113, v68
	ds_bpermute_b32 v73, v113, v69
	ds_bpermute_b32 v74, v113, v66
	ds_bpermute_b32 v75, v113, v67
	ds_bpermute_b32 v76, v113, v64
	ds_bpermute_b32 v77, v113, v65
	ds_bpermute_b32 v78, v113, v70
	ds_bpermute_b32 v79, v113, v71
	s_waitcnt lgkmcnt(7)
; __device__ __forceinline__ void fx_add(float* p, size_t idx, float s) { atomicAdd((unsigned long long*)p + idx, (unsigned long long)(long long)(s * 4294967296.0f)); }
;     __device__ __forceinline__ void operator()(const f32x4 (&acc)[2][2][4][2], const Unit& u, int wr, int wc, int fr, int fq) const {
;     ...
;                     for (int e = 0; e < 8; ++e) { float s = cs[e]; s += __shfl_xor(s, 1); s += __shfl_xor(s, 2); s += __shfl_xor(s, 4); s += __shfl_xor(s, 8); cs[e] = s; }
;                     if (fr == 0) { const int rowb = u.pm * BM; const int b = rowb >> S_shift, blk = (rowb & ((1 << S_shift) - 1)) >> 8;
;                         const size_t kd = ((size_t)((b * kvh + head) << (S_shift - 8)) + blk) * DH + d;
; #pragma unroll
;                         for (int e = 0; e < 8; ++e) fx_add(ksum, kd + e, cs[e]); }
	v_add_f32_e32 v68, v68, v72
	s_waitcnt lgkmcnt(6)
	v_add_f32_e32 v69, v69, v73
	s_waitcnt lgkmcnt(5)
	v_add_f32_e32 v66, v66, v74
	s_waitcnt lgkmcnt(4)
	v_add_f32_e32 v67, v67, v75
	s_waitcnt lgkmcnt(3)
	v_add_f32_e32 v64, v64, v76
	s_waitcnt lgkmcnt(2)
	v_add_f32_e32 v65, v65, v77
	s_waitcnt lgkmcnt(1)
	v_add_f32_e32 v70, v70, v78
	s_waitcnt lgkmcnt(0)
	v_add_f32_e32 v71, v71, v79
	ds_bpermute_b32 v72, v116, v68
	ds_bpermute_b32 v73, v116, v69
	ds_bpermute_b32 v74, v116, v66
	ds_bpermute_b32 v75, v116, v67
	ds_bpermute_b32 v76, v116, v64
	ds_bpermute_b32 v77, v116, v65
	ds_bpermute_b32 v78, v116, v70
	ds_bpermute_b32 v79, v116, v71
	s_waitcnt lgkmcnt(7)
	v_add_f32_e32 v68, v68, v72
	s_waitcnt lgkmcnt(6)
	v_add_f32_e32 v69, v69, v73
	s_waitcnt lgkmcnt(5)
	v_add_f32_e32 v66, v66, v74
	s_waitcnt lgkmcnt(4)
	v_add_f32_e32 v67, v67, v75
	s_waitcnt lgkmcnt(3)
	v_add_f32_e32 v72, v64, v76
	s_waitcnt lgkmcnt(2)
	v_add_f32_e32 v73, v65, v77
	s_waitcnt lgkmcnt(1)
	v_add_f32_e32 v70, v70, v78
	s_waitcnt lgkmcnt(0)
	v_add_f32_e32 v74, v71, v79
	ds_bpermute_b32 v64, v112, v68
	ds_bpermute_b32 v65, v112, v69
	ds_bpermute_b32 v71, v112, v66
	ds_bpermute_b32 v75, v112, v67
	ds_bpermute_b32 v76, v112, v72
	ds_bpermute_b32 v77, v112, v73
	ds_bpermute_b32 v78, v112, v70
	ds_bpermute_b32 v79, v112, v74
	s_waitcnt lgkmcnt(7)
	v_add_f32_e32 v64, v68, v64
	s_waitcnt lgkmcnt(6)
	v_add_f32_e32 v65, v69, v65
	s_waitcnt lgkmcnt(5)
	v_add_f32_e32 v66, v66, v71
	s_waitcnt lgkmcnt(4)
	v_add_f32_e32 v67, v67, v75
	s_waitcnt lgkmcnt(3)
	v_add_f32_e32 v69, v72, v76
	s_waitcnt lgkmcnt(2)
	v_add_f32_e32 v71, v73, v77
	s_waitcnt lgkmcnt(1)
	v_add_f32_e32 v73, v70, v78
	s_waitcnt lgkmcnt(0)
	v_add_f32_e32 v75, v74, v79
	ds_bpermute_b32 v68, v117, v64
	ds_bpermute_b32 v70, v117, v65
	ds_bpermute_b32 v72, v117, v66
	ds_bpermute_b32 v74, v117, v67
	ds_bpermute_b32 v76, v117, v69
	ds_bpermute_b32 v77, v117, v71
	ds_bpermute_b32 v78, v117, v73
	ds_bpermute_b32 v79, v117, v75
	global_store_dwordx4 v[84:85], v[80:83], off sc1
	s_and_saveexec_b64 s[60:61], s[10:11]
	s_cbranch_execz .LBB0_1308
	s_waitcnt lgkmcnt(7)
	v_add_f32_e32 v64, v64, v68
	v_mul_f32_e32 v64, 0x4f800000, v64
	s_waitcnt lgkmcnt(5)
	v_add_f32_e32 v72, v66, v72
	v_trunc_f32_e32 v66, v64
	v_mul_f32_e64 v64, |v66|, s77
	v_floor_f32_e32 v64, v64
	v_add_f32_e32 v70, v65, v70
	v_fma_f32 v65, v64, s83, |v66|
	v_cvt_u32_f32_e32 v68, v65
	s_waitcnt lgkmcnt(3)
	v_add_f32_e32 v69, v69, v76
	v_add_f32_e32 v74, v67, v74
	v_cvt_u32_f32_e32 v67, v64
	v_ashrrev_i32_e32 v76, 31, v66
	v_xor_b32_e32 v66, v68, v76
	v_mul_f32_e32 v68, 0x4f800000, v70
	s_and_b32 s51, s56, 15
	s_lshr_b32 s56, s56, 2
	v_trunc_f32_e32 v68, v68
	s_and_b32 s56, s56, 0xffffffc
	v_mul_f32_e64 v70, |v68|, s77
	s_add_i32 s56, s56, s49
	v_xor_b32_e32 v67, v67, v76
	v_sub_co_u32_e32 v66, vcc, v66, v76
	v_floor_f32_e32 v70, v70
	s_lshl_b32 s49, s56, 4
	v_subb_co_u32_e32 v67, vcc, v67, v76, vcc
	v_fma_f32 v76, v70, s83, |v68|
	s_ashr_i32 s63, s49, 31
	s_or_b32 s62, s49, s51
	v_cvt_u32_f32_e32 v76, v76
	s_lshl_b64 s[62:63], s[62:63], 10
	v_cvt_u32_f32_e32 v70, v70
	v_lshl_add_u64 v[64:65], v[150:151], 0, s[62:63]
	global_atomic_add_x2 v[64:65], v[66:67], off
	v_ashrrev_i32_e32 v67, 31, v68
	v_xor_b32_e32 v66, v76, v67
	v_xor_b32_e32 v68, v70, v67
	v_sub_co_u32_e32 v66, vcc, v66, v67
	s_waitcnt lgkmcnt(2)
	v_add_f32_e32 v71, v71, v77
	v_subb_co_u32_e32 v67, vcc, v68, v67, vcc
	v_mul_f32_e32 v68, 0x4f800000, v72
	v_trunc_f32_e32 v68, v68
	v_mul_f32_e64 v70, |v68|, s77
	v_floor_f32_e32 v70, v70
	v_fma_f32 v72, v70, s83, |v68|
	v_cvt_u32_f32_e32 v72, v72
	v_cvt_u32_f32_e32 v70, v70
	global_atomic_add_x2 v[64:65], v[66:67], off offset:8
	v_ashrrev_i32_e32 v67, 31, v68
	v_xor_b32_e32 v66, v72, v67
	v_xor_b32_e32 v68, v70, v67
	v_sub_co_u32_e32 v66, vcc, v66, v67
	s_waitcnt lgkmcnt(1)
	v_add_f32_e32 v73, v73, v78
	v_subb_co_u32_e32 v67, vcc, v68, v67, vcc
	v_mul_f32_e32 v68, 0x4f800000, v74
	v_trunc_f32_e32 v68, v68
	v_mul_f32_e64 v70, |v68|, s77
	v_floor_f32_e32 v70, v70
	v_fma_f32 v72, v70, s83, |v68|
	v_cvt_u32_f32_e32 v72, v72
	v_cvt_u32_f32_e32 v70, v70
	global_atomic_add_x2 v[64:65], v[66:67], off offset:16
	v_ashrrev_i32_e32 v67, 31, v68
	v_xor_b32_e32 v66, v72, v67
	v_xor_b32_e32 v68, v70, v67
	v_sub_co_u32_e32 v66, vcc, v66, v67
	s_waitcnt lgkmcnt(0)
	v_add_f32_e32 v75, v75, v79
	v_subb_co_u32_e32 v67, vcc, v68, v67, vcc
	v_mul_f32_e32 v68, 0x4f800000, v69
	v_trunc_f32_e32 v68, v68
	v_mul_f32_e64 v69, |v68|, s77
	v_floor_f32_e32 v69, v69
	v_fma_f32 v70, v69, s83, |v68|
	v_cvt_u32_f32_e32 v70, v70
	v_cvt_u32_f32_e32 v69, v69
	global_atomic_add_x2 v[64:65], v[66:67], off offset:24
	v_ashrrev_i32_e32 v67, 31, v68
	v_xor_b32_e32 v66, v70, v67
	v_xor_b32_e32 v68, v69, v67
	v_sub_co_u32_e32 v66, vcc, v66, v67
	s_nop 1
	v_subb_co_u32_e32 v67, vcc, v68, v67, vcc
	v_mul_f32_e32 v68, 0x4f800000, v71
	v_trunc_f32_e32 v68, v68
	v_mul_f32_e64 v69, |v68|, s77
	v_floor_f32_e32 v69, v69
	v_fma_f32 v70, v69, s83, |v68|
	v_cvt_u32_f32_e32 v70, v70
	v_cvt_u32_f32_e32 v69, v69
	global_atomic_add_x2 v[64:65], v[66:67], off offset:32
	v_ashrrev_i32_e32 v67, 31, v68
	v_xor_b32_e32 v66, v70, v67
	v_xor_b32_e32 v68, v69, v67
	v_sub_co_u32_e32 v66, vcc, v66, v67
	s_nop 1
	v_subb_co_u32_e32 v67, vcc, v68, v67, vcc
	v_mul_f32_e32 v68, 0x4f800000, v73
	v_trunc_f32_e32 v68, v68
	v_mul_f32_e64 v69, |v68|, s77
	v_floor_f32_e32 v69, v69
	v_fma_f32 v70, v69, s83, |v68|
	v_cvt_u32_f32_e32 v70, v70
	v_cvt_u32_f32_e32 v69, v69
	global_atomic_add_x2 v[64:65], v[66:67], off offset:40
	v_ashrrev_i32_e32 v67, 31, v68
	v_xor_b32_e32 v66, v70, v67
	v_xor_b32_e32 v68, v69, v67
	v_sub_co_u32_e32 v66, vcc, v66, v67
	s_nop 1
	v_subb_co_u32_e32 v67, vcc, v68, v67, vcc
	v_mul_f32_e32 v68, 0x4f800000, v75
	v_trunc_f32_e32 v68, v68
	v_mul_f32_e64 v69, |v68|, s77
	v_floor_f32_e32 v69, v69
	v_fma_f32 v70, v69, s83, |v68|
	v_cvt_u32_f32_e32 v70, v70
	v_cvt_u32_f32_e32 v69, v69
	global_atomic_add_x2 v[64:65], v[66:67], off offset:48
	v_ashrrev_i32_e32 v67, 31, v68
	v_xor_b32_e32 v66, v70, v67
	v_xor_b32_e32 v68, v69, v67
	v_sub_co_u32_e32 v66, vcc, v66, v67
	s_nop 1
	v_subb_co_u32_e32 v67, vcc, v68, v67, vcc
	global_atomic_add_x2 v[64:65], v[66:67], off offset:56

; __device__ __forceinline__ unsigned cvtpk(float lo, float hi) { f32x2v_ v = {lo, hi}; bf16x2v_ b = __builtin_convertvector(v, bf16x2v_); return __builtin_bit_cast(unsigned, b); }
;     __device__ __forceinline__ void operator()(const f32x4 (&acc)[2][2][4][2], const Unit& u, int wr, int wc, int fr, int fq) const {
;     ...
;                     for (int m = 0; m < 4; ++m) { const int row = row0 + ai * HALF + m * 16; const float rs = ss ? row_rs(ss, row) : 1.0f;
;                         const f32x4 v0 = acc[ai][bj][m][0] * rs, v1 = acc[ai][bj][m][1] * rs;
;                         u32x4 w; w.x = cvtpk(v0[0], v0[1]); w.y = cvtpk(v0[2], v0[3]); w.z = cvtpk(v1[0], v1[1]); w.w = cvtpk(v1[2], v1[3]);
;                         *(u32x4*)(O + (size_t)row * ldc + c0) = w; }
.LBB0_1310:
	v_lshl_add_u64 v[64:65], v[160:161], 3, s[36:37]
	global_load_dwordx2 v[66:67], v[64:65], off
	s_waitcnt lgkmcnt(0)
	v_lshlrev_b64 v[68:69], 12, v[160:161]
	s_ashr_i32 s59, s58, 31
	s_waitcnt vmcnt(0)
	v_ffbh_u32_e32 v70, v67
	v_min_u32_e32 v72, 32, v70
	v_lshlrev_b64 v[66:67], v72, v[66:67]
	v_min_u32_e32 v66, 1, v66
	v_or_b32_e32 v66, v67, v66
	v_cvt_f32_u32_e32 v73, v66
	v_lshl_add_u64 v[66:67], s[20:21], 0, v[68:69]
	v_sub_u32_e32 v68, 32, v72
	v_lshl_add_u64 v[70:71], v[162:163], 3, s[36:37]
	v_ldexp_f32 v68, v73, v68
	v_mul_f32_e32 v68, 0x2f800000, v68
	v_fmamk_f32 v68, v68, 0x3a800000, v209
	v_rsq_f32_e32 v68, v68
	v_lshl_add_u64 v[72:73], s[58:59], 0, v[142:143]
	v_lshlrev_b64 v[72:73], 1, v[72:73]
	v_lshl_add_u64 v[66:67], v[66:67], 0, v[72:73]
	v_pk_mul_f32 v[62:63], v[62:63], v[68:69] op_sel_hi:[1,0]
	v_pk_mul_f32 v[60:61], v[60:61], v[68:69] op_sel_hi:[1,0]
	v_pk_mul_f32 v[74:75], v[58:59], v[68:69] op_sel_hi:[1,0]
	v_pk_mul_f32 v[58:59], v[56:57], v[68:69] op_sel_hi:[1,0]
	v_cvt_pk_bf16_f32 v56, v60, v61
	v_cvt_pk_bf16_f32 v57, v62, v63
	v_cvt_pk_bf16_f32 v58, v58, v59
	v_cvt_pk_bf16_f32 v59, v74, v75
	global_store_dwordx4 v[66:67], v[56:59], off offset:256 sc1
	global_load_dwordx2 v[56:57], v[70:71], off
	v_lshl_add_u64 v[60:61], v[130:131], 3, s[36:37]
	s_waitcnt vmcnt(0)
	v_ffbh_u32_e32 v58, v57
	v_min_u32_e32 v58, 32, v58
	v_lshlrev_b64 v[56:57], v58, v[56:57]
	v_min_u32_e32 v56, 1, v56
	v_or_b32_e32 v56, v57, v56
	v_cvt_f32_u32_e32 v59, v56
	v_sub_u32_e32 v58, 32, v58
	v_lshlrev_b64 v[56:57], 12, v[162:163]
	v_lshl_add_u64 v[56:57], s[20:21], 0, v[56:57]
	v_ldexp_f32 v58, v59, v58
	v_mul_f32_e32 v58, 0x2f800000, v58
	v_fmamk_f32 v58, v58, 0x3a800000, v209
	v_rsq_f32_e32 v58, v58
	v_lshl_add_u64 v[56:57], v[56:57], 0, v[72:73]
	v_pk_mul_f32 v[54:55], v[54:55], v[58:59] op_sel_hi:[1,0]
	v_pk_mul_f32 v[52:53], v[52:53], v[58:59] op_sel_hi:[1,0]
	v_pk_mul_f32 v[62:63], v[50:51], v[58:59] op_sel_hi:[1,0]
	v_pk_mul_f32 v[50:51], v[48:49], v[58:59] op_sel_hi:[1,0]
	v_cvt_pk_bf16_f32 v48, v52, v53
	v_cvt_pk_bf16_f32 v49, v54, v55
	v_cvt_pk_bf16_f32 v50, v50, v51
	v_cvt_pk_bf16_f32 v51, v62, v63
	global_store_dwordx4 v[56:57], v[48:51], off offset:256 sc1
	global_load_dwordx2 v[48:49], v[60:61], off
	v_lshl_add_u64 v[52:53], v[128:129], 3, s[36:37]
	s_waitcnt vmcnt(0)
	v_ffbh_u32_e32 v50, v49
	v_min_u32_e32 v50, 32, v50
	v_lshlrev_b64 v[48:49], v50, v[48:49]
	v_min_u32_e32 v48, 1, v48
	v_or_b32_e32 v48, v49, v48
	v_cvt_f32_u32_e32 v51, v48
	v_sub_u32_e32 v50, 32, v50
	v_lshlrev_b64 v[48:49], 12, v[130:131]
	v_lshl_add_u64 v[48:49], s[20:21], 0, v[48:49]
	v_ldexp_f32 v50, v51, v50
	v_mul_f32_e32 v50, 0x2f800000, v50
	v_fmamk_f32 v50, v50, 0x3a800000, v209
	v_rsq_f32_e32 v50, v50
	v_lshl_add_u64 v[48:49], v[48:49], 0, v[72:73]
	v_pk_mul_f32 v[46:47], v[46:47], v[50:51] op_sel_hi:[1,0]
	v_pk_mul_f32 v[44:45], v[44:45], v[50:51] op_sel_hi:[1,0]
	v_pk_mul_f32 v[54:55], v[42:43], v[50:51] op_sel_hi:[1,0]
	v_pk_mul_f32 v[42:43], v[40:41], v[50:51] op_sel_hi:[1,0]
	v_cvt_pk_bf16_f32 v40, v44, v45
	v_cvt_pk_bf16_f32 v41, v46, v47
	v_cvt_pk_bf16_f32 v42, v42, v43
	v_cvt_pk_bf16_f32 v43, v54, v55
	global_store_dwordx4 v[48:49], v[40:43], off offset:256 sc1
	global_load_dwordx2 v[40:41], v[52:53], off
	s_waitcnt vmcnt(0)
	v_ffbh_u32_e32 v42, v41
	v_min_u32_e32 v42, 32, v42
	v_lshlrev_b64 v[40:41], v42, v[40:41]
	v_min_u32_e32 v40, 1, v40
	v_or_b32_e32 v40, v41, v40
	v_cvt_f32_u32_e32 v40, v40
	v_sub_u32_e32 v41, 32, v42
	v_lshlrev_b64 v[42:43], 12, v[128:129]
	v_lshl_add_u64 v[42:43], s[20:21], 0, v[42:43]
	v_ldexp_f32 v40, v40, v41
	v_mul_f32_e32 v40, 0x2f800000, v40
	v_fmamk_f32 v40, v40, 0x3a800000, v209
	v_rsq_f32_e32 v40, v40
	v_lshl_add_u64 v[42:43], v[42:43], 0, v[72:73]
	v_pk_mul_f32 v[38:39], v[38:39], v[40:41] op_sel_hi:[1,0]
	v_pk_mul_f32 v[36:37], v[36:37], v[40:41] op_sel_hi:[1,0]
	v_pk_mul_f32 v[44:45], v[34:35], v[40:41] op_sel_hi:[1,0]
	v_pk_mul_f32 v[34:35], v[32:33], v[40:41] op_sel_hi:[1,0]
	v_cvt_pk_bf16_f32 v32, v36, v37
	v_cvt_pk_bf16_f32 v33, v38, v39
	v_cvt_pk_bf16_f32 v34, v34, v35
	v_cvt_pk_bf16_f32 v35, v44, v45
	global_store_dwordx4 v[42:43], v[32:35], off offset:256 sc1
	global_load_dwordx2 v[32:33], v[64:65], off offset:1024
	s_waitcnt vmcnt(0)
; __device__ __forceinline__ unsigned cvtpk(float lo, float hi) { f32x2v_ v = {lo, hi}; bf16x2v_ b = __builtin_convertvector(v, bf16x2v_); return __builtin_bit_cast(unsigned, b); }
;     __device__ __forceinline__ void operator()(const f32x4 (&acc)[2][2][4][2], const Unit& u, int wr, int wc, int fr, int fq) const {
;     ...
;                     for (int m = 0; m < 4; ++m) { const int row = row0 + ai * HALF + m * 16; const float rs = ss ? row_rs(ss, row) : 1.0f;
;                         const f32x4 v0 = acc[ai][bj][m][0] * rs, v1 = acc[ai][bj][m][1] * rs;
;                         u32x4 w; w.x = cvtpk(v0[0], v0[1]); w.y = cvtpk(v0[2], v0[3]); w.z = cvtpk(v1[0], v1[1]); w.w = cvtpk(v1[2], v1[3]);
;                         *(u32x4*)(O + (size_t)row * ldc + c0) = w; }
	v_ffbh_u32_e32 v34, v33
	v_min_u32_e32 v34, 32, v34
	v_lshlrev_b64 v[32:33], v34, v[32:33]
	v_min_u32_e32 v32, 1, v32
	v_or_b32_e32 v32, v33, v32
	v_cvt_f32_u32_e32 v32, v32
	v_sub_u32_e32 v33, 32, v34
	v_add_co_u32_e32 v34, vcc, s84, v66
	v_ldexp_f32 v32, v32, v33
	v_mul_f32_e32 v32, 0x2f800000, v32
	v_fmamk_f32 v32, v32, 0x3a800000, v209
	v_rsq_f32_e32 v32, v32
	v_addc_co_u32_e32 v35, vcc, 0, v67, vcc
	v_pk_mul_f32 v[30:31], v[30:31], v[32:33] op_sel_hi:[1,0]
	v_pk_mul_f32 v[28:29], v[28:29], v[32:33] op_sel_hi:[1,0]
	v_pk_mul_f32 v[36:37], v[26:27], v[32:33] op_sel_hi:[1,0]
	v_pk_mul_f32 v[26:27], v[24:25], v[32:33] op_sel_hi:[1,0]
	v_cvt_pk_bf16_f32 v24, v28, v29
	v_cvt_pk_bf16_f32 v25, v30, v31
	v_cvt_pk_bf16_f32 v26, v26, v27
	v_cvt_pk_bf16_f32 v27, v36, v37
	global_store_dwordx4 v[34:35], v[24:27], off offset:256 sc1
	global_load_dwordx2 v[24:25], v[64:65], off offset:1152
	s_waitcnt vmcnt(0)
	v_ffbh_u32_e32 v26, v25
	v_min_u32_e32 v26, 32, v26
	v_lshlrev_b64 v[24:25], v26, v[24:25]
	v_min_u32_e32 v24, 1, v24
	v_or_b32_e32 v24, v25, v24
	v_cvt_f32_u32_e32 v24, v24
	v_sub_u32_e32 v25, 32, v26
	v_add_co_u32_e32 v26, vcc, s85, v66
	v_ldexp_f32 v24, v24, v25
	v_mul_f32_e32 v24, 0x2f800000, v24
	v_fmamk_f32 v24, v24, 0x3a800000, v209
	v_rsq_f32_e32 v24, v24
	v_addc_co_u32_e32 v27, vcc, 0, v67, vcc
	v_pk_mul_f32 v[22:23], v[22:23], v[24:25] op_sel_hi:[1,0]
	v_pk_mul_f32 v[20:21], v[20:21], v[24:25] op_sel_hi:[1,0]
	v_pk_mul_f32 v[28:29], v[18:19], v[24:25] op_sel_hi:[1,0]
	v_pk_mul_f32 v[18:19], v[16:17], v[24:25] op_sel_hi:[1,0]
	v_cvt_pk_bf16_f32 v16, v20, v21
	v_cvt_pk_bf16_f32 v17, v22, v23
	v_cvt_pk_bf16_f32 v18, v18, v19
	v_cvt_pk_bf16_f32 v19, v28, v29
	global_store_dwordx4 v[26:27], v[16:19], off offset:256 sc1
	global_load_dwordx2 v[16:17], v[64:65], off offset:1280
	s_waitcnt vmcnt(0)
	v_ffbh_u32_e32 v18, v17
	v_min_u32_e32 v18, 32, v18
	v_lshlrev_b64 v[16:17], v18, v[16:17]
	v_min_u32_e32 v16, 1, v16
	v_or_b32_e32 v16, v17, v16
	v_cvt_f32_u32_e32 v16, v16
	v_sub_u32_e32 v17, 32, v18
	v_add_co_u32_e32 v18, vcc, s86, v66
	v_ldexp_f32 v16, v16, v17
	v_mul_f32_e32 v16, 0x2f800000, v16
	v_fmamk_f32 v16, v16, 0x3a800000, v209
	v_rsq_f32_e32 v16, v16
	v_addc_co_u32_e32 v19, vcc, 0, v67, vcc
	v_pk_mul_f32 v[14:15], v[14:15], v[16:17] op_sel_hi:[1,0]
	v_pk_mul_f32 v[12:13], v[12:13], v[16:17] op_sel_hi:[1,0]
	v_pk_mul_f32 v[20:21], v[10:11], v[16:17] op_sel_hi:[1,0]
	v_pk_mul_f32 v[10:11], v[8:9], v[16:17] op_sel_hi:[1,0]
	v_cvt_pk_bf16_f32 v8, v12, v13
	v_cvt_pk_bf16_f32 v9, v14, v15
	v_cvt_pk_bf16_f32 v10, v10, v11
	v_cvt_pk_bf16_f32 v11, v20, v21
	global_store_dwordx4 v[18:19], v[8:11], off offset:256 sc1
	global_load_dwordx2 v[8:9], v[64:65], off offset:1408
	s_waitcnt vmcnt(0)
	v_ffbh_u32_e32 v10, v9
	v_min_u32_e32 v10, 32, v10
	v_lshlrev_b64 v[8:9], v10, v[8:9]
	v_min_u32_e32 v8, 1, v8
	v_or_b32_e32 v8, v9, v8
	v_cvt_f32_u32_e32 v8, v8
	v_sub_u32_e32 v9, 32, v10
	v_add_co_u32_e32 v10, vcc, 0xb0000, v66
	v_ldexp_f32 v8, v8, v9
	v_mul_f32_e32 v8, 0x2f800000, v8
	v_fmamk_f32 v8, v8, 0x3a800000, v209
	v_rsq_f32_e32 v8, v8
	v_addc_co_u32_e32 v11, vcc, 0, v67, vcc
	v_pk_mul_f32 v[6:7], v[6:7], v[8:9] op_sel_hi:[1,0]
	v_pk_mul_f32 v[4:5], v[4:5], v[8:9] op_sel_hi:[1,0]
	v_pk_mul_f32 v[12:13], v[2:3], v[8:9] op_sel_hi:[1,0]
	v_pk_mul_f32 v[2:3], v[0:1], v[8:9] op_sel_hi:[1,0]
	v_cvt_pk_bf16_f32 v0, v4, v5
	v_cvt_pk_bf16_f32 v1, v6, v7
	v_cvt_pk_bf16_f32 v2, v2, v3
	v_cvt_pk_bf16_f32 v3, v12, v13
	global_store_dwordx4 v[10:11], v[0:3], off offset:256 sc1
	s_andn2_b64 vcc, exec, s[12:13]
	s_mov_b64 s[12:13], -1
	s_cbranch_vccnz .LBB0_1279

; __device__ __forceinline__ void fx_add(float* p, size_t idx, float s) { atomicAdd((unsigned long long*)p + idx, (unsigned long long)(long long)(s * 4294967296.0f)); }
; __device__ __forceinline__ unsigned cvtpk(float lo, float hi) { f32x2v_ v = {lo, hi}; bf16x2v_ b = __builtin_convertvector(v, bf16x2v_); return __builtin_bit_cast(unsigned, b); }
;     __device__ __forceinline__ void operator()(const f32x4 (&acc)[2][2][4][2], const Unit& u, int wr, int wc, int fr, int fq) const {
;     ...
;             for (int m = 0; m < 4; ++m) { const int row = row0 + ai * HALF + m * 16; const size_t off = (size_t)row * 1024 + col0; float s = 0.f;
; #pragma unroll
;                 for (int bj = 0; bj < 2; ++bj) { f32x4 a0, a1;
;                     if (xin32) { const float* p = xin32 + off + bj * HALF; a0 = *(const f32x4*)p; a1 = *(const f32x4*)(p + 4); }
;                     else { const u32x4 w = *(const u32x4*)(xb + off + bj * HALF);
;                         a0 = (f32x4){__uint_as_float(w.x << 16), __uint_as_float(w.x & 0xffff0000u), __uint_as_float(w.y << 16), __uint_as_float(w.y & 0xffff0000u)};
;                         a1 = (f32x4){__uint_as_float(w.z << 16), __uint_as_float(w.z & 0xffff0000u), __uint_as_float(w.w << 16), __uint_as_float(w.w & 0xffff0000u)}; }
;                     const f32x4 v0 = a0 + acc[ai][bj][m][0] * alpha, v1 = a1 + acc[ai][bj][m][1] * alpha;
;                     u32x4 w; w.x = cvtpk(v0[0], v0[1]); w.y = cvtpk(v0[2], v0[3]); w.z = cvtpk(v1[0], v1[1]); w.w = cvtpk(v1[2], v1[3]);
;                     *(u32x4*)(xb + off + bj * HALF) = w;
;                     s += (v0[0] * v0[0] + v0[1] * v0[1]) + (v0[2] * v0[2] + v0[3] * v0[3]) + (v1[0] * v1[0] + v1[1] * v1[1]) + (v1[2] * v1[2] + v1[3] * v1[3]); }
;                 s += __shfl_xor(s, 16); s += __shfl_xor(s, 32);
;                 if (fq == 0) fx_add(ssout, row, s); }
.LBB0_1596:
	v_lshl_add_u32 v148, s48, 8, v145
	v_ashrrev_i32_e32 v149, 31, v148
	v_lshl_or_b32 v146, s46, 8, v151
	v_lshlrev_b64 v[156:157], 11, v[148:149]
	v_ashrrev_i32_e32 v147, 31, v146
	v_lshl_add_u64 v[156:157], s[22:23], 0, v[156:157]
	v_lshl_add_u64 v[166:167], v[146:147], 1, v[156:157]
	global_load_dwordx4 v[158:161], v[166:167], off
	global_load_dwordx4 v[162:165], v[166:167], off offset:256
	v_and_b32_e32 v157, 64, v155
	v_xor_b32_e32 v156, 16, v155
	v_add_u32_e32 v157, 64, v157
	v_xor_b32_e32 v168, 32, v155
	v_cmp_lt_i32_e32 vcc, v156, v157
	s_waitcnt vmcnt(0)
	v_and_b32_e32 v169, 0xffff0000, v158
	v_cndmask_b32_e32 v156, v155, v156, vcc
	v_cmp_lt_i32_e32 vcc, v168, v157
	v_lshlrev_b32_e32 v157, 2, v156
	v_lshlrev_b32_e32 v172, 16, v162
	v_cndmask_b32_e32 v168, v155, v168, vcc
	v_lshlrev_b32_e32 v156, 2, v168
	v_lshlrev_b32_e32 v168, 16, v158
	v_lshlrev_b32_e32 v158, 16, v159
	v_and_b32_e32 v159, 0xffff0000, v159
	v_and_b32_e32 v173, 0xffff0000, v162
	v_lshlrev_b32_e32 v162, 16, v163
	v_and_b32_e32 v163, 0xffff0000, v163
	v_lshlrev_b32_e32 v170, 16, v160
	v_and_b32_e32 v171, 0xffff0000, v160
	v_lshlrev_b32_e32 v160, 16, v161
	v_and_b32_e32 v161, 0xffff0000, v161
	v_lshlrev_b32_e32 v174, 16, v164
	v_and_b32_e32 v175, 0xffff0000, v164
	v_lshlrev_b32_e32 v164, 16, v165
	v_and_b32_e32 v165, 0xffff0000, v165
	v_pk_add_f32 v[126:127], v[126:127], v[158:159]
	v_pk_add_f32 v[124:125], v[124:125], v[168:169]
	v_pk_add_f32 v[118:119], v[118:119], v[162:163]
	v_pk_add_f32 v[116:117], v[116:117], v[172:173]
	v_pk_add_f32 v[122:123], v[122:123], v[160:161]
	v_pk_add_f32 v[120:121], v[120:121], v[170:171]
	v_pk_add_f32 v[158:159], v[114:115], v[164:165]
	v_pk_add_f32 v[160:161], v[112:113], v[174:175]
	v_mul_f32_e32 v114, v125, v125
	v_mul_f32_e32 v115, v127, v127
	v_mul_f32_e32 v162, v117, v117
	v_mul_f32_e32 v163, v119, v119
	v_cvt_pk_bf16_f32 v112, v124, v125
	v_mul_f32_e32 v125, v121, v121
	v_mul_f32_e32 v164, v161, v161
	v_fmac_f32_e32 v114, v124, v124
	v_fmac_f32_e32 v115, v126, v126
	v_fmac_f32_e32 v162, v116, v116
	v_fmac_f32_e32 v163, v118, v118
	v_cvt_pk_bf16_f32 v113, v126, v127
	v_mul_f32_e32 v127, v123, v123
	v_mul_f32_e32 v165, v159, v159
	v_fmac_f32_e32 v125, v120, v120
	v_fmac_f32_e32 v164, v160, v160
	v_add_f32_e32 v114, v114, v115
	v_add_f32_e32 v115, v162, v163
	v_fmac_f32_e32 v127, v122, v122
	v_fmac_f32_e32 v165, v158, v158
	v_add_f32_e32 v114, v125, v114
	v_add_f32_e32 v115, v164, v115
	v_add_f32_e32 v114, v127, v114
	v_add_f32_e32 v115, v165, v115
	v_add_f32_e32 v124, v114, v115
	v_mov_b32_e32 v125, v124
	s_nop 1
	v_permlane16_swap_b32_e32 v125, v124
	v_cvt_pk_bf16_f32 v114, v120, v121
	v_cvt_pk_bf16_f32 v115, v122, v123
	global_store_dwordx4 v[166:167], v[112:115], off sc1
	s_waitcnt lgkmcnt(0)
	s_nop 0
	v_add_f32_e32 v112, v124, v125
	v_mov_b32_e32 v113, v112
	s_nop 1
	v_permlane32_swap_b32_e32 v113, v112
	v_cvt_pk_bf16_f32 v114, v116, v117
	v_cvt_pk_bf16_f32 v115, v118, v119
	v_cvt_pk_bf16_f32 v116, v160, v161
	v_cvt_pk_bf16_f32 v117, v158, v159
	global_store_dwordx4 v[166:167], v[114:117], off offset:256 sc1
	s_and_saveexec_b64 s[46:47], s[4:5]
	s_cbranch_execz .LBB0_1598
	s_waitcnt lgkmcnt(0)
	v_add_f32_e32 v112, v112, v113
	v_mul_f32_e32 v112, 0x4f800000, v112
	v_trunc_f32_e32 v112, v112
	v_mul_f32_e64 v113, |v112|, s62
	v_floor_f32_e32 v113, v113
	v_fma_f32 v114, v113, s63, |v112|
	v_cvt_u32_f32_e32 v112, v114
	v_cvt_u32_f32_e32 v113, v113
	v_lshl_add_u64 v[114:115], v[148:149], 3, s[12:13]
	global_atomic_add_x2 v[114:115], v[112:113], off
.LBB0_1598:
	s_or_b64 exec, exec, s[46:47]
	v_or_b32_e32 v112, 16, v148
	s_waitcnt lgkmcnt(0)
	v_ashrrev_i32_e32 v113, 31, v112
	v_lshlrev_b64 v[114:115], 11, v[112:113]
	v_lshl_add_u64 v[114:115], s[22:23], 0, v[114:115]
	v_lshl_add_u64 v[122:123], v[146:147], 1, v[114:115]
	global_load_dwordx4 v[114:117], v[122:123], off
	global_load_dwordx4 v[118:121], v[122:123], off offset:256
	s_waitcnt vmcnt(1)
	v_lshlrev_b32_e32 v124, 16, v114
	v_and_b32_e32 v125, 0xffff0000, v114
	v_lshlrev_b32_e32 v114, 16, v115
	v_and_b32_e32 v115, 0xffff0000, v115
	s_waitcnt vmcnt(0)
	v_lshlrev_b32_e32 v158, 16, v118
	v_and_b32_e32 v159, 0xffff0000, v118
	v_lshlrev_b32_e32 v118, 16, v119
	v_and_b32_e32 v119, 0xffff0000, v119
	v_lshlrev_b32_e32 v126, 16, v116
	v_and_b32_e32 v127, 0xffff0000, v116
	v_lshlrev_b32_e32 v116, 16, v117
	v_and_b32_e32 v117, 0xffff0000, v117
	v_lshlrev_b32_e32 v160, 16, v120
	v_and_b32_e32 v161, 0xffff0000, v120
	v_lshlrev_b32_e32 v120, 16, v121
	v_and_b32_e32 v121, 0xffff0000, v121
	v_pk_add_f32 v[110:111], v[110:111], v[114:115]
	v_pk_add_f32 v[108:109], v[108:109], v[124:125]
	v_pk_add_f32 v[102:103], v[102:103], v[118:119]
	v_pk_add_f32 v[100:101], v[100:101], v[158:159]
	v_pk_add_f32 v[106:107], v[106:107], v[116:117]
	v_pk_add_f32 v[104:105], v[104:105], v[126:127]
	v_pk_add_f32 v[114:115], v[98:99], v[120:121]
	v_pk_add_f32 v[116:117], v[96:97], v[160:161]
	v_mul_f32_e32 v98, v109, v109
	v_mul_f32_e32 v99, v111, v111
	v_mul_f32_e32 v118, v101, v101
	v_mul_f32_e32 v119, v103, v103
	v_cvt_pk_bf16_f32 v96, v108, v109
	v_mul_f32_e32 v109, v105, v105
	v_mul_f32_e32 v120, v117, v117
	v_fmac_f32_e32 v98, v108, v108
	v_fmac_f32_e32 v99, v110, v110
	v_fmac_f32_e32 v118, v100, v100
	v_fmac_f32_e32 v119, v102, v102
	v_cvt_pk_bf16_f32 v97, v110, v111
	v_mul_f32_e32 v111, v107, v107
	v_mul_f32_e32 v121, v115, v115
	v_fmac_f32_e32 v109, v104, v104
	v_fmac_f32_e32 v120, v116, v116
	v_add_f32_e32 v98, v98, v99
	v_add_f32_e32 v99, v118, v119
	v_fmac_f32_e32 v111, v106, v106
	v_fmac_f32_e32 v121, v114, v114
	v_add_f32_e32 v98, v109, v98
	v_add_f32_e32 v99, v120, v99
	v_add_f32_e32 v98, v111, v98
	v_add_f32_e32 v99, v121, v99
	v_add_f32_e32 v108, v98, v99
	v_mov_b32_e32 v109, v108
	s_nop 1
	v_permlane16_swap_b32_e32 v109, v108
	v_cvt_pk_bf16_f32 v98, v104, v105
	v_cvt_pk_bf16_f32 v99, v106, v107
	global_store_dwordx4 v[122:123], v[96:99], off sc1
	s_waitcnt lgkmcnt(0)
	s_nop 0
	v_add_f32_e32 v96, v108, v109
	v_mov_b32_e32 v97, v96
	s_nop 1
	v_permlane32_swap_b32_e32 v97, v96
	v_cvt_pk_bf16_f32 v98, v100, v101
	v_cvt_pk_bf16_f32 v99, v102, v103
	v_cvt_pk_bf16_f32 v100, v116, v117
	v_cvt_pk_bf16_f32 v101, v114, v115
	global_store_dwordx4 v[122:123], v[98:101], off offset:256 sc1
	s_and_saveexec_b64 s[46:47], s[4:5]
	s_cbranch_execz .LBB0_1600
	s_waitcnt lgkmcnt(0)
	v_add_f32_e32 v96, v96, v97
	v_mul_f32_e32 v96, 0x4f800000, v96
	v_trunc_f32_e32 v96, v96
	v_mul_f32_e64 v97, |v96|, s62
	v_floor_f32_e32 v97, v97
	v_fma_f32 v98, v97, s63, |v96|
	v_cvt_u32_f32_e32 v96, v98
	v_cvt_u32_f32_e32 v97, v97
	v_lshl_add_u64 v[98:99], v[112:113], 3, s[12:13]
	global_atomic_add_x2 v[98:99], v[96:97], off
; __device__ __forceinline__ void fx_add(float* p, size_t idx, float s) { atomicAdd((unsigned long long*)p + idx, (unsigned long long)(long long)(s * 4294967296.0f)); }
; __device__ __forceinline__ unsigned cvtpk(float lo, float hi) { f32x2v_ v = {lo, hi}; bf16x2v_ b = __builtin_convertvector(v, bf16x2v_); return __builtin_bit_cast(unsigned, b); }
;     __device__ __forceinline__ void operator()(const f32x4 (&acc)[2][2][4][2], const Unit& u, int wr, int wc, int fr, int fq) const {
;     ...
;             for (int m = 0; m < 4; ++m) { const int row = row0 + ai * HALF + m * 16; const size_t off = (size_t)row * 1024 + col0; float s = 0.f;
; #pragma unroll
;                 for (int bj = 0; bj < 2; ++bj) { f32x4 a0, a1;
;                     if (xin32) { const float* p = xin32 + off + bj * HALF; a0 = *(const f32x4*)p; a1 = *(const f32x4*)(p + 4); }
;                     else { const u32x4 w = *(const u32x4*)(xb + off + bj * HALF);
;                         a0 = (f32x4){__uint_as_float(w.x << 16), __uint_as_float(w.x & 0xffff0000u), __uint_as_float(w.y << 16), __uint_as_float(w.y & 0xffff0000u)};
;                         a1 = (f32x4){__uint_as_float(w.z << 16), __uint_as_float(w.z & 0xffff0000u), __uint_as_float(w.w << 16), __uint_as_float(w.w & 0xffff0000u)}; }
;                     const f32x4 v0 = a0 + acc[ai][bj][m][0] * alpha, v1 = a1 + acc[ai][bj][m][1] * alpha;
;                     u32x4 w; w.x = cvtpk(v0[0], v0[1]); w.y = cvtpk(v0[2], v0[3]); w.z = cvtpk(v1[0], v1[1]); w.w = cvtpk(v1[2], v1[3]);
;                     *(u32x4*)(xb + off + bj * HALF) = w;
;                     s += (v0[0] * v0[0] + v0[1] * v0[1]) + (v0[2] * v0[2] + v0[3] * v0[3]) + (v1[0] * v1[0] + v1[1] * v1[1]) + (v1[2] * v1[2] + v1[3] * v1[3]); }
;                 s += __shfl_xor(s, 16); s += __shfl_xor(s, 32);
;                 if (fq == 0) fx_add(ssout, row, s); }
.LBB0_1600:
	s_or_b64 exec, exec, s[46:47]
	v_or_b32_e32 v96, 32, v148
	s_waitcnt lgkmcnt(0)
	v_ashrrev_i32_e32 v97, 31, v96
	v_lshlrev_b64 v[98:99], 11, v[96:97]
	v_lshl_add_u64 v[98:99], s[22:23], 0, v[98:99]
	v_lshl_add_u64 v[106:107], v[146:147], 1, v[98:99]
	global_load_dwordx4 v[98:101], v[106:107], off
	global_load_dwordx4 v[102:105], v[106:107], off offset:256
	s_waitcnt vmcnt(1)
	v_lshlrev_b32_e32 v108, 16, v98
	v_and_b32_e32 v109, 0xffff0000, v98
	v_lshlrev_b32_e32 v98, 16, v99
	v_and_b32_e32 v99, 0xffff0000, v99
	s_waitcnt vmcnt(0)
	v_lshlrev_b32_e32 v112, 16, v102
	v_and_b32_e32 v113, 0xffff0000, v102
	v_lshlrev_b32_e32 v102, 16, v103
	v_and_b32_e32 v103, 0xffff0000, v103
	v_lshlrev_b32_e32 v110, 16, v100
	v_and_b32_e32 v111, 0xffff0000, v100
	v_lshlrev_b32_e32 v100, 16, v101
	v_and_b32_e32 v101, 0xffff0000, v101
	v_lshlrev_b32_e32 v114, 16, v104
	v_and_b32_e32 v115, 0xffff0000, v104
	v_lshlrev_b32_e32 v104, 16, v105
	v_and_b32_e32 v105, 0xffff0000, v105
	v_pk_add_f32 v[94:95], v[94:95], v[98:99]
	v_pk_add_f32 v[92:93], v[92:93], v[108:109]
	v_pk_add_f32 v[86:87], v[86:87], v[102:103]
	v_pk_add_f32 v[84:85], v[84:85], v[112:113]
	v_pk_add_f32 v[90:91], v[90:91], v[100:101]
	v_pk_add_f32 v[88:89], v[88:89], v[110:111]
	v_pk_add_f32 v[98:99], v[82:83], v[104:105]
	v_pk_add_f32 v[100:101], v[80:81], v[114:115]
	v_mul_f32_e32 v82, v93, v93
	v_mul_f32_e32 v83, v95, v95
	v_mul_f32_e32 v102, v85, v85
	v_mul_f32_e32 v103, v87, v87
	v_cvt_pk_bf16_f32 v80, v92, v93
	v_mul_f32_e32 v93, v89, v89
	v_mul_f32_e32 v104, v101, v101
	v_fmac_f32_e32 v82, v92, v92
	v_fmac_f32_e32 v83, v94, v94
	v_fmac_f32_e32 v102, v84, v84
	v_fmac_f32_e32 v103, v86, v86
	v_cvt_pk_bf16_f32 v81, v94, v95
	v_mul_f32_e32 v95, v91, v91
	v_mul_f32_e32 v105, v99, v99
	v_fmac_f32_e32 v93, v88, v88
	v_fmac_f32_e32 v104, v100, v100
	v_add_f32_e32 v82, v82, v83
	v_add_f32_e32 v83, v102, v103
	v_fmac_f32_e32 v95, v90, v90
	v_fmac_f32_e32 v105, v98, v98
	v_add_f32_e32 v82, v93, v82
	v_add_f32_e32 v83, v104, v83
	v_add_f32_e32 v82, v95, v82
	v_add_f32_e32 v83, v105, v83
	v_add_f32_e32 v92, v82, v83
	v_mov_b32_e32 v93, v92
	s_nop 1
	v_permlane16_swap_b32_e32 v93, v92
	v_cvt_pk_bf16_f32 v82, v88, v89
	v_cvt_pk_bf16_f32 v83, v90, v91
	global_store_dwordx4 v[106:107], v[80:83], off sc1
	s_waitcnt lgkmcnt(0)
	s_nop 0
	v_add_f32_e32 v80, v92, v93
	v_mov_b32_e32 v81, v80
	s_nop 1
	v_permlane32_swap_b32_e32 v81, v80
	v_cvt_pk_bf16_f32 v82, v84, v85
	v_cvt_pk_bf16_f32 v83, v86, v87
	v_cvt_pk_bf16_f32 v84, v100, v101
	v_cvt_pk_bf16_f32 v85, v98, v99
	global_store_dwordx4 v[106:107], v[82:85], off offset:256 sc1
	s_and_saveexec_b64 s[46:47], s[4:5]
	s_cbranch_execz .LBB0_1602
	s_waitcnt lgkmcnt(0)
	v_add_f32_e32 v80, v80, v81
	v_mul_f32_e32 v80, 0x4f800000, v80
	v_trunc_f32_e32 v80, v80
	v_mul_f32_e64 v81, |v80|, s62
	v_floor_f32_e32 v81, v81
	v_fma_f32 v82, v81, s63, |v80|
	v_cvt_u32_f32_e32 v80, v82
	v_cvt_u32_f32_e32 v81, v81
	v_lshl_add_u64 v[82:83], v[96:97], 3, s[12:13]
	global_atomic_add_x2 v[82:83], v[80:81], off
.LBB0_1602:
	s_or_b64 exec, exec, s[46:47]
	v_or_b32_e32 v80, 48, v148
	s_waitcnt lgkmcnt(0)
	v_ashrrev_i32_e32 v81, 31, v80
	v_lshlrev_b64 v[82:83], 11, v[80:81]
	v_lshl_add_u64 v[82:83], s[22:23], 0, v[82:83]
	v_lshl_add_u64 v[90:91], v[146:147], 1, v[82:83]
	global_load_dwordx4 v[82:85], v[90:91], off
	global_load_dwordx4 v[86:89], v[90:91], off offset:256
	s_waitcnt vmcnt(1)
	v_lshlrev_b32_e32 v92, 16, v82
	v_and_b32_e32 v93, 0xffff0000, v82
	v_lshlrev_b32_e32 v82, 16, v83
	v_and_b32_e32 v83, 0xffff0000, v83
	s_waitcnt vmcnt(0)
	v_lshlrev_b32_e32 v96, 16, v86
	v_and_b32_e32 v97, 0xffff0000, v86
	v_lshlrev_b32_e32 v86, 16, v87
	v_and_b32_e32 v87, 0xffff0000, v87
	v_lshlrev_b32_e32 v94, 16, v84
	v_and_b32_e32 v95, 0xffff0000, v84
	v_lshlrev_b32_e32 v84, 16, v85
	v_and_b32_e32 v85, 0xffff0000, v85
	v_lshlrev_b32_e32 v98, 16, v88
	v_and_b32_e32 v99, 0xffff0000, v88
	v_lshlrev_b32_e32 v88, 16, v89
	v_and_b32_e32 v89, 0xffff0000, v89
	v_pk_add_f32 v[78:79], v[78:79], v[82:83]
	v_pk_add_f32 v[76:77], v[76:77], v[92:93]
	v_pk_add_f32 v[70:71], v[70:71], v[86:87]
	v_pk_add_f32 v[68:69], v[68:69], v[96:97]
	v_pk_add_f32 v[74:75], v[74:75], v[84:85]
	v_pk_add_f32 v[72:73], v[72:73], v[94:95]
	v_pk_add_f32 v[82:83], v[66:67], v[88:89]
	v_pk_add_f32 v[84:85], v[64:65], v[98:99]
	v_mul_f32_e32 v66, v77, v77
	v_mul_f32_e32 v67, v79, v79
	v_mul_f32_e32 v86, v69, v69
	v_mul_f32_e32 v87, v71, v71
	v_cvt_pk_bf16_f32 v64, v76, v77
	v_mul_f32_e32 v77, v73, v73
	v_mul_f32_e32 v88, v85, v85
	v_fmac_f32_e32 v66, v76, v76
	v_fmac_f32_e32 v67, v78, v78
	v_fmac_f32_e32 v86, v68, v68
	v_fmac_f32_e32 v87, v70, v70
	v_cvt_pk_bf16_f32 v65, v78, v79
	v_mul_f32_e32 v79, v75, v75
	v_mul_f32_e32 v89, v83, v83
	v_fmac_f32_e32 v77, v72, v72
	v_fmac_f32_e32 v88, v84, v84
	v_add_f32_e32 v66, v66, v67
	v_add_f32_e32 v67, v86, v87
	v_fmac_f32_e32 v79, v74, v74
	v_fmac_f32_e32 v89, v82, v82
	v_add_f32_e32 v66, v77, v66
	v_add_f32_e32 v67, v88, v67
	v_add_f32_e32 v66, v79, v66
	v_add_f32_e32 v67, v89, v67
	v_add_f32_e32 v76, v66, v67
	v_mov_b32_e32 v77, v76
	s_nop 1
	v_permlane16_swap_b32_e32 v77, v76
	v_cvt_pk_bf16_f32 v66, v72, v73
	v_cvt_pk_bf16_f32 v67, v74, v75
	global_store_dwordx4 v[90:91], v[64:67], off sc1
	s_waitcnt lgkmcnt(0)
	s_nop 0
	v_add_f32_e32 v64, v76, v77
	v_mov_b32_e32 v65, v64
	s_nop 1
	v_permlane32_swap_b32_e32 v65, v64
	v_cvt_pk_bf16_f32 v66, v68, v69
	v_cvt_pk_bf16_f32 v67, v70, v71
	v_cvt_pk_bf16_f32 v68, v84, v85
	v_cvt_pk_bf16_f32 v69, v82, v83
	global_store_dwordx4 v[90:91], v[66:69], off offset:256 sc1
	s_and_saveexec_b64 s[46:47], s[4:5]
	s_cbranch_execz .LBB0_1604
	s_waitcnt lgkmcnt(0)
	v_add_f32_e32 v64, v64, v65
	v_mul_f32_e32 v64, 0x4f800000, v64
	v_trunc_f32_e32 v64, v64
	v_mul_f32_e64 v65, |v64|, s62
	v_floor_f32_e32 v65, v65
	v_fma_f32 v66, v65, s63, |v64|
	v_cvt_u32_f32_e32 v64, v66
	v_cvt_u32_f32_e32 v65, v65
	v_lshl_add_u64 v[66:67], v[80:81], 3, s[12:13]
	global_atomic_add_x2 v[66:67], v[64:65], off
; __device__ __forceinline__ void fx_add(float* p, size_t idx, float s) { atomicAdd((unsigned long long*)p + idx, (unsigned long long)(long long)(s * 4294967296.0f)); }
; __device__ __forceinline__ unsigned cvtpk(float lo, float hi) { f32x2v_ v = {lo, hi}; bf16x2v_ b = __builtin_convertvector(v, bf16x2v_); return __builtin_bit_cast(unsigned, b); }
;     __device__ __forceinline__ void operator()(const f32x4 (&acc)[2][2][4][2], const Unit& u, int wr, int wc, int fr, int fq) const {
;     ...
;             for (int m = 0; m < 4; ++m) { const int row = row0 + ai * HALF + m * 16; const size_t off = (size_t)row * 1024 + col0; float s = 0.f;
; #pragma unroll
;                 for (int bj = 0; bj < 2; ++bj) { f32x4 a0, a1;
;                     if (xin32) { const float* p = xin32 + off + bj * HALF; a0 = *(const f32x4*)p; a1 = *(const f32x4*)(p + 4); }
;                     else { const u32x4 w = *(const u32x4*)(xb + off + bj * HALF);
;                         a0 = (f32x4){__uint_as_float(w.x << 16), __uint_as_float(w.x & 0xffff0000u), __uint_as_float(w.y << 16), __uint_as_float(w.y & 0xffff0000u)};
;                         a1 = (f32x4){__uint_as_float(w.z << 16), __uint_as_float(w.z & 0xffff0000u), __uint_as_float(w.w << 16), __uint_as_float(w.w & 0xffff0000u)}; }
;                     const f32x4 v0 = a0 + acc[ai][bj][m][0] * alpha, v1 = a1 + acc[ai][bj][m][1] * alpha;
;                     u32x4 w; w.x = cvtpk(v0[0], v0[1]); w.y = cvtpk(v0[2], v0[3]); w.z = cvtpk(v1[0], v1[1]); w.w = cvtpk(v1[2], v1[3]);
;                     *(u32x4*)(xb + off + bj * HALF) = w;
;                     s += (v0[0] * v0[0] + v0[1] * v0[1]) + (v0[2] * v0[2] + v0[3] * v0[3]) + (v1[0] * v1[0] + v1[1] * v1[1]) + (v1[2] * v1[2] + v1[3] * v1[3]); }
;                 s += __shfl_xor(s, 16); s += __shfl_xor(s, 32);
;                 if (fq == 0) fx_add(ssout, row, s); }
.LBB0_1604:
	s_or_b64 exec, exec, s[46:47]
	v_add_u32_e32 v64, 0x80, v148
	s_waitcnt lgkmcnt(0)
	v_ashrrev_i32_e32 v65, 31, v64
	v_lshlrev_b64 v[66:67], 11, v[64:65]
	v_lshl_add_u64 v[66:67], s[22:23], 0, v[66:67]
	v_lshl_add_u64 v[74:75], v[146:147], 1, v[66:67]
	global_load_dwordx4 v[66:69], v[74:75], off
	global_load_dwordx4 v[70:73], v[74:75], off offset:256
	s_waitcnt vmcnt(1)
	v_lshlrev_b32_e32 v76, 16, v66
	v_and_b32_e32 v77, 0xffff0000, v66
	v_lshlrev_b32_e32 v66, 16, v67
	v_and_b32_e32 v67, 0xffff0000, v67
	s_waitcnt vmcnt(0)
	v_lshlrev_b32_e32 v80, 16, v70
	v_and_b32_e32 v81, 0xffff0000, v70
	v_lshlrev_b32_e32 v70, 16, v71
	v_and_b32_e32 v71, 0xffff0000, v71
	v_lshlrev_b32_e32 v78, 16, v68
	v_and_b32_e32 v79, 0xffff0000, v68
	v_lshlrev_b32_e32 v68, 16, v69
	v_and_b32_e32 v69, 0xffff0000, v69
	v_lshlrev_b32_e32 v82, 16, v72
	v_and_b32_e32 v83, 0xffff0000, v72
	v_lshlrev_b32_e32 v72, 16, v73
	v_and_b32_e32 v73, 0xffff0000, v73
	v_pk_add_f32 v[62:63], v[62:63], v[66:67]
	v_pk_add_f32 v[60:61], v[60:61], v[76:77]
	v_pk_add_f32 v[54:55], v[54:55], v[70:71]
	v_pk_add_f32 v[52:53], v[52:53], v[80:81]
	v_pk_add_f32 v[58:59], v[58:59], v[68:69]
	v_pk_add_f32 v[56:57], v[56:57], v[78:79]
	v_pk_add_f32 v[66:67], v[50:51], v[72:73]
	v_pk_add_f32 v[68:69], v[48:49], v[82:83]
	v_mul_f32_e32 v50, v61, v61
	v_mul_f32_e32 v51, v63, v63
	v_mul_f32_e32 v70, v53, v53
	v_mul_f32_e32 v71, v55, v55
	v_cvt_pk_bf16_f32 v48, v60, v61
	v_mul_f32_e32 v61, v57, v57
	v_mul_f32_e32 v72, v69, v69
	v_fmac_f32_e32 v50, v60, v60
	v_fmac_f32_e32 v51, v62, v62
	v_fmac_f32_e32 v70, v52, v52
	v_fmac_f32_e32 v71, v54, v54
	v_cvt_pk_bf16_f32 v49, v62, v63
	v_mul_f32_e32 v63, v59, v59
	v_mul_f32_e32 v73, v67, v67
	v_fmac_f32_e32 v61, v56, v56
	v_fmac_f32_e32 v72, v68, v68
	v_add_f32_e32 v50, v50, v51
	v_add_f32_e32 v51, v70, v71
	v_fmac_f32_e32 v63, v58, v58
	v_fmac_f32_e32 v73, v66, v66
	v_add_f32_e32 v50, v61, v50
	v_add_f32_e32 v51, v72, v51
	v_add_f32_e32 v50, v63, v50
	v_add_f32_e32 v51, v73, v51
	v_add_f32_e32 v60, v50, v51
	v_mov_b32_e32 v61, v60
	s_nop 1
	v_permlane16_swap_b32_e32 v61, v60
	v_cvt_pk_bf16_f32 v50, v56, v57
	v_cvt_pk_bf16_f32 v51, v58, v59
	global_store_dwordx4 v[74:75], v[48:51], off sc1
	s_waitcnt lgkmcnt(0)
	s_nop 0
	v_add_f32_e32 v48, v60, v61
	v_mov_b32_e32 v49, v48
	s_nop 1
	v_permlane32_swap_b32_e32 v49, v48
	v_cvt_pk_bf16_f32 v50, v52, v53
	v_cvt_pk_bf16_f32 v51, v54, v55
	v_cvt_pk_bf16_f32 v52, v68, v69
	v_cvt_pk_bf16_f32 v53, v66, v67
	global_store_dwordx4 v[74:75], v[50:53], off offset:256 sc1
	s_and_saveexec_b64 s[46:47], s[4:5]
	s_cbranch_execz .LBB0_1606
	s_waitcnt lgkmcnt(0)
	v_add_f32_e32 v48, v48, v49
	v_mul_f32_e32 v48, 0x4f800000, v48
	v_trunc_f32_e32 v48, v48
	v_mul_f32_e64 v49, |v48|, s62
	v_floor_f32_e32 v49, v49
	v_fma_f32 v50, v49, s63, |v48|
	v_cvt_u32_f32_e32 v48, v50
	v_cvt_u32_f32_e32 v49, v49
	v_lshl_add_u64 v[50:51], v[64:65], 3, s[12:13]
	global_atomic_add_x2 v[50:51], v[48:49], off
.LBB0_1606:
	s_or_b64 exec, exec, s[46:47]
	v_add_u32_e32 v48, 0x90, v148
	s_waitcnt lgkmcnt(0)
	v_ashrrev_i32_e32 v49, 31, v48
	v_lshlrev_b64 v[50:51], 11, v[48:49]
	v_lshl_add_u64 v[50:51], s[22:23], 0, v[50:51]
	v_lshl_add_u64 v[58:59], v[146:147], 1, v[50:51]
	global_load_dwordx4 v[50:53], v[58:59], off
	global_load_dwordx4 v[54:57], v[58:59], off offset:256
	s_waitcnt vmcnt(1)
	v_lshlrev_b32_e32 v60, 16, v50
	v_and_b32_e32 v61, 0xffff0000, v50
	v_lshlrev_b32_e32 v50, 16, v51
	v_and_b32_e32 v51, 0xffff0000, v51
	s_waitcnt vmcnt(0)
	v_lshlrev_b32_e32 v64, 16, v54
	v_and_b32_e32 v65, 0xffff0000, v54
	v_lshlrev_b32_e32 v54, 16, v55
	v_and_b32_e32 v55, 0xffff0000, v55
	v_lshlrev_b32_e32 v62, 16, v52
	v_and_b32_e32 v63, 0xffff0000, v52
	v_lshlrev_b32_e32 v52, 16, v53
	v_and_b32_e32 v53, 0xffff0000, v53
	v_lshlrev_b32_e32 v66, 16, v56
	v_and_b32_e32 v67, 0xffff0000, v56
	v_lshlrev_b32_e32 v56, 16, v57
	v_and_b32_e32 v57, 0xffff0000, v57
	v_pk_add_f32 v[46:47], v[46:47], v[50:51]
	v_pk_add_f32 v[44:45], v[44:45], v[60:61]
	v_pk_add_f32 v[38:39], v[38:39], v[54:55]
	v_pk_add_f32 v[36:37], v[36:37], v[64:65]
	v_pk_add_f32 v[42:43], v[42:43], v[52:53]
	v_pk_add_f32 v[40:41], v[40:41], v[62:63]
	v_pk_add_f32 v[50:51], v[34:35], v[56:57]
	v_pk_add_f32 v[52:53], v[32:33], v[66:67]
	v_mul_f32_e32 v34, v45, v45
	v_mul_f32_e32 v35, v47, v47
	v_mul_f32_e32 v54, v37, v37
	v_mul_f32_e32 v55, v39, v39
	v_cvt_pk_bf16_f32 v32, v44, v45
	v_mul_f32_e32 v45, v41, v41
	v_mul_f32_e32 v56, v53, v53
	v_fmac_f32_e32 v34, v44, v44
	v_fmac_f32_e32 v35, v46, v46
	v_fmac_f32_e32 v54, v36, v36
	v_fmac_f32_e32 v55, v38, v38
	v_cvt_pk_bf16_f32 v33, v46, v47
	v_mul_f32_e32 v47, v43, v43
	v_mul_f32_e32 v57, v51, v51
	v_fmac_f32_e32 v45, v40, v40
	v_fmac_f32_e32 v56, v52, v52
	v_add_f32_e32 v34, v34, v35
	v_add_f32_e32 v35, v54, v55
	v_fmac_f32_e32 v47, v42, v42
	v_fmac_f32_e32 v57, v50, v50
	v_add_f32_e32 v34, v45, v34
	v_add_f32_e32 v35, v56, v35
	v_add_f32_e32 v34, v47, v34
	v_add_f32_e32 v35, v57, v35
	v_add_f32_e32 v44, v34, v35
	v_mov_b32_e32 v45, v44
	s_nop 1
	v_permlane16_swap_b32_e32 v45, v44
	v_cvt_pk_bf16_f32 v34, v40, v41
	v_cvt_pk_bf16_f32 v35, v42, v43
	global_store_dwordx4 v[58:59], v[32:35], off sc1
	s_waitcnt lgkmcnt(0)
	s_nop 0
	v_add_f32_e32 v32, v44, v45
	v_mov_b32_e32 v33, v32
	s_nop 1
	v_permlane32_swap_b32_e32 v33, v32
	v_cvt_pk_bf16_f32 v34, v36, v37
	v_cvt_pk_bf16_f32 v35, v38, v39
	v_cvt_pk_bf16_f32 v36, v52, v53
	v_cvt_pk_bf16_f32 v37, v50, v51
	global_store_dwordx4 v[58:59], v[34:37], off offset:256 sc1
	s_and_saveexec_b64 s[46:47], s[4:5]
	s_cbranch_execz .LBB0_1608
	s_waitcnt lgkmcnt(0)
	v_add_f32_e32 v32, v32, v33
	v_mul_f32_e32 v32, 0x4f800000, v32
	v_trunc_f32_e32 v32, v32
	v_mul_f32_e64 v33, |v32|, s62
	v_floor_f32_e32 v33, v33
	v_fma_f32 v34, v33, s63, |v32|
	v_cvt_u32_f32_e32 v32, v34
	v_cvt_u32_f32_e32 v33, v33
	v_lshl_add_u64 v[34:35], v[48:49], 3, s[12:13]
	global_atomic_add_x2 v[34:35], v[32:33], off
; __device__ __forceinline__ void fx_add(float* p, size_t idx, float s) { atomicAdd((unsigned long long*)p + idx, (unsigned long long)(long long)(s * 4294967296.0f)); }
; __device__ __forceinline__ unsigned cvtpk(float lo, float hi) { f32x2v_ v = {lo, hi}; bf16x2v_ b = __builtin_convertvector(v, bf16x2v_); return __builtin_bit_cast(unsigned, b); }
;     __device__ __forceinline__ void operator()(const f32x4 (&acc)[2][2][4][2], const Unit& u, int wr, int wc, int fr, int fq) const {
;     ...
;             for (int m = 0; m < 4; ++m) { const int row = row0 + ai * HALF + m * 16; const size_t off = (size_t)row * 1024 + col0; float s = 0.f;
; #pragma unroll
;                 for (int bj = 0; bj < 2; ++bj) { f32x4 a0, a1;
;                     if (xin32) { const float* p = xin32 + off + bj * HALF; a0 = *(const f32x4*)p; a1 = *(const f32x4*)(p + 4); }
;                     else { const u32x4 w = *(const u32x4*)(xb + off + bj * HALF);
;                         a0 = (f32x4){__uint_as_float(w.x << 16), __uint_as_float(w.x & 0xffff0000u), __uint_as_float(w.y << 16), __uint_as_float(w.y & 0xffff0000u)};
;                         a1 = (f32x4){__uint_as_float(w.z << 16), __uint_as_float(w.z & 0xffff0000u), __uint_as_float(w.w << 16), __uint_as_float(w.w & 0xffff0000u)}; }
;                     const f32x4 v0 = a0 + acc[ai][bj][m][0] * alpha, v1 = a1 + acc[ai][bj][m][1] * alpha;
;                     u32x4 w; w.x = cvtpk(v0[0], v0[1]); w.y = cvtpk(v0[2], v0[3]); w.z = cvtpk(v1[0], v1[1]); w.w = cvtpk(v1[2], v1[3]);
;                     *(u32x4*)(xb + off + bj * HALF) = w;
;                     s += (v0[0] * v0[0] + v0[1] * v0[1]) + (v0[2] * v0[2] + v0[3] * v0[3]) + (v1[0] * v1[0] + v1[1] * v1[1]) + (v1[2] * v1[2] + v1[3] * v1[3]); }
;                 s += __shfl_xor(s, 16); s += __shfl_xor(s, 32);
;                 if (fq == 0) fx_add(ssout, row, s); }
.LBB0_1608:
	s_or_b64 exec, exec, s[46:47]
	v_add_u32_e32 v32, 0xa0, v148
	s_waitcnt lgkmcnt(0)
	v_ashrrev_i32_e32 v33, 31, v32
	v_lshlrev_b64 v[34:35], 11, v[32:33]
	v_lshl_add_u64 v[34:35], s[22:23], 0, v[34:35]
	v_lshl_add_u64 v[42:43], v[146:147], 1, v[34:35]
	global_load_dwordx4 v[34:37], v[42:43], off
	global_load_dwordx4 v[38:41], v[42:43], off offset:256
	s_waitcnt vmcnt(1)
	v_lshlrev_b32_e32 v44, 16, v34
	v_and_b32_e32 v45, 0xffff0000, v34
	v_lshlrev_b32_e32 v34, 16, v35
	v_and_b32_e32 v35, 0xffff0000, v35
	s_waitcnt vmcnt(0)
	v_lshlrev_b32_e32 v48, 16, v38
	v_and_b32_e32 v49, 0xffff0000, v38
	v_lshlrev_b32_e32 v38, 16, v39
	v_and_b32_e32 v39, 0xffff0000, v39
	v_lshlrev_b32_e32 v46, 16, v36
	v_and_b32_e32 v47, 0xffff0000, v36
	v_lshlrev_b32_e32 v36, 16, v37
	v_and_b32_e32 v37, 0xffff0000, v37
	v_lshlrev_b32_e32 v50, 16, v40
	v_and_b32_e32 v51, 0xffff0000, v40
	v_lshlrev_b32_e32 v40, 16, v41
	v_and_b32_e32 v41, 0xffff0000, v41
	v_pk_add_f32 v[30:31], v[30:31], v[34:35]
	v_pk_add_f32 v[28:29], v[28:29], v[44:45]
	v_pk_add_f32 v[22:23], v[22:23], v[38:39]
	v_pk_add_f32 v[20:21], v[20:21], v[48:49]
	v_pk_add_f32 v[26:27], v[26:27], v[36:37]
	v_pk_add_f32 v[24:25], v[24:25], v[46:47]
	v_pk_add_f32 v[34:35], v[18:19], v[40:41]
	v_pk_add_f32 v[36:37], v[16:17], v[50:51]
	v_mul_f32_e32 v18, v29, v29
	v_mul_f32_e32 v19, v31, v31
	v_mul_f32_e32 v38, v21, v21
	v_mul_f32_e32 v39, v23, v23
	v_cvt_pk_bf16_f32 v16, v28, v29
	v_mul_f32_e32 v29, v25, v25
	v_mul_f32_e32 v40, v37, v37
	v_fmac_f32_e32 v18, v28, v28
	v_fmac_f32_e32 v19, v30, v30
	v_fmac_f32_e32 v38, v20, v20
	v_fmac_f32_e32 v39, v22, v22
	v_cvt_pk_bf16_f32 v17, v30, v31
	v_mul_f32_e32 v31, v27, v27
	v_mul_f32_e32 v41, v35, v35
	v_fmac_f32_e32 v29, v24, v24
	v_fmac_f32_e32 v40, v36, v36
	v_add_f32_e32 v18, v18, v19
	v_add_f32_e32 v19, v38, v39
	v_fmac_f32_e32 v31, v26, v26
	v_fmac_f32_e32 v41, v34, v34
	v_add_f32_e32 v18, v29, v18
	v_add_f32_e32 v19, v40, v19
	v_add_f32_e32 v18, v31, v18
	v_add_f32_e32 v19, v41, v19
	v_add_f32_e32 v28, v18, v19
	v_mov_b32_e32 v29, v28
	s_nop 1
	v_permlane16_swap_b32_e32 v29, v28
	v_cvt_pk_bf16_f32 v18, v24, v25
	v_cvt_pk_bf16_f32 v19, v26, v27
	global_store_dwordx4 v[42:43], v[16:19], off sc1
	s_waitcnt lgkmcnt(0)
	s_nop 0
	v_add_f32_e32 v16, v28, v29
	v_mov_b32_e32 v17, v16
	s_nop 1
	v_permlane32_swap_b32_e32 v17, v16
	v_cvt_pk_bf16_f32 v18, v20, v21
	v_cvt_pk_bf16_f32 v19, v22, v23
	v_cvt_pk_bf16_f32 v20, v36, v37
	v_cvt_pk_bf16_f32 v21, v34, v35
	global_store_dwordx4 v[42:43], v[18:21], off offset:256 sc1
	s_and_saveexec_b64 s[46:47], s[4:5]
	s_cbranch_execz .LBB0_1610
	s_waitcnt lgkmcnt(0)
	v_add_f32_e32 v16, v16, v17
	v_mul_f32_e32 v16, 0x4f800000, v16
	v_trunc_f32_e32 v16, v16
	v_mul_f32_e64 v17, |v16|, s62
	v_floor_f32_e32 v17, v17
	v_fma_f32 v18, v17, s63, |v16|
	v_cvt_u32_f32_e32 v16, v18
	v_cvt_u32_f32_e32 v17, v17
	v_lshl_add_u64 v[18:19], v[32:33], 3, s[12:13]
	global_atomic_add_x2 v[18:19], v[16:17], off
.LBB0_1610:
	s_or_b64 exec, exec, s[46:47]
	v_add_u32_e32 v16, 0xb0, v148
	s_waitcnt lgkmcnt(0)
	v_ashrrev_i32_e32 v17, 31, v16
	v_lshlrev_b64 v[18:19], 11, v[16:17]
	v_lshl_add_u64 v[18:19], s[22:23], 0, v[18:19]
	v_lshl_add_u64 v[26:27], v[146:147], 1, v[18:19]
	global_load_dwordx4 v[18:21], v[26:27], off
	global_load_dwordx4 v[22:25], v[26:27], off offset:256
	s_waitcnt vmcnt(1)
	v_lshlrev_b32_e32 v28, 16, v18
	v_and_b32_e32 v29, 0xffff0000, v18
	v_lshlrev_b32_e32 v18, 16, v19
	v_and_b32_e32 v19, 0xffff0000, v19
	s_waitcnt vmcnt(0)
	v_lshlrev_b32_e32 v32, 16, v22
	v_and_b32_e32 v33, 0xffff0000, v22
	v_lshlrev_b32_e32 v22, 16, v23
	v_and_b32_e32 v23, 0xffff0000, v23
	v_lshlrev_b32_e32 v30, 16, v20
	v_and_b32_e32 v31, 0xffff0000, v20
	v_lshlrev_b32_e32 v20, 16, v21
	v_and_b32_e32 v21, 0xffff0000, v21
	v_lshlrev_b32_e32 v34, 16, v24
	v_and_b32_e32 v35, 0xffff0000, v24
	v_lshlrev_b32_e32 v24, 16, v25
	v_and_b32_e32 v25, 0xffff0000, v25
	v_pk_add_f32 v[14:15], v[14:15], v[18:19]
	v_pk_add_f32 v[12:13], v[12:13], v[28:29]
	v_pk_add_f32 v[6:7], v[6:7], v[22:23]
	v_pk_add_f32 v[4:5], v[4:5], v[32:33]
	v_pk_add_f32 v[10:11], v[10:11], v[20:21]
	v_pk_add_f32 v[8:9], v[8:9], v[30:31]
	v_pk_add_f32 v[18:19], v[2:3], v[24:25]
	v_pk_add_f32 v[20:21], v[0:1], v[34:35]
	v_mul_f32_e32 v2, v13, v13
	v_mul_f32_e32 v3, v15, v15
	v_mul_f32_e32 v22, v5, v5
	v_mul_f32_e32 v23, v7, v7
	v_cvt_pk_bf16_f32 v0, v12, v13
	v_mul_f32_e32 v13, v9, v9
	v_mul_f32_e32 v24, v21, v21
	v_fmac_f32_e32 v2, v12, v12
	v_fmac_f32_e32 v3, v14, v14
	v_fmac_f32_e32 v22, v4, v4
	v_fmac_f32_e32 v23, v6, v6
	v_cvt_pk_bf16_f32 v1, v14, v15
	v_mul_f32_e32 v15, v11, v11
	v_mul_f32_e32 v25, v19, v19
	v_fmac_f32_e32 v13, v8, v8
	v_fmac_f32_e32 v24, v20, v20
	v_add_f32_e32 v2, v2, v3
	v_add_f32_e32 v3, v22, v23
	v_fmac_f32_e32 v15, v10, v10
	v_fmac_f32_e32 v25, v18, v18
	v_add_f32_e32 v2, v13, v2
	v_add_f32_e32 v3, v24, v3
	v_add_f32_e32 v2, v15, v2
	v_add_f32_e32 v3, v25, v3
	v_add_f32_e32 v12, v2, v3
	v_mov_b32_e32 v13, v12
	s_nop 1
	v_permlane16_swap_b32_e32 v13, v12
	v_cvt_pk_bf16_f32 v2, v8, v9
	v_cvt_pk_bf16_f32 v3, v10, v11
	global_store_dwordx4 v[26:27], v[0:3], off sc1
	s_waitcnt lgkmcnt(0)
	s_nop 0
	v_add_f32_e32 v0, v12, v13
	v_mov_b32_e32 v1, v0
	s_nop 1
	v_permlane32_swap_b32_e32 v1, v0
	v_cvt_pk_bf16_f32 v2, v4, v5
	v_cvt_pk_bf16_f32 v3, v6, v7
	v_cvt_pk_bf16_f32 v4, v20, v21
	v_cvt_pk_bf16_f32 v5, v18, v19
	global_store_dwordx4 v[26:27], v[2:5], off offset:256 sc1
	s_and_saveexec_b64 s[46:47], s[4:5]
	s_cbranch_execz .LBB0_1612
	s_waitcnt lgkmcnt(0)
	v_add_f32_e32 v0, v0, v1
	v_mul_f32_e32 v0, 0x4f800000, v0
	v_trunc_f32_e32 v0, v0
	v_mul_f32_e64 v1, |v0|, s62
	v_floor_f32_e32 v1, v1
	v_fma_f32 v2, v1, s63, |v0|
	v_cvt_u32_f32_e32 v0, v2
	v_cvt_u32_f32_e32 v1, v1
	v_lshl_add_u64 v[2:3], v[16:17], 3, s[12:13]
	global_atomic_add_x2 v[2:3], v[0:1], off

; __device__ __forceinline__ unsigned cvtpk(float lo, float hi) { f32x2v_ v = {lo, hi}; bf16x2v_ b = __builtin_convertvector(v, bf16x2v_); return __builtin_bit_cast(unsigned, b); }
;     __device__ __forceinline__ void operator()(const f32x4 (&acc)[2][2][4][2], const Unit& u, int wr, int wc, int fr, int fq) const {
;     ...
;             for (int m = 0; m < 4; ++m) { const int row = row0 + ai * HALF + m * 16; const float rs = ss ? row_rs(ss, row) : 1.0f;
; #pragma unroll
;                 for (int bj = 0; bj < 2; ++bj) { const f32x4 v0 = acc[ai][bj][m][0] * rs, v1 = acc[ai][bj][m][1] * rs;
;                     u32x4 w; w.x = cvtpk(v0[0], v0[1]); w.y = cvtpk(v0[2], v0[3]); w.z = cvtpk(v1[0], v1[1]); w.w = cvtpk(v1[2], v1[3]);
;                     *(u32x4*)(O + (size_t)row * ldc + col0 + bj * HALF) = w; } }
.LBB0_1684:
	v_lshl_add_u32 v156, s0, 8, v145
	v_ashrrev_i32_e32 v157, 31, v156
	v_lshl_add_u64 v[146:147], v[156:157], 3, s[12:13]
	global_load_dwordx2 v[148:149], v[146:147], off
	v_lshlrev_b64 v[162:163], 10, v[156:157]
	v_lshl_or_b32 v158, s1, 8, v151
	v_ashrrev_i32_e32 v159, 31, v158
	v_or_b32_e32 v160, 16, v156
	v_lshlrev_b64 v[158:159], 1, v[158:159]
	v_ashrrev_i32_e32 v161, 31, v160
	s_waitcnt vmcnt(0)
	v_ffbh_u32_e32 v157, v149
	v_min_u32_e32 v157, 32, v157
	v_lshlrev_b64 v[148:149], v157, v[148:149]
	v_min_u32_e32 v148, 1, v148
	v_or_b32_e32 v148, v149, v148
	v_cvt_f32_u32_e32 v148, v148
	v_sub_u32_e32 v149, 32, v157
	v_ldexp_f32 v148, v148, v149
	v_mul_f32_e32 v148, 0x2f800000, v148
	v_fmamk_f32 v148, v148, 0x3a800000, v155
	v_rsq_f32_e32 v164, v148
	v_lshl_add_u64 v[148:149], s[20:21], 0, v[162:163]
	v_lshl_add_u64 v[148:149], v[148:149], 0, v[158:159]
	v_lshl_add_u64 v[162:163], v[160:161], 3, s[12:13]
	v_pk_mul_f32 v[126:127], v[126:127], v[164:165] op_sel_hi:[1,0]
	v_pk_mul_f32 v[124:125], v[124:125], v[164:165] op_sel_hi:[1,0]
	v_pk_mul_f32 v[122:123], v[122:123], v[164:165] op_sel_hi:[1,0]
	v_pk_mul_f32 v[120:121], v[120:121], v[164:165] op_sel_hi:[1,0]
	v_pk_mul_f32 v[118:119], v[118:119], v[164:165] op_sel_hi:[1,0]
	v_pk_mul_f32 v[116:117], v[116:117], v[164:165] op_sel_hi:[1,0]
	v_pk_mul_f32 v[166:167], v[114:115], v[164:165] op_sel_hi:[1,0]
	v_pk_mul_f32 v[164:165], v[112:113], v[164:165] op_sel_hi:[1,0]
	v_cvt_pk_bf16_f32 v112, v124, v125
	v_cvt_pk_bf16_f32 v113, v126, v127
	v_cvt_pk_bf16_f32 v114, v120, v121
	v_cvt_pk_bf16_f32 v115, v122, v123
	v_cvt_pk_bf16_f32 v116, v116, v117
	v_cvt_pk_bf16_f32 v117, v118, v119
	v_cvt_pk_bf16_f32 v118, v164, v165
	v_cvt_pk_bf16_f32 v119, v166, v167
	global_store_dwordx4 v[148:149], v[112:115], off sc1
	global_store_dwordx4 v[148:149], v[116:119], off offset:256 sc1
	global_load_dwordx2 v[112:113], v[162:163], off
	v_or_b32_e32 v114, 32, v156
	s_waitcnt vmcnt(0)
	v_ffbh_u32_e32 v115, v113
	v_min_u32_e32 v116, 32, v115
	v_lshlrev_b64 v[112:113], v116, v[112:113]
	v_min_u32_e32 v112, 1, v112
	v_or_b32_e32 v112, v113, v112
	v_cvt_f32_u32_e32 v117, v112
	v_sub_u32_e32 v116, 32, v116
	v_lshlrev_b64 v[112:113], 10, v[160:161]
	v_lshl_add_u64 v[112:113], s[20:21], 0, v[112:113]
	v_ldexp_f32 v116, v117, v116
	v_mul_f32_e32 v116, 0x2f800000, v116
	v_fmamk_f32 v116, v116, 0x3a800000, v155
	v_rsq_f32_e32 v116, v116
	v_ashrrev_i32_e32 v115, 31, v114
	v_lshl_add_u64 v[112:113], v[112:113], 0, v[158:159]
	v_lshl_add_u64 v[118:119], v[114:115], 3, s[12:13]
	v_pk_mul_f32 v[110:111], v[110:111], v[116:117] op_sel_hi:[1,0]
	v_pk_mul_f32 v[108:109], v[108:109], v[116:117] op_sel_hi:[1,0]
	v_pk_mul_f32 v[106:107], v[106:107], v[116:117] op_sel_hi:[1,0]
	v_pk_mul_f32 v[104:105], v[104:105], v[116:117] op_sel_hi:[1,0]
	v_pk_mul_f32 v[102:103], v[102:103], v[116:117] op_sel_hi:[1,0]
	v_pk_mul_f32 v[100:101], v[100:101], v[116:117] op_sel_hi:[1,0]
	v_pk_mul_f32 v[120:121], v[98:99], v[116:117] op_sel_hi:[1,0]
	v_pk_mul_f32 v[116:117], v[96:97], v[116:117] op_sel_hi:[1,0]
	v_cvt_pk_bf16_f32 v96, v108, v109
	v_cvt_pk_bf16_f32 v97, v110, v111
	v_cvt_pk_bf16_f32 v98, v104, v105
	v_cvt_pk_bf16_f32 v99, v106, v107
	v_cvt_pk_bf16_f32 v100, v100, v101
	v_cvt_pk_bf16_f32 v101, v102, v103
	v_cvt_pk_bf16_f32 v102, v116, v117
	v_cvt_pk_bf16_f32 v103, v120, v121
	global_store_dwordx4 v[112:113], v[96:99], off sc1
	global_store_dwordx4 v[112:113], v[100:103], off offset:256 sc1
	global_load_dwordx2 v[96:97], v[118:119], off
	v_or_b32_e32 v98, 48, v156
	s_waitcnt vmcnt(0)
	v_ffbh_u32_e32 v99, v97
	v_min_u32_e32 v100, 32, v99
	v_lshlrev_b64 v[96:97], v100, v[96:97]
	v_min_u32_e32 v96, 1, v96
	v_or_b32_e32 v96, v97, v96
	v_cvt_f32_u32_e32 v101, v96
	v_sub_u32_e32 v100, 32, v100
	v_lshlrev_b64 v[96:97], 10, v[114:115]
	v_lshl_add_u64 v[96:97], s[20:21], 0, v[96:97]
	v_ldexp_f32 v100, v101, v100
	v_mul_f32_e32 v100, 0x2f800000, v100
	v_fmamk_f32 v100, v100, 0x3a800000, v155
	v_rsq_f32_e32 v100, v100
	v_ashrrev_i32_e32 v99, 31, v98
	v_lshl_add_u64 v[96:97], v[96:97], 0, v[158:159]
	v_lshl_add_u64 v[102:103], v[98:99], 3, s[12:13]
	v_pk_mul_f32 v[94:95], v[94:95], v[100:101] op_sel_hi:[1,0]
	v_pk_mul_f32 v[92:93], v[92:93], v[100:101] op_sel_hi:[1,0]
	v_pk_mul_f32 v[90:91], v[90:91], v[100:101] op_sel_hi:[1,0]
	v_pk_mul_f32 v[88:89], v[88:89], v[100:101] op_sel_hi:[1,0]
	v_pk_mul_f32 v[86:87], v[86:87], v[100:101] op_sel_hi:[1,0]
	v_pk_mul_f32 v[84:85], v[84:85], v[100:101] op_sel_hi:[1,0]
	v_pk_mul_f32 v[104:105], v[82:83], v[100:101] op_sel_hi:[1,0]
	v_pk_mul_f32 v[100:101], v[80:81], v[100:101] op_sel_hi:[1,0]
	v_cvt_pk_bf16_f32 v80, v92, v93
	v_cvt_pk_bf16_f32 v81, v94, v95
	v_cvt_pk_bf16_f32 v82, v88, v89
	v_cvt_pk_bf16_f32 v83, v90, v91
	v_cvt_pk_bf16_f32 v84, v84, v85
	v_cvt_pk_bf16_f32 v85, v86, v87
	v_cvt_pk_bf16_f32 v86, v100, v101
	v_cvt_pk_bf16_f32 v87, v104, v105
	global_store_dwordx4 v[96:97], v[80:83], off sc1
	global_store_dwordx4 v[96:97], v[84:87], off offset:256 sc1
	global_load_dwordx2 v[80:81], v[102:103], off
	s_waitcnt vmcnt(0)
; __device__ __forceinline__ unsigned cvtpk(float lo, float hi) { f32x2v_ v = {lo, hi}; bf16x2v_ b = __builtin_convertvector(v, bf16x2v_); return __builtin_bit_cast(unsigned, b); }
;     __device__ __forceinline__ void operator()(const f32x4 (&acc)[2][2][4][2], const Unit& u, int wr, int wc, int fr, int fq) const {
;     ...
;             for (int m = 0; m < 4; ++m) { const int row = row0 + ai * HALF + m * 16; const float rs = ss ? row_rs(ss, row) : 1.0f;
; #pragma unroll
;                 for (int bj = 0; bj < 2; ++bj) { const f32x4 v0 = acc[ai][bj][m][0] * rs, v1 = acc[ai][bj][m][1] * rs;
;                     u32x4 w; w.x = cvtpk(v0[0], v0[1]); w.y = cvtpk(v0[2], v0[3]); w.z = cvtpk(v1[0], v1[1]); w.w = cvtpk(v1[2], v1[3]);
;                     *(u32x4*)(O + (size_t)row * ldc + col0 + bj * HALF) = w; } }
	v_ffbh_u32_e32 v82, v81
	v_min_u32_e32 v82, 32, v82
	v_lshlrev_b64 v[80:81], v82, v[80:81]
	v_min_u32_e32 v80, 1, v80
	v_or_b32_e32 v80, v81, v80
	v_cvt_f32_u32_e32 v80, v80
	v_sub_u32_e32 v81, 32, v82
	v_lshlrev_b64 v[82:83], 10, v[98:99]
	v_lshl_add_u64 v[82:83], s[20:21], 0, v[82:83]
	v_ldexp_f32 v80, v80, v81
	v_mul_f32_e32 v80, 0x2f800000, v80
	v_fmamk_f32 v80, v80, 0x3a800000, v155
	v_rsq_f32_e32 v80, v80
	v_lshl_add_u64 v[82:83], v[82:83], 0, v[158:159]
	v_pk_mul_f32 v[78:79], v[78:79], v[80:81] op_sel_hi:[1,0]
	v_pk_mul_f32 v[76:77], v[76:77], v[80:81] op_sel_hi:[1,0]
	v_pk_mul_f32 v[74:75], v[74:75], v[80:81] op_sel_hi:[1,0]
	v_pk_mul_f32 v[72:73], v[72:73], v[80:81] op_sel_hi:[1,0]
	v_pk_mul_f32 v[70:71], v[70:71], v[80:81] op_sel_hi:[1,0]
	v_pk_mul_f32 v[68:69], v[68:69], v[80:81] op_sel_hi:[1,0]
	v_pk_mul_f32 v[84:85], v[66:67], v[80:81] op_sel_hi:[1,0]
	v_pk_mul_f32 v[80:81], v[64:65], v[80:81] op_sel_hi:[1,0]
	v_cvt_pk_bf16_f32 v64, v76, v77
	v_cvt_pk_bf16_f32 v65, v78, v79
	v_cvt_pk_bf16_f32 v66, v72, v73
	v_cvt_pk_bf16_f32 v67, v74, v75
	v_cvt_pk_bf16_f32 v68, v68, v69
	v_cvt_pk_bf16_f32 v69, v70, v71
	v_cvt_pk_bf16_f32 v70, v80, v81
	v_cvt_pk_bf16_f32 v71, v84, v85
	global_store_dwordx4 v[82:83], v[64:67], off sc1
	global_store_dwordx4 v[82:83], v[68:71], off offset:256 sc1
	global_load_dwordx2 v[64:65], v[146:147], off offset:1024
	s_waitcnt vmcnt(0)
	v_ffbh_u32_e32 v66, v65
	v_min_u32_e32 v66, 32, v66
	v_lshlrev_b64 v[64:65], v66, v[64:65]
	v_min_u32_e32 v64, 1, v64
	v_or_b32_e32 v64, v65, v64
	v_cvt_f32_u32_e32 v67, v64
	v_sub_u32_e32 v66, 32, v66
	v_add_co_u32_e32 v68, vcc, s67, v148
	v_ldexp_f32 v66, v67, v66
	v_mul_f32_e32 v66, 0x2f800000, v66
	v_fmamk_f32 v66, v66, 0x3a800000, v155
	v_rsq_f32_e32 v66, v66
	v_addc_co_u32_e32 v69, vcc, 0, v149, vcc
	v_lshl_add_u64 v[64:65], v[148:149], 0, s[36:37]
	v_pk_mul_f32 v[62:63], v[62:63], v[66:67] op_sel_hi:[1,0]
	v_pk_mul_f32 v[60:61], v[60:61], v[66:67] op_sel_hi:[1,0]
	v_pk_mul_f32 v[58:59], v[58:59], v[66:67] op_sel_hi:[1,0]
	v_pk_mul_f32 v[56:57], v[56:57], v[66:67] op_sel_hi:[1,0]
	v_pk_mul_f32 v[54:55], v[54:55], v[66:67] op_sel_hi:[1,0]
	v_pk_mul_f32 v[52:53], v[52:53], v[66:67] op_sel_hi:[1,0]
	v_pk_mul_f32 v[70:71], v[50:51], v[66:67] op_sel_hi:[1,0]
	v_pk_mul_f32 v[66:67], v[48:49], v[66:67] op_sel_hi:[1,0]
	v_cvt_pk_bf16_f32 v48, v60, v61
	v_cvt_pk_bf16_f32 v49, v62, v63
	v_cvt_pk_bf16_f32 v50, v56, v57
	v_cvt_pk_bf16_f32 v51, v58, v59
	v_cvt_pk_bf16_f32 v52, v52, v53
	v_cvt_pk_bf16_f32 v53, v54, v55
	v_cvt_pk_bf16_f32 v54, v66, v67
	v_cvt_pk_bf16_f32 v55, v70, v71
	global_store_dwordx4 v[68:69], v[48:51], off sc1
	global_store_dwordx4 v[64:65], v[52:55], off offset:256 sc1
	global_load_dwordx2 v[48:49], v[146:147], off offset:1152
	s_waitcnt vmcnt(0)
	v_ffbh_u32_e32 v50, v49
	v_min_u32_e32 v50, 32, v50
	v_lshlrev_b64 v[48:49], v50, v[48:49]
	v_min_u32_e32 v48, 1, v48
	v_or_b32_e32 v48, v49, v48
	v_cvt_f32_u32_e32 v51, v48
	v_sub_u32_e32 v50, 32, v50
	v_add_co_u32_e32 v52, vcc, s74, v148
	v_ldexp_f32 v50, v51, v50
	v_mul_f32_e32 v50, 0x2f800000, v50
	v_fmamk_f32 v50, v50, 0x3a800000, v155
	v_rsq_f32_e32 v50, v50
	v_addc_co_u32_e32 v53, vcc, 0, v149, vcc
	v_lshl_add_u64 v[48:49], v[148:149], 0, s[38:39]
	v_pk_mul_f32 v[46:47], v[46:47], v[50:51] op_sel_hi:[1,0]
	v_pk_mul_f32 v[44:45], v[44:45], v[50:51] op_sel_hi:[1,0]
	v_pk_mul_f32 v[42:43], v[42:43], v[50:51] op_sel_hi:[1,0]
	v_pk_mul_f32 v[40:41], v[40:41], v[50:51] op_sel_hi:[1,0]
	v_pk_mul_f32 v[38:39], v[38:39], v[50:51] op_sel_hi:[1,0]
	v_pk_mul_f32 v[36:37], v[36:37], v[50:51] op_sel_hi:[1,0]
	v_pk_mul_f32 v[54:55], v[34:35], v[50:51] op_sel_hi:[1,0]
	v_pk_mul_f32 v[50:51], v[32:33], v[50:51] op_sel_hi:[1,0]
	v_cvt_pk_bf16_f32 v32, v44, v45
	v_cvt_pk_bf16_f32 v33, v46, v47
	v_cvt_pk_bf16_f32 v34, v40, v41
	v_cvt_pk_bf16_f32 v35, v42, v43
	v_cvt_pk_bf16_f32 v36, v36, v37
	v_cvt_pk_bf16_f32 v37, v38, v39
	v_cvt_pk_bf16_f32 v38, v50, v51
	v_cvt_pk_bf16_f32 v39, v54, v55
	global_store_dwordx4 v[52:53], v[32:35], off sc1
	global_store_dwordx4 v[48:49], v[36:39], off offset:256 sc1
	global_load_dwordx2 v[32:33], v[146:147], off offset:1280
	s_waitcnt vmcnt(0)
	v_ffbh_u32_e32 v34, v33
	v_min_u32_e32 v34, 32, v34
	v_lshlrev_b64 v[32:33], v34, v[32:33]
	v_min_u32_e32 v32, 1, v32
	v_or_b32_e32 v32, v33, v32
	v_cvt_f32_u32_e32 v35, v32
	v_sub_u32_e32 v34, 32, v34
	v_add_co_u32_e32 v36, vcc, s75, v148
	v_ldexp_f32 v34, v35, v34
	v_mul_f32_e32 v34, 0x2f800000, v34
	v_fmamk_f32 v34, v34, 0x3a800000, v155
	v_rsq_f32_e32 v34, v34
	v_addc_co_u32_e32 v37, vcc, 0, v149, vcc
	v_lshl_add_u64 v[32:33], v[148:149], 0, s[40:41]
	v_pk_mul_f32 v[30:31], v[30:31], v[34:35] op_sel_hi:[1,0]
	v_pk_mul_f32 v[28:29], v[28:29], v[34:35] op_sel_hi:[1,0]
	v_pk_mul_f32 v[26:27], v[26:27], v[34:35] op_sel_hi:[1,0]
	v_pk_mul_f32 v[24:25], v[24:25], v[34:35] op_sel_hi:[1,0]
	v_pk_mul_f32 v[22:23], v[22:23], v[34:35] op_sel_hi:[1,0]
	v_pk_mul_f32 v[20:21], v[20:21], v[34:35] op_sel_hi:[1,0]
	v_pk_mul_f32 v[38:39], v[18:19], v[34:35] op_sel_hi:[1,0]
	v_pk_mul_f32 v[34:35], v[16:17], v[34:35] op_sel_hi:[1,0]
	v_cvt_pk_bf16_f32 v16, v28, v29
	v_cvt_pk_bf16_f32 v17, v30, v31
	v_cvt_pk_bf16_f32 v18, v24, v25
	v_cvt_pk_bf16_f32 v19, v26, v27
	v_cvt_pk_bf16_f32 v20, v20, v21
	v_cvt_pk_bf16_f32 v21, v22, v23
	v_cvt_pk_bf16_f32 v22, v34, v35
	v_cvt_pk_bf16_f32 v23, v38, v39
	global_store_dwordx4 v[36:37], v[16:19], off sc1
	global_store_dwordx4 v[32:33], v[20:23], off offset:256 sc1
	global_load_dwordx2 v[16:17], v[146:147], off offset:1408
	s_andn2_b64 vcc, exec, s[4:5]
	v_add_co_u32_e64 v20, s[0:1], s76, v148
	s_waitcnt vmcnt(0)
	v_ffbh_u32_e32 v18, v17
	v_min_u32_e32 v18, 32, v18
	v_lshlrev_b64 v[16:17], v18, v[16:17]
	v_min_u32_e32 v16, 1, v16
	v_or_b32_e32 v16, v17, v16
	v_cvt_f32_u32_e32 v19, v16
	v_sub_u32_e32 v18, 32, v18
	v_addc_co_u32_e64 v21, s[0:1], 0, v149, s[0:1]
	v_ldexp_f32 v18, v19, v18
	v_mul_f32_e32 v18, 0x2f800000, v18
	v_fmamk_f32 v18, v18, 0x3a800000, v155
	v_rsq_f32_e32 v18, v18
	s_mov_b64 s[0:1], -1
	v_lshl_add_u64 v[16:17], v[148:149], 0, s[42:43]
	v_pk_mul_f32 v[14:15], v[14:15], v[18:19] op_sel_hi:[1,0]
	v_pk_mul_f32 v[12:13], v[12:13], v[18:19] op_sel_hi:[1,0]
	v_pk_mul_f32 v[10:11], v[10:11], v[18:19] op_sel_hi:[1,0]
	v_pk_mul_f32 v[8:9], v[8:9], v[18:19] op_sel_hi:[1,0]
	v_pk_mul_f32 v[6:7], v[6:7], v[18:19] op_sel_hi:[1,0]
	v_pk_mul_f32 v[4:5], v[4:5], v[18:19] op_sel_hi:[1,0]
	v_pk_mul_f32 v[22:23], v[2:3], v[18:19] op_sel_hi:[1,0]
	v_pk_mul_f32 v[18:19], v[0:1], v[18:19] op_sel_hi:[1,0]
	v_cvt_pk_bf16_f32 v0, v12, v13
	v_cvt_pk_bf16_f32 v1, v14, v15
	v_cvt_pk_bf16_f32 v2, v8, v9
	v_cvt_pk_bf16_f32 v3, v10, v11
	v_cvt_pk_bf16_f32 v4, v4, v5
	v_cvt_pk_bf16_f32 v5, v6, v7
	v_cvt_pk_bf16_f32 v6, v18, v19
	v_cvt_pk_bf16_f32 v7, v22, v23
	global_store_dwordx4 v[20:21], v[0:3], off sc1
	global_store_dwordx4 v[16:17], v[4:7], off offset:256 sc1
	s_cbranch_vccnz .LBB0_1673
	s_andn2_b64 vcc, exec, s[10:11]
	s_cbranch_vccnz .LBB0_1672
	s_barrier
	s_branch .LBB0_1672

; __device__ __forceinline__ void fx_add(float* p, size_t idx, float s) { atomicAdd((unsigned long long*)p + idx, (unsigned long long)(long long)(s * 4294967296.0f)); }
; __device__ __forceinline__ unsigned cvtpk(float lo, float hi) { f32x2v_ v = {lo, hi}; bf16x2v_ b = __builtin_convertvector(v, bf16x2v_); return __builtin_bit_cast(unsigned, b); }
;     __device__ __forceinline__ void operator()(const f32x4 (&acc)[2][2][4][2], const Unit& u, int wr, int wc, int fr, int fq) const {
;     ...
;             for (int m = 0; m < 4; ++m) { const int row = row0 + ai * HALF + m * 16; const size_t off = (size_t)row * 1024 + col0; float s = 0.f;
; #pragma unroll
;                 for (int bj = 0; bj < 2; ++bj) { f32x4 a0, a1;
;                     if (xin32) { const float* p = xin32 + off + bj * HALF; a0 = *(const f32x4*)p; a1 = *(const f32x4*)(p + 4); }
;                     else { const u32x4 w = *(const u32x4*)(xb + off + bj * HALF);
;                         a0 = (f32x4){__uint_as_float(w.x << 16), __uint_as_float(w.x & 0xffff0000u), __uint_as_float(w.y << 16), __uint_as_float(w.y & 0xffff0000u)};
;                         a1 = (f32x4){__uint_as_float(w.z << 16), __uint_as_float(w.z & 0xffff0000u), __uint_as_float(w.w << 16), __uint_as_float(w.w & 0xffff0000u)}; }
;                     const f32x4 v0 = a0 + acc[ai][bj][m][0] * alpha, v1 = a1 + acc[ai][bj][m][1] * alpha;
;                     u32x4 w; w.x = cvtpk(v0[0], v0[1]); w.y = cvtpk(v0[2], v0[3]); w.z = cvtpk(v1[0], v1[1]); w.w = cvtpk(v1[2], v1[3]);
;                     *(u32x4*)(xb + off + bj * HALF) = w;
;                     s += (v0[0] * v0[0] + v0[1] * v0[1]) + (v0[2] * v0[2] + v0[3] * v0[3]) + (v1[0] * v1[0] + v1[1] * v1[1]) + (v1[2] * v1[2] + v1[3] * v1[3]); }
;                 s += __shfl_xor(s, 16); s += __shfl_xor(s, 32);
;                 if (fq == 0) fx_add(ssout, row, s); }
.LBB0_1819:
	v_lshl_add_u32 v146, s42, 8, v148
	v_ashrrev_i32_e32 v147, 31, v146
	v_lshl_or_b32 v144, s40, 8, v150
	v_lshlrev_b64 v[156:157], 11, v[146:147]
	v_ashrrev_i32_e32 v145, 31, v144
	v_lshl_add_u64 v[156:157], s[22:23], 0, v[156:157]
	v_lshl_add_u64 v[166:167], v[144:145], 1, v[156:157]
	global_load_dwordx4 v[158:161], v[166:167], off
	global_load_dwordx4 v[162:165], v[166:167], off offset:256
	v_and_b32_e32 v156, 64, v154
	v_xor_b32_e32 v155, 16, v154
	v_add_u32_e32 v156, 64, v156
	v_xor_b32_e32 v157, 32, v154
	v_cmp_lt_i32_e32 vcc, v155, v156
	s_waitcnt vmcnt(0)
	v_lshlrev_b32_e32 v168, 16, v158
	v_cndmask_b32_e32 v155, v154, v155, vcc
	v_cmp_lt_i32_e32 vcc, v157, v156
	v_and_b32_e32 v169, 0xffff0000, v158
	v_lshlrev_b32_e32 v158, 16, v159
	v_and_b32_e32 v159, 0xffff0000, v159
	v_lshlrev_b32_e32 v172, 16, v162
	v_and_b32_e32 v173, 0xffff0000, v162
	v_lshlrev_b32_e32 v162, 16, v163
	v_and_b32_e32 v163, 0xffff0000, v163
	v_cndmask_b32_e32 v157, v154, v157, vcc
	v_lshlrev_b32_e32 v170, 16, v160
	v_and_b32_e32 v171, 0xffff0000, v160
	v_lshlrev_b32_e32 v160, 16, v161
	v_and_b32_e32 v161, 0xffff0000, v161
	v_lshlrev_b32_e32 v174, 16, v164
	v_and_b32_e32 v175, 0xffff0000, v164
	v_lshlrev_b32_e32 v164, 16, v165
	v_and_b32_e32 v165, 0xffff0000, v165
	v_pk_add_f32 v[126:127], v[126:127], v[158:159]
	v_pk_add_f32 v[124:125], v[124:125], v[168:169]
	v_pk_add_f32 v[118:119], v[118:119], v[162:163]
	v_pk_add_f32 v[116:117], v[116:117], v[172:173]
	v_lshlrev_b32_e32 v156, 2, v155
	v_lshlrev_b32_e32 v155, 2, v157
	v_pk_add_f32 v[122:123], v[122:123], v[160:161]
	v_pk_add_f32 v[120:121], v[120:121], v[170:171]
	v_pk_add_f32 v[158:159], v[114:115], v[164:165]
	v_pk_add_f32 v[160:161], v[112:113], v[174:175]
	v_mul_f32_e32 v114, v125, v125
	v_mul_f32_e32 v115, v127, v127
	v_mul_f32_e32 v157, v117, v117
	v_mul_f32_e32 v162, v119, v119
	v_cvt_pk_bf16_f32 v112, v124, v125
	v_mul_f32_e32 v125, v121, v121
	v_mul_f32_e32 v163, v161, v161
	v_fmac_f32_e32 v114, v124, v124
	v_fmac_f32_e32 v115, v126, v126
	v_fmac_f32_e32 v157, v116, v116
	v_fmac_f32_e32 v162, v118, v118
	v_cvt_pk_bf16_f32 v113, v126, v127
	v_mul_f32_e32 v127, v123, v123
	v_mul_f32_e32 v164, v159, v159
	v_fmac_f32_e32 v125, v120, v120
	v_fmac_f32_e32 v163, v160, v160
	v_add_f32_e32 v114, v114, v115
	v_add_f32_e32 v115, v157, v162
	v_fmac_f32_e32 v127, v122, v122
	v_fmac_f32_e32 v164, v158, v158
	v_add_f32_e32 v114, v125, v114
	v_add_f32_e32 v115, v163, v115
	v_add_f32_e32 v114, v127, v114
	v_add_f32_e32 v115, v164, v115
	v_add_f32_e32 v124, v114, v115
	v_mov_b32_e32 v125, v124
	s_nop 1
	v_permlane16_swap_b32_e32 v125, v124
	v_cvt_pk_bf16_f32 v114, v120, v121
	v_cvt_pk_bf16_f32 v115, v122, v123
	global_store_dwordx4 v[166:167], v[112:115], off sc1
	s_waitcnt lgkmcnt(0)
	s_nop 0
	v_add_f32_e32 v112, v124, v125
	v_mov_b32_e32 v113, v112
	s_nop 1
	v_permlane32_swap_b32_e32 v113, v112
	v_cvt_pk_bf16_f32 v114, v116, v117
	v_cvt_pk_bf16_f32 v115, v118, v119
	v_cvt_pk_bf16_f32 v116, v160, v161
	v_cvt_pk_bf16_f32 v117, v158, v159
	global_store_dwordx4 v[166:167], v[114:117], off offset:256 sc1
	s_and_saveexec_b64 s[40:41], s[4:5]
	s_cbranch_execz .LBB0_1821
	s_waitcnt lgkmcnt(0)
	v_add_f32_e32 v112, v112, v113
	v_mul_f32_e32 v112, 0x4f800000, v112
	v_trunc_f32_e32 v112, v112
	v_mul_f32_e64 v113, |v112|, s56
	v_floor_f32_e32 v113, v113
	v_fma_f32 v114, v113, s57, |v112|
	v_cvt_u32_f32_e32 v112, v114
	v_cvt_u32_f32_e32 v113, v113
	v_lshl_add_u64 v[114:115], v[146:147], 3, s[0:1]
	global_atomic_add_x2 v[114:115], v[112:113], off
.LBB0_1821:
	s_or_b64 exec, exec, s[40:41]
	v_or_b32_e32 v112, 16, v146
	s_waitcnt lgkmcnt(0)
	v_ashrrev_i32_e32 v113, 31, v112
	v_lshlrev_b64 v[114:115], 11, v[112:113]
	v_lshl_add_u64 v[114:115], s[22:23], 0, v[114:115]
	v_lshl_add_u64 v[122:123], v[144:145], 1, v[114:115]
	global_load_dwordx4 v[114:117], v[122:123], off
	global_load_dwordx4 v[118:121], v[122:123], off offset:256
	s_waitcnt vmcnt(1)
	v_lshlrev_b32_e32 v124, 16, v114
	v_and_b32_e32 v125, 0xffff0000, v114
	v_lshlrev_b32_e32 v114, 16, v115
	v_and_b32_e32 v115, 0xffff0000, v115
	s_waitcnt vmcnt(0)
	v_lshlrev_b32_e32 v158, 16, v118
	v_and_b32_e32 v159, 0xffff0000, v118
	v_lshlrev_b32_e32 v118, 16, v119
	v_and_b32_e32 v119, 0xffff0000, v119
	v_lshlrev_b32_e32 v126, 16, v116
	v_and_b32_e32 v127, 0xffff0000, v116
	v_lshlrev_b32_e32 v116, 16, v117
	v_and_b32_e32 v117, 0xffff0000, v117
	v_lshlrev_b32_e32 v160, 16, v120
	v_and_b32_e32 v161, 0xffff0000, v120
	v_lshlrev_b32_e32 v120, 16, v121
	v_and_b32_e32 v121, 0xffff0000, v121
	v_pk_add_f32 v[110:111], v[110:111], v[114:115]
	v_pk_add_f32 v[108:109], v[108:109], v[124:125]
	v_pk_add_f32 v[102:103], v[102:103], v[118:119]
	v_pk_add_f32 v[100:101], v[100:101], v[158:159]
	v_pk_add_f32 v[106:107], v[106:107], v[116:117]
	v_pk_add_f32 v[104:105], v[104:105], v[126:127]
	v_pk_add_f32 v[114:115], v[98:99], v[120:121]
	v_pk_add_f32 v[116:117], v[96:97], v[160:161]
	v_mul_f32_e32 v98, v109, v109
	v_mul_f32_e32 v99, v111, v111
	v_mul_f32_e32 v118, v101, v101
	v_mul_f32_e32 v119, v103, v103
	v_cvt_pk_bf16_f32 v96, v108, v109
	v_mul_f32_e32 v109, v105, v105
	v_mul_f32_e32 v120, v117, v117
	v_fmac_f32_e32 v98, v108, v108
	v_fmac_f32_e32 v99, v110, v110
	v_fmac_f32_e32 v118, v100, v100
	v_fmac_f32_e32 v119, v102, v102
	v_cvt_pk_bf16_f32 v97, v110, v111
	v_mul_f32_e32 v111, v107, v107
	v_mul_f32_e32 v121, v115, v115
	v_fmac_f32_e32 v109, v104, v104
	v_fmac_f32_e32 v120, v116, v116
	v_add_f32_e32 v98, v98, v99
	v_add_f32_e32 v99, v118, v119
	v_fmac_f32_e32 v111, v106, v106
	v_fmac_f32_e32 v121, v114, v114
	v_add_f32_e32 v98, v109, v98
	v_add_f32_e32 v99, v120, v99
	v_add_f32_e32 v98, v111, v98
	v_add_f32_e32 v99, v121, v99
	v_add_f32_e32 v108, v98, v99
	v_mov_b32_e32 v109, v108
	s_nop 1
	v_permlane16_swap_b32_e32 v109, v108
	v_cvt_pk_bf16_f32 v98, v104, v105
	v_cvt_pk_bf16_f32 v99, v106, v107
	global_store_dwordx4 v[122:123], v[96:99], off sc1
	s_waitcnt lgkmcnt(0)
	s_nop 0
	v_add_f32_e32 v96, v108, v109
	v_mov_b32_e32 v97, v96
	s_nop 1
	v_permlane32_swap_b32_e32 v97, v96
	v_cvt_pk_bf16_f32 v98, v100, v101
	v_cvt_pk_bf16_f32 v99, v102, v103
	v_cvt_pk_bf16_f32 v100, v116, v117
	v_cvt_pk_bf16_f32 v101, v114, v115
	global_store_dwordx4 v[122:123], v[98:101], off offset:256 sc1
	s_and_saveexec_b64 s[40:41], s[4:5]
	s_cbranch_execz .LBB0_1823
	s_waitcnt lgkmcnt(0)
	v_add_f32_e32 v96, v96, v97
	v_mul_f32_e32 v96, 0x4f800000, v96
	v_trunc_f32_e32 v96, v96
	v_mul_f32_e64 v97, |v96|, s56
	v_floor_f32_e32 v97, v97
	v_fma_f32 v98, v97, s57, |v96|
	v_cvt_u32_f32_e32 v96, v98
	v_cvt_u32_f32_e32 v97, v97
	v_lshl_add_u64 v[98:99], v[112:113], 3, s[0:1]
	global_atomic_add_x2 v[98:99], v[96:97], off
; __device__ __forceinline__ void fx_add(float* p, size_t idx, float s) { atomicAdd((unsigned long long*)p + idx, (unsigned long long)(long long)(s * 4294967296.0f)); }
; __device__ __forceinline__ unsigned cvtpk(float lo, float hi) { f32x2v_ v = {lo, hi}; bf16x2v_ b = __builtin_convertvector(v, bf16x2v_); return __builtin_bit_cast(unsigned, b); }
;     __device__ __forceinline__ void operator()(const f32x4 (&acc)[2][2][4][2], const Unit& u, int wr, int wc, int fr, int fq) const {
;     ...
;             for (int m = 0; m < 4; ++m) { const int row = row0 + ai * HALF + m * 16; const size_t off = (size_t)row * 1024 + col0; float s = 0.f;
; #pragma unroll
;                 for (int bj = 0; bj < 2; ++bj) { f32x4 a0, a1;
;                     if (xin32) { const float* p = xin32 + off + bj * HALF; a0 = *(const f32x4*)p; a1 = *(const f32x4*)(p + 4); }
;                     else { const u32x4 w = *(const u32x4*)(xb + off + bj * HALF);
;                         a0 = (f32x4){__uint_as_float(w.x << 16), __uint_as_float(w.x & 0xffff0000u), __uint_as_float(w.y << 16), __uint_as_float(w.y & 0xffff0000u)};
;                         a1 = (f32x4){__uint_as_float(w.z << 16), __uint_as_float(w.z & 0xffff0000u), __uint_as_float(w.w << 16), __uint_as_float(w.w & 0xffff0000u)}; }
;                     const f32x4 v0 = a0 + acc[ai][bj][m][0] * alpha, v1 = a1 + acc[ai][bj][m][1] * alpha;
;                     u32x4 w; w.x = cvtpk(v0[0], v0[1]); w.y = cvtpk(v0[2], v0[3]); w.z = cvtpk(v1[0], v1[1]); w.w = cvtpk(v1[2], v1[3]);
;                     *(u32x4*)(xb + off + bj * HALF) = w;
;                     s += (v0[0] * v0[0] + v0[1] * v0[1]) + (v0[2] * v0[2] + v0[3] * v0[3]) + (v1[0] * v1[0] + v1[1] * v1[1]) + (v1[2] * v1[2] + v1[3] * v1[3]); }
;                 s += __shfl_xor(s, 16); s += __shfl_xor(s, 32);
;                 if (fq == 0) fx_add(ssout, row, s); }
.LBB0_1823:
	s_or_b64 exec, exec, s[40:41]
	v_or_b32_e32 v96, 32, v146
	s_waitcnt lgkmcnt(0)
	v_ashrrev_i32_e32 v97, 31, v96
	v_lshlrev_b64 v[98:99], 11, v[96:97]
	v_lshl_add_u64 v[98:99], s[22:23], 0, v[98:99]
	v_lshl_add_u64 v[106:107], v[144:145], 1, v[98:99]
	global_load_dwordx4 v[98:101], v[106:107], off
	global_load_dwordx4 v[102:105], v[106:107], off offset:256
	s_waitcnt vmcnt(1)
	v_lshlrev_b32_e32 v108, 16, v98
	v_and_b32_e32 v109, 0xffff0000, v98
	v_lshlrev_b32_e32 v98, 16, v99
	v_and_b32_e32 v99, 0xffff0000, v99
	s_waitcnt vmcnt(0)
	v_lshlrev_b32_e32 v112, 16, v102
	v_and_b32_e32 v113, 0xffff0000, v102
	v_lshlrev_b32_e32 v102, 16, v103
	v_and_b32_e32 v103, 0xffff0000, v103
	v_lshlrev_b32_e32 v110, 16, v100
	v_and_b32_e32 v111, 0xffff0000, v100
	v_lshlrev_b32_e32 v100, 16, v101
	v_and_b32_e32 v101, 0xffff0000, v101
	v_lshlrev_b32_e32 v114, 16, v104
	v_and_b32_e32 v115, 0xffff0000, v104
	v_lshlrev_b32_e32 v104, 16, v105
	v_and_b32_e32 v105, 0xffff0000, v105
	v_pk_add_f32 v[94:95], v[94:95], v[98:99]
	v_pk_add_f32 v[92:93], v[92:93], v[108:109]
	v_pk_add_f32 v[86:87], v[86:87], v[102:103]
	v_pk_add_f32 v[84:85], v[84:85], v[112:113]
	v_pk_add_f32 v[90:91], v[90:91], v[100:101]
	v_pk_add_f32 v[88:89], v[88:89], v[110:111]
	v_pk_add_f32 v[98:99], v[82:83], v[104:105]
	v_pk_add_f32 v[100:101], v[80:81], v[114:115]
	v_mul_f32_e32 v82, v93, v93
	v_mul_f32_e32 v83, v95, v95
	v_mul_f32_e32 v102, v85, v85
	v_mul_f32_e32 v103, v87, v87
	v_cvt_pk_bf16_f32 v80, v92, v93
	v_mul_f32_e32 v93, v89, v89
	v_mul_f32_e32 v104, v101, v101
	v_fmac_f32_e32 v82, v92, v92
	v_fmac_f32_e32 v83, v94, v94
	v_fmac_f32_e32 v102, v84, v84
	v_fmac_f32_e32 v103, v86, v86
	v_cvt_pk_bf16_f32 v81, v94, v95
	v_mul_f32_e32 v95, v91, v91
	v_mul_f32_e32 v105, v99, v99
	v_fmac_f32_e32 v93, v88, v88
	v_fmac_f32_e32 v104, v100, v100
	v_add_f32_e32 v82, v82, v83
	v_add_f32_e32 v83, v102, v103
	v_fmac_f32_e32 v95, v90, v90
	v_fmac_f32_e32 v105, v98, v98
	v_add_f32_e32 v82, v93, v82
	v_add_f32_e32 v83, v104, v83
	v_add_f32_e32 v82, v95, v82
	v_add_f32_e32 v83, v105, v83
	v_add_f32_e32 v92, v82, v83
	v_mov_b32_e32 v93, v92
	s_nop 1
	v_permlane16_swap_b32_e32 v93, v92
	v_cvt_pk_bf16_f32 v82, v88, v89
	v_cvt_pk_bf16_f32 v83, v90, v91
	global_store_dwordx4 v[106:107], v[80:83], off sc1
	s_waitcnt lgkmcnt(0)
	s_nop 0
	v_add_f32_e32 v80, v92, v93
	v_mov_b32_e32 v81, v80
	s_nop 1
	v_permlane32_swap_b32_e32 v81, v80
	v_cvt_pk_bf16_f32 v82, v84, v85
	v_cvt_pk_bf16_f32 v83, v86, v87
	v_cvt_pk_bf16_f32 v84, v100, v101
	v_cvt_pk_bf16_f32 v85, v98, v99
	global_store_dwordx4 v[106:107], v[82:85], off offset:256 sc1
	s_and_saveexec_b64 s[40:41], s[4:5]
	s_cbranch_execz .LBB0_1825
	s_waitcnt lgkmcnt(0)
	v_add_f32_e32 v80, v80, v81
	v_mul_f32_e32 v80, 0x4f800000, v80
	v_trunc_f32_e32 v80, v80
	v_mul_f32_e64 v81, |v80|, s56
	v_floor_f32_e32 v81, v81
	v_fma_f32 v82, v81, s57, |v80|
	v_cvt_u32_f32_e32 v80, v82
	v_cvt_u32_f32_e32 v81, v81
	v_lshl_add_u64 v[82:83], v[96:97], 3, s[0:1]
	global_atomic_add_x2 v[82:83], v[80:81], off
.LBB0_1825:
	s_or_b64 exec, exec, s[40:41]
	v_or_b32_e32 v80, 48, v146
	s_waitcnt lgkmcnt(0)
	v_ashrrev_i32_e32 v81, 31, v80
	v_lshlrev_b64 v[82:83], 11, v[80:81]
	v_lshl_add_u64 v[82:83], s[22:23], 0, v[82:83]
	v_lshl_add_u64 v[90:91], v[144:145], 1, v[82:83]
	global_load_dwordx4 v[82:85], v[90:91], off
	global_load_dwordx4 v[86:89], v[90:91], off offset:256
	s_waitcnt vmcnt(1)
	v_lshlrev_b32_e32 v92, 16, v82
	v_and_b32_e32 v93, 0xffff0000, v82
	v_lshlrev_b32_e32 v82, 16, v83
	v_and_b32_e32 v83, 0xffff0000, v83
	s_waitcnt vmcnt(0)
	v_lshlrev_b32_e32 v96, 16, v86
	v_and_b32_e32 v97, 0xffff0000, v86
	v_lshlrev_b32_e32 v86, 16, v87
	v_and_b32_e32 v87, 0xffff0000, v87
	v_lshlrev_b32_e32 v94, 16, v84
	v_and_b32_e32 v95, 0xffff0000, v84
	v_lshlrev_b32_e32 v84, 16, v85
	v_and_b32_e32 v85, 0xffff0000, v85
	v_lshlrev_b32_e32 v98, 16, v88
	v_and_b32_e32 v99, 0xffff0000, v88
	v_lshlrev_b32_e32 v88, 16, v89
	v_and_b32_e32 v89, 0xffff0000, v89
	v_pk_add_f32 v[78:79], v[78:79], v[82:83]
	v_pk_add_f32 v[76:77], v[76:77], v[92:93]
	v_pk_add_f32 v[70:71], v[70:71], v[86:87]
	v_pk_add_f32 v[68:69], v[68:69], v[96:97]
	v_pk_add_f32 v[74:75], v[74:75], v[84:85]
	v_pk_add_f32 v[72:73], v[72:73], v[94:95]
	v_pk_add_f32 v[82:83], v[66:67], v[88:89]
	v_pk_add_f32 v[84:85], v[64:65], v[98:99]
	v_mul_f32_e32 v66, v77, v77
	v_mul_f32_e32 v67, v79, v79
	v_mul_f32_e32 v86, v69, v69
	v_mul_f32_e32 v87, v71, v71
	v_cvt_pk_bf16_f32 v64, v76, v77
	v_mul_f32_e32 v77, v73, v73
	v_mul_f32_e32 v88, v85, v85
	v_fmac_f32_e32 v66, v76, v76
	v_fmac_f32_e32 v67, v78, v78
	v_fmac_f32_e32 v86, v68, v68
	v_fmac_f32_e32 v87, v70, v70
	v_cvt_pk_bf16_f32 v65, v78, v79
	v_mul_f32_e32 v79, v75, v75
	v_mul_f32_e32 v89, v83, v83
	v_fmac_f32_e32 v77, v72, v72
	v_fmac_f32_e32 v88, v84, v84
	v_add_f32_e32 v66, v66, v67
	v_add_f32_e32 v67, v86, v87
	v_fmac_f32_e32 v79, v74, v74
	v_fmac_f32_e32 v89, v82, v82
	v_add_f32_e32 v66, v77, v66
	v_add_f32_e32 v67, v88, v67
	v_add_f32_e32 v66, v79, v66
	v_add_f32_e32 v67, v89, v67
	v_add_f32_e32 v76, v66, v67
	v_mov_b32_e32 v77, v76
	s_nop 1
	v_permlane16_swap_b32_e32 v77, v76
	v_cvt_pk_bf16_f32 v66, v72, v73
	v_cvt_pk_bf16_f32 v67, v74, v75
	global_store_dwordx4 v[90:91], v[64:67], off sc1
	s_waitcnt lgkmcnt(0)
	s_nop 0
	v_add_f32_e32 v64, v76, v77
	v_mov_b32_e32 v65, v64
	s_nop 1
	v_permlane32_swap_b32_e32 v65, v64
	v_cvt_pk_bf16_f32 v66, v68, v69
	v_cvt_pk_bf16_f32 v67, v70, v71
	v_cvt_pk_bf16_f32 v68, v84, v85
	v_cvt_pk_bf16_f32 v69, v82, v83
	global_store_dwordx4 v[90:91], v[66:69], off offset:256 sc1
	s_and_saveexec_b64 s[40:41], s[4:5]
	s_cbranch_execz .LBB0_1827
	s_waitcnt lgkmcnt(0)
	v_add_f32_e32 v64, v64, v65
	v_mul_f32_e32 v64, 0x4f800000, v64
	v_trunc_f32_e32 v64, v64
	v_mul_f32_e64 v65, |v64|, s56
	v_floor_f32_e32 v65, v65
	v_fma_f32 v66, v65, s57, |v64|
	v_cvt_u32_f32_e32 v64, v66
	v_cvt_u32_f32_e32 v65, v65
	v_lshl_add_u64 v[66:67], v[80:81], 3, s[0:1]
	global_atomic_add_x2 v[66:67], v[64:65], off
; __device__ __forceinline__ void fx_add(float* p, size_t idx, float s) { atomicAdd((unsigned long long*)p + idx, (unsigned long long)(long long)(s * 4294967296.0f)); }
; __device__ __forceinline__ unsigned cvtpk(float lo, float hi) { f32x2v_ v = {lo, hi}; bf16x2v_ b = __builtin_convertvector(v, bf16x2v_); return __builtin_bit_cast(unsigned, b); }
;     __device__ __forceinline__ void operator()(const f32x4 (&acc)[2][2][4][2], const Unit& u, int wr, int wc, int fr, int fq) const {
;     ...
;             for (int m = 0; m < 4; ++m) { const int row = row0 + ai * HALF + m * 16; const size_t off = (size_t)row * 1024 + col0; float s = 0.f;
; #pragma unroll
;                 for (int bj = 0; bj < 2; ++bj) { f32x4 a0, a1;
;                     if (xin32) { const float* p = xin32 + off + bj * HALF; a0 = *(const f32x4*)p; a1 = *(const f32x4*)(p + 4); }
;                     else { const u32x4 w = *(const u32x4*)(xb + off + bj * HALF);
;                         a0 = (f32x4){__uint_as_float(w.x << 16), __uint_as_float(w.x & 0xffff0000u), __uint_as_float(w.y << 16), __uint_as_float(w.y & 0xffff0000u)};
;                         a1 = (f32x4){__uint_as_float(w.z << 16), __uint_as_float(w.z & 0xffff0000u), __uint_as_float(w.w << 16), __uint_as_float(w.w & 0xffff0000u)}; }
;                     const f32x4 v0 = a0 + acc[ai][bj][m][0] * alpha, v1 = a1 + acc[ai][bj][m][1] * alpha;
;                     u32x4 w; w.x = cvtpk(v0[0], v0[1]); w.y = cvtpk(v0[2], v0[3]); w.z = cvtpk(v1[0], v1[1]); w.w = cvtpk(v1[2], v1[3]);
;                     *(u32x4*)(xb + off + bj * HALF) = w;
;                     s += (v0[0] * v0[0] + v0[1] * v0[1]) + (v0[2] * v0[2] + v0[3] * v0[3]) + (v1[0] * v1[0] + v1[1] * v1[1]) + (v1[2] * v1[2] + v1[3] * v1[3]); }
;                 s += __shfl_xor(s, 16); s += __shfl_xor(s, 32);
;                 if (fq == 0) fx_add(ssout, row, s); }
.LBB0_1827:
	s_or_b64 exec, exec, s[40:41]
	v_add_u32_e32 v64, 0x80, v146
	s_waitcnt lgkmcnt(0)
	v_ashrrev_i32_e32 v65, 31, v64
	v_lshlrev_b64 v[66:67], 11, v[64:65]
	v_lshl_add_u64 v[66:67], s[22:23], 0, v[66:67]
	v_lshl_add_u64 v[74:75], v[144:145], 1, v[66:67]
	global_load_dwordx4 v[66:69], v[74:75], off
	global_load_dwordx4 v[70:73], v[74:75], off offset:256
	s_waitcnt vmcnt(1)
	v_lshlrev_b32_e32 v76, 16, v66
	v_and_b32_e32 v77, 0xffff0000, v66
	v_lshlrev_b32_e32 v66, 16, v67
	v_and_b32_e32 v67, 0xffff0000, v67
	s_waitcnt vmcnt(0)
	v_lshlrev_b32_e32 v80, 16, v70
	v_and_b32_e32 v81, 0xffff0000, v70
	v_lshlrev_b32_e32 v70, 16, v71
	v_and_b32_e32 v71, 0xffff0000, v71
	v_lshlrev_b32_e32 v78, 16, v68
	v_and_b32_e32 v79, 0xffff0000, v68
	v_lshlrev_b32_e32 v68, 16, v69
	v_and_b32_e32 v69, 0xffff0000, v69
	v_lshlrev_b32_e32 v82, 16, v72
	v_and_b32_e32 v83, 0xffff0000, v72
	v_lshlrev_b32_e32 v72, 16, v73
	v_and_b32_e32 v73, 0xffff0000, v73
	v_pk_add_f32 v[62:63], v[62:63], v[66:67]
	v_pk_add_f32 v[60:61], v[60:61], v[76:77]
	v_pk_add_f32 v[54:55], v[54:55], v[70:71]
	v_pk_add_f32 v[52:53], v[52:53], v[80:81]
	v_pk_add_f32 v[58:59], v[58:59], v[68:69]
	v_pk_add_f32 v[56:57], v[56:57], v[78:79]
	v_pk_add_f32 v[66:67], v[50:51], v[72:73]
	v_pk_add_f32 v[68:69], v[48:49], v[82:83]
	v_mul_f32_e32 v50, v61, v61
	v_mul_f32_e32 v51, v63, v63
	v_mul_f32_e32 v70, v53, v53
	v_mul_f32_e32 v71, v55, v55
	v_cvt_pk_bf16_f32 v48, v60, v61
	v_mul_f32_e32 v61, v57, v57
	v_mul_f32_e32 v72, v69, v69
	v_fmac_f32_e32 v50, v60, v60
	v_fmac_f32_e32 v51, v62, v62
	v_fmac_f32_e32 v70, v52, v52
	v_fmac_f32_e32 v71, v54, v54
	v_cvt_pk_bf16_f32 v49, v62, v63
	v_mul_f32_e32 v63, v59, v59
	v_mul_f32_e32 v73, v67, v67
	v_fmac_f32_e32 v61, v56, v56
	v_fmac_f32_e32 v72, v68, v68
	v_add_f32_e32 v50, v50, v51
	v_add_f32_e32 v51, v70, v71
	v_fmac_f32_e32 v63, v58, v58
	v_fmac_f32_e32 v73, v66, v66
	v_add_f32_e32 v50, v61, v50
	v_add_f32_e32 v51, v72, v51
	v_add_f32_e32 v50, v63, v50
	v_add_f32_e32 v51, v73, v51
	v_add_f32_e32 v60, v50, v51
	v_mov_b32_e32 v61, v60
	s_nop 1
	v_permlane16_swap_b32_e32 v61, v60
	v_cvt_pk_bf16_f32 v50, v56, v57
	v_cvt_pk_bf16_f32 v51, v58, v59
	global_store_dwordx4 v[74:75], v[48:51], off sc1
	s_waitcnt lgkmcnt(0)
	s_nop 0
	v_add_f32_e32 v48, v60, v61
	v_mov_b32_e32 v49, v48
	s_nop 1
	v_permlane32_swap_b32_e32 v49, v48
	v_cvt_pk_bf16_f32 v50, v52, v53
	v_cvt_pk_bf16_f32 v51, v54, v55
	v_cvt_pk_bf16_f32 v52, v68, v69
	v_cvt_pk_bf16_f32 v53, v66, v67
	global_store_dwordx4 v[74:75], v[50:53], off offset:256 sc1
	s_and_saveexec_b64 s[40:41], s[4:5]
	s_cbranch_execz .LBB0_1829
	s_waitcnt lgkmcnt(0)
	v_add_f32_e32 v48, v48, v49
	v_mul_f32_e32 v48, 0x4f800000, v48
	v_trunc_f32_e32 v48, v48
	v_mul_f32_e64 v49, |v48|, s56
	v_floor_f32_e32 v49, v49
	v_fma_f32 v50, v49, s57, |v48|
	v_cvt_u32_f32_e32 v48, v50
	v_cvt_u32_f32_e32 v49, v49
	v_lshl_add_u64 v[50:51], v[64:65], 3, s[0:1]
	global_atomic_add_x2 v[50:51], v[48:49], off
.LBB0_1829:
	s_or_b64 exec, exec, s[40:41]
	v_add_u32_e32 v48, 0x90, v146
	s_waitcnt lgkmcnt(0)
	v_ashrrev_i32_e32 v49, 31, v48
	v_lshlrev_b64 v[50:51], 11, v[48:49]
	v_lshl_add_u64 v[50:51], s[22:23], 0, v[50:51]
	v_lshl_add_u64 v[58:59], v[144:145], 1, v[50:51]
	global_load_dwordx4 v[50:53], v[58:59], off
	global_load_dwordx4 v[54:57], v[58:59], off offset:256
	s_waitcnt vmcnt(1)
	v_lshlrev_b32_e32 v60, 16, v50
	v_and_b32_e32 v61, 0xffff0000, v50
	v_lshlrev_b32_e32 v50, 16, v51
	v_and_b32_e32 v51, 0xffff0000, v51
	s_waitcnt vmcnt(0)
	v_lshlrev_b32_e32 v64, 16, v54
	v_and_b32_e32 v65, 0xffff0000, v54
	v_lshlrev_b32_e32 v54, 16, v55
	v_and_b32_e32 v55, 0xffff0000, v55
	v_lshlrev_b32_e32 v62, 16, v52
	v_and_b32_e32 v63, 0xffff0000, v52
	v_lshlrev_b32_e32 v52, 16, v53
	v_and_b32_e32 v53, 0xffff0000, v53
	v_lshlrev_b32_e32 v66, 16, v56
	v_and_b32_e32 v67, 0xffff0000, v56
	v_lshlrev_b32_e32 v56, 16, v57
	v_and_b32_e32 v57, 0xffff0000, v57
	v_pk_add_f32 v[46:47], v[46:47], v[50:51]
	v_pk_add_f32 v[44:45], v[44:45], v[60:61]
	v_pk_add_f32 v[38:39], v[38:39], v[54:55]
	v_pk_add_f32 v[36:37], v[36:37], v[64:65]
	v_pk_add_f32 v[42:43], v[42:43], v[52:53]
	v_pk_add_f32 v[40:41], v[40:41], v[62:63]
	v_pk_add_f32 v[50:51], v[34:35], v[56:57]
	v_pk_add_f32 v[52:53], v[32:33], v[66:67]
	v_mul_f32_e32 v34, v45, v45
	v_mul_f32_e32 v35, v47, v47
	v_mul_f32_e32 v54, v37, v37
	v_mul_f32_e32 v55, v39, v39
	v_cvt_pk_bf16_f32 v32, v44, v45
	v_mul_f32_e32 v45, v41, v41
	v_mul_f32_e32 v56, v53, v53
	v_fmac_f32_e32 v34, v44, v44
	v_fmac_f32_e32 v35, v46, v46
	v_fmac_f32_e32 v54, v36, v36
	v_fmac_f32_e32 v55, v38, v38
	v_cvt_pk_bf16_f32 v33, v46, v47
	v_mul_f32_e32 v47, v43, v43
	v_mul_f32_e32 v57, v51, v51
	v_fmac_f32_e32 v45, v40, v40
	v_fmac_f32_e32 v56, v52, v52
	v_add_f32_e32 v34, v34, v35
	v_add_f32_e32 v35, v54, v55
	v_fmac_f32_e32 v47, v42, v42
	v_fmac_f32_e32 v57, v50, v50
	v_add_f32_e32 v34, v45, v34
	v_add_f32_e32 v35, v56, v35
	v_add_f32_e32 v34, v47, v34
	v_add_f32_e32 v35, v57, v35
	v_add_f32_e32 v44, v34, v35
	v_mov_b32_e32 v45, v44
	s_nop 1
	v_permlane16_swap_b32_e32 v45, v44
	v_cvt_pk_bf16_f32 v34, v40, v41
	v_cvt_pk_bf16_f32 v35, v42, v43
	global_store_dwordx4 v[58:59], v[32:35], off sc1
	s_waitcnt lgkmcnt(0)
	s_nop 0
	v_add_f32_e32 v32, v44, v45
	v_mov_b32_e32 v33, v32
	s_nop 1
	v_permlane32_swap_b32_e32 v33, v32
	v_cvt_pk_bf16_f32 v34, v36, v37
	v_cvt_pk_bf16_f32 v35, v38, v39
	v_cvt_pk_bf16_f32 v36, v52, v53
	v_cvt_pk_bf16_f32 v37, v50, v51
	global_store_dwordx4 v[58:59], v[34:37], off offset:256 sc1
	s_and_saveexec_b64 s[40:41], s[4:5]
	s_cbranch_execz .LBB0_1831
	s_waitcnt lgkmcnt(0)
	v_add_f32_e32 v32, v32, v33
	v_mul_f32_e32 v32, 0x4f800000, v32
	v_trunc_f32_e32 v32, v32
	v_mul_f32_e64 v33, |v32|, s56
	v_floor_f32_e32 v33, v33
	v_fma_f32 v34, v33, s57, |v32|
	v_cvt_u32_f32_e32 v32, v34
	v_cvt_u32_f32_e32 v33, v33
	v_lshl_add_u64 v[34:35], v[48:49], 3, s[0:1]
	global_atomic_add_x2 v[34:35], v[32:33], off
; __device__ __forceinline__ void fx_add(float* p, size_t idx, float s) { atomicAdd((unsigned long long*)p + idx, (unsigned long long)(long long)(s * 4294967296.0f)); }
; __device__ __forceinline__ unsigned cvtpk(float lo, float hi) { f32x2v_ v = {lo, hi}; bf16x2v_ b = __builtin_convertvector(v, bf16x2v_); return __builtin_bit_cast(unsigned, b); }
;     __device__ __forceinline__ void operator()(const f32x4 (&acc)[2][2][4][2], const Unit& u, int wr, int wc, int fr, int fq) const {
;     ...
;             for (int m = 0; m < 4; ++m) { const int row = row0 + ai * HALF + m * 16; const size_t off = (size_t)row * 1024 + col0; float s = 0.f;
; #pragma unroll
;                 for (int bj = 0; bj < 2; ++bj) { f32x4 a0, a1;
;                     if (xin32) { const float* p = xin32 + off + bj * HALF; a0 = *(const f32x4*)p; a1 = *(const f32x4*)(p + 4); }
;                     else { const u32x4 w = *(const u32x4*)(xb + off + bj * HALF);
;                         a0 = (f32x4){__uint_as_float(w.x << 16), __uint_as_float(w.x & 0xffff0000u), __uint_as_float(w.y << 16), __uint_as_float(w.y & 0xffff0000u)};
;                         a1 = (f32x4){__uint_as_float(w.z << 16), __uint_as_float(w.z & 0xffff0000u), __uint_as_float(w.w << 16), __uint_as_float(w.w & 0xffff0000u)}; }
;                     const f32x4 v0 = a0 + acc[ai][bj][m][0] * alpha, v1 = a1 + acc[ai][bj][m][1] * alpha;
;                     u32x4 w; w.x = cvtpk(v0[0], v0[1]); w.y = cvtpk(v0[2], v0[3]); w.z = cvtpk(v1[0], v1[1]); w.w = cvtpk(v1[2], v1[3]);
;                     *(u32x4*)(xb + off + bj * HALF) = w;
;                     s += (v0[0] * v0[0] + v0[1] * v0[1]) + (v0[2] * v0[2] + v0[3] * v0[3]) + (v1[0] * v1[0] + v1[1] * v1[1]) + (v1[2] * v1[2] + v1[3] * v1[3]); }
;                 s += __shfl_xor(s, 16); s += __shfl_xor(s, 32);
;                 if (fq == 0) fx_add(ssout, row, s); }
.LBB0_1831:
	s_or_b64 exec, exec, s[40:41]
	v_add_u32_e32 v32, 0xa0, v146
	s_waitcnt lgkmcnt(0)
	v_ashrrev_i32_e32 v33, 31, v32
	v_lshlrev_b64 v[34:35], 11, v[32:33]
	v_lshl_add_u64 v[34:35], s[22:23], 0, v[34:35]
	v_lshl_add_u64 v[42:43], v[144:145], 1, v[34:35]
	global_load_dwordx4 v[34:37], v[42:43], off
	global_load_dwordx4 v[38:41], v[42:43], off offset:256
	s_waitcnt vmcnt(1)
	v_lshlrev_b32_e32 v44, 16, v34
	v_and_b32_e32 v45, 0xffff0000, v34
	v_lshlrev_b32_e32 v34, 16, v35
	v_and_b32_e32 v35, 0xffff0000, v35
	s_waitcnt vmcnt(0)
	v_lshlrev_b32_e32 v48, 16, v38
	v_and_b32_e32 v49, 0xffff0000, v38
	v_lshlrev_b32_e32 v38, 16, v39
	v_and_b32_e32 v39, 0xffff0000, v39
	v_lshlrev_b32_e32 v46, 16, v36
	v_and_b32_e32 v47, 0xffff0000, v36
	v_lshlrev_b32_e32 v36, 16, v37
	v_and_b32_e32 v37, 0xffff0000, v37
	v_lshlrev_b32_e32 v50, 16, v40
	v_and_b32_e32 v51, 0xffff0000, v40
	v_lshlrev_b32_e32 v40, 16, v41
	v_and_b32_e32 v41, 0xffff0000, v41
	v_pk_add_f32 v[30:31], v[30:31], v[34:35]
	v_pk_add_f32 v[28:29], v[28:29], v[44:45]
	v_pk_add_f32 v[22:23], v[22:23], v[38:39]
	v_pk_add_f32 v[20:21], v[20:21], v[48:49]
	v_pk_add_f32 v[26:27], v[26:27], v[36:37]
	v_pk_add_f32 v[24:25], v[24:25], v[46:47]
	v_pk_add_f32 v[34:35], v[18:19], v[40:41]
	v_pk_add_f32 v[36:37], v[16:17], v[50:51]
	v_mul_f32_e32 v18, v29, v29
	v_mul_f32_e32 v19, v31, v31
	v_mul_f32_e32 v38, v21, v21
	v_mul_f32_e32 v39, v23, v23
	v_cvt_pk_bf16_f32 v16, v28, v29
	v_mul_f32_e32 v29, v25, v25
	v_mul_f32_e32 v40, v37, v37
	v_fmac_f32_e32 v18, v28, v28
	v_fmac_f32_e32 v19, v30, v30
	v_fmac_f32_e32 v38, v20, v20
	v_fmac_f32_e32 v39, v22, v22
	v_cvt_pk_bf16_f32 v17, v30, v31
	v_mul_f32_e32 v31, v27, v27
	v_mul_f32_e32 v41, v35, v35
	v_fmac_f32_e32 v29, v24, v24
	v_fmac_f32_e32 v40, v36, v36
	v_add_f32_e32 v18, v18, v19
	v_add_f32_e32 v19, v38, v39
	v_fmac_f32_e32 v31, v26, v26
	v_fmac_f32_e32 v41, v34, v34
	v_add_f32_e32 v18, v29, v18
	v_add_f32_e32 v19, v40, v19
	v_add_f32_e32 v18, v31, v18
	v_add_f32_e32 v19, v41, v19
	v_add_f32_e32 v28, v18, v19
	v_mov_b32_e32 v29, v28
	s_nop 1
	v_permlane16_swap_b32_e32 v29, v28
	v_cvt_pk_bf16_f32 v18, v24, v25
	v_cvt_pk_bf16_f32 v19, v26, v27
	global_store_dwordx4 v[42:43], v[16:19], off sc1
	s_waitcnt lgkmcnt(0)
	s_nop 0
	v_add_f32_e32 v16, v28, v29
	v_mov_b32_e32 v17, v16
	s_nop 1
	v_permlane32_swap_b32_e32 v17, v16
	v_cvt_pk_bf16_f32 v18, v20, v21
	v_cvt_pk_bf16_f32 v19, v22, v23
	v_cvt_pk_bf16_f32 v20, v36, v37
	v_cvt_pk_bf16_f32 v21, v34, v35
	global_store_dwordx4 v[42:43], v[18:21], off offset:256 sc1
	s_and_saveexec_b64 s[40:41], s[4:5]
	s_cbranch_execz .LBB0_1833
	s_waitcnt lgkmcnt(0)
	v_add_f32_e32 v16, v16, v17
	v_mul_f32_e32 v16, 0x4f800000, v16
	v_trunc_f32_e32 v16, v16
	v_mul_f32_e64 v17, |v16|, s56
	v_floor_f32_e32 v17, v17
	v_fma_f32 v18, v17, s57, |v16|
	v_cvt_u32_f32_e32 v16, v18
	v_cvt_u32_f32_e32 v17, v17
	v_lshl_add_u64 v[18:19], v[32:33], 3, s[0:1]
	global_atomic_add_x2 v[18:19], v[16:17], off
.LBB0_1833:
	s_or_b64 exec, exec, s[40:41]
	v_add_u32_e32 v16, 0xb0, v146
	s_waitcnt lgkmcnt(0)
	v_ashrrev_i32_e32 v17, 31, v16
	v_lshlrev_b64 v[18:19], 11, v[16:17]
	v_lshl_add_u64 v[18:19], s[22:23], 0, v[18:19]
	v_lshl_add_u64 v[26:27], v[144:145], 1, v[18:19]
	global_load_dwordx4 v[18:21], v[26:27], off
	global_load_dwordx4 v[22:25], v[26:27], off offset:256
	s_waitcnt vmcnt(1)
	v_lshlrev_b32_e32 v28, 16, v18
	v_and_b32_e32 v29, 0xffff0000, v18
	v_lshlrev_b32_e32 v18, 16, v19
	v_and_b32_e32 v19, 0xffff0000, v19
	s_waitcnt vmcnt(0)
	v_lshlrev_b32_e32 v32, 16, v22
	v_and_b32_e32 v33, 0xffff0000, v22
	v_lshlrev_b32_e32 v22, 16, v23
	v_and_b32_e32 v23, 0xffff0000, v23
	v_lshlrev_b32_e32 v30, 16, v20
	v_and_b32_e32 v31, 0xffff0000, v20
	v_lshlrev_b32_e32 v20, 16, v21
	v_and_b32_e32 v21, 0xffff0000, v21
	v_lshlrev_b32_e32 v34, 16, v24
	v_and_b32_e32 v35, 0xffff0000, v24
	v_lshlrev_b32_e32 v24, 16, v25
	v_and_b32_e32 v25, 0xffff0000, v25
	v_pk_add_f32 v[14:15], v[14:15], v[18:19]
	v_pk_add_f32 v[12:13], v[12:13], v[28:29]
	v_pk_add_f32 v[6:7], v[6:7], v[22:23]
	v_pk_add_f32 v[4:5], v[4:5], v[32:33]
	v_pk_add_f32 v[10:11], v[10:11], v[20:21]
	v_pk_add_f32 v[8:9], v[8:9], v[30:31]
	v_pk_add_f32 v[18:19], v[2:3], v[24:25]
	v_pk_add_f32 v[20:21], v[0:1], v[34:35]
	v_mul_f32_e32 v2, v13, v13
	v_mul_f32_e32 v3, v15, v15
	v_mul_f32_e32 v22, v5, v5
	v_mul_f32_e32 v23, v7, v7
	v_cvt_pk_bf16_f32 v0, v12, v13
	v_mul_f32_e32 v13, v9, v9
	v_mul_f32_e32 v24, v21, v21
	v_fmac_f32_e32 v2, v12, v12
	v_fmac_f32_e32 v3, v14, v14
	v_fmac_f32_e32 v22, v4, v4
	v_fmac_f32_e32 v23, v6, v6
	v_cvt_pk_bf16_f32 v1, v14, v15
	v_mul_f32_e32 v15, v11, v11
	v_mul_f32_e32 v25, v19, v19
	v_fmac_f32_e32 v13, v8, v8
	v_fmac_f32_e32 v24, v20, v20
	v_add_f32_e32 v2, v2, v3
	v_add_f32_e32 v3, v22, v23
	v_fmac_f32_e32 v15, v10, v10
	v_fmac_f32_e32 v25, v18, v18
	v_add_f32_e32 v2, v13, v2
	v_add_f32_e32 v3, v24, v3
	v_add_f32_e32 v2, v15, v2
	v_add_f32_e32 v3, v25, v3
	v_add_f32_e32 v12, v2, v3
	v_mov_b32_e32 v13, v12
	s_nop 1
	v_permlane16_swap_b32_e32 v13, v12
	v_cvt_pk_bf16_f32 v2, v8, v9
	v_cvt_pk_bf16_f32 v3, v10, v11
	global_store_dwordx4 v[26:27], v[0:3], off sc1
	s_waitcnt lgkmcnt(0)
	s_nop 0
	v_add_f32_e32 v0, v12, v13
	v_mov_b32_e32 v1, v0
	s_nop 1
	v_permlane32_swap_b32_e32 v1, v0
	v_cvt_pk_bf16_f32 v2, v4, v5
	v_cvt_pk_bf16_f32 v3, v6, v7
	v_cvt_pk_bf16_f32 v4, v20, v21
	v_cvt_pk_bf16_f32 v5, v18, v19
	global_store_dwordx4 v[26:27], v[2:5], off offset:256 sc1
	s_and_saveexec_b64 s[40:41], s[4:5]
	s_cbranch_execz .LBB0_1835
	s_waitcnt lgkmcnt(0)
	v_add_f32_e32 v0, v0, v1
	v_mul_f32_e32 v0, 0x4f800000, v0
	v_trunc_f32_e32 v0, v0
	v_mul_f32_e64 v1, |v0|, s56
	v_floor_f32_e32 v1, v1
	v_fma_f32 v2, v1, s57, |v0|
	v_cvt_u32_f32_e32 v0, v2
	v_cvt_u32_f32_e32 v1, v1
	v_lshl_add_u64 v[2:3], v[16:17], 3, s[0:1]
	global_atomic_add_x2 v[2:3], v[0:1], off

; __device__ __forceinline__ unsigned cvtpk(float lo, float hi) { f32x2v_ v = {lo, hi}; bf16x2v_ b = __builtin_convertvector(v, bf16x2v_); return __builtin_bit_cast(unsigned, b); }
;     __device__ __forceinline__ void operator()(const f32x4 (&acc)[2][2][4][2], const Unit& u, int wr, int wc, int fr, int fq) const {
;     ...
;             for (int m = 0; m < 4; ++m) { const int row = row0 + ai * HALF + m * 16; const float rs = row_rs(ss, row);
;                 float hv[8];
; #pragma unroll
;                 for (int n = 0; n < 2; ++n)
; #pragma unroll
;                     for (int i = 0; i < 4; ++i) { const float g = acc[ai][0][m][n][i] * rs, uu = acc[ai][1][m][n][i] * rs;
;                         hv[n * 4 + i] = g * __builtin_amdgcn_rcpf(1.0f + __expf(-g)) * uu; }
;                 u32x4 w; w.x = cvtpk(hv[0], hv[1]); w.y = cvtpk(hv[2], hv[3]); w.z = cvtpk(hv[4], hv[5]); w.w = cvtpk(hv[6], hv[7]);
;                 *(u32x4*)(H + (size_t)row * ldh + col0) = w; }
.LBB0_1903:
	v_lshl_or_b32 v160, s52, 7, v154
	v_ashrrev_i32_e32 v161, 31, v160
	v_or_b32_e32 v164, 16, v144
	v_ashrrev_i32_e32 v165, 31, v164
	v_lshl_add_u64 v[166:167], v[164:165], 3, s[0:1]
	v_mov_b64_e32 v[146:147], s[20:21]
	v_mad_i64_i32 v[162:163], s[38:39], v144, s51, v[146:147]
	s_andn2_b64 vcc, exec, s[4:5]
	s_mov_b64 s[4:5], -1
	s_waitcnt vmcnt(7)
	v_cvt_f32_u32_e32 v159, v183
	v_cvt_f32_u32_e32 v145, v182
	v_lshlrev_b64 v[148:149], 1, v[160:161]
	v_lshl_add_u64 v[162:163], v[162:163], 0, v[148:149]
	v_fmamk_f32 v145, v145, 0x2f800000, v159
	v_fmamk_f32 v145, v145, 0x3a800000, v158
	v_rsq_f32_e32 v160, v145
	s_nop 0
	v_mul_f32_e32 v182, 0xbfb8aa3b, v160
	v_mul_f32_e32 v183, v160, v160
	v_pk_mul_f32 v[160:161], v[124:125], v[182:183] op_sel_hi:[1,0]
	v_pk_mul_f32 v[168:169], v[126:127], v[182:183] op_sel_hi:[1,0]
	v_pk_mul_f32 v[170:171], v[120:121], v[182:183] op_sel_hi:[1,0]
	v_pk_mul_f32 v[172:173], v[122:123], v[182:183] op_sel_hi:[1,0]
	v_pk_mul_f32 v[116:117], v[116:117], v[124:125]
	v_pk_mul_f32 v[118:119], v[118:119], v[126:127]
	v_pk_mul_f32 v[120:121], v[112:113], v[120:121]
	v_pk_mul_f32 v[122:123], v[114:115], v[122:123]
	v_exp_f32_e32 v160, v160
	v_exp_f32_e32 v161, v161
	v_exp_f32_e32 v168, v168
	v_exp_f32_e32 v169, v169
	v_exp_f32_e32 v170, v170
	v_exp_f32_e32 v171, v171
	v_exp_f32_e32 v172, v172
	v_exp_f32_e32 v173, v173
	v_pk_mul_f32 v[116:117], v[116:117], v[182:183] op_sel:[0,1] op_sel_hi:[1,1]
	v_pk_mul_f32 v[118:119], v[118:119], v[182:183] op_sel:[0,1] op_sel_hi:[1,1]
	v_pk_mul_f32 v[120:121], v[120:121], v[182:183] op_sel:[0,1] op_sel_hi:[1,1]
	v_pk_mul_f32 v[122:123], v[122:123], v[182:183] op_sel:[0,1] op_sel_hi:[1,1]
	v_pk_add_f32 v[160:161], v[160:161], 1.0 op_sel_hi:[1,0]
	v_pk_add_f32 v[168:169], v[168:169], 1.0 op_sel_hi:[1,0]
	v_pk_add_f32 v[170:171], v[170:171], 1.0 op_sel_hi:[1,0]
	v_pk_add_f32 v[172:173], v[172:173], 1.0 op_sel_hi:[1,0]
	v_rcp_f32_e32 v160, v160
	v_rcp_f32_e32 v161, v161
	v_rcp_f32_e32 v168, v168
	v_rcp_f32_e32 v169, v169
	v_rcp_f32_e32 v170, v170
	v_rcp_f32_e32 v171, v171
	v_rcp_f32_e32 v172, v172
	v_rcp_f32_e32 v173, v173
	v_pk_mul_f32 v[116:117], v[116:117], v[160:161]
	v_pk_mul_f32 v[118:119], v[118:119], v[168:169]
	v_pk_mul_f32 v[120:121], v[120:121], v[170:171]
	v_pk_mul_f32 v[122:123], v[122:123], v[172:173]
	v_cvt_pk_bf16_f32 v112, v116, v117
	v_cvt_pk_bf16_f32 v113, v118, v119
	v_cvt_pk_bf16_f32 v114, v120, v121
	v_cvt_pk_bf16_f32 v115, v122, v123
	global_store_dwordx4 v[162:163], v[112:115], off sc1
	s_nop 0
	s_nop 0
	v_or_b32_e32 v114, 32, v144
	s_waitcnt vmcnt(7)
	v_cvt_f32_u32_e32 v116, v185
	v_cvt_f32_u32_e32 v115, v184
	v_mad_i64_i32 v[112:113], s[38:39], v164, s51, v[146:147]
	v_fmamk_f32 v115, v115, 0x2f800000, v116
	v_fmamk_f32 v115, v115, 0x3a800000, v158
	v_rsq_f32_e32 v116, v115
	v_ashrrev_i32_e32 v115, 31, v114
	v_lshl_add_u64 v[118:119], v[114:115], 3, s[0:1]
	v_lshl_add_u64 v[112:113], v[112:113], 0, v[148:149]
	v_mul_f32_e32 v184, 0xbfb8aa3b, v116
	v_mul_f32_e32 v185, v116, v116
	v_pk_mul_f32 v[116:117], v[108:109], v[184:185] op_sel_hi:[1,0]
	v_pk_mul_f32 v[120:121], v[110:111], v[184:185] op_sel_hi:[1,0]
	v_pk_mul_f32 v[122:123], v[104:105], v[184:185] op_sel_hi:[1,0]
	v_pk_mul_f32 v[124:125], v[106:107], v[184:185] op_sel_hi:[1,0]
	v_pk_mul_f32 v[100:101], v[100:101], v[108:109]
	v_pk_mul_f32 v[102:103], v[102:103], v[110:111]
	v_pk_mul_f32 v[104:105], v[96:97], v[104:105]
	v_pk_mul_f32 v[106:107], v[98:99], v[106:107]
	v_exp_f32_e32 v116, v116
	v_exp_f32_e32 v117, v117
	v_exp_f32_e32 v120, v120
	v_exp_f32_e32 v121, v121
	v_exp_f32_e32 v122, v122
	v_exp_f32_e32 v123, v123
	v_exp_f32_e32 v124, v124
	v_exp_f32_e32 v125, v125
	v_pk_mul_f32 v[100:101], v[100:101], v[184:185] op_sel:[0,1] op_sel_hi:[1,1]
	v_pk_mul_f32 v[102:103], v[102:103], v[184:185] op_sel:[0,1] op_sel_hi:[1,1]
	v_pk_mul_f32 v[104:105], v[104:105], v[184:185] op_sel:[0,1] op_sel_hi:[1,1]
	v_pk_mul_f32 v[106:107], v[106:107], v[184:185] op_sel:[0,1] op_sel_hi:[1,1]
	v_pk_add_f32 v[116:117], v[116:117], 1.0 op_sel_hi:[1,0]
	v_pk_add_f32 v[120:121], v[120:121], 1.0 op_sel_hi:[1,0]
	v_pk_add_f32 v[122:123], v[122:123], 1.0 op_sel_hi:[1,0]
	v_pk_add_f32 v[124:125], v[124:125], 1.0 op_sel_hi:[1,0]
	v_rcp_f32_e32 v116, v116
	v_rcp_f32_e32 v117, v117
	v_rcp_f32_e32 v120, v120
	v_rcp_f32_e32 v121, v121
	v_rcp_f32_e32 v122, v122
	v_rcp_f32_e32 v123, v123
	v_rcp_f32_e32 v124, v124
	v_rcp_f32_e32 v125, v125
	v_pk_mul_f32 v[100:101], v[100:101], v[116:117]
	v_pk_mul_f32 v[102:103], v[102:103], v[120:121]
	v_pk_mul_f32 v[104:105], v[104:105], v[122:123]
	v_pk_mul_f32 v[106:107], v[106:107], v[124:125]
	v_cvt_pk_bf16_f32 v96, v100, v101
	v_cvt_pk_bf16_f32 v97, v102, v103
	v_cvt_pk_bf16_f32 v98, v104, v105
	v_cvt_pk_bf16_f32 v99, v106, v107
	global_store_dwordx4 v[112:113], v[96:99], off sc1
	s_nop 0
	s_nop 0
	v_or_b32_e32 v98, 48, v144
	s_waitcnt vmcnt(7)
; __device__ __forceinline__ unsigned cvtpk(float lo, float hi) { f32x2v_ v = {lo, hi}; bf16x2v_ b = __builtin_convertvector(v, bf16x2v_); return __builtin_bit_cast(unsigned, b); }
;     __device__ __forceinline__ void operator()(const f32x4 (&acc)[2][2][4][2], const Unit& u, int wr, int wc, int fr, int fq) const {
;     ...
;             for (int m = 0; m < 4; ++m) { const int row = row0 + ai * HALF + m * 16; const float rs = row_rs(ss, row);
;                 float hv[8];
; #pragma unroll
;                 for (int n = 0; n < 2; ++n)
; #pragma unroll
;                     for (int i = 0; i < 4; ++i) { const float g = acc[ai][0][m][n][i] * rs, uu = acc[ai][1][m][n][i] * rs;
;                         hv[n * 4 + i] = g * __builtin_amdgcn_rcpf(1.0f + __expf(-g)) * uu; }
;                 u32x4 w; w.x = cvtpk(hv[0], hv[1]); w.y = cvtpk(hv[2], hv[3]); w.z = cvtpk(hv[4], hv[5]); w.w = cvtpk(hv[6], hv[7]);
;                 *(u32x4*)(H + (size_t)row * ldh + col0) = w; }
	v_cvt_f32_u32_e32 v100, v187
	v_cvt_f32_u32_e32 v99, v186
	v_mad_i64_i32 v[96:97], s[38:39], v114, s51, v[146:147]
	v_fmamk_f32 v99, v99, 0x2f800000, v100
	v_fmamk_f32 v99, v99, 0x3a800000, v158
	v_rsq_f32_e32 v100, v99
	v_ashrrev_i32_e32 v99, 31, v98
	v_lshl_add_u64 v[102:103], v[98:99], 3, s[0:1]
	v_lshl_add_u64 v[96:97], v[96:97], 0, v[148:149]
	v_mul_f32_e32 v186, 0xbfb8aa3b, v100
	v_mul_f32_e32 v187, v100, v100
	v_pk_mul_f32 v[100:101], v[92:93], v[186:187] op_sel_hi:[1,0]
	v_pk_mul_f32 v[104:105], v[94:95], v[186:187] op_sel_hi:[1,0]
	v_pk_mul_f32 v[106:107], v[88:89], v[186:187] op_sel_hi:[1,0]
	v_pk_mul_f32 v[108:109], v[90:91], v[186:187] op_sel_hi:[1,0]
	v_pk_mul_f32 v[84:85], v[84:85], v[92:93]
	v_pk_mul_f32 v[86:87], v[86:87], v[94:95]
	v_pk_mul_f32 v[88:89], v[80:81], v[88:89]
	v_pk_mul_f32 v[90:91], v[82:83], v[90:91]
	v_exp_f32_e32 v100, v100
	v_exp_f32_e32 v101, v101
	v_exp_f32_e32 v104, v104
	v_exp_f32_e32 v105, v105
	v_exp_f32_e32 v106, v106
	v_exp_f32_e32 v107, v107
	v_exp_f32_e32 v108, v108
	v_exp_f32_e32 v109, v109
	v_pk_mul_f32 v[84:85], v[84:85], v[186:187] op_sel:[0,1] op_sel_hi:[1,1]
	v_pk_mul_f32 v[86:87], v[86:87], v[186:187] op_sel:[0,1] op_sel_hi:[1,1]
	v_pk_mul_f32 v[88:89], v[88:89], v[186:187] op_sel:[0,1] op_sel_hi:[1,1]
	v_pk_mul_f32 v[90:91], v[90:91], v[186:187] op_sel:[0,1] op_sel_hi:[1,1]
	v_pk_add_f32 v[100:101], v[100:101], 1.0 op_sel_hi:[1,0]
	v_pk_add_f32 v[104:105], v[104:105], 1.0 op_sel_hi:[1,0]
	v_pk_add_f32 v[106:107], v[106:107], 1.0 op_sel_hi:[1,0]
	v_pk_add_f32 v[108:109], v[108:109], 1.0 op_sel_hi:[1,0]
	v_rcp_f32_e32 v100, v100
	v_rcp_f32_e32 v101, v101
	v_rcp_f32_e32 v104, v104
	v_rcp_f32_e32 v105, v105
	v_rcp_f32_e32 v106, v106
	v_rcp_f32_e32 v107, v107
	v_rcp_f32_e32 v108, v108
	v_rcp_f32_e32 v109, v109
	v_pk_mul_f32 v[84:85], v[84:85], v[100:101]
	v_pk_mul_f32 v[86:87], v[86:87], v[104:105]
	v_pk_mul_f32 v[88:89], v[88:89], v[106:107]
	v_pk_mul_f32 v[90:91], v[90:91], v[108:109]
	v_cvt_pk_bf16_f32 v80, v84, v85
	v_cvt_pk_bf16_f32 v81, v86, v87
	v_cvt_pk_bf16_f32 v82, v88, v89
	v_cvt_pk_bf16_f32 v83, v90, v91
	global_store_dwordx4 v[96:97], v[80:83], off sc1
	s_nop 0
	s_waitcnt vmcnt(7)
	v_cvt_f32_u32_e32 v80, v189
	v_cvt_f32_u32_e32 v81, v188
	v_mad_i64_i32 v[82:83], s[38:39], v98, s51, v[146:147]
	v_fmamk_f32 v80, v81, 0x2f800000, v80
	v_fmamk_f32 v80, v80, 0x3a800000, v158
	v_rsq_f32_e32 v80, v80
	v_lshl_add_u64 v[82:83], v[82:83], 0, v[148:149]
	v_mul_f32_e32 v188, 0xbfb8aa3b, v80
	v_mul_f32_e32 v189, v80, v80
	v_pk_mul_f32 v[80:81], v[76:77], v[188:189] op_sel_hi:[1,0]
	v_pk_mul_f32 v[84:85], v[78:79], v[188:189] op_sel_hi:[1,0]
	v_pk_mul_f32 v[86:87], v[72:73], v[188:189] op_sel_hi:[1,0]
	v_pk_mul_f32 v[88:89], v[74:75], v[188:189] op_sel_hi:[1,0]
	v_pk_mul_f32 v[68:69], v[68:69], v[76:77]
	v_pk_mul_f32 v[70:71], v[70:71], v[78:79]
	v_pk_mul_f32 v[72:73], v[64:65], v[72:73]
	v_pk_mul_f32 v[74:75], v[66:67], v[74:75]
	v_exp_f32_e32 v80, v80
	v_exp_f32_e32 v81, v81
	v_exp_f32_e32 v84, v84
	v_exp_f32_e32 v85, v85
	v_exp_f32_e32 v86, v86
	v_exp_f32_e32 v87, v87
	v_exp_f32_e32 v88, v88
	v_exp_f32_e32 v89, v89
	v_pk_mul_f32 v[68:69], v[68:69], v[188:189] op_sel:[0,1] op_sel_hi:[1,1]
	v_pk_mul_f32 v[70:71], v[70:71], v[188:189] op_sel:[0,1] op_sel_hi:[1,1]
	v_pk_mul_f32 v[72:73], v[72:73], v[188:189] op_sel:[0,1] op_sel_hi:[1,1]
	v_pk_mul_f32 v[74:75], v[74:75], v[188:189] op_sel:[0,1] op_sel_hi:[1,1]
	v_pk_add_f32 v[80:81], v[80:81], 1.0 op_sel_hi:[1,0]
	v_pk_add_f32 v[84:85], v[84:85], 1.0 op_sel_hi:[1,0]
	v_pk_add_f32 v[86:87], v[86:87], 1.0 op_sel_hi:[1,0]
	v_pk_add_f32 v[88:89], v[88:89], 1.0 op_sel_hi:[1,0]
	v_rcp_f32_e32 v80, v80
	v_rcp_f32_e32 v81, v81
	v_rcp_f32_e32 v84, v84
	v_rcp_f32_e32 v85, v85
	v_rcp_f32_e32 v86, v86
	v_rcp_f32_e32 v87, v87
	v_rcp_f32_e32 v88, v88
	v_rcp_f32_e32 v89, v89
	v_pk_mul_f32 v[68:69], v[68:69], v[80:81]
	v_pk_mul_f32 v[70:71], v[70:71], v[84:85]
	v_pk_mul_f32 v[72:73], v[72:73], v[86:87]
	v_pk_mul_f32 v[74:75], v[74:75], v[88:89]
	v_cvt_pk_bf16_f32 v64, v68, v69
	v_cvt_pk_bf16_f32 v65, v70, v71
	v_cvt_pk_bf16_f32 v66, v72, v73
	v_cvt_pk_bf16_f32 v67, v74, v75
	global_store_dwordx4 v[82:83], v[64:67], off sc1
	s_nop 0
	s_waitcnt vmcnt(7)
	v_cvt_f32_u32_e32 v64, v191
	v_cvt_f32_u32_e32 v66, v190
	v_add_u32_e32 v65, 0x80, v144
	v_fmamk_f32 v64, v66, 0x2f800000, v64
	v_fmamk_f32 v64, v64, 0x3a800000, v158
	v_rsq_f32_e32 v64, v64
	v_mad_i64_i32 v[66:67], s[38:39], v65, s51, v[146:147]
	v_lshl_add_u64 v[66:67], v[66:67], 0, v[148:149]
	v_mul_f32_e32 v190, 0xbfb8aa3b, v64
	v_mul_f32_e32 v191, v64, v64
	v_pk_mul_f32 v[64:65], v[60:61], v[190:191] op_sel_hi:[1,0]
	v_pk_mul_f32 v[68:69], v[62:63], v[190:191] op_sel_hi:[1,0]
	v_pk_mul_f32 v[70:71], v[56:57], v[190:191] op_sel_hi:[1,0]
	v_pk_mul_f32 v[72:73], v[58:59], v[190:191] op_sel_hi:[1,0]
	v_pk_mul_f32 v[52:53], v[52:53], v[60:61]
	v_pk_mul_f32 v[54:55], v[54:55], v[62:63]
	v_pk_mul_f32 v[56:57], v[48:49], v[56:57]
	v_pk_mul_f32 v[58:59], v[50:51], v[58:59]
	v_exp_f32_e32 v64, v64
	v_exp_f32_e32 v65, v65
	v_exp_f32_e32 v68, v68
	v_exp_f32_e32 v69, v69
	v_exp_f32_e32 v70, v70
	v_exp_f32_e32 v71, v71
	v_exp_f32_e32 v72, v72
	v_exp_f32_e32 v73, v73
	v_pk_mul_f32 v[52:53], v[52:53], v[190:191] op_sel:[0,1] op_sel_hi:[1,1]
	v_pk_mul_f32 v[54:55], v[54:55], v[190:191] op_sel:[0,1] op_sel_hi:[1,1]
	v_pk_mul_f32 v[56:57], v[56:57], v[190:191] op_sel:[0,1] op_sel_hi:[1,1]
	v_pk_mul_f32 v[58:59], v[58:59], v[190:191] op_sel:[0,1] op_sel_hi:[1,1]
	v_pk_add_f32 v[64:65], v[64:65], 1.0 op_sel_hi:[1,0]
	v_pk_add_f32 v[68:69], v[68:69], 1.0 op_sel_hi:[1,0]
	v_pk_add_f32 v[70:71], v[70:71], 1.0 op_sel_hi:[1,0]
	v_pk_add_f32 v[72:73], v[72:73], 1.0 op_sel_hi:[1,0]
	v_rcp_f32_e32 v64, v64
	v_rcp_f32_e32 v65, v65
	v_rcp_f32_e32 v68, v68
	v_rcp_f32_e32 v69, v69
	v_rcp_f32_e32 v70, v70
	v_rcp_f32_e32 v71, v71
	v_rcp_f32_e32 v72, v72
	v_rcp_f32_e32 v73, v73
	v_pk_mul_f32 v[52:53], v[52:53], v[64:65]
	v_pk_mul_f32 v[54:55], v[54:55], v[68:69]
	v_pk_mul_f32 v[56:57], v[56:57], v[70:71]
	v_pk_mul_f32 v[58:59], v[58:59], v[72:73]
	v_cvt_pk_bf16_f32 v48, v52, v53
	v_cvt_pk_bf16_f32 v49, v54, v55
	v_cvt_pk_bf16_f32 v50, v56, v57
	v_cvt_pk_bf16_f32 v51, v58, v59
	global_store_dwordx4 v[66:67], v[48:51], off sc1
	s_nop 0
	s_waitcnt vmcnt(7)
; __device__ __forceinline__ unsigned cvtpk(float lo, float hi) { f32x2v_ v = {lo, hi}; bf16x2v_ b = __builtin_convertvector(v, bf16x2v_); return __builtin_bit_cast(unsigned, b); }
;     __device__ __forceinline__ void operator()(const f32x4 (&acc)[2][2][4][2], const Unit& u, int wr, int wc, int fr, int fq) const {
;     ...
;             for (int m = 0; m < 4; ++m) { const int row = row0 + ai * HALF + m * 16; const float rs = row_rs(ss, row);
;                 float hv[8];
; #pragma unroll
;                 for (int n = 0; n < 2; ++n)
; #pragma unroll
;                     for (int i = 0; i < 4; ++i) { const float g = acc[ai][0][m][n][i] * rs, uu = acc[ai][1][m][n][i] * rs;
;                         hv[n * 4 + i] = g * __builtin_amdgcn_rcpf(1.0f + __expf(-g)) * uu; }
;                 u32x4 w; w.x = cvtpk(hv[0], hv[1]); w.y = cvtpk(hv[2], hv[3]); w.z = cvtpk(hv[4], hv[5]); w.w = cvtpk(hv[6], hv[7]);
;                 *(u32x4*)(H + (size_t)row * ldh + col0) = w; }
	v_cvt_f32_u32_e32 v48, v193
	v_cvt_f32_u32_e32 v50, v192
	v_add_u32_e32 v49, 0x90, v144
	v_fmamk_f32 v48, v50, 0x2f800000, v48
	v_fmamk_f32 v48, v48, 0x3a800000, v158
	v_rsq_f32_e32 v48, v48
	v_mad_i64_i32 v[50:51], s[38:39], v49, s51, v[146:147]
	v_lshl_add_u64 v[50:51], v[50:51], 0, v[148:149]
	v_mul_f32_e32 v192, 0xbfb8aa3b, v48
	v_mul_f32_e32 v193, v48, v48
	v_pk_mul_f32 v[48:49], v[44:45], v[192:193] op_sel_hi:[1,0]
	v_pk_mul_f32 v[52:53], v[46:47], v[192:193] op_sel_hi:[1,0]
	v_pk_mul_f32 v[54:55], v[40:41], v[192:193] op_sel_hi:[1,0]
	v_pk_mul_f32 v[56:57], v[42:43], v[192:193] op_sel_hi:[1,0]
	v_pk_mul_f32 v[36:37], v[36:37], v[44:45]
	v_pk_mul_f32 v[38:39], v[38:39], v[46:47]
	v_pk_mul_f32 v[40:41], v[32:33], v[40:41]
	v_pk_mul_f32 v[42:43], v[34:35], v[42:43]
	v_exp_f32_e32 v48, v48
	v_exp_f32_e32 v49, v49
	v_exp_f32_e32 v52, v52
	v_exp_f32_e32 v53, v53
	v_exp_f32_e32 v54, v54
	v_exp_f32_e32 v55, v55
	v_exp_f32_e32 v56, v56
	v_exp_f32_e32 v57, v57
	v_pk_mul_f32 v[36:37], v[36:37], v[192:193] op_sel:[0,1] op_sel_hi:[1,1]
	v_pk_mul_f32 v[38:39], v[38:39], v[192:193] op_sel:[0,1] op_sel_hi:[1,1]
	v_pk_mul_f32 v[40:41], v[40:41], v[192:193] op_sel:[0,1] op_sel_hi:[1,1]
	v_pk_mul_f32 v[42:43], v[42:43], v[192:193] op_sel:[0,1] op_sel_hi:[1,1]
	v_pk_add_f32 v[48:49], v[48:49], 1.0 op_sel_hi:[1,0]
	v_pk_add_f32 v[52:53], v[52:53], 1.0 op_sel_hi:[1,0]
	v_pk_add_f32 v[54:55], v[54:55], 1.0 op_sel_hi:[1,0]
	v_pk_add_f32 v[56:57], v[56:57], 1.0 op_sel_hi:[1,0]
	v_rcp_f32_e32 v48, v48
	v_rcp_f32_e32 v49, v49
	v_rcp_f32_e32 v52, v52
	v_rcp_f32_e32 v53, v53
	v_rcp_f32_e32 v54, v54
	v_rcp_f32_e32 v55, v55
	v_rcp_f32_e32 v56, v56
	v_rcp_f32_e32 v57, v57
	v_pk_mul_f32 v[36:37], v[36:37], v[48:49]
	v_pk_mul_f32 v[38:39], v[38:39], v[52:53]
	v_pk_mul_f32 v[40:41], v[40:41], v[54:55]
	v_pk_mul_f32 v[42:43], v[42:43], v[56:57]
	v_cvt_pk_bf16_f32 v32, v36, v37
	v_cvt_pk_bf16_f32 v33, v38, v39
	v_cvt_pk_bf16_f32 v34, v40, v41
	v_cvt_pk_bf16_f32 v35, v42, v43
	global_store_dwordx4 v[50:51], v[32:35], off sc1
	s_nop 0
	s_waitcnt vmcnt(7)
	v_cvt_f32_u32_e32 v32, v195
	v_cvt_f32_u32_e32 v34, v194
	v_add_u32_e32 v33, 0xa0, v144
	v_fmamk_f32 v32, v34, 0x2f800000, v32
	v_fmamk_f32 v32, v32, 0x3a800000, v158
	v_rsq_f32_e32 v32, v32
	v_mad_i64_i32 v[34:35], s[38:39], v33, s51, v[146:147]
	v_lshl_add_u64 v[34:35], v[34:35], 0, v[148:149]
	v_mul_f32_e32 v194, 0xbfb8aa3b, v32
	v_mul_f32_e32 v195, v32, v32
	v_pk_mul_f32 v[32:33], v[28:29], v[194:195] op_sel_hi:[1,0]
	v_pk_mul_f32 v[36:37], v[30:31], v[194:195] op_sel_hi:[1,0]
	v_pk_mul_f32 v[38:39], v[24:25], v[194:195] op_sel_hi:[1,0]
	v_pk_mul_f32 v[40:41], v[26:27], v[194:195] op_sel_hi:[1,0]
	v_pk_mul_f32 v[20:21], v[20:21], v[28:29]
	v_pk_mul_f32 v[22:23], v[22:23], v[30:31]
	v_pk_mul_f32 v[24:25], v[16:17], v[24:25]
	v_pk_mul_f32 v[26:27], v[18:19], v[26:27]
	v_exp_f32_e32 v32, v32
	v_exp_f32_e32 v33, v33
	v_exp_f32_e32 v36, v36
	v_exp_f32_e32 v37, v37
	v_exp_f32_e32 v38, v38
	v_exp_f32_e32 v39, v39
	v_exp_f32_e32 v40, v40
	v_exp_f32_e32 v41, v41
	v_pk_mul_f32 v[20:21], v[20:21], v[194:195] op_sel:[0,1] op_sel_hi:[1,1]
	v_pk_mul_f32 v[22:23], v[22:23], v[194:195] op_sel:[0,1] op_sel_hi:[1,1]
	v_pk_mul_f32 v[24:25], v[24:25], v[194:195] op_sel:[0,1] op_sel_hi:[1,1]
	v_pk_mul_f32 v[26:27], v[26:27], v[194:195] op_sel:[0,1] op_sel_hi:[1,1]
	v_pk_add_f32 v[32:33], v[32:33], 1.0 op_sel_hi:[1,0]
	v_pk_add_f32 v[36:37], v[36:37], 1.0 op_sel_hi:[1,0]
	v_pk_add_f32 v[38:39], v[38:39], 1.0 op_sel_hi:[1,0]
	v_pk_add_f32 v[40:41], v[40:41], 1.0 op_sel_hi:[1,0]
	v_rcp_f32_e32 v32, v32
	v_rcp_f32_e32 v33, v33
	v_rcp_f32_e32 v36, v36
	v_rcp_f32_e32 v37, v37
	v_rcp_f32_e32 v38, v38
	v_rcp_f32_e32 v39, v39
	v_rcp_f32_e32 v40, v40
	v_rcp_f32_e32 v41, v41
	v_pk_mul_f32 v[20:21], v[20:21], v[32:33]
	v_pk_mul_f32 v[22:23], v[22:23], v[36:37]
	v_pk_mul_f32 v[24:25], v[24:25], v[38:39]
	v_pk_mul_f32 v[26:27], v[26:27], v[40:41]
	v_cvt_pk_bf16_f32 v16, v20, v21
	v_cvt_pk_bf16_f32 v17, v22, v23
	v_cvt_pk_bf16_f32 v18, v24, v25
	v_cvt_pk_bf16_f32 v19, v26, v27
	global_store_dwordx4 v[34:35], v[16:19], off sc1
	s_nop 0
	s_waitcnt vmcnt(7)
	v_cvt_f32_u32_e32 v16, v197
	v_cvt_f32_u32_e32 v18, v196
	v_add_u32_e32 v17, 0xb0, v144
	v_fmamk_f32 v16, v18, 0x2f800000, v16
	v_fmamk_f32 v16, v16, 0x3a800000, v158
	v_rsq_f32_e32 v16, v16
	v_mad_i64_i32 v[18:19], s[38:39], v17, s51, v[146:147]
	v_lshl_add_u64 v[18:19], v[18:19], 0, v[148:149]
	v_mul_f32_e32 v196, 0xbfb8aa3b, v16
	v_mul_f32_e32 v197, v16, v16
	v_pk_mul_f32 v[16:17], v[12:13], v[196:197] op_sel_hi:[1,0]
	v_pk_mul_f32 v[20:21], v[14:15], v[196:197] op_sel_hi:[1,0]
	v_pk_mul_f32 v[22:23], v[8:9], v[196:197] op_sel_hi:[1,0]
	v_pk_mul_f32 v[24:25], v[10:11], v[196:197] op_sel_hi:[1,0]
	v_pk_mul_f32 v[4:5], v[4:5], v[12:13]
	v_pk_mul_f32 v[6:7], v[6:7], v[14:15]
	v_pk_mul_f32 v[8:9], v[0:1], v[8:9]
	v_pk_mul_f32 v[10:11], v[2:3], v[10:11]
	v_exp_f32_e32 v16, v16
	v_exp_f32_e32 v17, v17
	v_exp_f32_e32 v20, v20
	v_exp_f32_e32 v21, v21
	v_exp_f32_e32 v22, v22
	v_exp_f32_e32 v23, v23
	v_exp_f32_e32 v24, v24
	v_exp_f32_e32 v25, v25
	v_pk_mul_f32 v[4:5], v[4:5], v[196:197] op_sel:[0,1] op_sel_hi:[1,1]
	v_pk_mul_f32 v[6:7], v[6:7], v[196:197] op_sel:[0,1] op_sel_hi:[1,1]
	v_pk_mul_f32 v[8:9], v[8:9], v[196:197] op_sel:[0,1] op_sel_hi:[1,1]
	v_pk_mul_f32 v[10:11], v[10:11], v[196:197] op_sel:[0,1] op_sel_hi:[1,1]
	v_pk_add_f32 v[16:17], v[16:17], 1.0 op_sel_hi:[1,0]
	v_pk_add_f32 v[20:21], v[20:21], 1.0 op_sel_hi:[1,0]
	v_pk_add_f32 v[22:23], v[22:23], 1.0 op_sel_hi:[1,0]
	v_pk_add_f32 v[24:25], v[24:25], 1.0 op_sel_hi:[1,0]
	v_rcp_f32_e32 v16, v16
	v_rcp_f32_e32 v17, v17
	v_rcp_f32_e32 v20, v20
	v_rcp_f32_e32 v21, v21
	v_rcp_f32_e32 v22, v22
	v_rcp_f32_e32 v23, v23
	v_rcp_f32_e32 v24, v24
	v_rcp_f32_e32 v25, v25
	v_pk_mul_f32 v[4:5], v[4:5], v[16:17]
	v_pk_mul_f32 v[6:7], v[6:7], v[20:21]
	v_pk_mul_f32 v[8:9], v[8:9], v[22:23]
	v_pk_mul_f32 v[10:11], v[10:11], v[24:25]
	v_cvt_pk_bf16_f32 v0, v4, v5
	v_cvt_pk_bf16_f32 v1, v6, v7
	v_cvt_pk_bf16_f32 v2, v8, v9
	v_cvt_pk_bf16_f32 v3, v10, v11
	global_store_dwordx4 v[18:19], v[0:3], off sc1
	s_cbranch_vccnz .LBB0_1896
	s_andn2_b64 vcc, exec, s[6:7]
	s_cbranch_vccnz .LBB0_1895
	s_barrier
	s_branch .LBB0_1895

; __device__ __forceinline__ void fx_add(float* p, size_t idx, float s) { atomicAdd((unsigned long long*)p + idx, (unsigned long long)(long long)(s * 4294967296.0f)); }
; __device__ __forceinline__ unsigned cvtpk(float lo, float hi) { f32x2v_ v = {lo, hi}; bf16x2v_ b = __builtin_convertvector(v, bf16x2v_); return __builtin_bit_cast(unsigned, b); }
;     __device__ __forceinline__ void operator()(const f32x4 (&acc)[2][2][4][2], const Unit& u, int wr, int wc, int fr, int fq) const {
;     ...
;             for (int m = 0; m < 4; ++m) { const int row = row0 + ai * HALF + m * 16; const size_t off = (size_t)row * 1024 + col0; float s = 0.f;
; #pragma unroll
;                 for (int bj = 0; bj < 2; ++bj) { f32x4 a0, a1;
;                     if (xin32) { const float* p = xin32 + off + bj * HALF; a0 = *(const f32x4*)p; a1 = *(const f32x4*)(p + 4); }
;                     else { const u32x4 w = *(const u32x4*)(xb + off + bj * HALF);
;                         a0 = (f32x4){__uint_as_float(w.x << 16), __uint_as_float(w.x & 0xffff0000u), __uint_as_float(w.y << 16), __uint_as_float(w.y & 0xffff0000u)};
;                         a1 = (f32x4){__uint_as_float(w.z << 16), __uint_as_float(w.z & 0xffff0000u), __uint_as_float(w.w << 16), __uint_as_float(w.w & 0xffff0000u)}; }
;                     const f32x4 v0 = a0 + acc[ai][bj][m][0] * alpha, v1 = a1 + acc[ai][bj][m][1] * alpha;
;                     u32x4 w; w.x = cvtpk(v0[0], v0[1]); w.y = cvtpk(v0[2], v0[3]); w.z = cvtpk(v1[0], v1[1]); w.w = cvtpk(v1[2], v1[3]);
;                     *(u32x4*)(xb + off + bj * HALF) = w;
;                     s += (v0[0] * v0[0] + v0[1] * v0[1]) + (v0[2] * v0[2] + v0[3] * v0[3]) + (v1[0] * v1[0] + v1[1] * v1[1]) + (v1[2] * v1[2] + v1[3] * v1[3]); }
;                 s += __shfl_xor(s, 16); s += __shfl_xor(s, 32);
;                 if (fq == 0) fx_add(ssout, row, s); }
.LBB0_1981:
	v_lshl_add_u32 v146, s52, 8, v148
	v_ashrrev_i32_e32 v147, 31, v146
	v_lshl_or_b32 v144, s51, 8, v150
	v_lshlrev_b64 v[156:157], 11, v[146:147]
	v_ashrrev_i32_e32 v145, 31, v144
	v_lshl_add_u64 v[156:157], s[22:23], 0, v[156:157]
	v_lshl_add_u64 v[166:167], v[144:145], 1, v[156:157]
	global_load_dwordx4 v[158:161], v[166:167], off
	global_load_dwordx4 v[162:165], v[166:167], off offset:256
	v_and_b32_e32 v156, 64, v154
	v_xor_b32_e32 v155, 16, v154
	v_add_u32_e32 v156, 64, v156
	v_xor_b32_e32 v157, 32, v154
	v_cmp_lt_i32_e32 vcc, v155, v156
	s_waitcnt vmcnt(0)
	v_lshlrev_b32_e32 v168, 16, v158
	v_cndmask_b32_e32 v155, v154, v155, vcc
	v_cmp_lt_i32_e32 vcc, v157, v156
	v_and_b32_e32 v169, 0xffff0000, v158
	v_lshlrev_b32_e32 v158, 16, v159
	v_and_b32_e32 v159, 0xffff0000, v159
	v_lshlrev_b32_e32 v172, 16, v162
	v_and_b32_e32 v173, 0xffff0000, v162
	v_lshlrev_b32_e32 v162, 16, v163
	v_and_b32_e32 v163, 0xffff0000, v163
	v_cndmask_b32_e32 v157, v154, v157, vcc
	v_lshlrev_b32_e32 v170, 16, v160
	v_and_b32_e32 v171, 0xffff0000, v160
	v_lshlrev_b32_e32 v160, 16, v161
	v_and_b32_e32 v161, 0xffff0000, v161
	v_lshlrev_b32_e32 v174, 16, v164
	v_and_b32_e32 v175, 0xffff0000, v164
	v_lshlrev_b32_e32 v164, 16, v165
	v_and_b32_e32 v165, 0xffff0000, v165
	v_pk_fma_f32 v[126:127], v[126:127], 0.5, v[158:159] op_sel_hi:[1,0,1]
	v_pk_fma_f32 v[124:125], v[124:125], 0.5, v[168:169] op_sel_hi:[1,0,1]
	v_pk_fma_f32 v[118:119], v[118:119], 0.5, v[162:163] op_sel_hi:[1,0,1]
	v_pk_fma_f32 v[116:117], v[116:117], 0.5, v[172:173] op_sel_hi:[1,0,1]
	v_lshlrev_b32_e32 v156, 2, v155
	v_lshlrev_b32_e32 v155, 2, v157
	v_pk_fma_f32 v[122:123], v[122:123], 0.5, v[160:161] op_sel_hi:[1,0,1]
	v_pk_fma_f32 v[120:121], v[120:121], 0.5, v[170:171] op_sel_hi:[1,0,1]
	v_pk_fma_f32 v[158:159], v[114:115], 0.5, v[164:165] op_sel_hi:[1,0,1]
	v_pk_fma_f32 v[160:161], v[112:113], 0.5, v[174:175] op_sel_hi:[1,0,1]
	v_mul_f32_e32 v114, v125, v125
	v_mul_f32_e32 v115, v127, v127
	v_mul_f32_e32 v157, v117, v117
	v_mul_f32_e32 v162, v119, v119
	v_cvt_pk_bf16_f32 v112, v124, v125
	v_mul_f32_e32 v125, v121, v121
	v_mul_f32_e32 v163, v161, v161
	v_fmac_f32_e32 v114, v124, v124
	v_fmac_f32_e32 v115, v126, v126
	v_fmac_f32_e32 v157, v116, v116
	v_fmac_f32_e32 v162, v118, v118
	v_cvt_pk_bf16_f32 v113, v126, v127
	v_mul_f32_e32 v127, v123, v123
	v_mul_f32_e32 v164, v159, v159
	v_fmac_f32_e32 v125, v120, v120
	v_fmac_f32_e32 v163, v160, v160
	v_add_f32_e32 v114, v114, v115
	v_add_f32_e32 v115, v157, v162
	v_fmac_f32_e32 v127, v122, v122
	v_fmac_f32_e32 v164, v158, v158
	v_add_f32_e32 v114, v125, v114
	v_add_f32_e32 v115, v163, v115
	v_add_f32_e32 v114, v127, v114
	v_add_f32_e32 v115, v164, v115
	v_add_f32_e32 v124, v114, v115
	v_mov_b32_e32 v125, v124
	s_nop 1
	v_permlane16_swap_b32_e32 v125, v124
	v_cvt_pk_bf16_f32 v114, v120, v121
	v_cvt_pk_bf16_f32 v115, v122, v123
	global_store_dwordx4 v[166:167], v[112:115], off sc1
	s_waitcnt lgkmcnt(0)
	s_nop 0
	v_add_f32_e32 v112, v124, v125
	v_mov_b32_e32 v113, v112
	s_nop 1
	v_permlane32_swap_b32_e32 v113, v112
	v_cvt_pk_bf16_f32 v114, v116, v117
	v_cvt_pk_bf16_f32 v115, v118, v119
	v_cvt_pk_bf16_f32 v116, v160, v161
	v_cvt_pk_bf16_f32 v117, v158, v159
	global_store_dwordx4 v[166:167], v[114:117], off offset:256 sc1
	s_and_saveexec_b64 s[26:27], s[6:7]
	s_cbranch_execz .LBB0_1983
	s_waitcnt lgkmcnt(0)
	v_add_f32_e32 v112, v112, v113
	v_mul_f32_e32 v112, 0x4f800000, v112
	v_trunc_f32_e32 v112, v112
	v_mul_f32_e64 v113, |v112|, s47
	v_floor_f32_e32 v113, v113
	v_fma_f32 v114, v113, s48, |v112|
	v_cvt_u32_f32_e32 v112, v114
	v_cvt_u32_f32_e32 v113, v113
	v_lshl_add_u64 v[114:115], v[146:147], 3, s[10:11]
	global_atomic_add_x2 v[114:115], v[112:113], off
.LBB0_1983:
	s_or_b64 exec, exec, s[26:27]
	v_or_b32_e32 v112, 16, v146
	s_waitcnt lgkmcnt(0)
	v_ashrrev_i32_e32 v113, 31, v112
	v_lshlrev_b64 v[114:115], 11, v[112:113]
	v_lshl_add_u64 v[114:115], s[22:23], 0, v[114:115]
	v_lshl_add_u64 v[122:123], v[144:145], 1, v[114:115]
	global_load_dwordx4 v[114:117], v[122:123], off
	global_load_dwordx4 v[118:121], v[122:123], off offset:256
	s_waitcnt vmcnt(1)
	v_lshlrev_b32_e32 v124, 16, v114
	v_and_b32_e32 v125, 0xffff0000, v114
	v_lshlrev_b32_e32 v114, 16, v115
	v_and_b32_e32 v115, 0xffff0000, v115
	s_waitcnt vmcnt(0)
	v_lshlrev_b32_e32 v158, 16, v118
	v_and_b32_e32 v159, 0xffff0000, v118
	v_lshlrev_b32_e32 v118, 16, v119
	v_and_b32_e32 v119, 0xffff0000, v119
	v_lshlrev_b32_e32 v126, 16, v116
	v_and_b32_e32 v127, 0xffff0000, v116
	v_lshlrev_b32_e32 v116, 16, v117
	v_and_b32_e32 v117, 0xffff0000, v117
	v_lshlrev_b32_e32 v160, 16, v120
	v_and_b32_e32 v161, 0xffff0000, v120
	v_lshlrev_b32_e32 v120, 16, v121
	v_and_b32_e32 v121, 0xffff0000, v121
	v_pk_fma_f32 v[110:111], v[110:111], 0.5, v[114:115] op_sel_hi:[1,0,1]
	v_pk_fma_f32 v[108:109], v[108:109], 0.5, v[124:125] op_sel_hi:[1,0,1]
	v_pk_fma_f32 v[102:103], v[102:103], 0.5, v[118:119] op_sel_hi:[1,0,1]
	v_pk_fma_f32 v[100:101], v[100:101], 0.5, v[158:159] op_sel_hi:[1,0,1]
	v_pk_fma_f32 v[106:107], v[106:107], 0.5, v[116:117] op_sel_hi:[1,0,1]
	v_pk_fma_f32 v[104:105], v[104:105], 0.5, v[126:127] op_sel_hi:[1,0,1]
	v_pk_fma_f32 v[114:115], v[98:99], 0.5, v[120:121] op_sel_hi:[1,0,1]
	v_pk_fma_f32 v[116:117], v[96:97], 0.5, v[160:161] op_sel_hi:[1,0,1]
	v_mul_f32_e32 v98, v109, v109
	v_mul_f32_e32 v99, v111, v111
	v_mul_f32_e32 v118, v101, v101
	v_mul_f32_e32 v119, v103, v103
	v_cvt_pk_bf16_f32 v96, v108, v109
	v_mul_f32_e32 v109, v105, v105
	v_mul_f32_e32 v120, v117, v117
	v_fmac_f32_e32 v98, v108, v108
	v_fmac_f32_e32 v99, v110, v110
	v_fmac_f32_e32 v118, v100, v100
	v_fmac_f32_e32 v119, v102, v102
	v_cvt_pk_bf16_f32 v97, v110, v111
	v_mul_f32_e32 v111, v107, v107
	v_mul_f32_e32 v121, v115, v115
	v_fmac_f32_e32 v109, v104, v104
	v_fmac_f32_e32 v120, v116, v116
	v_add_f32_e32 v98, v98, v99
	v_add_f32_e32 v99, v118, v119
	v_fmac_f32_e32 v111, v106, v106
	v_fmac_f32_e32 v121, v114, v114
	v_add_f32_e32 v98, v109, v98
	v_add_f32_e32 v99, v120, v99
	v_add_f32_e32 v98, v111, v98
	v_add_f32_e32 v99, v121, v99
	v_add_f32_e32 v108, v98, v99
	v_mov_b32_e32 v109, v108
	s_nop 1
	v_permlane16_swap_b32_e32 v109, v108
	v_cvt_pk_bf16_f32 v98, v104, v105
	v_cvt_pk_bf16_f32 v99, v106, v107
	global_store_dwordx4 v[122:123], v[96:99], off sc1
	s_waitcnt lgkmcnt(0)
	s_nop 0
	v_add_f32_e32 v96, v108, v109
	v_mov_b32_e32 v97, v96
	s_nop 1
	v_permlane32_swap_b32_e32 v97, v96
	v_cvt_pk_bf16_f32 v98, v100, v101
	v_cvt_pk_bf16_f32 v99, v102, v103
	v_cvt_pk_bf16_f32 v100, v116, v117
	v_cvt_pk_bf16_f32 v101, v114, v115
	global_store_dwordx4 v[122:123], v[98:101], off offset:256 sc1
	s_and_saveexec_b64 s[26:27], s[6:7]
	s_cbranch_execz .LBB0_1985
	s_waitcnt lgkmcnt(0)
	v_add_f32_e32 v96, v96, v97
	v_mul_f32_e32 v96, 0x4f800000, v96
	v_trunc_f32_e32 v96, v96
	v_mul_f32_e64 v97, |v96|, s47
	v_floor_f32_e32 v97, v97
	v_fma_f32 v98, v97, s48, |v96|
	v_cvt_u32_f32_e32 v96, v98
	v_cvt_u32_f32_e32 v97, v97
	v_lshl_add_u64 v[98:99], v[112:113], 3, s[10:11]
	global_atomic_add_x2 v[98:99], v[96:97], off
; __device__ __forceinline__ void fx_add(float* p, size_t idx, float s) { atomicAdd((unsigned long long*)p + idx, (unsigned long long)(long long)(s * 4294967296.0f)); }
; __device__ __forceinline__ unsigned cvtpk(float lo, float hi) { f32x2v_ v = {lo, hi}; bf16x2v_ b = __builtin_convertvector(v, bf16x2v_); return __builtin_bit_cast(unsigned, b); }
;     __device__ __forceinline__ void operator()(const f32x4 (&acc)[2][2][4][2], const Unit& u, int wr, int wc, int fr, int fq) const {
;     ...
;             for (int m = 0; m < 4; ++m) { const int row = row0 + ai * HALF + m * 16; const size_t off = (size_t)row * 1024 + col0; float s = 0.f;
; #pragma unroll
;                 for (int bj = 0; bj < 2; ++bj) { f32x4 a0, a1;
;                     if (xin32) { const float* p = xin32 + off + bj * HALF; a0 = *(const f32x4*)p; a1 = *(const f32x4*)(p + 4); }
;                     else { const u32x4 w = *(const u32x4*)(xb + off + bj * HALF);
;                         a0 = (f32x4){__uint_as_float(w.x << 16), __uint_as_float(w.x & 0xffff0000u), __uint_as_float(w.y << 16), __uint_as_float(w.y & 0xffff0000u)};
;                         a1 = (f32x4){__uint_as_float(w.z << 16), __uint_as_float(w.z & 0xffff0000u), __uint_as_float(w.w << 16), __uint_as_float(w.w & 0xffff0000u)}; }
;                     const f32x4 v0 = a0 + acc[ai][bj][m][0] * alpha, v1 = a1 + acc[ai][bj][m][1] * alpha;
;                     u32x4 w; w.x = cvtpk(v0[0], v0[1]); w.y = cvtpk(v0[2], v0[3]); w.z = cvtpk(v1[0], v1[1]); w.w = cvtpk(v1[2], v1[3]);
;                     *(u32x4*)(xb + off + bj * HALF) = w;
;                     s += (v0[0] * v0[0] + v0[1] * v0[1]) + (v0[2] * v0[2] + v0[3] * v0[3]) + (v1[0] * v1[0] + v1[1] * v1[1]) + (v1[2] * v1[2] + v1[3] * v1[3]); }
;                 s += __shfl_xor(s, 16); s += __shfl_xor(s, 32);
;                 if (fq == 0) fx_add(ssout, row, s); }
.LBB0_1985:
	s_or_b64 exec, exec, s[26:27]
	v_or_b32_e32 v96, 32, v146
	s_waitcnt lgkmcnt(0)
	v_ashrrev_i32_e32 v97, 31, v96
	v_lshlrev_b64 v[98:99], 11, v[96:97]
	v_lshl_add_u64 v[98:99], s[22:23], 0, v[98:99]
	v_lshl_add_u64 v[106:107], v[144:145], 1, v[98:99]
	global_load_dwordx4 v[98:101], v[106:107], off
	global_load_dwordx4 v[102:105], v[106:107], off offset:256
	s_waitcnt vmcnt(1)
	v_lshlrev_b32_e32 v108, 16, v98
	v_and_b32_e32 v109, 0xffff0000, v98
	v_lshlrev_b32_e32 v98, 16, v99
	v_and_b32_e32 v99, 0xffff0000, v99
	s_waitcnt vmcnt(0)
	v_lshlrev_b32_e32 v112, 16, v102
	v_and_b32_e32 v113, 0xffff0000, v102
	v_lshlrev_b32_e32 v102, 16, v103
	v_and_b32_e32 v103, 0xffff0000, v103
	v_lshlrev_b32_e32 v110, 16, v100
	v_and_b32_e32 v111, 0xffff0000, v100
	v_lshlrev_b32_e32 v100, 16, v101
	v_and_b32_e32 v101, 0xffff0000, v101
	v_lshlrev_b32_e32 v114, 16, v104
	v_and_b32_e32 v115, 0xffff0000, v104
	v_lshlrev_b32_e32 v104, 16, v105
	v_and_b32_e32 v105, 0xffff0000, v105
	v_pk_fma_f32 v[94:95], v[94:95], 0.5, v[98:99] op_sel_hi:[1,0,1]
	v_pk_fma_f32 v[92:93], v[92:93], 0.5, v[108:109] op_sel_hi:[1,0,1]
	v_pk_fma_f32 v[86:87], v[86:87], 0.5, v[102:103] op_sel_hi:[1,0,1]
	v_pk_fma_f32 v[84:85], v[84:85], 0.5, v[112:113] op_sel_hi:[1,0,1]
	v_pk_fma_f32 v[90:91], v[90:91], 0.5, v[100:101] op_sel_hi:[1,0,1]
	v_pk_fma_f32 v[88:89], v[88:89], 0.5, v[110:111] op_sel_hi:[1,0,1]
	v_pk_fma_f32 v[98:99], v[82:83], 0.5, v[104:105] op_sel_hi:[1,0,1]
	v_pk_fma_f32 v[100:101], v[80:81], 0.5, v[114:115] op_sel_hi:[1,0,1]
	v_mul_f32_e32 v82, v93, v93
	v_mul_f32_e32 v83, v95, v95
	v_mul_f32_e32 v102, v85, v85
	v_mul_f32_e32 v103, v87, v87
	v_cvt_pk_bf16_f32 v80, v92, v93
	v_mul_f32_e32 v93, v89, v89
	v_mul_f32_e32 v104, v101, v101
	v_fmac_f32_e32 v82, v92, v92
	v_fmac_f32_e32 v83, v94, v94
	v_fmac_f32_e32 v102, v84, v84
	v_fmac_f32_e32 v103, v86, v86
	v_cvt_pk_bf16_f32 v81, v94, v95
	v_mul_f32_e32 v95, v91, v91
	v_mul_f32_e32 v105, v99, v99
	v_fmac_f32_e32 v93, v88, v88
	v_fmac_f32_e32 v104, v100, v100
	v_add_f32_e32 v82, v82, v83
	v_add_f32_e32 v83, v102, v103
	v_fmac_f32_e32 v95, v90, v90
	v_fmac_f32_e32 v105, v98, v98
	v_add_f32_e32 v82, v93, v82
	v_add_f32_e32 v83, v104, v83
	v_add_f32_e32 v82, v95, v82
	v_add_f32_e32 v83, v105, v83
	v_add_f32_e32 v92, v82, v83
	v_mov_b32_e32 v93, v92
	s_nop 1
	v_permlane16_swap_b32_e32 v93, v92
	v_cvt_pk_bf16_f32 v82, v88, v89
	v_cvt_pk_bf16_f32 v83, v90, v91
	global_store_dwordx4 v[106:107], v[80:83], off sc1
	s_waitcnt lgkmcnt(0)
	s_nop 0
	v_add_f32_e32 v80, v92, v93
	v_mov_b32_e32 v81, v80
	s_nop 1
	v_permlane32_swap_b32_e32 v81, v80
	v_cvt_pk_bf16_f32 v82, v84, v85
	v_cvt_pk_bf16_f32 v83, v86, v87
	v_cvt_pk_bf16_f32 v84, v100, v101
	v_cvt_pk_bf16_f32 v85, v98, v99
	global_store_dwordx4 v[106:107], v[82:85], off offset:256 sc1
	s_and_saveexec_b64 s[26:27], s[6:7]
	s_cbranch_execz .LBB0_1987
	s_waitcnt lgkmcnt(0)
	v_add_f32_e32 v80, v80, v81
	v_mul_f32_e32 v80, 0x4f800000, v80
	v_trunc_f32_e32 v80, v80
	v_mul_f32_e64 v81, |v80|, s47
	v_floor_f32_e32 v81, v81
	v_fma_f32 v82, v81, s48, |v80|
	v_cvt_u32_f32_e32 v80, v82
	v_cvt_u32_f32_e32 v81, v81
	v_lshl_add_u64 v[82:83], v[96:97], 3, s[10:11]
	global_atomic_add_x2 v[82:83], v[80:81], off
.LBB0_1987:
	s_or_b64 exec, exec, s[26:27]
	v_or_b32_e32 v80, 48, v146
	s_waitcnt lgkmcnt(0)
	v_ashrrev_i32_e32 v81, 31, v80
	v_lshlrev_b64 v[82:83], 11, v[80:81]
	v_lshl_add_u64 v[82:83], s[22:23], 0, v[82:83]
	v_lshl_add_u64 v[90:91], v[144:145], 1, v[82:83]
	global_load_dwordx4 v[82:85], v[90:91], off
	global_load_dwordx4 v[86:89], v[90:91], off offset:256
	s_waitcnt vmcnt(1)
	v_lshlrev_b32_e32 v92, 16, v82
	v_and_b32_e32 v93, 0xffff0000, v82
	v_lshlrev_b32_e32 v82, 16, v83
	v_and_b32_e32 v83, 0xffff0000, v83
	s_waitcnt vmcnt(0)
	v_lshlrev_b32_e32 v96, 16, v86
	v_and_b32_e32 v97, 0xffff0000, v86
	v_lshlrev_b32_e32 v86, 16, v87
	v_and_b32_e32 v87, 0xffff0000, v87
	v_lshlrev_b32_e32 v94, 16, v84
	v_and_b32_e32 v95, 0xffff0000, v84
	v_lshlrev_b32_e32 v84, 16, v85
	v_and_b32_e32 v85, 0xffff0000, v85
	v_lshlrev_b32_e32 v98, 16, v88
	v_and_b32_e32 v99, 0xffff0000, v88
	v_lshlrev_b32_e32 v88, 16, v89
	v_and_b32_e32 v89, 0xffff0000, v89
	v_pk_fma_f32 v[78:79], v[78:79], 0.5, v[82:83] op_sel_hi:[1,0,1]
	v_pk_fma_f32 v[76:77], v[76:77], 0.5, v[92:93] op_sel_hi:[1,0,1]
	v_pk_fma_f32 v[70:71], v[70:71], 0.5, v[86:87] op_sel_hi:[1,0,1]
	v_pk_fma_f32 v[68:69], v[68:69], 0.5, v[96:97] op_sel_hi:[1,0,1]
	v_pk_fma_f32 v[74:75], v[74:75], 0.5, v[84:85] op_sel_hi:[1,0,1]
	v_pk_fma_f32 v[72:73], v[72:73], 0.5, v[94:95] op_sel_hi:[1,0,1]
	v_pk_fma_f32 v[82:83], v[66:67], 0.5, v[88:89] op_sel_hi:[1,0,1]
	v_pk_fma_f32 v[84:85], v[64:65], 0.5, v[98:99] op_sel_hi:[1,0,1]
	v_mul_f32_e32 v66, v77, v77
	v_mul_f32_e32 v67, v79, v79
	v_mul_f32_e32 v86, v69, v69
	v_mul_f32_e32 v87, v71, v71
	v_cvt_pk_bf16_f32 v64, v76, v77
	v_mul_f32_e32 v77, v73, v73
	v_mul_f32_e32 v88, v85, v85
	v_fmac_f32_e32 v66, v76, v76
	v_fmac_f32_e32 v67, v78, v78
	v_fmac_f32_e32 v86, v68, v68
	v_fmac_f32_e32 v87, v70, v70
	v_cvt_pk_bf16_f32 v65, v78, v79
	v_mul_f32_e32 v79, v75, v75
	v_mul_f32_e32 v89, v83, v83
	v_fmac_f32_e32 v77, v72, v72
	v_fmac_f32_e32 v88, v84, v84
	v_add_f32_e32 v66, v66, v67
	v_add_f32_e32 v67, v86, v87
	v_fmac_f32_e32 v79, v74, v74
	v_fmac_f32_e32 v89, v82, v82
	v_add_f32_e32 v66, v77, v66
	v_add_f32_e32 v67, v88, v67
	v_add_f32_e32 v66, v79, v66
	v_add_f32_e32 v67, v89, v67
	v_add_f32_e32 v76, v66, v67
	v_mov_b32_e32 v77, v76
	s_nop 1
	v_permlane16_swap_b32_e32 v77, v76
	v_cvt_pk_bf16_f32 v66, v72, v73
	v_cvt_pk_bf16_f32 v67, v74, v75
	global_store_dwordx4 v[90:91], v[64:67], off sc1
	s_waitcnt lgkmcnt(0)
	s_nop 0
	v_add_f32_e32 v64, v76, v77
	v_mov_b32_e32 v65, v64
	s_nop 1
	v_permlane32_swap_b32_e32 v65, v64
	v_cvt_pk_bf16_f32 v66, v68, v69
	v_cvt_pk_bf16_f32 v67, v70, v71
	v_cvt_pk_bf16_f32 v68, v84, v85
	v_cvt_pk_bf16_f32 v69, v82, v83
	global_store_dwordx4 v[90:91], v[66:69], off offset:256 sc1
	s_and_saveexec_b64 s[26:27], s[6:7]
	s_cbranch_execz .LBB0_1989
	s_waitcnt lgkmcnt(0)
	v_add_f32_e32 v64, v64, v65
	v_mul_f32_e32 v64, 0x4f800000, v64
	v_trunc_f32_e32 v64, v64
	v_mul_f32_e64 v65, |v64|, s47
	v_floor_f32_e32 v65, v65
	v_fma_f32 v66, v65, s48, |v64|
	v_cvt_u32_f32_e32 v64, v66
	v_cvt_u32_f32_e32 v65, v65
	v_lshl_add_u64 v[66:67], v[80:81], 3, s[10:11]
	global_atomic_add_x2 v[66:67], v[64:65], off
; __device__ __forceinline__ void fx_add(float* p, size_t idx, float s) { atomicAdd((unsigned long long*)p + idx, (unsigned long long)(long long)(s * 4294967296.0f)); }
; __device__ __forceinline__ unsigned cvtpk(float lo, float hi) { f32x2v_ v = {lo, hi}; bf16x2v_ b = __builtin_convertvector(v, bf16x2v_); return __builtin_bit_cast(unsigned, b); }
;     __device__ __forceinline__ void operator()(const f32x4 (&acc)[2][2][4][2], const Unit& u, int wr, int wc, int fr, int fq) const {
;     ...
;             for (int m = 0; m < 4; ++m) { const int row = row0 + ai * HALF + m * 16; const size_t off = (size_t)row * 1024 + col0; float s = 0.f;
; #pragma unroll
;                 for (int bj = 0; bj < 2; ++bj) { f32x4 a0, a1;
;                     if (xin32) { const float* p = xin32 + off + bj * HALF; a0 = *(const f32x4*)p; a1 = *(const f32x4*)(p + 4); }
;                     else { const u32x4 w = *(const u32x4*)(xb + off + bj * HALF);
;                         a0 = (f32x4){__uint_as_float(w.x << 16), __uint_as_float(w.x & 0xffff0000u), __uint_as_float(w.y << 16), __uint_as_float(w.y & 0xffff0000u)};
;                         a1 = (f32x4){__uint_as_float(w.z << 16), __uint_as_float(w.z & 0xffff0000u), __uint_as_float(w.w << 16), __uint_as_float(w.w & 0xffff0000u)}; }
;                     const f32x4 v0 = a0 + acc[ai][bj][m][0] * alpha, v1 = a1 + acc[ai][bj][m][1] * alpha;
;                     u32x4 w; w.x = cvtpk(v0[0], v0[1]); w.y = cvtpk(v0[2], v0[3]); w.z = cvtpk(v1[0], v1[1]); w.w = cvtpk(v1[2], v1[3]);
;                     *(u32x4*)(xb + off + bj * HALF) = w;
;                     s += (v0[0] * v0[0] + v0[1] * v0[1]) + (v0[2] * v0[2] + v0[3] * v0[3]) + (v1[0] * v1[0] + v1[1] * v1[1]) + (v1[2] * v1[2] + v1[3] * v1[3]); }
;                 s += __shfl_xor(s, 16); s += __shfl_xor(s, 32);
;                 if (fq == 0) fx_add(ssout, row, s); }
.LBB0_1989:
	s_or_b64 exec, exec, s[26:27]
	v_add_u32_e32 v64, 0x80, v146
	s_waitcnt lgkmcnt(0)
	v_ashrrev_i32_e32 v65, 31, v64
	v_lshlrev_b64 v[66:67], 11, v[64:65]
	v_lshl_add_u64 v[66:67], s[22:23], 0, v[66:67]
	v_lshl_add_u64 v[74:75], v[144:145], 1, v[66:67]
	global_load_dwordx4 v[66:69], v[74:75], off
	global_load_dwordx4 v[70:73], v[74:75], off offset:256
	s_waitcnt vmcnt(1)
	v_lshlrev_b32_e32 v76, 16, v66
	v_and_b32_e32 v77, 0xffff0000, v66
	v_lshlrev_b32_e32 v66, 16, v67
	v_and_b32_e32 v67, 0xffff0000, v67
	s_waitcnt vmcnt(0)
	v_lshlrev_b32_e32 v80, 16, v70
	v_and_b32_e32 v81, 0xffff0000, v70
	v_lshlrev_b32_e32 v70, 16, v71
	v_and_b32_e32 v71, 0xffff0000, v71
	v_lshlrev_b32_e32 v78, 16, v68
	v_and_b32_e32 v79, 0xffff0000, v68
	v_lshlrev_b32_e32 v68, 16, v69
	v_and_b32_e32 v69, 0xffff0000, v69
	v_lshlrev_b32_e32 v82, 16, v72
	v_and_b32_e32 v83, 0xffff0000, v72
	v_lshlrev_b32_e32 v72, 16, v73
	v_and_b32_e32 v73, 0xffff0000, v73
	v_pk_fma_f32 v[62:63], v[62:63], 0.5, v[66:67] op_sel_hi:[1,0,1]
	v_pk_fma_f32 v[60:61], v[60:61], 0.5, v[76:77] op_sel_hi:[1,0,1]
	v_pk_fma_f32 v[54:55], v[54:55], 0.5, v[70:71] op_sel_hi:[1,0,1]
	v_pk_fma_f32 v[52:53], v[52:53], 0.5, v[80:81] op_sel_hi:[1,0,1]
	v_pk_fma_f32 v[58:59], v[58:59], 0.5, v[68:69] op_sel_hi:[1,0,1]
	v_pk_fma_f32 v[56:57], v[56:57], 0.5, v[78:79] op_sel_hi:[1,0,1]
	v_pk_fma_f32 v[66:67], v[50:51], 0.5, v[72:73] op_sel_hi:[1,0,1]
	v_pk_fma_f32 v[68:69], v[48:49], 0.5, v[82:83] op_sel_hi:[1,0,1]
	v_mul_f32_e32 v50, v61, v61
	v_mul_f32_e32 v51, v63, v63
	v_mul_f32_e32 v70, v53, v53
	v_mul_f32_e32 v71, v55, v55
	v_cvt_pk_bf16_f32 v48, v60, v61
	v_mul_f32_e32 v61, v57, v57
	v_mul_f32_e32 v72, v69, v69
	v_fmac_f32_e32 v50, v60, v60
	v_fmac_f32_e32 v51, v62, v62
	v_fmac_f32_e32 v70, v52, v52
	v_fmac_f32_e32 v71, v54, v54
	v_cvt_pk_bf16_f32 v49, v62, v63
	v_mul_f32_e32 v63, v59, v59
	v_mul_f32_e32 v73, v67, v67
	v_fmac_f32_e32 v61, v56, v56
	v_fmac_f32_e32 v72, v68, v68
	v_add_f32_e32 v50, v50, v51
	v_add_f32_e32 v51, v70, v71
	v_fmac_f32_e32 v63, v58, v58
	v_fmac_f32_e32 v73, v66, v66
	v_add_f32_e32 v50, v61, v50
	v_add_f32_e32 v51, v72, v51
	v_add_f32_e32 v50, v63, v50
	v_add_f32_e32 v51, v73, v51
	v_add_f32_e32 v60, v50, v51
	v_mov_b32_e32 v61, v60
	s_nop 1
	v_permlane16_swap_b32_e32 v61, v60
	v_cvt_pk_bf16_f32 v50, v56, v57
	v_cvt_pk_bf16_f32 v51, v58, v59
	global_store_dwordx4 v[74:75], v[48:51], off sc1
	s_waitcnt lgkmcnt(0)
	s_nop 0
	v_add_f32_e32 v48, v60, v61
	v_mov_b32_e32 v49, v48
	s_nop 1
	v_permlane32_swap_b32_e32 v49, v48
	v_cvt_pk_bf16_f32 v50, v52, v53
	v_cvt_pk_bf16_f32 v51, v54, v55
	v_cvt_pk_bf16_f32 v52, v68, v69
	v_cvt_pk_bf16_f32 v53, v66, v67
	global_store_dwordx4 v[74:75], v[50:53], off offset:256 sc1
	s_and_saveexec_b64 s[26:27], s[6:7]
	s_cbranch_execz .LBB0_1991
	s_waitcnt lgkmcnt(0)
	v_add_f32_e32 v48, v48, v49
	v_mul_f32_e32 v48, 0x4f800000, v48
	v_trunc_f32_e32 v48, v48
	v_mul_f32_e64 v49, |v48|, s47
	v_floor_f32_e32 v49, v49
	v_fma_f32 v50, v49, s48, |v48|
	v_cvt_u32_f32_e32 v48, v50
	v_cvt_u32_f32_e32 v49, v49
	v_lshl_add_u64 v[50:51], v[64:65], 3, s[10:11]
	global_atomic_add_x2 v[50:51], v[48:49], off
.LBB0_1991:
	s_or_b64 exec, exec, s[26:27]
	v_add_u32_e32 v48, 0x90, v146
	s_waitcnt lgkmcnt(0)
	v_ashrrev_i32_e32 v49, 31, v48
	v_lshlrev_b64 v[50:51], 11, v[48:49]
	v_lshl_add_u64 v[50:51], s[22:23], 0, v[50:51]
	v_lshl_add_u64 v[58:59], v[144:145], 1, v[50:51]
	global_load_dwordx4 v[50:53], v[58:59], off
	global_load_dwordx4 v[54:57], v[58:59], off offset:256
	s_waitcnt vmcnt(1)
	v_lshlrev_b32_e32 v60, 16, v50
	v_and_b32_e32 v61, 0xffff0000, v50
	v_lshlrev_b32_e32 v50, 16, v51
	v_and_b32_e32 v51, 0xffff0000, v51
	s_waitcnt vmcnt(0)
	v_lshlrev_b32_e32 v64, 16, v54
	v_and_b32_e32 v65, 0xffff0000, v54
	v_lshlrev_b32_e32 v54, 16, v55
	v_and_b32_e32 v55, 0xffff0000, v55
	v_lshlrev_b32_e32 v62, 16, v52
	v_and_b32_e32 v63, 0xffff0000, v52
	v_lshlrev_b32_e32 v52, 16, v53
	v_and_b32_e32 v53, 0xffff0000, v53
	v_lshlrev_b32_e32 v66, 16, v56
	v_and_b32_e32 v67, 0xffff0000, v56
	v_lshlrev_b32_e32 v56, 16, v57
	v_and_b32_e32 v57, 0xffff0000, v57
	v_pk_fma_f32 v[46:47], v[46:47], 0.5, v[50:51] op_sel_hi:[1,0,1]
	v_pk_fma_f32 v[44:45], v[44:45], 0.5, v[60:61] op_sel_hi:[1,0,1]
	v_pk_fma_f32 v[38:39], v[38:39], 0.5, v[54:55] op_sel_hi:[1,0,1]
	v_pk_fma_f32 v[36:37], v[36:37], 0.5, v[64:65] op_sel_hi:[1,0,1]
	v_pk_fma_f32 v[42:43], v[42:43], 0.5, v[52:53] op_sel_hi:[1,0,1]
	v_pk_fma_f32 v[40:41], v[40:41], 0.5, v[62:63] op_sel_hi:[1,0,1]
	v_pk_fma_f32 v[50:51], v[34:35], 0.5, v[56:57] op_sel_hi:[1,0,1]
	v_pk_fma_f32 v[52:53], v[32:33], 0.5, v[66:67] op_sel_hi:[1,0,1]
	v_mul_f32_e32 v34, v45, v45
	v_mul_f32_e32 v35, v47, v47
	v_mul_f32_e32 v54, v37, v37
	v_mul_f32_e32 v55, v39, v39
	v_cvt_pk_bf16_f32 v32, v44, v45
	v_mul_f32_e32 v45, v41, v41
	v_mul_f32_e32 v56, v53, v53
	v_fmac_f32_e32 v34, v44, v44
	v_fmac_f32_e32 v35, v46, v46
	v_fmac_f32_e32 v54, v36, v36
	v_fmac_f32_e32 v55, v38, v38
	v_cvt_pk_bf16_f32 v33, v46, v47
	v_mul_f32_e32 v47, v43, v43
	v_mul_f32_e32 v57, v51, v51
	v_fmac_f32_e32 v45, v40, v40
	v_fmac_f32_e32 v56, v52, v52
	v_add_f32_e32 v34, v34, v35
	v_add_f32_e32 v35, v54, v55
	v_fmac_f32_e32 v47, v42, v42
	v_fmac_f32_e32 v57, v50, v50
	v_add_f32_e32 v34, v45, v34
	v_add_f32_e32 v35, v56, v35
	v_add_f32_e32 v34, v47, v34
	v_add_f32_e32 v35, v57, v35
	v_add_f32_e32 v44, v34, v35
	v_mov_b32_e32 v45, v44
	s_nop 1
	v_permlane16_swap_b32_e32 v45, v44
	v_cvt_pk_bf16_f32 v34, v40, v41
	v_cvt_pk_bf16_f32 v35, v42, v43
	global_store_dwordx4 v[58:59], v[32:35], off sc1
	s_waitcnt lgkmcnt(0)
	s_nop 0
	v_add_f32_e32 v32, v44, v45
	v_mov_b32_e32 v33, v32
	s_nop 1
	v_permlane32_swap_b32_e32 v33, v32
	v_cvt_pk_bf16_f32 v34, v36, v37
	v_cvt_pk_bf16_f32 v35, v38, v39
	v_cvt_pk_bf16_f32 v36, v52, v53
	v_cvt_pk_bf16_f32 v37, v50, v51
	global_store_dwordx4 v[58:59], v[34:37], off offset:256 sc1
	s_and_saveexec_b64 s[26:27], s[6:7]
	s_cbranch_execz .LBB0_1993
	s_waitcnt lgkmcnt(0)
	v_add_f32_e32 v32, v32, v33
	v_mul_f32_e32 v32, 0x4f800000, v32
	v_trunc_f32_e32 v32, v32
	v_mul_f32_e64 v33, |v32|, s47
	v_floor_f32_e32 v33, v33
	v_fma_f32 v34, v33, s48, |v32|
	v_cvt_u32_f32_e32 v32, v34
	v_cvt_u32_f32_e32 v33, v33
	v_lshl_add_u64 v[34:35], v[48:49], 3, s[10:11]
	global_atomic_add_x2 v[34:35], v[32:33], off
; __device__ __forceinline__ void fx_add(float* p, size_t idx, float s) { atomicAdd((unsigned long long*)p + idx, (unsigned long long)(long long)(s * 4294967296.0f)); }
; __device__ __forceinline__ unsigned cvtpk(float lo, float hi) { f32x2v_ v = {lo, hi}; bf16x2v_ b = __builtin_convertvector(v, bf16x2v_); return __builtin_bit_cast(unsigned, b); }
;     __device__ __forceinline__ void operator()(const f32x4 (&acc)[2][2][4][2], const Unit& u, int wr, int wc, int fr, int fq) const {
;     ...
;             for (int m = 0; m < 4; ++m) { const int row = row0 + ai * HALF + m * 16; const size_t off = (size_t)row * 1024 + col0; float s = 0.f;
; #pragma unroll
;                 for (int bj = 0; bj < 2; ++bj) { f32x4 a0, a1;
;                     if (xin32) { const float* p = xin32 + off + bj * HALF; a0 = *(const f32x4*)p; a1 = *(const f32x4*)(p + 4); }
;                     else { const u32x4 w = *(const u32x4*)(xb + off + bj * HALF);
;                         a0 = (f32x4){__uint_as_float(w.x << 16), __uint_as_float(w.x & 0xffff0000u), __uint_as_float(w.y << 16), __uint_as_float(w.y & 0xffff0000u)};
;                         a1 = (f32x4){__uint_as_float(w.z << 16), __uint_as_float(w.z & 0xffff0000u), __uint_as_float(w.w << 16), __uint_as_float(w.w & 0xffff0000u)}; }
;                     const f32x4 v0 = a0 + acc[ai][bj][m][0] * alpha, v1 = a1 + acc[ai][bj][m][1] * alpha;
;                     u32x4 w; w.x = cvtpk(v0[0], v0[1]); w.y = cvtpk(v0[2], v0[3]); w.z = cvtpk(v1[0], v1[1]); w.w = cvtpk(v1[2], v1[3]);
;                     *(u32x4*)(xb + off + bj * HALF) = w;
;                     s += (v0[0] * v0[0] + v0[1] * v0[1]) + (v0[2] * v0[2] + v0[3] * v0[3]) + (v1[0] * v1[0] + v1[1] * v1[1]) + (v1[2] * v1[2] + v1[3] * v1[3]); }
;                 s += __shfl_xor(s, 16); s += __shfl_xor(s, 32);
;                 if (fq == 0) fx_add(ssout, row, s); }
.LBB0_1993:
	s_or_b64 exec, exec, s[26:27]
	v_add_u32_e32 v32, 0xa0, v146
	s_waitcnt lgkmcnt(0)
	v_ashrrev_i32_e32 v33, 31, v32
	v_lshlrev_b64 v[34:35], 11, v[32:33]
	v_lshl_add_u64 v[34:35], s[22:23], 0, v[34:35]
	v_lshl_add_u64 v[42:43], v[144:145], 1, v[34:35]
	global_load_dwordx4 v[34:37], v[42:43], off
	global_load_dwordx4 v[38:41], v[42:43], off offset:256
	s_waitcnt vmcnt(1)
	v_lshlrev_b32_e32 v44, 16, v34
	v_and_b32_e32 v45, 0xffff0000, v34
	v_lshlrev_b32_e32 v34, 16, v35
	v_and_b32_e32 v35, 0xffff0000, v35
	s_waitcnt vmcnt(0)
	v_lshlrev_b32_e32 v48, 16, v38
	v_and_b32_e32 v49, 0xffff0000, v38
	v_lshlrev_b32_e32 v38, 16, v39
	v_and_b32_e32 v39, 0xffff0000, v39
	v_lshlrev_b32_e32 v46, 16, v36
	v_and_b32_e32 v47, 0xffff0000, v36
	v_lshlrev_b32_e32 v36, 16, v37
	v_and_b32_e32 v37, 0xffff0000, v37
	v_lshlrev_b32_e32 v50, 16, v40
	v_and_b32_e32 v51, 0xffff0000, v40
	v_lshlrev_b32_e32 v40, 16, v41
	v_and_b32_e32 v41, 0xffff0000, v41
	v_pk_fma_f32 v[30:31], v[30:31], 0.5, v[34:35] op_sel_hi:[1,0,1]
	v_pk_fma_f32 v[28:29], v[28:29], 0.5, v[44:45] op_sel_hi:[1,0,1]
	v_pk_fma_f32 v[22:23], v[22:23], 0.5, v[38:39] op_sel_hi:[1,0,1]
	v_pk_fma_f32 v[20:21], v[20:21], 0.5, v[48:49] op_sel_hi:[1,0,1]
	v_pk_fma_f32 v[26:27], v[26:27], 0.5, v[36:37] op_sel_hi:[1,0,1]
	v_pk_fma_f32 v[24:25], v[24:25], 0.5, v[46:47] op_sel_hi:[1,0,1]
	v_pk_fma_f32 v[34:35], v[18:19], 0.5, v[40:41] op_sel_hi:[1,0,1]
	v_pk_fma_f32 v[36:37], v[16:17], 0.5, v[50:51] op_sel_hi:[1,0,1]
	v_mul_f32_e32 v18, v29, v29
	v_mul_f32_e32 v19, v31, v31
	v_mul_f32_e32 v38, v21, v21
	v_mul_f32_e32 v39, v23, v23
	v_cvt_pk_bf16_f32 v16, v28, v29
	v_mul_f32_e32 v29, v25, v25
	v_mul_f32_e32 v40, v37, v37
	v_fmac_f32_e32 v18, v28, v28
	v_fmac_f32_e32 v19, v30, v30
	v_fmac_f32_e32 v38, v20, v20
	v_fmac_f32_e32 v39, v22, v22
	v_cvt_pk_bf16_f32 v17, v30, v31
	v_mul_f32_e32 v31, v27, v27
	v_mul_f32_e32 v41, v35, v35
	v_fmac_f32_e32 v29, v24, v24
	v_fmac_f32_e32 v40, v36, v36
	v_add_f32_e32 v18, v18, v19
	v_add_f32_e32 v19, v38, v39
	v_fmac_f32_e32 v31, v26, v26
	v_fmac_f32_e32 v41, v34, v34
	v_add_f32_e32 v18, v29, v18
	v_add_f32_e32 v19, v40, v19
	v_add_f32_e32 v18, v31, v18
	v_add_f32_e32 v19, v41, v19
	v_add_f32_e32 v28, v18, v19
	v_mov_b32_e32 v29, v28
	s_nop 1
	v_permlane16_swap_b32_e32 v29, v28
	v_cvt_pk_bf16_f32 v18, v24, v25
	v_cvt_pk_bf16_f32 v19, v26, v27
	global_store_dwordx4 v[42:43], v[16:19], off sc1
	s_waitcnt lgkmcnt(0)
	s_nop 0
	v_add_f32_e32 v16, v28, v29
	v_mov_b32_e32 v17, v16
	s_nop 1
	v_permlane32_swap_b32_e32 v17, v16
	v_cvt_pk_bf16_f32 v18, v20, v21
	v_cvt_pk_bf16_f32 v19, v22, v23
	v_cvt_pk_bf16_f32 v20, v36, v37
	v_cvt_pk_bf16_f32 v21, v34, v35
	global_store_dwordx4 v[42:43], v[18:21], off offset:256 sc1
	s_and_saveexec_b64 s[26:27], s[6:7]
	s_cbranch_execz .LBB0_1995
	s_waitcnt lgkmcnt(0)
	v_add_f32_e32 v16, v16, v17
	v_mul_f32_e32 v16, 0x4f800000, v16
	v_trunc_f32_e32 v16, v16
	v_mul_f32_e64 v17, |v16|, s47
	v_floor_f32_e32 v17, v17
	v_fma_f32 v18, v17, s48, |v16|
	v_cvt_u32_f32_e32 v16, v18
	v_cvt_u32_f32_e32 v17, v17
	v_lshl_add_u64 v[18:19], v[32:33], 3, s[10:11]
	global_atomic_add_x2 v[18:19], v[16:17], off
.LBB0_1995:
	s_or_b64 exec, exec, s[26:27]
	v_add_u32_e32 v16, 0xb0, v146
	s_waitcnt lgkmcnt(0)
	v_ashrrev_i32_e32 v17, 31, v16
	v_lshlrev_b64 v[18:19], 11, v[16:17]
	v_lshl_add_u64 v[18:19], s[22:23], 0, v[18:19]
	v_lshl_add_u64 v[26:27], v[144:145], 1, v[18:19]
	global_load_dwordx4 v[18:21], v[26:27], off
	global_load_dwordx4 v[22:25], v[26:27], off offset:256
	s_waitcnt vmcnt(1)
	v_lshlrev_b32_e32 v28, 16, v18
	v_and_b32_e32 v29, 0xffff0000, v18
	v_lshlrev_b32_e32 v18, 16, v19
	v_and_b32_e32 v19, 0xffff0000, v19
	s_waitcnt vmcnt(0)
	v_lshlrev_b32_e32 v32, 16, v22
	v_and_b32_e32 v33, 0xffff0000, v22
	v_lshlrev_b32_e32 v22, 16, v23
	v_and_b32_e32 v23, 0xffff0000, v23
	v_lshlrev_b32_e32 v30, 16, v20
	v_and_b32_e32 v31, 0xffff0000, v20
	v_lshlrev_b32_e32 v20, 16, v21
	v_and_b32_e32 v21, 0xffff0000, v21
	v_lshlrev_b32_e32 v34, 16, v24
	v_and_b32_e32 v35, 0xffff0000, v24
	v_lshlrev_b32_e32 v24, 16, v25
	v_and_b32_e32 v25, 0xffff0000, v25
	v_pk_fma_f32 v[14:15], v[14:15], 0.5, v[18:19] op_sel_hi:[1,0,1]
	v_pk_fma_f32 v[12:13], v[12:13], 0.5, v[28:29] op_sel_hi:[1,0,1]
	v_pk_fma_f32 v[6:7], v[6:7], 0.5, v[22:23] op_sel_hi:[1,0,1]
	v_pk_fma_f32 v[4:5], v[4:5], 0.5, v[32:33] op_sel_hi:[1,0,1]
	v_pk_fma_f32 v[10:11], v[10:11], 0.5, v[20:21] op_sel_hi:[1,0,1]
	v_pk_fma_f32 v[8:9], v[8:9], 0.5, v[30:31] op_sel_hi:[1,0,1]
	v_pk_fma_f32 v[18:19], v[2:3], 0.5, v[24:25] op_sel_hi:[1,0,1]
	v_pk_fma_f32 v[20:21], v[0:1], 0.5, v[34:35] op_sel_hi:[1,0,1]
	v_mul_f32_e32 v2, v13, v13
	v_mul_f32_e32 v3, v15, v15
	v_mul_f32_e32 v22, v5, v5
	v_mul_f32_e32 v23, v7, v7
	v_cvt_pk_bf16_f32 v0, v12, v13
	v_mul_f32_e32 v13, v9, v9
	v_mul_f32_e32 v24, v21, v21
	v_fmac_f32_e32 v2, v12, v12
	v_fmac_f32_e32 v3, v14, v14
	v_fmac_f32_e32 v22, v4, v4
	v_fmac_f32_e32 v23, v6, v6
	v_cvt_pk_bf16_f32 v1, v14, v15
	v_mul_f32_e32 v15, v11, v11
	v_mul_f32_e32 v25, v19, v19
	v_fmac_f32_e32 v13, v8, v8
	v_fmac_f32_e32 v24, v20, v20
	v_add_f32_e32 v2, v2, v3
	v_add_f32_e32 v3, v22, v23
	v_fmac_f32_e32 v15, v10, v10
	v_fmac_f32_e32 v25, v18, v18
	v_add_f32_e32 v2, v13, v2
	v_add_f32_e32 v3, v24, v3
	v_add_f32_e32 v2, v15, v2
	v_add_f32_e32 v3, v25, v3
	v_add_f32_e32 v12, v2, v3
	v_mov_b32_e32 v13, v12
	s_nop 1
	v_permlane16_swap_b32_e32 v13, v12
	v_cvt_pk_bf16_f32 v2, v8, v9
	v_cvt_pk_bf16_f32 v3, v10, v11
	global_store_dwordx4 v[26:27], v[0:3], off sc1
	s_waitcnt lgkmcnt(0)
	s_nop 0
	v_add_f32_e32 v0, v12, v13
	v_mov_b32_e32 v1, v0
	s_nop 1
	v_permlane32_swap_b32_e32 v1, v0
	v_cvt_pk_bf16_f32 v2, v4, v5
	v_cvt_pk_bf16_f32 v3, v6, v7
	v_cvt_pk_bf16_f32 v4, v20, v21
	v_cvt_pk_bf16_f32 v5, v18, v19
	global_store_dwordx4 v[26:27], v[2:5], off offset:256 sc1
	s_and_saveexec_b64 s[26:27], s[6:7]
	s_cbranch_execz .LBB0_1997
	s_waitcnt lgkmcnt(0)
	v_add_f32_e32 v0, v0, v1
	v_mul_f32_e32 v0, 0x4f800000, v0
	v_trunc_f32_e32 v0, v0
	v_mul_f32_e64 v1, |v0|, s47
	v_floor_f32_e32 v1, v1
	v_fma_f32 v2, v1, s48, |v0|
	v_cvt_u32_f32_e32 v0, v2
	v_cvt_u32_f32_e32 v1, v1
	v_lshl_add_u64 v[2:3], v[16:17], 3, s[10:11]
	global_atomic_add_x2 v[2:3], v[0:1], off
